# ResLN epilogues: lane^16 / lane^32 statistics reductions by v_permlane16/32_swap in place instead of ds_bpermute pairs (two exposed LDS round trips per row removed; bit-identical), lgkmcnt re-derived
# baseline (speedup 1.0000x reference)
;     __device__ __forceinline__ void operator()(const f32x4 (&acc)[2][2][4][2], const Unit& u, int wr, int wc, int fr, int fq, const EpiCtx& X) const {
;     ...
;         f32x2* ps = PSn + ((size_t)u.pm * BM + wr * 64 + fe) * 64 + u.pn * 4 + wc;
; #pragma unroll
;         for (int ai = 0; ai < 2; ++ai) {
;             u32x4 raw[8];
; #pragma unroll
;             for (int m = 0; m < 4; ++m) { const unsigned off = lo + (unsigned)((ai * HALF + m * 16) * 64) * 2u; raw[2 * m] = *(const u32x4*)(xb + off); raw[2 * m + 1] = *(const u32x4*)(xb + off + 128); }
; #pragma unroll
;             for (int m = 0; m < 4; ++m) {
;                 const int rl = ai * HALF + m * 16; const unsigned off = lo + (unsigned)(rl * 64) * 2u;
;                 const f32x4 o0a = acc[ai][0][m][0], o0b = acc[ai][0][m][1], o1a = acc[ai][1][m][0], o1b = acc[ai][1][m][1];
;                 const f32x4 ra_ = dpp_swap1(odd ? o0a : o1a), rb_ = dpp_swap1(odd ? o0b : o1b);
;                 const f32x4 pa[2] = {odd ? ra_ : o0a, odd ? o1a : ra_}, pb[2] = {odd ? rb_ : o0b, odd ? o1b : rb_};
; #pragma unroll
;                 for (int q = 0; q < 2; ++q) {
;                     const u32x4 w0 = raw[2 * m + q];
;                     const f32x4 r0 = (f32x4){bf_lo(w0.x), bf_hi(w0.x), bf_lo(w0.y), bf_hi(w0.y)}, r1 = (f32x4){bf_lo(w0.z), bf_hi(w0.z), bf_lo(w0.w), bf_hi(w0.w)};
;                     f32x4 y0, y1;
;                     if (RESN) { const f32x2 t = tbl[rl + q]; const float mu = t.x, ra = t.y * ALPHA; y0 = (r0 - mu) * ra * g0 + b0 + pa[q]; y1 = (r1 - mu) * ra * g1 + b1 + pb[q]; }
;                     else { y0 = r0 * ALPHA + pa[q]; y1 = r1 * ALPHA + pb[q]; }
;                     { const u32x4 w = pack8f(y0, y1); *(u32x4*)(xb + off + q * 128) = w;
;                         y0 = (f32x4){bf_lo(w.x), bf_hi(w.x), bf_lo(w.y), bf_hi(w.y)}; y1 = (f32x4){bf_lo(w.z), bf_hi(w.z), bf_lo(w.w), bf_hi(w.w)}; }
;                     float sa = ((y0[0] + y0[1]) + (y0[2] + y0[3])) + ((y1[0] + y1[1]) + (y1[2] + y1[3]));
;                     float sb = ((y0[0] * y0[0] + y0[1] * y0[1]) + (y0[2] * y0[2] + y0[3] * y0[3])) + ((y1[0] * y1[0] + y1[1] * y1[1]) + (y1[2] * y1[2] + y1[3] * y1[3]));
;                     sa += dpp_x1(sa);
;                     sb += dpp_x1(sb);
;                     sa += __shfl_xor(sa, 16); sa += __shfl_xor(sa, 32); sb += __shfl_xor(sb, 16); sb += __shfl_xor(sb, 32);
.LBB0_582:
	s_ashr_i32 s57, s56, 31
	s_lshl_b64 s[52:53], s[56:57], 21
	s_add_u32 s21, s46, s52
	s_addc_u32 s23, s47, s53
	s_lshl_b32 s58, s54, 2
	s_or_b32 s52, s58, s41
	s_ashr_i32 s53, s52, 31
	s_lshl_b64 s[52:53], s[52:53], 15
	s_add_u32 s54, s21, s52
	s_addc_u32 s55, s23, s53
	v_mov_b32_e32 v164, v183
	global_load_dwordx4 v[194:197], v164, s[54:55]
	v_add_u32_e32 v180, 0x800, v164
	v_add_u32_e32 v178, 0x1000, v164
	v_add_u32_e32 v176, 0x1800, v164
	global_load_dwordx4 v[152:155], v164, s[54:55] offset:128
	global_load_dwordx4 v[148:151], v180, s[54:55]
	global_load_dwordx4 v[144:147], v180, s[54:55] offset:128
	global_load_dwordx4 v[140:143], v178, s[54:55]
	global_load_dwordx4 v[136:139], v178, s[54:55] offset:128
	global_load_dwordx4 v[132:135], v176, s[54:55]
	global_load_dwordx4 v[120:123], v176, s[54:55] offset:128
	v_cndmask_b32_e64 v199, v129, v117, s[8:9]
	v_cndmask_b32_e64 v200, v128, v116, s[8:9]
	v_mov_b32_e32 v177, 0
	v_mov_b32_e32 v181, 0
	v_cndmask_b32_e64 v201, v127, v115, s[8:9]
	v_cndmask_b32_e64 v202, v126, v114, s[8:9]
	v_cndmask_b32_e64 v203, v125, v113, s[8:9]
	v_cndmask_b32_e64 v204, v124, v112, s[8:9]
	v_mov_b32_e32 v189, 0
	v_mov_b32_e32 v191, 0
	v_mov_b32_e32 v190, 0
	v_mov_b32_e32 v192, 0
	v_cndmask_b32_e64 v193, v131, v119, s[8:9]
	v_cndmask_b32_e64 v198, v130, v118, s[8:9]
	v_mov_b32_e32 v179, 0
	v_mov_b32_e32 v188, 0
	v_mov_b32_dpp v177, v200 quad_perm:[1,0,3,2] row_mask:0xf bank_mask:0xf
	v_mov_b32_dpp v181, v199 quad_perm:[1,0,3,2] row_mask:0xf bank_mask:0xf
	v_mov_b32_dpp v189, v204 quad_perm:[1,0,3,2] row_mask:0xf bank_mask:0xf
	v_mov_b32_dpp v191, v203 quad_perm:[1,0,3,2] row_mask:0xf bank_mask:0xf
	v_mov_b32_dpp v190, v202 quad_perm:[1,0,3,2] row_mask:0xf bank_mask:0xf
	v_mov_b32_dpp v192, v201 quad_perm:[1,0,3,2] row_mask:0xf bank_mask:0xf
	v_mov_b32_dpp v179, v198 quad_perm:[1,0,3,2] row_mask:0xf bank_mask:0xf
	v_mov_b32_dpp v188, v193 quad_perm:[1,0,3,2] row_mask:0xf bank_mask:0xf
	v_cndmask_b32_e64 v129, v181, v129, s[8:9]
	v_cndmask_b32_e64 v128, v177, v128, s[8:9]
	v_cndmask_b32_e64 v125, v191, v125, s[8:9]
	v_cndmask_b32_e64 v124, v189, v124, s[8:9]
	v_cndmask_b32_e64 v127, v192, v127, s[8:9]
	v_cndmask_b32_e64 v126, v190, v126, s[8:9]
	v_and_b32_e32 v206, 64, v187
	v_cndmask_b32_e64 v131, v188, v131, s[8:9]
	v_cndmask_b32_e64 v130, v179, v130, s[8:9]
	v_xor_b32_e32 v205, 16, v187
	v_add_u32_e32 v193, 64, v206
	v_cmp_lt_i32_e32 vcc, v205, v193
	s_lshl_b64 s[52:53], s[56:57], 17
	v_lshl_add_u64 v[198:199], v[166:167], 0, s[52:53]
	v_cndmask_b32_e32 v210, v187, v205, vcc
	s_ashr_i32 s59, s58, 31
	v_add_u32_e32 v246, 0x4000, v164
	v_add_u32_e32 v247, 0x4800, v164
	global_load_dwordx4 v[230:233], v246, s[54:55]
	global_load_dwordx4 v[234:237], v246, s[54:55] offset:128
	global_load_dwordx4 v[238:241], v247, s[54:55]
	global_load_dwordx4 v[242:245], v247, s[54:55] offset:128
	s_waitcnt vmcnt(11)
	v_lshlrev_b32_e32 v200, 16, v194
	v_and_b32_e32 v201, 0xffff0000, v194
	v_lshlrev_b32_e32 v202, 16, v196
	v_and_b32_e32 v203, 0xffff0000, v196
	v_lshlrev_b32_e32 v196, 16, v197
	v_and_b32_e32 v197, 0xffff0000, v197
	v_lshlrev_b32_e32 v194, 16, v195
	v_and_b32_e32 v195, 0xffff0000, v195
	v_pk_fma_f32 v[128:129], v[200:201], s[18:19], v[128:129] op_sel_hi:[1,0,1]
	v_pk_fma_f32 v[126:127], v[196:197], s[18:19], v[126:127] op_sel_hi:[1,0,1]
	v_pk_fma_f32 v[124:125], v[202:203], s[18:19], v[124:125] op_sel_hi:[1,0,1]
	v_pk_fma_f32 v[130:131], v[194:195], s[18:19], v[130:131] op_sel_hi:[1,0,1]
	v_cvt_pk_bf16_f32 v194, v128, v129
	s_nop 0
	v_cvt_pk_bf16_f32 v195, v130, v131
	v_cvt_pk_bf16_f32 v196, v124, v125
	v_cvt_pk_bf16_f32 v197, v126, v127
	v_lshlrev_b32_e32 v124, 16, v194
	v_and_b32_e32 v126, 0xffff0000, v194
	v_lshlrev_b32_e32 v128, 16, v195
	v_and_b32_e32 v200, 0xffff0000, v195
	v_lshlrev_b32_e32 v202, 16, v196
	v_and_b32_e32 v204, 0xffff0000, v196
	v_lshlrev_b32_e32 v206, 16, v197
	v_and_b32_e32 v208, 0xffff0000, v197
	v_mul_f32_e32 v125, v124, v124
	v_mul_f32_e32 v127, v126, v126
	v_mul_f32_e32 v129, v128, v128
	v_mul_f32_e32 v201, v200, v200
	v_mul_f32_e32 v203, v202, v202
	v_mul_f32_e32 v205, v204, v204
	v_mul_f32_e32 v207, v206, v206
	v_mul_f32_e32 v209, v208, v208
	v_pk_add_f32 v[124:125], v[124:125], v[126:127]
	v_pk_add_f32 v[126:127], v[128:129], v[200:201]
	v_pk_add_f32 v[128:129], v[206:207], v[208:209]
	v_pk_add_f32 v[124:125], v[124:125], v[126:127]
	v_pk_add_f32 v[126:127], v[202:203], v[204:205]
	v_lshlrev_b32_e32 v130, 2, v210
	v_pk_add_f32 v[126:127], v[126:127], v[128:129]
	v_xor_b32_e32 v128, 32, v187
	v_pk_add_f32 v[124:125], v[124:125], v[126:127]
	v_mov_b32_e32 v126, 0
	v_mov_b32_e32 v127, 0
	v_cmp_lt_i32_e32 vcc, v128, v193
	v_mov_b32_dpp v126, v124 quad_perm:[1,0,3,2] row_mask:0xf bank_mask:0xf
	v_mov_b32_dpp v127, v125 quad_perm:[1,0,3,2] row_mask:0xf bank_mask:0xf
	v_pk_add_f32 v[124:125], v[124:125], v[126:127]
	v_mov_b32_e32 v126, v124
	v_mov_b32_e32 v127, v125
	s_nop 1
	v_permlane16_swap_b32_e32 v124, v126
	v_permlane16_swap_b32_e32 v125, v127
	v_cndmask_b32_e32 v128, v187, v128, vcc
	v_lshlrev_b32_e32 v131, 2, v128
	global_store_dwordx4 v164, v[194:197], s[54:55]
	s_waitcnt lgkmcnt(0)
	v_pk_add_f32 v[126:127], v[124:125], v[126:127]
	v_mov_b32_e32 v128, v126
	v_mov_b32_e32 v129, v127
	s_nop 1
	v_permlane32_swap_b32_e32 v126, v128
	v_permlane32_swap_b32_e32 v127, v129
	v_lshl_add_u64 v[124:125], s[58:59], 3, v[198:199]
	v_lshl_add_u64 v[124:125], v[124:125], 0, s[14:15]
	s_and_saveexec_b64 s[52:53], s[10:11]
	s_waitcnt lgkmcnt(0)
	v_pk_add_f32 v[126:127], v[126:127], v[128:129]
	global_store_dwordx2 v[124:125], v[126:127], off
; __device__ __forceinline__ u32x4 pack8f(f32x4 a, f32x4 b) { u32x4 w; w.x = cvt_pk_bf16(a[0], a[1]); w.y = cvt_pk_bf16(a[2], a[3]); w.z = cvt_pk_bf16(b[0], b[1]); w.w = cvt_pk_bf16(b[2], b[3]); return w; }
;     __device__ __forceinline__ void operator()(const f32x4 (&acc)[2][2][4][2], const Unit& u, int wr, int wc, int fr, int fq, const EpiCtx& X) const {
;     ...
;             for (int m = 0; m < 4; ++m) {
;                 const int rl = ai * HALF + m * 16; const unsigned off = lo + (unsigned)(rl * 64) * 2u;
;                 const f32x4 o0a = acc[ai][0][m][0], o0b = acc[ai][0][m][1], o1a = acc[ai][1][m][0], o1b = acc[ai][1][m][1];
;                 const f32x4 ra_ = dpp_swap1(odd ? o0a : o1a), rb_ = dpp_swap1(odd ? o0b : o1b);
;                 const f32x4 pa[2] = {odd ? ra_ : o0a, odd ? o1a : ra_}, pb[2] = {odd ? rb_ : o0b, odd ? o1b : rb_};
; #pragma unroll
;                 for (int q = 0; q < 2; ++q) {
;                     const u32x4 w0 = raw[2 * m + q];
;                     const f32x4 r0 = (f32x4){bf_lo(w0.x), bf_hi(w0.x), bf_lo(w0.y), bf_hi(w0.y)}, r1 = (f32x4){bf_lo(w0.z), bf_hi(w0.z), bf_lo(w0.w), bf_hi(w0.w)};
;                     f32x4 y0, y1;
;                     if (RESN) { const f32x2 t = tbl[rl + q]; const float mu = t.x, ra = t.y * ALPHA; y0 = (r0 - mu) * ra * g0 + b0 + pa[q]; y1 = (r1 - mu) * ra * g1 + b1 + pb[q]; }
;                     else { y0 = r0 * ALPHA + pa[q]; y1 = r1 * ALPHA + pb[q]; }
;                     { const u32x4 w = pack8f(y0, y1); *(u32x4*)(xb + off + q * 128) = w;
;                         y0 = (f32x4){bf_lo(w.x), bf_hi(w.x), bf_lo(w.y), bf_hi(w.y)}; y1 = (f32x4){bf_lo(w.z), bf_hi(w.z), bf_lo(w.w), bf_hi(w.w)}; }
;                     float sa = ((y0[0] + y0[1]) + (y0[2] + y0[3])) + ((y1[0] + y1[1]) + (y1[2] + y1[3]));
;                     float sb = ((y0[0] * y0[0] + y0[1] * y0[1]) + (y0[2] * y0[2] + y0[3] * y0[3])) + ((y1[0] * y1[0] + y1[1] * y1[1]) + (y1[2] * y1[2] + y1[3] * y1[3]));
;                     sa += dpp_x1(sa);
;                     sb += dpp_x1(sb);
;                     sa += __shfl_xor(sa, 16); sa += __shfl_xor(sa, 32); sb += __shfl_xor(sb, 16); sb += __shfl_xor(sb, 32);
;                     if (fq == 0 && !odd) ps[(size_t)(rl + q) * 64] = (f32x2){sa, sb};
.LBB0_584:
	s_or_b64 exec, exec, s[52:53]
	v_cndmask_b32_e64 v117, v117, v181, s[8:9]
	v_cndmask_b32_e64 v116, v116, v177, s[8:9]
	v_cndmask_b32_e64 v119, v119, v188, s[8:9]
	v_cndmask_b32_e64 v118, v118, v179, s[8:9]
	v_cndmask_b32_e64 v113, v113, v191, s[8:9]
	v_cndmask_b32_e64 v112, v112, v189, s[8:9]
	v_cndmask_b32_e64 v115, v115, v192, s[8:9]
	v_cndmask_b32_e64 v114, v114, v190, s[8:9]
	s_waitcnt vmcnt(12)
	v_lshlrev_b32_e32 v126, 16, v152
	v_and_b32_e32 v127, 0xffff0000, v152
	s_waitcnt lgkmcnt(0)
	v_lshlrev_b32_e32 v128, 16, v153
	s_waitcnt lgkmcnt(0)
	v_and_b32_e32 v129, 0xffff0000, v153
	v_lshlrev_b32_e32 v152, 16, v154
	v_and_b32_e32 v153, 0xffff0000, v154
	v_lshlrev_b32_e32 v154, 16, v155
	v_and_b32_e32 v155, 0xffff0000, v155
	v_pk_fma_f32 v[118:119], v[128:129], s[18:19], v[118:119] op_sel_hi:[1,0,1]
	v_pk_fma_f32 v[116:117], v[126:127], s[18:19], v[116:117] op_sel_hi:[1,0,1]
	v_pk_fma_f32 v[114:115], v[154:155], s[18:19], v[114:115] op_sel_hi:[1,0,1]
	v_pk_fma_f32 v[112:113], v[152:153], s[18:19], v[112:113] op_sel_hi:[1,0,1]
	v_cvt_pk_bf16_f32 v116, v116, v117
	v_cvt_pk_bf16_f32 v117, v118, v119
	s_nop 0
	v_cvt_pk_bf16_f32 v118, v112, v113
	v_cvt_pk_bf16_f32 v119, v114, v115
	v_lshlrev_b32_e32 v112, 16, v116
	v_and_b32_e32 v114, 0xffff0000, v116
	v_lshlrev_b32_e32 v126, 16, v117
	v_and_b32_e32 v128, 0xffff0000, v117
	v_lshlrev_b32_e32 v152, 16, v118
	v_and_b32_e32 v154, 0xffff0000, v118
	v_lshlrev_b32_e32 v188, 16, v119
	v_and_b32_e32 v190, 0xffff0000, v119
	v_mul_f32_e32 v113, v112, v112
	v_mul_f32_e32 v115, v114, v114
	v_mul_f32_e32 v127, v126, v126
	v_mul_f32_e32 v129, v128, v128
	v_mul_f32_e32 v153, v152, v152
	v_mul_f32_e32 v155, v154, v154
	v_mul_f32_e32 v189, v188, v188
	v_mul_f32_e32 v191, v190, v190
	v_pk_add_f32 v[112:113], v[112:113], v[114:115]
	v_pk_add_f32 v[114:115], v[126:127], v[128:129]
	v_pk_add_f32 v[126:127], v[188:189], v[190:191]
	v_pk_add_f32 v[112:113], v[112:113], v[114:115]
	v_pk_add_f32 v[114:115], v[152:153], v[154:155]
	s_nop 0
	v_pk_add_f32 v[114:115], v[114:115], v[126:127]
	v_lshl_add_u64 v[126:127], s[54:55], 0, v[164:165]
	v_pk_add_f32 v[112:113], v[112:113], v[114:115]
	v_mov_b32_e32 v114, v165
	v_mov_b32_e32 v115, v165
	global_store_dwordx4 v[126:127], v[116:119], off offset:128
	v_mov_b32_dpp v114, v112 quad_perm:[1,0,3,2] row_mask:0xf bank_mask:0xf
	v_mov_b32_dpp v115, v113 quad_perm:[1,0,3,2] row_mask:0xf bank_mask:0xf
	v_pk_add_f32 v[112:113], v[112:113], v[114:115]
	v_mov_b32_e32 v114, v112
	v_mov_b32_e32 v115, v113
	s_nop 1
	v_permlane16_swap_b32_e32 v112, v114
	v_permlane16_swap_b32_e32 v113, v115
	s_waitcnt lgkmcnt(0)
	v_pk_add_f32 v[112:113], v[112:113], v[114:115]
	v_mov_b32_e32 v114, v112
	v_mov_b32_e32 v115, v113
	s_nop 1
	v_permlane32_swap_b32_e32 v112, v114
	v_permlane32_swap_b32_e32 v113, v115
	s_and_saveexec_b64 s[52:53], s[10:11]
	s_waitcnt lgkmcnt(0)
	v_pk_add_f32 v[112:113], v[112:113], v[114:115]
	global_store_dwordx2 v[124:125], v[112:113], off offset:512
.LBB0_586:
	s_or_b64 exec, exec, s[52:53]
	s_waitcnt lgkmcnt(0)
	v_cndmask_b32_e64 v114, v108, v100, s[8:9]
	v_mov_b32_e32 v112, 0
	v_cndmask_b32_e64 v113, v109, v101, s[8:9]
	s_waitcnt lgkmcnt(0)
	v_cndmask_b32_e64 v115, v110, v102, s[8:9]
	v_mov_b32_dpp v112, v114 quad_perm:[1,0,3,2] row_mask:0xf bank_mask:0xf
	v_mov_b32_e32 v114, 0
	v_cndmask_b32_e64 v116, v111, v103, s[8:9]
	v_cndmask_b32_e64 v118, v104, v96, s[8:9]
	v_mov_b32_dpp v114, v113 quad_perm:[1,0,3,2] row_mask:0xf bank_mask:0xf
	v_mov_b32_e32 v113, 0
	v_cndmask_b32_e64 v117, v105, v97, s[8:9]
	v_cndmask_b32_e64 v119, v106, v98, s[8:9]
	v_mov_b32_dpp v113, v115 quad_perm:[1,0,3,2] row_mask:0xf bank_mask:0xf
	v_mov_b32_e32 v115, 0
	v_cndmask_b32_e64 v126, v107, v99, s[8:9]
	v_cndmask_b32_e64 v109, v114, v109, s[8:9]
	v_mov_b32_dpp v115, v116 quad_perm:[1,0,3,2] row_mask:0xf bank_mask:0xf
	v_mov_b32_e32 v116, 0
	v_cndmask_b32_e64 v108, v112, v108, s[8:9]
	v_cndmask_b32_e64 v111, v115, v111, s[8:9]
	v_mov_b32_dpp v116, v118 quad_perm:[1,0,3,2] row_mask:0xf bank_mask:0xf
	v_mov_b32_e32 v118, 0
	v_cndmask_b32_e64 v110, v113, v110, s[8:9]
	v_cndmask_b32_e64 v104, v116, v104, s[8:9]
	v_mov_b32_dpp v118, v117 quad_perm:[1,0,3,2] row_mask:0xf bank_mask:0xf
	v_mov_b32_e32 v117, 0
	v_cndmask_b32_e64 v105, v118, v105, s[8:9]
	s_waitcnt vmcnt(13)
	v_and_b32_e32 v127, 0xffff0000, v148
	v_mov_b32_dpp v117, v119 quad_perm:[1,0,3,2] row_mask:0xf bank_mask:0xf
	v_mov_b32_e32 v119, 0
	v_cndmask_b32_e64 v106, v117, v106, s[8:9]
	v_lshlrev_b32_e32 v128, 16, v149
	v_mov_b32_dpp v119, v126 quad_perm:[1,0,3,2] row_mask:0xf bank_mask:0xf
	v_cndmask_b32_e64 v107, v119, v107, s[8:9]
	v_lshlrev_b32_e32 v126, 16, v148
	v_and_b32_e32 v129, 0xffff0000, v149
	v_lshlrev_b32_e32 v148, 16, v150
	v_and_b32_e32 v149, 0xffff0000, v150
	v_lshlrev_b32_e32 v150, 16, v151
	v_and_b32_e32 v151, 0xffff0000, v151
	v_pk_fma_f32 v[110:111], v[128:129], s[18:19], v[110:111] op_sel_hi:[1,0,1]
	v_pk_fma_f32 v[108:109], v[126:127], s[18:19], v[108:109] op_sel_hi:[1,0,1]
	v_pk_fma_f32 v[106:107], v[150:151], s[18:19], v[106:107] op_sel_hi:[1,0,1]
	v_pk_fma_f32 v[104:105], v[148:149], s[18:19], v[104:105] op_sel_hi:[1,0,1]
	v_cvt_pk_bf16_f32 v126, v108, v109
	v_cvt_pk_bf16_f32 v127, v110, v111
	v_mov_b32_e32 v181, v165
	v_cvt_pk_bf16_f32 v128, v104, v105
	v_cvt_pk_bf16_f32 v129, v106, v107
	v_lshlrev_b32_e32 v104, 16, v126
	v_and_b32_e32 v106, 0xffff0000, v126
	v_lshlrev_b32_e32 v108, 16, v127
	v_and_b32_e32 v110, 0xffff0000, v127
	v_lshlrev_b32_e32 v148, 16, v128
	v_and_b32_e32 v150, 0xffff0000, v128
	v_lshlrev_b32_e32 v152, 16, v129
	v_and_b32_e32 v154, 0xffff0000, v129
	v_mul_f32_e32 v105, v104, v104
	v_mul_f32_e32 v107, v106, v106
	v_mul_f32_e32 v109, v108, v108
	v_mul_f32_e32 v111, v110, v110
	v_mul_f32_e32 v149, v148, v148
	v_mul_f32_e32 v151, v150, v150
	v_mul_f32_e32 v153, v152, v152
	v_mul_f32_e32 v155, v154, v154
	v_pk_add_f32 v[104:105], v[104:105], v[106:107]
	v_pk_add_f32 v[106:107], v[108:109], v[110:111]
	v_pk_add_f32 v[108:109], v[152:153], v[154:155]
	v_pk_add_f32 v[104:105], v[104:105], v[106:107]
	v_pk_add_f32 v[106:107], v[148:149], v[150:151]
	s_nop 0
	v_pk_add_f32 v[106:107], v[106:107], v[108:109]
	s_nop 0
	v_pk_add_f32 v[104:105], v[104:105], v[106:107]
	v_mov_b32_e32 v106, v165
	v_mov_b32_e32 v107, v165
	s_nop 0
	v_mov_b32_dpp v106, v104 quad_perm:[1,0,3,2] row_mask:0xf bank_mask:0xf
	v_mov_b32_dpp v107, v105 quad_perm:[1,0,3,2] row_mask:0xf bank_mask:0xf
	v_pk_add_f32 v[104:105], v[104:105], v[106:107]
	v_mov_b32_e32 v106, v104
	v_mov_b32_e32 v107, v105
	s_nop 1
	v_permlane16_swap_b32_e32 v104, v106
	v_permlane16_swap_b32_e32 v105, v107
	s_waitcnt lgkmcnt(0)
; __device__ __forceinline__ u32x4 pack8f(f32x4 a, f32x4 b) { u32x4 w; w.x = cvt_pk_bf16(a[0], a[1]); w.y = cvt_pk_bf16(a[2], a[3]); w.z = cvt_pk_bf16(b[0], b[1]); w.w = cvt_pk_bf16(b[2], b[3]); return w; }
;     __device__ __forceinline__ void operator()(const f32x4 (&acc)[2][2][4][2], const Unit& u, int wr, int wc, int fr, int fq, const EpiCtx& X) const {
;     ...
;             for (int m = 0; m < 4; ++m) {
;                 const int rl = ai * HALF + m * 16; const unsigned off = lo + (unsigned)(rl * 64) * 2u;
;                 const f32x4 o0a = acc[ai][0][m][0], o0b = acc[ai][0][m][1], o1a = acc[ai][1][m][0], o1b = acc[ai][1][m][1];
;                 const f32x4 ra_ = dpp_swap1(odd ? o0a : o1a), rb_ = dpp_swap1(odd ? o0b : o1b);
;                 const f32x4 pa[2] = {odd ? ra_ : o0a, odd ? o1a : ra_}, pb[2] = {odd ? rb_ : o0b, odd ? o1b : rb_};
; #pragma unroll
;                 for (int q = 0; q < 2; ++q) {
;                     const u32x4 w0 = raw[2 * m + q];
;                     const f32x4 r0 = (f32x4){bf_lo(w0.x), bf_hi(w0.x), bf_lo(w0.y), bf_hi(w0.y)}, r1 = (f32x4){bf_lo(w0.z), bf_hi(w0.z), bf_lo(w0.w), bf_hi(w0.w)};
;                     f32x4 y0, y1;
;                     if (RESN) { const f32x2 t = tbl[rl + q]; const float mu = t.x, ra = t.y * ALPHA; y0 = (r0 - mu) * ra * g0 + b0 + pa[q]; y1 = (r1 - mu) * ra * g1 + b1 + pb[q]; }
;                     else { y0 = r0 * ALPHA + pa[q]; y1 = r1 * ALPHA + pb[q]; }
;                     { const u32x4 w = pack8f(y0, y1); *(u32x4*)(xb + off + q * 128) = w;
;                         y0 = (f32x4){bf_lo(w.x), bf_hi(w.x), bf_lo(w.y), bf_hi(w.y)}; y1 = (f32x4){bf_lo(w.z), bf_hi(w.z), bf_lo(w.w), bf_hi(w.w)}; }
;                     float sa = ((y0[0] + y0[1]) + (y0[2] + y0[3])) + ((y1[0] + y1[1]) + (y1[2] + y1[3]));
;                     float sb = ((y0[0] * y0[0] + y0[1] * y0[1]) + (y0[2] * y0[2] + y0[3] * y0[3])) + ((y1[0] * y1[0] + y1[1] * y1[1]) + (y1[2] * y1[2] + y1[3] * y1[3]));
;                     sa += dpp_x1(sa);
;                     sb += dpp_x1(sb);
;                     sa += __shfl_xor(sa, 16); sa += __shfl_xor(sa, 32); sb += __shfl_xor(sb, 16); sb += __shfl_xor(sb, 32);
;                     if (fq == 0 && !odd) ps[(size_t)(rl + q) * 64] = (f32x2){sa, sb};
	v_pk_add_f32 v[106:107], v[104:105], v[106:107]
	v_mov_b32_e32 v108, v106
	v_mov_b32_e32 v109, v107
	s_nop 1
	v_permlane32_swap_b32_e32 v106, v108
	v_permlane32_swap_b32_e32 v107, v109
	v_lshl_add_u64 v[104:105], s[54:55], 0, v[180:181]
	global_store_dwordx4 v[104:105], v[126:129], off
	s_and_saveexec_b64 s[56:57], s[10:11]
	s_waitcnt lgkmcnt(0)
	v_pk_add_f32 v[106:107], v[106:107], v[108:109]
	v_add_co_u32_e32 v108, vcc, 0x2000, v124
	s_nop 1
	v_addc_co_u32_e32 v109, vcc, 0, v125, vcc
	global_store_dwordx2 v[108:109], v[106:107], off
.LBB0_588:
	s_or_b64 exec, exec, s[56:57]
	v_cndmask_b32_e64 v101, v101, v114, s[8:9]
	v_cndmask_b32_e64 v100, v100, v112, s[8:9]
	v_cndmask_b32_e64 v103, v103, v115, s[8:9]
	v_cndmask_b32_e64 v102, v102, v113, s[8:9]
	v_cndmask_b32_e64 v97, v97, v118, s[8:9]
	v_cndmask_b32_e64 v96, v96, v116, s[8:9]
	v_cndmask_b32_e64 v99, v99, v119, s[8:9]
	v_cndmask_b32_e64 v98, v98, v117, s[8:9]
	s_waitcnt vmcnt(14)
	v_lshlrev_b32_e32 v106, 16, v144
	v_and_b32_e32 v107, 0xffff0000, v144
	s_waitcnt lgkmcnt(0)
	v_lshlrev_b32_e32 v108, 16, v145
	s_waitcnt lgkmcnt(0)
	v_and_b32_e32 v109, 0xffff0000, v145
	v_lshlrev_b32_e32 v110, 16, v146
	v_and_b32_e32 v111, 0xffff0000, v146
	v_lshlrev_b32_e32 v112, 16, v147
	v_and_b32_e32 v113, 0xffff0000, v147
	v_pk_fma_f32 v[102:103], v[108:109], s[18:19], v[102:103] op_sel_hi:[1,0,1]
	v_pk_fma_f32 v[100:101], v[106:107], s[18:19], v[100:101] op_sel_hi:[1,0,1]
	v_pk_fma_f32 v[98:99], v[112:113], s[18:19], v[98:99] op_sel_hi:[1,0,1]
	v_pk_fma_f32 v[96:97], v[110:111], s[18:19], v[96:97] op_sel_hi:[1,0,1]
	v_cvt_pk_bf16_f32 v100, v100, v101
	v_cvt_pk_bf16_f32 v101, v102, v103
	s_nop 0
	v_cvt_pk_bf16_f32 v102, v96, v97
	v_cvt_pk_bf16_f32 v103, v98, v99
	v_lshlrev_b32_e32 v96, 16, v100
	v_and_b32_e32 v98, 0xffff0000, v100
	v_lshlrev_b32_e32 v106, 16, v101
	v_and_b32_e32 v108, 0xffff0000, v101
	v_lshlrev_b32_e32 v110, 16, v102
	v_and_b32_e32 v112, 0xffff0000, v102
	v_lshlrev_b32_e32 v114, 16, v103
	v_and_b32_e32 v116, 0xffff0000, v103
	v_mul_f32_e32 v97, v96, v96
	v_mul_f32_e32 v99, v98, v98
	v_mul_f32_e32 v107, v106, v106
	v_mul_f32_e32 v109, v108, v108
	v_mul_f32_e32 v111, v110, v110
	v_mul_f32_e32 v113, v112, v112
	v_mul_f32_e32 v115, v114, v114
	v_mul_f32_e32 v117, v116, v116
	v_pk_add_f32 v[96:97], v[96:97], v[98:99]
	v_pk_add_f32 v[98:99], v[106:107], v[108:109]
	v_pk_add_f32 v[106:107], v[114:115], v[116:117]
	v_pk_add_f32 v[96:97], v[96:97], v[98:99]
	v_pk_add_f32 v[98:99], v[110:111], v[112:113]
	global_store_dwordx4 v[104:105], v[100:103], off offset:128
	v_pk_add_f32 v[98:99], v[98:99], v[106:107]
	s_nop 0
	v_pk_add_f32 v[96:97], v[96:97], v[98:99]
	v_mov_b32_e32 v98, v165
	v_mov_b32_e32 v99, v165
	s_nop 0
	v_mov_b32_dpp v98, v96 quad_perm:[1,0,3,2] row_mask:0xf bank_mask:0xf
	v_mov_b32_dpp v99, v97 quad_perm:[1,0,3,2] row_mask:0xf bank_mask:0xf
	v_pk_add_f32 v[96:97], v[96:97], v[98:99]
	v_mov_b32_e32 v98, v96
	v_mov_b32_e32 v99, v97
	s_nop 1
	v_permlane16_swap_b32_e32 v96, v98
	v_permlane16_swap_b32_e32 v97, v99
	s_waitcnt lgkmcnt(0)
	v_pk_add_f32 v[96:97], v[96:97], v[98:99]
	v_mov_b32_e32 v98, v96
	v_mov_b32_e32 v99, v97
	s_nop 1
	v_permlane32_swap_b32_e32 v96, v98
	v_permlane32_swap_b32_e32 v97, v99
	s_and_saveexec_b64 s[56:57], s[10:11]
	s_waitcnt lgkmcnt(0)
	v_pk_add_f32 v[96:97], v[96:97], v[98:99]
	v_add_co_u32_e32 v98, vcc, 0x2000, v124
	s_nop 1
	v_addc_co_u32_e32 v99, vcc, 0, v125, vcc
	global_store_dwordx2 v[98:99], v[96:97], off offset:512
.LBB0_590:
	s_or_b64 exec, exec, s[56:57]
	s_waitcnt lgkmcnt(0)
	v_cndmask_b32_e64 v98, v92, v84, s[8:9]
	v_mov_b32_e32 v96, 0
	v_cndmask_b32_e64 v97, v93, v85, s[8:9]
	s_waitcnt lgkmcnt(0)
	v_cndmask_b32_e64 v99, v94, v86, s[8:9]
	v_mov_b32_dpp v96, v98 quad_perm:[1,0,3,2] row_mask:0xf bank_mask:0xf
	v_mov_b32_e32 v98, 0
	v_cndmask_b32_e64 v100, v95, v87, s[8:9]
	v_cndmask_b32_e64 v102, v88, v80, s[8:9]
	v_mov_b32_dpp v98, v97 quad_perm:[1,0,3,2] row_mask:0xf bank_mask:0xf
	v_mov_b32_e32 v97, 0
	v_cndmask_b32_e64 v101, v89, v81, s[8:9]
	v_cndmask_b32_e64 v103, v90, v82, s[8:9]
	v_mov_b32_dpp v97, v99 quad_perm:[1,0,3,2] row_mask:0xf bank_mask:0xf
	v_mov_b32_e32 v99, 0
	v_cndmask_b32_e64 v104, v91, v83, s[8:9]
	v_cndmask_b32_e64 v93, v98, v93, s[8:9]
	v_mov_b32_dpp v99, v100 quad_perm:[1,0,3,2] row_mask:0xf bank_mask:0xf
	v_mov_b32_e32 v100, 0
	v_cndmask_b32_e64 v92, v96, v92, s[8:9]
	v_cndmask_b32_e64 v95, v99, v95, s[8:9]
	v_mov_b32_dpp v100, v102 quad_perm:[1,0,3,2] row_mask:0xf bank_mask:0xf
	v_mov_b32_e32 v102, 0
	v_cndmask_b32_e64 v94, v97, v94, s[8:9]
	v_cndmask_b32_e64 v88, v100, v88, s[8:9]
	v_mov_b32_dpp v102, v101 quad_perm:[1,0,3,2] row_mask:0xf bank_mask:0xf
	v_mov_b32_e32 v101, 0
	v_cndmask_b32_e64 v89, v102, v89, s[8:9]
	s_waitcnt vmcnt(15)
; __device__ __forceinline__ u32x4 pack8f(f32x4 a, f32x4 b) { u32x4 w; w.x = cvt_pk_bf16(a[0], a[1]); w.y = cvt_pk_bf16(a[2], a[3]); w.z = cvt_pk_bf16(b[0], b[1]); w.w = cvt_pk_bf16(b[2], b[3]); return w; }
;     __device__ __forceinline__ void operator()(const f32x4 (&acc)[2][2][4][2], const Unit& u, int wr, int wc, int fr, int fq, const EpiCtx& X) const {
;     ...
;             for (int m = 0; m < 4; ++m) {
;                 const int rl = ai * HALF + m * 16; const unsigned off = lo + (unsigned)(rl * 64) * 2u;
;                 const f32x4 o0a = acc[ai][0][m][0], o0b = acc[ai][0][m][1], o1a = acc[ai][1][m][0], o1b = acc[ai][1][m][1];
;                 const f32x4 ra_ = dpp_swap1(odd ? o0a : o1a), rb_ = dpp_swap1(odd ? o0b : o1b);
;                 const f32x4 pa[2] = {odd ? ra_ : o0a, odd ? o1a : ra_}, pb[2] = {odd ? rb_ : o0b, odd ? o1b : rb_};
; #pragma unroll
;                 for (int q = 0; q < 2; ++q) {
;                     const u32x4 w0 = raw[2 * m + q];
;                     const f32x4 r0 = (f32x4){bf_lo(w0.x), bf_hi(w0.x), bf_lo(w0.y), bf_hi(w0.y)}, r1 = (f32x4){bf_lo(w0.z), bf_hi(w0.z), bf_lo(w0.w), bf_hi(w0.w)};
;                     f32x4 y0, y1;
;                     if (RESN) { const f32x2 t = tbl[rl + q]; const float mu = t.x, ra = t.y * ALPHA; y0 = (r0 - mu) * ra * g0 + b0 + pa[q]; y1 = (r1 - mu) * ra * g1 + b1 + pb[q]; }
;                     else { y0 = r0 * ALPHA + pa[q]; y1 = r1 * ALPHA + pb[q]; }
;                     { const u32x4 w = pack8f(y0, y1); *(u32x4*)(xb + off + q * 128) = w;
;                         y0 = (f32x4){bf_lo(w.x), bf_hi(w.x), bf_lo(w.y), bf_hi(w.y)}; y1 = (f32x4){bf_lo(w.z), bf_hi(w.z), bf_lo(w.w), bf_hi(w.w)}; }
;                     float sa = ((y0[0] + y0[1]) + (y0[2] + y0[3])) + ((y1[0] + y1[1]) + (y1[2] + y1[3]));
;                     float sb = ((y0[0] * y0[0] + y0[1] * y0[1]) + (y0[2] * y0[2] + y0[3] * y0[3])) + ((y1[0] * y1[0] + y1[1] * y1[1]) + (y1[2] * y1[2] + y1[3] * y1[3]));
;                     sa += dpp_x1(sa);
;                     sb += dpp_x1(sb);
;                     sa += __shfl_xor(sa, 16); sa += __shfl_xor(sa, 32); sb += __shfl_xor(sb, 16); sb += __shfl_xor(sb, 32);
;                     if (fq == 0 && !odd) ps[(size_t)(rl + q) * 64] = (f32x2){sa, sb};
	v_and_b32_e32 v105, 0xffff0000, v140
	v_mov_b32_dpp v101, v103 quad_perm:[1,0,3,2] row_mask:0xf bank_mask:0xf
	v_mov_b32_e32 v103, 0
	v_cndmask_b32_e64 v90, v101, v90, s[8:9]
	v_lshlrev_b32_e32 v106, 16, v141
	v_mov_b32_dpp v103, v104 quad_perm:[1,0,3,2] row_mask:0xf bank_mask:0xf
	v_cndmask_b32_e64 v91, v103, v91, s[8:9]
	v_lshlrev_b32_e32 v104, 16, v140
	v_and_b32_e32 v107, 0xffff0000, v141
	v_lshlrev_b32_e32 v108, 16, v142
	v_and_b32_e32 v109, 0xffff0000, v142
	v_lshlrev_b32_e32 v110, 16, v143
	v_and_b32_e32 v111, 0xffff0000, v143
	v_pk_fma_f32 v[94:95], v[106:107], s[18:19], v[94:95] op_sel_hi:[1,0,1]
	v_pk_fma_f32 v[92:93], v[104:105], s[18:19], v[92:93] op_sel_hi:[1,0,1]
	v_pk_fma_f32 v[90:91], v[110:111], s[18:19], v[90:91] op_sel_hi:[1,0,1]
	v_pk_fma_f32 v[88:89], v[108:109], s[18:19], v[88:89] op_sel_hi:[1,0,1]
	v_cvt_pk_bf16_f32 v104, v92, v93
	v_cvt_pk_bf16_f32 v105, v94, v95
	v_mov_b32_e32 v179, v165
	v_cvt_pk_bf16_f32 v106, v88, v89
	v_cvt_pk_bf16_f32 v107, v90, v91
	v_lshlrev_b32_e32 v88, 16, v104
	v_and_b32_e32 v90, 0xffff0000, v104
	v_lshlrev_b32_e32 v92, 16, v105
	v_and_b32_e32 v94, 0xffff0000, v105
	v_lshlrev_b32_e32 v108, 16, v106
	v_and_b32_e32 v110, 0xffff0000, v106
	v_lshlrev_b32_e32 v112, 16, v107
	v_and_b32_e32 v114, 0xffff0000, v107
	v_mul_f32_e32 v89, v88, v88
	v_mul_f32_e32 v91, v90, v90
	v_mul_f32_e32 v93, v92, v92
	v_mul_f32_e32 v95, v94, v94
	v_mul_f32_e32 v109, v108, v108
	v_mul_f32_e32 v111, v110, v110
	v_mul_f32_e32 v113, v112, v112
	v_mul_f32_e32 v115, v114, v114
	v_pk_add_f32 v[88:89], v[88:89], v[90:91]
	v_pk_add_f32 v[90:91], v[92:93], v[94:95]
	v_pk_add_f32 v[92:93], v[112:113], v[114:115]
	v_pk_add_f32 v[88:89], v[88:89], v[90:91]
	v_pk_add_f32 v[90:91], v[108:109], v[110:111]
	s_nop 0
	v_pk_add_f32 v[90:91], v[90:91], v[92:93]
	s_nop 0
	v_pk_add_f32 v[88:89], v[88:89], v[90:91]
	v_mov_b32_e32 v90, v165
	v_mov_b32_e32 v91, v165
	s_nop 0
	v_mov_b32_dpp v90, v88 quad_perm:[1,0,3,2] row_mask:0xf bank_mask:0xf
	v_mov_b32_dpp v91, v89 quad_perm:[1,0,3,2] row_mask:0xf bank_mask:0xf
	v_pk_add_f32 v[88:89], v[88:89], v[90:91]
	v_mov_b32_e32 v90, v88
	v_mov_b32_e32 v91, v89
	s_nop 1
	v_permlane16_swap_b32_e32 v88, v90
	v_permlane16_swap_b32_e32 v89, v91
	s_waitcnt lgkmcnt(0)
	v_pk_add_f32 v[90:91], v[88:89], v[90:91]
	v_mov_b32_e32 v92, v90
	v_mov_b32_e32 v93, v91
	s_nop 1
	v_permlane32_swap_b32_e32 v90, v92
	v_permlane32_swap_b32_e32 v91, v93
	v_lshl_add_u64 v[88:89], s[54:55], 0, v[178:179]
	global_store_dwordx4 v[88:89], v[104:107], off
	s_and_saveexec_b64 s[56:57], s[10:11]
	s_waitcnt lgkmcnt(0)
	v_pk_add_f32 v[90:91], v[90:91], v[92:93]
	v_add_co_u32_e32 v92, vcc, 0x4000, v124
	s_nop 1
	v_addc_co_u32_e32 v93, vcc, 0, v125, vcc
	global_store_dwordx2 v[92:93], v[90:91], off
.LBB0_592:
	s_or_b64 exec, exec, s[56:57]
	v_cndmask_b32_e64 v85, v85, v98, s[8:9]
	v_cndmask_b32_e64 v84, v84, v96, s[8:9]
	v_cndmask_b32_e64 v87, v87, v99, s[8:9]
	v_cndmask_b32_e64 v86, v86, v97, s[8:9]
	v_cndmask_b32_e64 v81, v81, v102, s[8:9]
	v_cndmask_b32_e64 v80, v80, v100, s[8:9]
	v_cndmask_b32_e64 v83, v83, v103, s[8:9]
	v_cndmask_b32_e64 v82, v82, v101, s[8:9]
	s_waitcnt vmcnt(16)
	v_lshlrev_b32_e32 v90, 16, v136
	v_and_b32_e32 v91, 0xffff0000, v136
	s_waitcnt lgkmcnt(0)
	v_lshlrev_b32_e32 v92, 16, v137
	s_waitcnt lgkmcnt(0)
	v_and_b32_e32 v93, 0xffff0000, v137
	v_lshlrev_b32_e32 v94, 16, v138
	v_and_b32_e32 v95, 0xffff0000, v138
	v_lshlrev_b32_e32 v96, 16, v139
	v_and_b32_e32 v97, 0xffff0000, v139
	v_pk_fma_f32 v[86:87], v[92:93], s[18:19], v[86:87] op_sel_hi:[1,0,1]
	v_pk_fma_f32 v[84:85], v[90:91], s[18:19], v[84:85] op_sel_hi:[1,0,1]
	v_pk_fma_f32 v[82:83], v[96:97], s[18:19], v[82:83] op_sel_hi:[1,0,1]
	v_pk_fma_f32 v[80:81], v[94:95], s[18:19], v[80:81] op_sel_hi:[1,0,1]
	v_cvt_pk_bf16_f32 v84, v84, v85
	v_cvt_pk_bf16_f32 v85, v86, v87
	s_nop 0
	v_cvt_pk_bf16_f32 v86, v80, v81
	v_cvt_pk_bf16_f32 v87, v82, v83
	v_lshlrev_b32_e32 v80, 16, v84
	v_and_b32_e32 v82, 0xffff0000, v84
	v_lshlrev_b32_e32 v90, 16, v85
	v_and_b32_e32 v92, 0xffff0000, v85
	v_lshlrev_b32_e32 v94, 16, v86
	v_and_b32_e32 v96, 0xffff0000, v86
	v_lshlrev_b32_e32 v98, 16, v87
	v_and_b32_e32 v100, 0xffff0000, v87
	v_mul_f32_e32 v81, v80, v80
	v_mul_f32_e32 v83, v82, v82
	v_mul_f32_e32 v91, v90, v90
	v_mul_f32_e32 v93, v92, v92
	v_mul_f32_e32 v95, v94, v94
	v_mul_f32_e32 v97, v96, v96
	v_mul_f32_e32 v99, v98, v98
	v_mul_f32_e32 v101, v100, v100
	v_pk_add_f32 v[80:81], v[80:81], v[82:83]
	v_pk_add_f32 v[82:83], v[90:91], v[92:93]
	v_pk_add_f32 v[90:91], v[98:99], v[100:101]
	v_pk_add_f32 v[80:81], v[80:81], v[82:83]
	v_pk_add_f32 v[82:83], v[94:95], v[96:97]
	global_store_dwordx4 v[88:89], v[84:87], off offset:128
	v_pk_add_f32 v[82:83], v[82:83], v[90:91]
	s_nop 0
	v_pk_add_f32 v[80:81], v[80:81], v[82:83]
	v_mov_b32_e32 v82, v165
	v_mov_b32_e32 v83, v165
	s_nop 0
	v_mov_b32_dpp v82, v80 quad_perm:[1,0,3,2] row_mask:0xf bank_mask:0xf
	v_mov_b32_dpp v83, v81 quad_perm:[1,0,3,2] row_mask:0xf bank_mask:0xf
	v_pk_add_f32 v[80:81], v[80:81], v[82:83]
	v_mov_b32_e32 v82, v80
	v_mov_b32_e32 v83, v81
	s_nop 1
	v_permlane16_swap_b32_e32 v80, v82
	v_permlane16_swap_b32_e32 v81, v83
	s_waitcnt lgkmcnt(0)
	v_pk_add_f32 v[80:81], v[80:81], v[82:83]
	v_mov_b32_e32 v82, v80
	v_mov_b32_e32 v83, v81
	s_nop 1
	v_permlane32_swap_b32_e32 v80, v82
	v_permlane32_swap_b32_e32 v81, v83
	s_and_saveexec_b64 s[56:57], s[10:11]
	s_waitcnt lgkmcnt(0)
	v_pk_add_f32 v[80:81], v[80:81], v[82:83]
	v_add_co_u32_e32 v82, vcc, 0x4000, v124
	s_nop 1
	v_addc_co_u32_e32 v83, vcc, 0, v125, vcc
	global_store_dwordx2 v[82:83], v[80:81], off offset:512
; __device__ __forceinline__ u32x4 pack8f(f32x4 a, f32x4 b) { u32x4 w; w.x = cvt_pk_bf16(a[0], a[1]); w.y = cvt_pk_bf16(a[2], a[3]); w.z = cvt_pk_bf16(b[0], b[1]); w.w = cvt_pk_bf16(b[2], b[3]); return w; }
;     __device__ __forceinline__ void operator()(const f32x4 (&acc)[2][2][4][2], const Unit& u, int wr, int wc, int fr, int fq, const EpiCtx& X) const {
;     ...
;             for (int m = 0; m < 4; ++m) {
;                 const int rl = ai * HALF + m * 16; const unsigned off = lo + (unsigned)(rl * 64) * 2u;
;                 const f32x4 o0a = acc[ai][0][m][0], o0b = acc[ai][0][m][1], o1a = acc[ai][1][m][0], o1b = acc[ai][1][m][1];
;                 const f32x4 ra_ = dpp_swap1(odd ? o0a : o1a), rb_ = dpp_swap1(odd ? o0b : o1b);
;                 const f32x4 pa[2] = {odd ? ra_ : o0a, odd ? o1a : ra_}, pb[2] = {odd ? rb_ : o0b, odd ? o1b : rb_};
; #pragma unroll
;                 for (int q = 0; q < 2; ++q) {
;                     const u32x4 w0 = raw[2 * m + q];
;                     const f32x4 r0 = (f32x4){bf_lo(w0.x), bf_hi(w0.x), bf_lo(w0.y), bf_hi(w0.y)}, r1 = (f32x4){bf_lo(w0.z), bf_hi(w0.z), bf_lo(w0.w), bf_hi(w0.w)};
;                     f32x4 y0, y1;
;                     if (RESN) { const f32x2 t = tbl[rl + q]; const float mu = t.x, ra = t.y * ALPHA; y0 = (r0 - mu) * ra * g0 + b0 + pa[q]; y1 = (r1 - mu) * ra * g1 + b1 + pb[q]; }
;                     else { y0 = r0 * ALPHA + pa[q]; y1 = r1 * ALPHA + pb[q]; }
;                     { const u32x4 w = pack8f(y0, y1); *(u32x4*)(xb + off + q * 128) = w;
;                         y0 = (f32x4){bf_lo(w.x), bf_hi(w.x), bf_lo(w.y), bf_hi(w.y)}; y1 = (f32x4){bf_lo(w.z), bf_hi(w.z), bf_lo(w.w), bf_hi(w.w)}; }
;                     float sa = ((y0[0] + y0[1]) + (y0[2] + y0[3])) + ((y1[0] + y1[1]) + (y1[2] + y1[3]));
;                     float sb = ((y0[0] * y0[0] + y0[1] * y0[1]) + (y0[2] * y0[2] + y0[3] * y0[3])) + ((y1[0] * y1[0] + y1[1] * y1[1]) + (y1[2] * y1[2] + y1[3] * y1[3]));
;                     sa += dpp_x1(sa);
;                     sb += dpp_x1(sb);
;                     sa += __shfl_xor(sa, 16); sa += __shfl_xor(sa, 32); sb += __shfl_xor(sb, 16); sb += __shfl_xor(sb, 32);
;                     if (fq == 0 && !odd) ps[(size_t)(rl + q) * 64] = (f32x2){sa, sb};
.LBB0_594:
	s_or_b64 exec, exec, s[56:57]
	s_waitcnt lgkmcnt(0)
	v_cndmask_b32_e64 v82, v76, v68, s[8:9]
	v_mov_b32_e32 v80, 0
	v_cndmask_b32_e64 v81, v77, v69, s[8:9]
	s_waitcnt lgkmcnt(0)
	v_cndmask_b32_e64 v83, v78, v70, s[8:9]
	v_mov_b32_dpp v80, v82 quad_perm:[1,0,3,2] row_mask:0xf bank_mask:0xf
	v_mov_b32_e32 v82, 0
	v_cndmask_b32_e64 v84, v79, v71, s[8:9]
	v_cndmask_b32_e64 v86, v72, v64, s[8:9]
	v_mov_b32_dpp v82, v81 quad_perm:[1,0,3,2] row_mask:0xf bank_mask:0xf
	v_mov_b32_e32 v81, 0
	v_cndmask_b32_e64 v85, v73, v65, s[8:9]
	v_cndmask_b32_e64 v87, v74, v66, s[8:9]
	v_mov_b32_dpp v81, v83 quad_perm:[1,0,3,2] row_mask:0xf bank_mask:0xf
	v_mov_b32_e32 v83, 0
	v_cndmask_b32_e64 v88, v75, v67, s[8:9]
	v_cndmask_b32_e64 v77, v82, v77, s[8:9]
	v_mov_b32_dpp v83, v84 quad_perm:[1,0,3,2] row_mask:0xf bank_mask:0xf
	v_mov_b32_e32 v84, 0
	v_cndmask_b32_e64 v76, v80, v76, s[8:9]
	v_cndmask_b32_e64 v79, v83, v79, s[8:9]
	v_mov_b32_dpp v84, v86 quad_perm:[1,0,3,2] row_mask:0xf bank_mask:0xf
	v_mov_b32_e32 v86, 0
	v_cndmask_b32_e64 v78, v81, v78, s[8:9]
	v_cndmask_b32_e64 v72, v84, v72, s[8:9]
	v_mov_b32_dpp v86, v85 quad_perm:[1,0,3,2] row_mask:0xf bank_mask:0xf
	v_mov_b32_e32 v85, 0
	v_cndmask_b32_e64 v73, v86, v73, s[8:9]
	s_waitcnt vmcnt(17)
	v_and_b32_e32 v89, 0xffff0000, v132
	v_mov_b32_dpp v85, v87 quad_perm:[1,0,3,2] row_mask:0xf bank_mask:0xf
	v_mov_b32_e32 v87, 0
	v_cndmask_b32_e64 v74, v85, v74, s[8:9]
	v_lshlrev_b32_e32 v90, 16, v133
	v_mov_b32_dpp v87, v88 quad_perm:[1,0,3,2] row_mask:0xf bank_mask:0xf
	v_cndmask_b32_e64 v75, v87, v75, s[8:9]
	v_lshlrev_b32_e32 v88, 16, v132
	v_and_b32_e32 v91, 0xffff0000, v133
	v_lshlrev_b32_e32 v92, 16, v134
	v_and_b32_e32 v93, 0xffff0000, v134
	v_lshlrev_b32_e32 v94, 16, v135
	v_and_b32_e32 v95, 0xffff0000, v135
	v_pk_fma_f32 v[78:79], v[90:91], s[18:19], v[78:79] op_sel_hi:[1,0,1]
	v_pk_fma_f32 v[76:77], v[88:89], s[18:19], v[76:77] op_sel_hi:[1,0,1]
	v_pk_fma_f32 v[74:75], v[94:95], s[18:19], v[74:75] op_sel_hi:[1,0,1]
	v_pk_fma_f32 v[72:73], v[92:93], s[18:19], v[72:73] op_sel_hi:[1,0,1]
	v_cvt_pk_bf16_f32 v88, v76, v77
	v_cvt_pk_bf16_f32 v89, v78, v79
	v_mov_b32_e32 v177, v165
	v_cvt_pk_bf16_f32 v90, v72, v73
	v_cvt_pk_bf16_f32 v91, v74, v75
	v_lshlrev_b32_e32 v72, 16, v88
	v_and_b32_e32 v74, 0xffff0000, v88
	v_lshlrev_b32_e32 v76, 16, v89
	v_and_b32_e32 v78, 0xffff0000, v89
	v_lshlrev_b32_e32 v92, 16, v90
	v_and_b32_e32 v94, 0xffff0000, v90
	v_lshlrev_b32_e32 v96, 16, v91
	v_and_b32_e32 v98, 0xffff0000, v91
	v_mul_f32_e32 v73, v72, v72
	v_mul_f32_e32 v75, v74, v74
	v_mul_f32_e32 v77, v76, v76
	v_mul_f32_e32 v79, v78, v78
	v_mul_f32_e32 v93, v92, v92
	v_mul_f32_e32 v95, v94, v94
	v_mul_f32_e32 v97, v96, v96
	v_mul_f32_e32 v99, v98, v98
	v_pk_add_f32 v[72:73], v[72:73], v[74:75]
	v_pk_add_f32 v[74:75], v[76:77], v[78:79]
	v_pk_add_f32 v[76:77], v[96:97], v[98:99]
	v_pk_add_f32 v[72:73], v[72:73], v[74:75]
	v_pk_add_f32 v[74:75], v[92:93], v[94:95]
	s_nop 0
	v_pk_add_f32 v[74:75], v[74:75], v[76:77]
	s_nop 0
	v_pk_add_f32 v[72:73], v[72:73], v[74:75]
	v_mov_b32_e32 v74, v165
	v_mov_b32_e32 v75, v165
	s_nop 0
	v_mov_b32_dpp v74, v72 quad_perm:[1,0,3,2] row_mask:0xf bank_mask:0xf
	v_mov_b32_dpp v75, v73 quad_perm:[1,0,3,2] row_mask:0xf bank_mask:0xf
	v_pk_add_f32 v[72:73], v[72:73], v[74:75]
	v_mov_b32_e32 v74, v72
	v_mov_b32_e32 v75, v73
	s_nop 1
	v_permlane16_swap_b32_e32 v72, v74
	v_permlane16_swap_b32_e32 v73, v75
	s_waitcnt lgkmcnt(0)
	v_pk_add_f32 v[74:75], v[72:73], v[74:75]
	v_mov_b32_e32 v76, v74
	v_mov_b32_e32 v77, v75
	s_nop 1
	v_permlane32_swap_b32_e32 v74, v76
	v_permlane32_swap_b32_e32 v75, v77
	v_lshl_add_u64 v[72:73], s[54:55], 0, v[176:177]
	global_store_dwordx4 v[72:73], v[88:91], off
	s_and_saveexec_b64 s[56:57], s[10:11]
	s_waitcnt lgkmcnt(0)
	v_pk_add_f32 v[74:75], v[74:75], v[76:77]
	v_add_co_u32_e32 v76, vcc, 0x6000, v124
	s_nop 1
	v_addc_co_u32_e32 v77, vcc, 0, v125, vcc
	global_store_dwordx2 v[76:77], v[74:75], off
.LBB0_596:
	s_or_b64 exec, exec, s[56:57]
	v_cndmask_b32_e64 v69, v69, v82, s[8:9]
	v_cndmask_b32_e64 v68, v68, v80, s[8:9]
	v_cndmask_b32_e64 v71, v71, v83, s[8:9]
	v_cndmask_b32_e64 v70, v70, v81, s[8:9]
	v_cndmask_b32_e64 v65, v65, v86, s[8:9]
	v_cndmask_b32_e64 v64, v64, v84, s[8:9]
	v_cndmask_b32_e64 v67, v67, v87, s[8:9]
	v_cndmask_b32_e64 v66, v66, v85, s[8:9]
	s_waitcnt vmcnt(18)
	v_lshlrev_b32_e32 v74, 16, v120
	v_and_b32_e32 v75, 0xffff0000, v120
	s_waitcnt lgkmcnt(0)
	v_lshlrev_b32_e32 v76, 16, v121
	s_waitcnt lgkmcnt(0)
	v_and_b32_e32 v77, 0xffff0000, v121
	v_lshlrev_b32_e32 v78, 16, v122
	v_and_b32_e32 v79, 0xffff0000, v122
	v_lshlrev_b32_e32 v80, 16, v123
	v_and_b32_e32 v81, 0xffff0000, v123
	v_pk_fma_f32 v[70:71], v[76:77], s[18:19], v[70:71] op_sel_hi:[1,0,1]
	v_pk_fma_f32 v[68:69], v[74:75], s[18:19], v[68:69] op_sel_hi:[1,0,1]
	v_pk_fma_f32 v[66:67], v[80:81], s[18:19], v[66:67] op_sel_hi:[1,0,1]
	v_pk_fma_f32 v[64:65], v[78:79], s[18:19], v[64:65] op_sel_hi:[1,0,1]
	v_cvt_pk_bf16_f32 v68, v68, v69
	v_cvt_pk_bf16_f32 v69, v70, v71
	s_nop 0
	v_cvt_pk_bf16_f32 v70, v64, v65
	v_cvt_pk_bf16_f32 v71, v66, v67
	v_lshlrev_b32_e32 v64, 16, v68
	v_and_b32_e32 v66, 0xffff0000, v68
	v_lshlrev_b32_e32 v74, 16, v69
	v_and_b32_e32 v76, 0xffff0000, v69
	v_lshlrev_b32_e32 v78, 16, v70
	v_and_b32_e32 v80, 0xffff0000, v70
	v_lshlrev_b32_e32 v82, 16, v71
	v_and_b32_e32 v84, 0xffff0000, v71
	v_mul_f32_e32 v65, v64, v64
	v_mul_f32_e32 v67, v66, v66
	v_mul_f32_e32 v75, v74, v74
	v_mul_f32_e32 v77, v76, v76
	v_mul_f32_e32 v79, v78, v78
	v_mul_f32_e32 v81, v80, v80
	v_mul_f32_e32 v83, v82, v82
	v_mul_f32_e32 v85, v84, v84
	v_pk_add_f32 v[64:65], v[64:65], v[66:67]
	v_pk_add_f32 v[66:67], v[74:75], v[76:77]
	v_pk_add_f32 v[74:75], v[82:83], v[84:85]
	v_pk_add_f32 v[64:65], v[64:65], v[66:67]
	v_pk_add_f32 v[66:67], v[78:79], v[80:81]
	global_store_dwordx4 v[72:73], v[68:71], off offset:128
	v_pk_add_f32 v[66:67], v[66:67], v[74:75]
	s_nop 0
	v_pk_add_f32 v[64:65], v[64:65], v[66:67]
	v_mov_b32_e32 v66, v165
	v_mov_b32_e32 v67, v165
	s_nop 0
	v_mov_b32_dpp v66, v64 quad_perm:[1,0,3,2] row_mask:0xf bank_mask:0xf
	v_mov_b32_dpp v67, v65 quad_perm:[1,0,3,2] row_mask:0xf bank_mask:0xf
	v_pk_add_f32 v[64:65], v[64:65], v[66:67]
	v_mov_b32_e32 v66, v64
	v_mov_b32_e32 v67, v65
	s_nop 1
	v_permlane16_swap_b32_e32 v64, v66
	v_permlane16_swap_b32_e32 v65, v67
	s_waitcnt lgkmcnt(0)
	v_pk_add_f32 v[64:65], v[64:65], v[66:67]
	v_mov_b32_e32 v66, v64
	v_mov_b32_e32 v67, v65
	s_nop 1
	v_permlane32_swap_b32_e32 v64, v66
	v_permlane32_swap_b32_e32 v65, v67
	s_and_saveexec_b64 s[56:57], s[10:11]
	s_waitcnt lgkmcnt(0)
	v_pk_add_f32 v[64:65], v[64:65], v[66:67]
	v_add_co_u32_e32 v66, vcc, 0x6000, v124
	s_nop 1
	v_addc_co_u32_e32 v67, vcc, 0, v125, vcc
	global_store_dwordx2 v[66:67], v[64:65], off offset:512
;     __device__ __forceinline__ void operator()(const f32x4 (&acc)[2][2][4][2], const Unit& u, int wr, int wc, int fr, int fq, const EpiCtx& X) const {
;     ...
;         for (int ai = 0; ai < 2; ++ai) {
;             u32x4 raw[8];
; #pragma unroll
;             for (int m = 0; m < 4; ++m) { const unsigned off = lo + (unsigned)((ai * HALF + m * 16) * 64) * 2u; raw[2 * m] = *(const u32x4*)(xb + off); raw[2 * m + 1] = *(const u32x4*)(xb + off + 128); }
; #pragma unroll
;             for (int m = 0; m < 4; ++m) {
;                 const int rl = ai * HALF + m * 16; const unsigned off = lo + (unsigned)(rl * 64) * 2u;
;                 const f32x4 o0a = acc[ai][0][m][0], o0b = acc[ai][0][m][1], o1a = acc[ai][1][m][0], o1b = acc[ai][1][m][1];
;                 const f32x4 ra_ = dpp_swap1(odd ? o0a : o1a), rb_ = dpp_swap1(odd ? o0b : o1b);
;                 const f32x4 pa[2] = {odd ? ra_ : o0a, odd ? o1a : ra_}, pb[2] = {odd ? rb_ : o0b, odd ? o1b : rb_};
; #pragma unroll
;                 for (int q = 0; q < 2; ++q) {
;                     const u32x4 w0 = raw[2 * m + q];
;                     const f32x4 r0 = (f32x4){bf_lo(w0.x), bf_hi(w0.x), bf_lo(w0.y), bf_hi(w0.y)}, r1 = (f32x4){bf_lo(w0.z), bf_hi(w0.z), bf_lo(w0.w), bf_hi(w0.w)};
;                     f32x4 y0, y1;
;                     if (RESN) { const f32x2 t = tbl[rl + q]; const float mu = t.x, ra = t.y * ALPHA; y0 = (r0 - mu) * ra * g0 + b0 + pa[q]; y1 = (r1 - mu) * ra * g1 + b1 + pb[q]; }
;                     else { y0 = r0 * ALPHA + pa[q]; y1 = r1 * ALPHA + pb[q]; }
;                     { const u32x4 w = pack8f(y0, y1); *(u32x4*)(xb + off + q * 128) = w;
;                         y0 = (f32x4){bf_lo(w.x), bf_hi(w.x), bf_lo(w.y), bf_hi(w.y)}; y1 = (f32x4){bf_lo(w.z), bf_hi(w.z), bf_lo(w.w), bf_hi(w.w)}; }
;                     float sa = ((y0[0] + y0[1]) + (y0[2] + y0[3])) + ((y1[0] + y1[1]) + (y1[2] + y1[3]));
;                     float sb = ((y0[0] * y0[0] + y0[1] * y0[1]) + (y0[2] * y0[2] + y0[3] * y0[3])) + ((y1[0] * y1[0] + y1[1] * y1[1]) + (y1[2] * y1[2] + y1[3] * y1[3]));
;                     sa += dpp_x1(sa);
;                     sb += dpp_x1(sb);
;                     sa += __shfl_xor(sa, 16); sa += __shfl_xor(sa, 32); sb += __shfl_xor(sb, 16); sb += __shfl_xor(sb, 32);
;                     if (fq == 0 && !odd) ps[(size_t)(rl + q) * 64] = (f32x2){sa, sb};
.LBB0_598:
	s_or_b64 exec, exec, s[56:57]
	v_add_u32_e32 v96, 0x4000, v164
	s_waitcnt vmcnt(16)
	v_mov_b32_e32 v104, v230
	v_mov_b32_e32 v105, v231
	v_mov_b32_e32 v106, v232
	v_mov_b32_e32 v107, v233
	v_add_u32_e32 v94, 0x4800, v164
	v_add_u32_e32 v92, 0x5000, v164
	v_add_u32_e32 v164, 0x5800, v164
	v_mov_b32_e32 v88, v234
	v_mov_b32_e32 v89, v235
	v_mov_b32_e32 v90, v236
	v_mov_b32_e32 v91, v237
	v_mov_b32_e32 v84, v238
	v_mov_b32_e32 v85, v239
	v_mov_b32_e32 v86, v240
	v_mov_b32_e32 v87, v241
	v_mov_b32_e32 v80, v242
	v_mov_b32_e32 v81, v243
	v_mov_b32_e32 v82, v244
	v_mov_b32_e32 v83, v245
	global_load_dwordx4 v[76:79], v92, s[54:55]
	global_load_dwordx4 v[72:75], v92, s[54:55] offset:128
	global_load_dwordx4 v[68:71], v164, s[54:55]
	s_waitcnt lgkmcnt(0)
	global_load_dwordx4 v[64:67], v164, s[54:55] offset:128
	v_cndmask_b32_e64 v103, v63, v55, s[8:9]
	v_cndmask_b32_e64 v110, v62, v54, s[8:9]
	v_cndmask_b32_e64 v111, v61, v53, s[8:9]
	v_cndmask_b32_e64 v112, v60, v52, s[8:9]
	v_mov_b32_e32 v93, 0
	v_mov_b32_e32 v97, 0
	v_mov_b32_e32 v95, 0
	v_mov_b32_e32 v98, 0
	v_cndmask_b32_e64 v113, v59, v51, s[8:9]
	v_cndmask_b32_e64 v114, v58, v50, s[8:9]
	v_cndmask_b32_e64 v115, v57, v49, s[8:9]
	v_cndmask_b32_e64 v116, v56, v48, s[8:9]
	v_mov_b32_e32 v99, 0
	v_mov_b32_e32 v101, 0
	v_mov_b32_e32 v100, 0
	v_mov_b32_e32 v102, 0
	v_mov_b32_dpp v93, v112 quad_perm:[1,0,3,2] row_mask:0xf bank_mask:0xf
	v_mov_b32_dpp v97, v111 quad_perm:[1,0,3,2] row_mask:0xf bank_mask:0xf
	v_mov_b32_dpp v95, v110 quad_perm:[1,0,3,2] row_mask:0xf bank_mask:0xf
	v_mov_b32_dpp v98, v103 quad_perm:[1,0,3,2] row_mask:0xf bank_mask:0xf
	v_mov_b32_dpp v99, v116 quad_perm:[1,0,3,2] row_mask:0xf bank_mask:0xf
	v_mov_b32_dpp v101, v115 quad_perm:[1,0,3,2] row_mask:0xf bank_mask:0xf
	v_mov_b32_dpp v100, v114 quad_perm:[1,0,3,2] row_mask:0xf bank_mask:0xf
	v_mov_b32_dpp v102, v113 quad_perm:[1,0,3,2] row_mask:0xf bank_mask:0xf
	v_cndmask_b32_e64 v61, v97, v61, s[8:9]
	v_cndmask_b32_e64 v60, v93, v60, s[8:9]
	v_cndmask_b32_e64 v63, v98, v63, s[8:9]
	v_cndmask_b32_e64 v62, v95, v62, s[8:9]
	v_cndmask_b32_e64 v57, v101, v57, s[8:9]
	v_cndmask_b32_e64 v56, v99, v56, s[8:9]
	v_cndmask_b32_e64 v59, v102, v59, s[8:9]
	v_cndmask_b32_e64 v58, v100, v58, s[8:9]
	v_mov_b32_e32 v108, v165
	v_mov_b32_e32 v109, v165
	v_lshlrev_b32_e32 v110, 16, v104
	v_and_b32_e32 v111, 0xffff0000, v104
	v_lshlrev_b32_e32 v104, 16, v105
	v_and_b32_e32 v105, 0xffff0000, v105
	v_lshlrev_b32_e32 v112, 16, v106
	v_and_b32_e32 v113, 0xffff0000, v106
	v_lshlrev_b32_e32 v106, 16, v107
	v_and_b32_e32 v107, 0xffff0000, v107
	v_pk_fma_f32 v[62:63], v[104:105], s[18:19], v[62:63] op_sel_hi:[1,0,1]
	v_pk_fma_f32 v[60:61], v[110:111], s[18:19], v[60:61] op_sel_hi:[1,0,1]
	v_pk_fma_f32 v[58:59], v[106:107], s[18:19], v[58:59] op_sel_hi:[1,0,1]
	v_pk_fma_f32 v[56:57], v[112:113], s[18:19], v[56:57] op_sel_hi:[1,0,1]
	v_cvt_pk_bf16_f32 v60, v60, v61
	v_cvt_pk_bf16_f32 v61, v62, v63
	s_nop 0
	v_cvt_pk_bf16_f32 v62, v56, v57
	v_cvt_pk_bf16_f32 v63, v58, v59
	v_lshlrev_b32_e32 v56, 16, v60
	v_and_b32_e32 v58, 0xffff0000, v60
	v_lshlrev_b32_e32 v104, 16, v61
	v_and_b32_e32 v106, 0xffff0000, v61
	v_lshlrev_b32_e32 v110, 16, v62
	v_and_b32_e32 v112, 0xffff0000, v62
	v_lshlrev_b32_e32 v114, 16, v63
	v_and_b32_e32 v116, 0xffff0000, v63
	v_mul_f32_e32 v57, v56, v56
	v_mul_f32_e32 v59, v58, v58
	v_mul_f32_e32 v105, v104, v104
	v_mul_f32_e32 v107, v106, v106
	v_mul_f32_e32 v111, v110, v110
	v_mul_f32_e32 v113, v112, v112
	v_mul_f32_e32 v115, v114, v114
	v_mul_f32_e32 v117, v116, v116
	v_pk_add_f32 v[56:57], v[56:57], v[58:59]
	v_pk_add_f32 v[58:59], v[104:105], v[106:107]
	v_pk_add_f32 v[104:105], v[110:111], v[112:113]
	v_pk_add_f32 v[106:107], v[114:115], v[116:117]
	v_pk_add_f32 v[56:57], v[56:57], v[58:59]
	v_pk_add_f32 v[58:59], v[104:105], v[106:107]
	global_store_dwordx4 v96, v[60:63], s[54:55]
	v_pk_add_f32 v[56:57], v[56:57], v[58:59]
	s_nop 1
	v_mov_b32_dpp v108, v56 quad_perm:[1,0,3,2] row_mask:0xf bank_mask:0xf
	v_mov_b32_dpp v109, v57 quad_perm:[1,0,3,2] row_mask:0xf bank_mask:0xf
	v_pk_add_f32 v[56:57], v[56:57], v[108:109]
	v_mov_b32_e32 v58, v56
	v_mov_b32_e32 v59, v57
	s_nop 1
	v_permlane16_swap_b32_e32 v56, v58
	v_permlane16_swap_b32_e32 v57, v59
	s_waitcnt lgkmcnt(0)
	v_pk_add_f32 v[56:57], v[56:57], v[58:59]
	v_mov_b32_e32 v58, v56
	v_mov_b32_e32 v59, v57
	s_nop 1
	v_permlane32_swap_b32_e32 v56, v58
	v_permlane32_swap_b32_e32 v57, v59
	s_and_saveexec_b64 s[56:57], s[10:11]
	s_cbranch_execz .LBB0_600
	s_waitcnt lgkmcnt(0)
	v_pk_add_f32 v[56:57], v[56:57], v[58:59]
	v_add_co_u32_e32 v58, vcc, 0x10000, v124
	s_nop 1
	v_addc_co_u32_e32 v59, vcc, 0, v125, vcc
	global_store_dwordx2 v[58:59], v[56:57], off
; __device__ __forceinline__ u32x4 pack8f(f32x4 a, f32x4 b) { u32x4 w; w.x = cvt_pk_bf16(a[0], a[1]); w.y = cvt_pk_bf16(a[2], a[3]); w.z = cvt_pk_bf16(b[0], b[1]); w.w = cvt_pk_bf16(b[2], b[3]); return w; }
;     __device__ __forceinline__ void operator()(const f32x4 (&acc)[2][2][4][2], const Unit& u, int wr, int wc, int fr, int fq, const EpiCtx& X) const {
;     ...
;             for (int m = 0; m < 4; ++m) {
;                 const int rl = ai * HALF + m * 16; const unsigned off = lo + (unsigned)(rl * 64) * 2u;
;                 const f32x4 o0a = acc[ai][0][m][0], o0b = acc[ai][0][m][1], o1a = acc[ai][1][m][0], o1b = acc[ai][1][m][1];
;                 const f32x4 ra_ = dpp_swap1(odd ? o0a : o1a), rb_ = dpp_swap1(odd ? o0b : o1b);
;                 const f32x4 pa[2] = {odd ? ra_ : o0a, odd ? o1a : ra_}, pb[2] = {odd ? rb_ : o0b, odd ? o1b : rb_};
; #pragma unroll
;                 for (int q = 0; q < 2; ++q) {
;                     const u32x4 w0 = raw[2 * m + q];
;                     const f32x4 r0 = (f32x4){bf_lo(w0.x), bf_hi(w0.x), bf_lo(w0.y), bf_hi(w0.y)}, r1 = (f32x4){bf_lo(w0.z), bf_hi(w0.z), bf_lo(w0.w), bf_hi(w0.w)};
;                     f32x4 y0, y1;
;                     if (RESN) { const f32x2 t = tbl[rl + q]; const float mu = t.x, ra = t.y * ALPHA; y0 = (r0 - mu) * ra * g0 + b0 + pa[q]; y1 = (r1 - mu) * ra * g1 + b1 + pb[q]; }
;                     else { y0 = r0 * ALPHA + pa[q]; y1 = r1 * ALPHA + pb[q]; }
;                     { const u32x4 w = pack8f(y0, y1); *(u32x4*)(xb + off + q * 128) = w;
;                         y0 = (f32x4){bf_lo(w.x), bf_hi(w.x), bf_lo(w.y), bf_hi(w.y)}; y1 = (f32x4){bf_lo(w.z), bf_hi(w.z), bf_lo(w.w), bf_hi(w.w)}; }
;                     float sa = ((y0[0] + y0[1]) + (y0[2] + y0[3])) + ((y1[0] + y1[1]) + (y1[2] + y1[3]));
;                     float sb = ((y0[0] * y0[0] + y0[1] * y0[1]) + (y0[2] * y0[2] + y0[3] * y0[3])) + ((y1[0] * y1[0] + y1[1] * y1[1]) + (y1[2] * y1[2] + y1[3] * y1[3]));
;                     sa += dpp_x1(sa);
;                     sb += dpp_x1(sb);
;                     sa += __shfl_xor(sa, 16); sa += __shfl_xor(sa, 32); sb += __shfl_xor(sb, 16); sb += __shfl_xor(sb, 32);
;                     if (fq == 0 && !odd) ps[(size_t)(rl + q) * 64] = (f32x2){sa, sb};
;                 }
.LBB0_600:
	s_or_b64 exec, exec, s[56:57]
	v_cndmask_b32_e64 v53, v53, v97, s[8:9]
	v_cndmask_b32_e64 v52, v52, v93, s[8:9]
	v_cndmask_b32_e64 v55, v55, v98, s[8:9]
	v_cndmask_b32_e64 v54, v54, v95, s[8:9]
	v_cndmask_b32_e64 v49, v49, v101, s[8:9]
	v_cndmask_b32_e64 v48, v48, v99, s[8:9]
	v_cndmask_b32_e64 v51, v51, v102, s[8:9]
	v_cndmask_b32_e64 v50, v50, v100, s[8:9]
	v_lshlrev_b32_e32 v56, 16, v88
	v_and_b32_e32 v57, 0xffff0000, v88
	s_waitcnt lgkmcnt(0)
	v_lshlrev_b32_e32 v58, 16, v89
	s_waitcnt lgkmcnt(0)
	v_and_b32_e32 v59, 0xffff0000, v89
	v_lshlrev_b32_e32 v60, 16, v90
	v_and_b32_e32 v61, 0xffff0000, v90
	v_lshlrev_b32_e32 v62, 16, v91
	v_and_b32_e32 v63, 0xffff0000, v91
	v_pk_fma_f32 v[54:55], v[58:59], s[18:19], v[54:55] op_sel_hi:[1,0,1]
	v_pk_fma_f32 v[52:53], v[56:57], s[18:19], v[52:53] op_sel_hi:[1,0,1]
	v_pk_fma_f32 v[50:51], v[62:63], s[18:19], v[50:51] op_sel_hi:[1,0,1]
	v_pk_fma_f32 v[48:49], v[60:61], s[18:19], v[48:49] op_sel_hi:[1,0,1]
	v_cvt_pk_bf16_f32 v52, v52, v53
	v_cvt_pk_bf16_f32 v53, v54, v55
	v_mov_b32_e32 v97, v165
	v_cvt_pk_bf16_f32 v54, v48, v49
	v_cvt_pk_bf16_f32 v55, v50, v51
	v_lshlrev_b32_e32 v48, 16, v52
	v_and_b32_e32 v50, 0xffff0000, v52
	v_lshlrev_b32_e32 v56, 16, v53
	v_and_b32_e32 v58, 0xffff0000, v53
	v_lshlrev_b32_e32 v60, 16, v54
	v_and_b32_e32 v62, 0xffff0000, v54
	v_lshlrev_b32_e32 v88, 16, v55
	v_and_b32_e32 v90, 0xffff0000, v55
	v_mul_f32_e32 v49, v48, v48
	v_mul_f32_e32 v51, v50, v50
	v_mul_f32_e32 v57, v56, v56
	v_mul_f32_e32 v59, v58, v58
	v_mul_f32_e32 v61, v60, v60
	v_mul_f32_e32 v63, v62, v62
	v_mul_f32_e32 v89, v88, v88
	v_mul_f32_e32 v91, v90, v90
	v_pk_add_f32 v[48:49], v[48:49], v[50:51]
	v_pk_add_f32 v[50:51], v[56:57], v[58:59]
	v_pk_add_f32 v[56:57], v[88:89], v[90:91]
	v_pk_add_f32 v[48:49], v[48:49], v[50:51]
	v_pk_add_f32 v[50:51], v[60:61], v[62:63]
	s_nop 0
	v_pk_add_f32 v[50:51], v[50:51], v[56:57]
	v_lshl_add_u64 v[56:57], s[54:55], 0, v[96:97]
	v_pk_add_f32 v[48:49], v[48:49], v[50:51]
	v_mov_b32_e32 v50, v165
	v_mov_b32_e32 v51, v165
	global_store_dwordx4 v[56:57], v[52:55], off offset:128
	v_mov_b32_dpp v50, v48 quad_perm:[1,0,3,2] row_mask:0xf bank_mask:0xf
	v_mov_b32_dpp v51, v49 quad_perm:[1,0,3,2] row_mask:0xf bank_mask:0xf
	v_pk_add_f32 v[48:49], v[48:49], v[50:51]
	v_mov_b32_e32 v50, v48
	v_mov_b32_e32 v51, v49
	s_nop 1
	v_permlane16_swap_b32_e32 v48, v50
	v_permlane16_swap_b32_e32 v49, v51
	s_waitcnt lgkmcnt(0)
	v_pk_add_f32 v[48:49], v[48:49], v[50:51]
	v_mov_b32_e32 v50, v48
	v_mov_b32_e32 v51, v49
	s_nop 1
	v_permlane32_swap_b32_e32 v48, v50
	v_permlane32_swap_b32_e32 v49, v51
	s_and_saveexec_b64 s[56:57], s[10:11]
	s_cbranch_execz .LBB0_602
	s_waitcnt lgkmcnt(0)
	v_pk_add_f32 v[48:49], v[48:49], v[50:51]
	v_add_co_u32_e32 v50, vcc, 0x10000, v124
	s_nop 1
	v_addc_co_u32_e32 v51, vcc, 0, v125, vcc
	global_store_dwordx2 v[50:51], v[48:49], off offset:512
.LBB0_602:
	s_or_b64 exec, exec, s[56:57]
	s_waitcnt lgkmcnt(0)
	v_cndmask_b32_e64 v50, v44, v36, s[8:9]
	v_mov_b32_e32 v48, 0
	v_cndmask_b32_e64 v49, v45, v37, s[8:9]
	s_waitcnt lgkmcnt(0)
	v_cndmask_b32_e64 v51, v46, v38, s[8:9]
	v_mov_b32_dpp v48, v50 quad_perm:[1,0,3,2] row_mask:0xf bank_mask:0xf
	v_mov_b32_e32 v50, 0
	v_cndmask_b32_e64 v52, v47, v39, s[8:9]
	v_cndmask_b32_e64 v54, v40, v32, s[8:9]
	v_mov_b32_dpp v50, v49 quad_perm:[1,0,3,2] row_mask:0xf bank_mask:0xf
	v_mov_b32_e32 v49, 0
	v_cndmask_b32_e64 v53, v41, v33, s[8:9]
	v_cndmask_b32_e64 v55, v42, v34, s[8:9]
	v_mov_b32_dpp v49, v51 quad_perm:[1,0,3,2] row_mask:0xf bank_mask:0xf
	v_mov_b32_e32 v51, 0
	v_cndmask_b32_e64 v56, v43, v35, s[8:9]
	v_cndmask_b32_e64 v45, v50, v45, s[8:9]
	v_mov_b32_dpp v51, v52 quad_perm:[1,0,3,2] row_mask:0xf bank_mask:0xf
	v_mov_b32_e32 v52, 0
	v_cndmask_b32_e64 v44, v48, v44, s[8:9]
	v_cndmask_b32_e64 v47, v51, v47, s[8:9]
	v_mov_b32_dpp v52, v54 quad_perm:[1,0,3,2] row_mask:0xf bank_mask:0xf
	v_mov_b32_e32 v54, 0
	v_cndmask_b32_e64 v46, v49, v46, s[8:9]
	v_cndmask_b32_e64 v40, v52, v40, s[8:9]
	v_mov_b32_dpp v54, v53 quad_perm:[1,0,3,2] row_mask:0xf bank_mask:0xf
	v_mov_b32_e32 v53, 0
	v_cndmask_b32_e64 v41, v54, v41, s[8:9]
	v_and_b32_e32 v57, 0xffff0000, v84
	v_mov_b32_dpp v53, v55 quad_perm:[1,0,3,2] row_mask:0xf bank_mask:0xf
	v_mov_b32_e32 v55, 0
	v_cndmask_b32_e64 v42, v53, v42, s[8:9]
	v_lshlrev_b32_e32 v58, 16, v85
	v_mov_b32_dpp v55, v56 quad_perm:[1,0,3,2] row_mask:0xf bank_mask:0xf
	v_cndmask_b32_e64 v43, v55, v43, s[8:9]
	v_lshlrev_b32_e32 v56, 16, v84
	v_and_b32_e32 v59, 0xffff0000, v85
	v_lshlrev_b32_e32 v60, 16, v86
	v_and_b32_e32 v61, 0xffff0000, v86
	v_lshlrev_b32_e32 v62, 16, v87
	v_and_b32_e32 v63, 0xffff0000, v87
	v_pk_fma_f32 v[46:47], v[58:59], s[18:19], v[46:47] op_sel_hi:[1,0,1]
	v_pk_fma_f32 v[44:45], v[56:57], s[18:19], v[44:45] op_sel_hi:[1,0,1]
	v_pk_fma_f32 v[42:43], v[62:63], s[18:19], v[42:43] op_sel_hi:[1,0,1]
	v_pk_fma_f32 v[40:41], v[60:61], s[18:19], v[40:41] op_sel_hi:[1,0,1]
	v_cvt_pk_bf16_f32 v56, v44, v45
	v_cvt_pk_bf16_f32 v57, v46, v47
	v_mov_b32_e32 v95, v165
	v_cvt_pk_bf16_f32 v58, v40, v41
	v_cvt_pk_bf16_f32 v59, v42, v43
	v_lshlrev_b32_e32 v40, 16, v56
	v_and_b32_e32 v42, 0xffff0000, v56
	v_lshlrev_b32_e32 v44, 16, v57
	v_and_b32_e32 v46, 0xffff0000, v57
	v_lshlrev_b32_e32 v60, 16, v58
	v_and_b32_e32 v62, 0xffff0000, v58
	v_lshlrev_b32_e32 v84, 16, v59
	v_and_b32_e32 v86, 0xffff0000, v59
	v_mul_f32_e32 v41, v40, v40
	v_mul_f32_e32 v43, v42, v42
	v_mul_f32_e32 v45, v44, v44
	v_mul_f32_e32 v47, v46, v46
	v_mul_f32_e32 v61, v60, v60
	v_mul_f32_e32 v63, v62, v62
	v_mul_f32_e32 v85, v84, v84
	v_mul_f32_e32 v87, v86, v86
	v_pk_add_f32 v[40:41], v[40:41], v[42:43]
	v_pk_add_f32 v[42:43], v[44:45], v[46:47]
	v_pk_add_f32 v[44:45], v[84:85], v[86:87]
	v_pk_add_f32 v[40:41], v[40:41], v[42:43]
	v_pk_add_f32 v[42:43], v[60:61], v[62:63]
	s_nop 0
	v_pk_add_f32 v[42:43], v[42:43], v[44:45]
	s_nop 0
	v_pk_add_f32 v[40:41], v[40:41], v[42:43]
	v_mov_b32_e32 v42, v165
	v_mov_b32_e32 v43, v165
	s_nop 0
	v_mov_b32_dpp v42, v40 quad_perm:[1,0,3,2] row_mask:0xf bank_mask:0xf
	v_mov_b32_dpp v43, v41 quad_perm:[1,0,3,2] row_mask:0xf bank_mask:0xf
	v_pk_add_f32 v[40:41], v[40:41], v[42:43]
	v_mov_b32_e32 v42, v40
	v_mov_b32_e32 v43, v41
	s_nop 1
	v_permlane16_swap_b32_e32 v40, v42
	v_permlane16_swap_b32_e32 v41, v43
	s_waitcnt lgkmcnt(0)
	v_pk_add_f32 v[42:43], v[40:41], v[42:43]
	v_mov_b32_e32 v44, v42
	v_mov_b32_e32 v45, v43
	s_nop 1
	v_permlane32_swap_b32_e32 v42, v44
	v_permlane32_swap_b32_e32 v43, v45
	v_lshl_add_u64 v[40:41], s[54:55], 0, v[94:95]
	global_store_dwordx4 v[40:41], v[56:59], off
	s_and_saveexec_b64 s[56:57], s[10:11]
	s_cbranch_execz .LBB0_604
	s_waitcnt lgkmcnt(0)
	v_pk_add_f32 v[42:43], v[42:43], v[44:45]
	v_add_co_u32_e32 v44, vcc, 0x12000, v124
	s_nop 1
	v_addc_co_u32_e32 v45, vcc, 0, v125, vcc
	global_store_dwordx2 v[44:45], v[42:43], off
; __device__ __forceinline__ u32x4 pack8f(f32x4 a, f32x4 b) { u32x4 w; w.x = cvt_pk_bf16(a[0], a[1]); w.y = cvt_pk_bf16(a[2], a[3]); w.z = cvt_pk_bf16(b[0], b[1]); w.w = cvt_pk_bf16(b[2], b[3]); return w; }
;     __device__ __forceinline__ void operator()(const f32x4 (&acc)[2][2][4][2], const Unit& u, int wr, int wc, int fr, int fq, const EpiCtx& X) const {
;     ...
;             for (int m = 0; m < 4; ++m) {
;                 const int rl = ai * HALF + m * 16; const unsigned off = lo + (unsigned)(rl * 64) * 2u;
;                 const f32x4 o0a = acc[ai][0][m][0], o0b = acc[ai][0][m][1], o1a = acc[ai][1][m][0], o1b = acc[ai][1][m][1];
;                 const f32x4 ra_ = dpp_swap1(odd ? o0a : o1a), rb_ = dpp_swap1(odd ? o0b : o1b);
;                 const f32x4 pa[2] = {odd ? ra_ : o0a, odd ? o1a : ra_}, pb[2] = {odd ? rb_ : o0b, odd ? o1b : rb_};
; #pragma unroll
;                 for (int q = 0; q < 2; ++q) {
;                     const u32x4 w0 = raw[2 * m + q];
;                     const f32x4 r0 = (f32x4){bf_lo(w0.x), bf_hi(w0.x), bf_lo(w0.y), bf_hi(w0.y)}, r1 = (f32x4){bf_lo(w0.z), bf_hi(w0.z), bf_lo(w0.w), bf_hi(w0.w)};
;                     f32x4 y0, y1;
;                     if (RESN) { const f32x2 t = tbl[rl + q]; const float mu = t.x, ra = t.y * ALPHA; y0 = (r0 - mu) * ra * g0 + b0 + pa[q]; y1 = (r1 - mu) * ra * g1 + b1 + pb[q]; }
;                     else { y0 = r0 * ALPHA + pa[q]; y1 = r1 * ALPHA + pb[q]; }
;                     { const u32x4 w = pack8f(y0, y1); *(u32x4*)(xb + off + q * 128) = w;
;                         y0 = (f32x4){bf_lo(w.x), bf_hi(w.x), bf_lo(w.y), bf_hi(w.y)}; y1 = (f32x4){bf_lo(w.z), bf_hi(w.z), bf_lo(w.w), bf_hi(w.w)}; }
;                     float sa = ((y0[0] + y0[1]) + (y0[2] + y0[3])) + ((y1[0] + y1[1]) + (y1[2] + y1[3]));
;                     float sb = ((y0[0] * y0[0] + y0[1] * y0[1]) + (y0[2] * y0[2] + y0[3] * y0[3])) + ((y1[0] * y1[0] + y1[1] * y1[1]) + (y1[2] * y1[2] + y1[3] * y1[3]));
;                     sa += dpp_x1(sa);
;                     sb += dpp_x1(sb);
;                     sa += __shfl_xor(sa, 16); sa += __shfl_xor(sa, 32); sb += __shfl_xor(sb, 16); sb += __shfl_xor(sb, 32);
;                     if (fq == 0 && !odd) ps[(size_t)(rl + q) * 64] = (f32x2){sa, sb};
;                 }
.LBB0_604:
	s_or_b64 exec, exec, s[56:57]
	v_cndmask_b32_e64 v37, v37, v50, s[8:9]
	v_cndmask_b32_e64 v36, v36, v48, s[8:9]
	v_cndmask_b32_e64 v39, v39, v51, s[8:9]
	v_cndmask_b32_e64 v38, v38, v49, s[8:9]
	v_cndmask_b32_e64 v33, v33, v54, s[8:9]
	v_cndmask_b32_e64 v32, v32, v52, s[8:9]
	v_cndmask_b32_e64 v35, v35, v55, s[8:9]
	v_cndmask_b32_e64 v34, v34, v53, s[8:9]
	v_lshlrev_b32_e32 v42, 16, v80
	v_and_b32_e32 v43, 0xffff0000, v80
	s_waitcnt lgkmcnt(0)
	v_lshlrev_b32_e32 v44, 16, v81
	s_waitcnt lgkmcnt(0)
	v_and_b32_e32 v45, 0xffff0000, v81
	v_lshlrev_b32_e32 v46, 16, v82
	v_and_b32_e32 v47, 0xffff0000, v82
	v_lshlrev_b32_e32 v48, 16, v83
	v_and_b32_e32 v49, 0xffff0000, v83
	v_pk_fma_f32 v[38:39], v[44:45], s[18:19], v[38:39] op_sel_hi:[1,0,1]
	v_pk_fma_f32 v[36:37], v[42:43], s[18:19], v[36:37] op_sel_hi:[1,0,1]
	v_pk_fma_f32 v[34:35], v[48:49], s[18:19], v[34:35] op_sel_hi:[1,0,1]
	v_pk_fma_f32 v[32:33], v[46:47], s[18:19], v[32:33] op_sel_hi:[1,0,1]
	v_cvt_pk_bf16_f32 v36, v36, v37
	v_cvt_pk_bf16_f32 v37, v38, v39
	s_nop 0
	v_cvt_pk_bf16_f32 v38, v32, v33
	v_cvt_pk_bf16_f32 v39, v34, v35
	v_lshlrev_b32_e32 v32, 16, v36
	v_and_b32_e32 v34, 0xffff0000, v36
	v_lshlrev_b32_e32 v42, 16, v37
	v_and_b32_e32 v44, 0xffff0000, v37
	v_lshlrev_b32_e32 v46, 16, v38
	v_and_b32_e32 v48, 0xffff0000, v38
	v_lshlrev_b32_e32 v50, 16, v39
	v_and_b32_e32 v52, 0xffff0000, v39
	v_mul_f32_e32 v33, v32, v32
	v_mul_f32_e32 v35, v34, v34
	v_mul_f32_e32 v43, v42, v42
	v_mul_f32_e32 v45, v44, v44
	v_mul_f32_e32 v47, v46, v46
	v_mul_f32_e32 v49, v48, v48
	v_mul_f32_e32 v51, v50, v50
	v_mul_f32_e32 v53, v52, v52
	v_pk_add_f32 v[32:33], v[32:33], v[34:35]
	v_pk_add_f32 v[34:35], v[42:43], v[44:45]
	v_pk_add_f32 v[42:43], v[50:51], v[52:53]
	v_pk_add_f32 v[32:33], v[32:33], v[34:35]
	v_pk_add_f32 v[34:35], v[46:47], v[48:49]
	global_store_dwordx4 v[40:41], v[36:39], off offset:128
	v_pk_add_f32 v[34:35], v[34:35], v[42:43]
	s_nop 0
	v_pk_add_f32 v[32:33], v[32:33], v[34:35]
	v_mov_b32_e32 v34, v165
	v_mov_b32_e32 v35, v165
	s_nop 0
	v_mov_b32_dpp v34, v32 quad_perm:[1,0,3,2] row_mask:0xf bank_mask:0xf
	v_mov_b32_dpp v35, v33 quad_perm:[1,0,3,2] row_mask:0xf bank_mask:0xf
	v_pk_add_f32 v[32:33], v[32:33], v[34:35]
	v_mov_b32_e32 v34, v32
	v_mov_b32_e32 v35, v33
	s_nop 1
	v_permlane16_swap_b32_e32 v32, v34
	v_permlane16_swap_b32_e32 v33, v35
	s_waitcnt lgkmcnt(0)
	v_pk_add_f32 v[32:33], v[32:33], v[34:35]
	v_mov_b32_e32 v34, v32
	v_mov_b32_e32 v35, v33
	s_nop 1
	v_permlane32_swap_b32_e32 v32, v34
	v_permlane32_swap_b32_e32 v33, v35
	s_and_saveexec_b64 s[56:57], s[10:11]
	s_cbranch_execz .LBB0_606
	s_waitcnt lgkmcnt(0)
	v_pk_add_f32 v[32:33], v[32:33], v[34:35]
	v_add_co_u32_e32 v34, vcc, 0x12000, v124
	s_nop 1
	v_addc_co_u32_e32 v35, vcc, 0, v125, vcc
	global_store_dwordx2 v[34:35], v[32:33], off offset:512
.LBB0_606:
	s_or_b64 exec, exec, s[56:57]
	s_waitcnt lgkmcnt(0)
	v_cndmask_b32_e64 v34, v28, v20, s[8:9]
	v_mov_b32_e32 v32, 0
	v_cndmask_b32_e64 v33, v29, v21, s[8:9]
	s_waitcnt lgkmcnt(0)
	v_cndmask_b32_e64 v35, v30, v22, s[8:9]
	v_mov_b32_dpp v32, v34 quad_perm:[1,0,3,2] row_mask:0xf bank_mask:0xf
	v_mov_b32_e32 v34, 0
	v_cndmask_b32_e64 v36, v31, v23, s[8:9]
	v_cndmask_b32_e64 v38, v24, v16, s[8:9]
	v_mov_b32_dpp v34, v33 quad_perm:[1,0,3,2] row_mask:0xf bank_mask:0xf
	v_mov_b32_e32 v33, 0
	v_cndmask_b32_e64 v37, v25, v17, s[8:9]
	v_cndmask_b32_e64 v39, v26, v18, s[8:9]
	v_mov_b32_dpp v33, v35 quad_perm:[1,0,3,2] row_mask:0xf bank_mask:0xf
	v_mov_b32_e32 v35, 0
	v_cndmask_b32_e64 v40, v27, v19, s[8:9]
	v_cndmask_b32_e64 v29, v34, v29, s[8:9]
	v_mov_b32_dpp v35, v36 quad_perm:[1,0,3,2] row_mask:0xf bank_mask:0xf
	v_mov_b32_e32 v36, 0
	v_cndmask_b32_e64 v28, v32, v28, s[8:9]
	v_cndmask_b32_e64 v31, v35, v31, s[8:9]
	v_mov_b32_dpp v36, v38 quad_perm:[1,0,3,2] row_mask:0xf bank_mask:0xf
	v_mov_b32_e32 v38, 0
	v_cndmask_b32_e64 v30, v33, v30, s[8:9]
	v_cndmask_b32_e64 v24, v36, v24, s[8:9]
	v_mov_b32_dpp v38, v37 quad_perm:[1,0,3,2] row_mask:0xf bank_mask:0xf
	v_mov_b32_e32 v37, 0
	v_cndmask_b32_e64 v25, v38, v25, s[8:9]
	s_waitcnt vmcnt(11)
	v_and_b32_e32 v41, 0xffff0000, v76
	v_mov_b32_dpp v37, v39 quad_perm:[1,0,3,2] row_mask:0xf bank_mask:0xf
	v_mov_b32_e32 v39, 0
	v_cndmask_b32_e64 v26, v37, v26, s[8:9]
	v_lshlrev_b32_e32 v42, 16, v77
	v_mov_b32_dpp v39, v40 quad_perm:[1,0,3,2] row_mask:0xf bank_mask:0xf
	v_cndmask_b32_e64 v27, v39, v27, s[8:9]
	v_lshlrev_b32_e32 v40, 16, v76
	v_and_b32_e32 v43, 0xffff0000, v77
	v_lshlrev_b32_e32 v44, 16, v78
	v_and_b32_e32 v45, 0xffff0000, v78
	v_lshlrev_b32_e32 v46, 16, v79
	v_and_b32_e32 v47, 0xffff0000, v79
	v_pk_fma_f32 v[30:31], v[42:43], s[18:19], v[30:31] op_sel_hi:[1,0,1]
	v_pk_fma_f32 v[28:29], v[40:41], s[18:19], v[28:29] op_sel_hi:[1,0,1]
	v_pk_fma_f32 v[26:27], v[46:47], s[18:19], v[26:27] op_sel_hi:[1,0,1]
	v_pk_fma_f32 v[24:25], v[44:45], s[18:19], v[24:25] op_sel_hi:[1,0,1]
	v_cvt_pk_bf16_f32 v40, v28, v29
	v_cvt_pk_bf16_f32 v41, v30, v31
	v_mov_b32_e32 v93, v165
	v_cvt_pk_bf16_f32 v42, v24, v25
	v_cvt_pk_bf16_f32 v43, v26, v27
	v_lshlrev_b32_e32 v24, 16, v40
	v_and_b32_e32 v26, 0xffff0000, v40
	v_lshlrev_b32_e32 v28, 16, v41
	v_and_b32_e32 v30, 0xffff0000, v41
	v_lshlrev_b32_e32 v44, 16, v42
	v_and_b32_e32 v46, 0xffff0000, v42
	v_lshlrev_b32_e32 v48, 16, v43
	v_and_b32_e32 v50, 0xffff0000, v43
	v_mul_f32_e32 v25, v24, v24
	v_mul_f32_e32 v27, v26, v26
	v_mul_f32_e32 v29, v28, v28
	v_mul_f32_e32 v31, v30, v30
	v_mul_f32_e32 v45, v44, v44
	v_mul_f32_e32 v47, v46, v46
	v_mul_f32_e32 v49, v48, v48
	v_mul_f32_e32 v51, v50, v50
	v_pk_add_f32 v[24:25], v[24:25], v[26:27]
	v_pk_add_f32 v[26:27], v[28:29], v[30:31]
	v_pk_add_f32 v[28:29], v[48:49], v[50:51]
	v_pk_add_f32 v[24:25], v[24:25], v[26:27]
	v_pk_add_f32 v[26:27], v[44:45], v[46:47]
	s_nop 0
	v_pk_add_f32 v[26:27], v[26:27], v[28:29]
	s_nop 0
	v_pk_add_f32 v[24:25], v[24:25], v[26:27]
	v_mov_b32_e32 v26, v165
	v_mov_b32_e32 v27, v165
	s_nop 0
	v_mov_b32_dpp v26, v24 quad_perm:[1,0,3,2] row_mask:0xf bank_mask:0xf
	v_mov_b32_dpp v27, v25 quad_perm:[1,0,3,2] row_mask:0xf bank_mask:0xf
	v_pk_add_f32 v[24:25], v[24:25], v[26:27]
	v_mov_b32_e32 v26, v24
	v_mov_b32_e32 v27, v25
	s_nop 1
	v_permlane16_swap_b32_e32 v24, v26
	v_permlane16_swap_b32_e32 v25, v27
	s_waitcnt lgkmcnt(0)
	v_pk_add_f32 v[26:27], v[24:25], v[26:27]
	v_mov_b32_e32 v28, v26
	v_mov_b32_e32 v29, v27
	s_nop 1
	v_permlane32_swap_b32_e32 v26, v28
	v_permlane32_swap_b32_e32 v27, v29
	v_lshl_add_u64 v[24:25], s[54:55], 0, v[92:93]
	global_store_dwordx4 v[24:25], v[40:43], off
	s_and_saveexec_b64 s[56:57], s[10:11]
	s_cbranch_execz .LBB0_608
	s_waitcnt lgkmcnt(0)
	v_pk_add_f32 v[26:27], v[26:27], v[28:29]
	v_add_co_u32_e32 v28, vcc, 0x14000, v124
	s_nop 1
	v_addc_co_u32_e32 v29, vcc, 0, v125, vcc
	global_store_dwordx2 v[28:29], v[26:27], off
; __device__ __forceinline__ u32x4 pack8f(f32x4 a, f32x4 b) { u32x4 w; w.x = cvt_pk_bf16(a[0], a[1]); w.y = cvt_pk_bf16(a[2], a[3]); w.z = cvt_pk_bf16(b[0], b[1]); w.w = cvt_pk_bf16(b[2], b[3]); return w; }
;     __device__ __forceinline__ void operator()(const f32x4 (&acc)[2][2][4][2], const Unit& u, int wr, int wc, int fr, int fq, const EpiCtx& X) const {
;     ...
;             for (int m = 0; m < 4; ++m) {
;                 const int rl = ai * HALF + m * 16; const unsigned off = lo + (unsigned)(rl * 64) * 2u;
;                 const f32x4 o0a = acc[ai][0][m][0], o0b = acc[ai][0][m][1], o1a = acc[ai][1][m][0], o1b = acc[ai][1][m][1];
;                 const f32x4 ra_ = dpp_swap1(odd ? o0a : o1a), rb_ = dpp_swap1(odd ? o0b : o1b);
;                 const f32x4 pa[2] = {odd ? ra_ : o0a, odd ? o1a : ra_}, pb[2] = {odd ? rb_ : o0b, odd ? o1b : rb_};
; #pragma unroll
;                 for (int q = 0; q < 2; ++q) {
;                     const u32x4 w0 = raw[2 * m + q];
;                     const f32x4 r0 = (f32x4){bf_lo(w0.x), bf_hi(w0.x), bf_lo(w0.y), bf_hi(w0.y)}, r1 = (f32x4){bf_lo(w0.z), bf_hi(w0.z), bf_lo(w0.w), bf_hi(w0.w)};
;                     f32x4 y0, y1;
;                     if (RESN) { const f32x2 t = tbl[rl + q]; const float mu = t.x, ra = t.y * ALPHA; y0 = (r0 - mu) * ra * g0 + b0 + pa[q]; y1 = (r1 - mu) * ra * g1 + b1 + pb[q]; }
;                     else { y0 = r0 * ALPHA + pa[q]; y1 = r1 * ALPHA + pb[q]; }
;                     { const u32x4 w = pack8f(y0, y1); *(u32x4*)(xb + off + q * 128) = w;
;                         y0 = (f32x4){bf_lo(w.x), bf_hi(w.x), bf_lo(w.y), bf_hi(w.y)}; y1 = (f32x4){bf_lo(w.z), bf_hi(w.z), bf_lo(w.w), bf_hi(w.w)}; }
;                     float sa = ((y0[0] + y0[1]) + (y0[2] + y0[3])) + ((y1[0] + y1[1]) + (y1[2] + y1[3]));
;                     float sb = ((y0[0] * y0[0] + y0[1] * y0[1]) + (y0[2] * y0[2] + y0[3] * y0[3])) + ((y1[0] * y1[0] + y1[1] * y1[1]) + (y1[2] * y1[2] + y1[3] * y1[3]));
;                     sa += dpp_x1(sa);
;                     sb += dpp_x1(sb);
;                     sa += __shfl_xor(sa, 16); sa += __shfl_xor(sa, 32); sb += __shfl_xor(sb, 16); sb += __shfl_xor(sb, 32);
;                     if (fq == 0 && !odd) ps[(size_t)(rl + q) * 64] = (f32x2){sa, sb};
;                 }
.LBB0_608:
	s_or_b64 exec, exec, s[56:57]
	v_cndmask_b32_e64 v21, v21, v34, s[8:9]
	v_cndmask_b32_e64 v20, v20, v32, s[8:9]
	v_cndmask_b32_e64 v23, v23, v35, s[8:9]
	v_cndmask_b32_e64 v22, v22, v33, s[8:9]
	v_cndmask_b32_e64 v17, v17, v38, s[8:9]
	v_cndmask_b32_e64 v16, v16, v36, s[8:9]
	v_cndmask_b32_e64 v19, v19, v39, s[8:9]
	v_cndmask_b32_e64 v18, v18, v37, s[8:9]
	s_waitcnt vmcnt(12)
	v_lshlrev_b32_e32 v26, 16, v72
	v_and_b32_e32 v27, 0xffff0000, v72
	s_waitcnt lgkmcnt(0)
	v_lshlrev_b32_e32 v28, 16, v73
	s_waitcnt lgkmcnt(0)
	v_and_b32_e32 v29, 0xffff0000, v73
	v_lshlrev_b32_e32 v30, 16, v74
	v_and_b32_e32 v31, 0xffff0000, v74
	v_lshlrev_b32_e32 v32, 16, v75
	v_and_b32_e32 v33, 0xffff0000, v75
	v_pk_fma_f32 v[22:23], v[28:29], s[18:19], v[22:23] op_sel_hi:[1,0,1]
	v_pk_fma_f32 v[20:21], v[26:27], s[18:19], v[20:21] op_sel_hi:[1,0,1]
	v_pk_fma_f32 v[18:19], v[32:33], s[18:19], v[18:19] op_sel_hi:[1,0,1]
	v_pk_fma_f32 v[16:17], v[30:31], s[18:19], v[16:17] op_sel_hi:[1,0,1]
	v_cvt_pk_bf16_f32 v20, v20, v21
	v_cvt_pk_bf16_f32 v21, v22, v23
	s_nop 0
	v_cvt_pk_bf16_f32 v22, v16, v17
	v_cvt_pk_bf16_f32 v23, v18, v19
	v_lshlrev_b32_e32 v16, 16, v20
	v_and_b32_e32 v18, 0xffff0000, v20
	v_lshlrev_b32_e32 v26, 16, v21
	v_and_b32_e32 v28, 0xffff0000, v21
	v_lshlrev_b32_e32 v30, 16, v22
	v_and_b32_e32 v32, 0xffff0000, v22
	v_lshlrev_b32_e32 v34, 16, v23
	v_and_b32_e32 v36, 0xffff0000, v23
	v_mul_f32_e32 v17, v16, v16
	v_mul_f32_e32 v19, v18, v18
	v_mul_f32_e32 v27, v26, v26
	v_mul_f32_e32 v29, v28, v28
	v_mul_f32_e32 v31, v30, v30
	v_mul_f32_e32 v33, v32, v32
	v_mul_f32_e32 v35, v34, v34
	v_mul_f32_e32 v37, v36, v36
	v_pk_add_f32 v[16:17], v[16:17], v[18:19]
	v_pk_add_f32 v[18:19], v[26:27], v[28:29]
	v_pk_add_f32 v[26:27], v[34:35], v[36:37]
	v_pk_add_f32 v[16:17], v[16:17], v[18:19]
	v_pk_add_f32 v[18:19], v[30:31], v[32:33]
	global_store_dwordx4 v[24:25], v[20:23], off offset:128
	v_pk_add_f32 v[18:19], v[18:19], v[26:27]
	s_nop 0
	v_pk_add_f32 v[16:17], v[16:17], v[18:19]
	v_mov_b32_e32 v18, v165
	v_mov_b32_e32 v19, v165
	s_nop 0
	v_mov_b32_dpp v18, v16 quad_perm:[1,0,3,2] row_mask:0xf bank_mask:0xf
	v_mov_b32_dpp v19, v17 quad_perm:[1,0,3,2] row_mask:0xf bank_mask:0xf
	v_pk_add_f32 v[16:17], v[16:17], v[18:19]
	v_mov_b32_e32 v18, v16
	v_mov_b32_e32 v19, v17
	s_nop 1
	v_permlane16_swap_b32_e32 v16, v18
	v_permlane16_swap_b32_e32 v17, v19
	s_waitcnt lgkmcnt(0)
	v_pk_add_f32 v[16:17], v[16:17], v[18:19]
	v_mov_b32_e32 v18, v16
	v_mov_b32_e32 v19, v17
	s_nop 1
	v_permlane32_swap_b32_e32 v16, v18
	v_permlane32_swap_b32_e32 v17, v19
	s_and_saveexec_b64 s[56:57], s[10:11]
	s_cbranch_execz .LBB0_610
	s_waitcnt lgkmcnt(0)
	v_pk_add_f32 v[16:17], v[16:17], v[18:19]
	v_add_co_u32_e32 v18, vcc, 0x14000, v124
	s_nop 1
	v_addc_co_u32_e32 v19, vcc, 0, v125, vcc
	global_store_dwordx2 v[18:19], v[16:17], off offset:512
; __device__ __forceinline__ u32x4 pack8f(f32x4 a, f32x4 b) { u32x4 w; w.x = cvt_pk_bf16(a[0], a[1]); w.y = cvt_pk_bf16(a[2], a[3]); w.z = cvt_pk_bf16(b[0], b[1]); w.w = cvt_pk_bf16(b[2], b[3]); return w; }
;     __device__ __forceinline__ void operator()(const f32x4 (&acc)[2][2][4][2], const Unit& u, int wr, int wc, int fr, int fq, const EpiCtx& X) const {
;     ...
;             for (int m = 0; m < 4; ++m) {
;                 const int rl = ai * HALF + m * 16; const unsigned off = lo + (unsigned)(rl * 64) * 2u;
;                 const f32x4 o0a = acc[ai][0][m][0], o0b = acc[ai][0][m][1], o1a = acc[ai][1][m][0], o1b = acc[ai][1][m][1];
;                 const f32x4 ra_ = dpp_swap1(odd ? o0a : o1a), rb_ = dpp_swap1(odd ? o0b : o1b);
;                 const f32x4 pa[2] = {odd ? ra_ : o0a, odd ? o1a : ra_}, pb[2] = {odd ? rb_ : o0b, odd ? o1b : rb_};
; #pragma unroll
;                 for (int q = 0; q < 2; ++q) {
;                     const u32x4 w0 = raw[2 * m + q];
;                     const f32x4 r0 = (f32x4){bf_lo(w0.x), bf_hi(w0.x), bf_lo(w0.y), bf_hi(w0.y)}, r1 = (f32x4){bf_lo(w0.z), bf_hi(w0.z), bf_lo(w0.w), bf_hi(w0.w)};
;                     f32x4 y0, y1;
;                     if (RESN) { const f32x2 t = tbl[rl + q]; const float mu = t.x, ra = t.y * ALPHA; y0 = (r0 - mu) * ra * g0 + b0 + pa[q]; y1 = (r1 - mu) * ra * g1 + b1 + pb[q]; }
;                     else { y0 = r0 * ALPHA + pa[q]; y1 = r1 * ALPHA + pb[q]; }
;                     { const u32x4 w = pack8f(y0, y1); *(u32x4*)(xb + off + q * 128) = w;
;                         y0 = (f32x4){bf_lo(w.x), bf_hi(w.x), bf_lo(w.y), bf_hi(w.y)}; y1 = (f32x4){bf_lo(w.z), bf_hi(w.z), bf_lo(w.w), bf_hi(w.w)}; }
;                     float sa = ((y0[0] + y0[1]) + (y0[2] + y0[3])) + ((y1[0] + y1[1]) + (y1[2] + y1[3]));
;                     float sb = ((y0[0] * y0[0] + y0[1] * y0[1]) + (y0[2] * y0[2] + y0[3] * y0[3])) + ((y1[0] * y1[0] + y1[1] * y1[1]) + (y1[2] * y1[2] + y1[3] * y1[3]));
;                     sa += dpp_x1(sa);
;                     sb += dpp_x1(sb);
;                     sa += __shfl_xor(sa, 16); sa += __shfl_xor(sa, 32); sb += __shfl_xor(sb, 16); sb += __shfl_xor(sb, 32);
;                     if (fq == 0 && !odd) ps[(size_t)(rl + q) * 64] = (f32x2){sa, sb};
;                 }
.LBB0_610:
	s_or_b64 exec, exec, s[56:57]
	s_waitcnt lgkmcnt(0)
	v_cndmask_b32_e64 v18, v12, v4, s[8:9]
	v_mov_b32_e32 v16, 0
	v_cndmask_b32_e64 v17, v13, v5, s[8:9]
	s_waitcnt lgkmcnt(0)
	v_cndmask_b32_e64 v19, v14, v6, s[8:9]
	v_mov_b32_dpp v16, v18 quad_perm:[1,0,3,2] row_mask:0xf bank_mask:0xf
	v_mov_b32_e32 v18, 0
	v_cndmask_b32_e64 v20, v15, v7, s[8:9]
	v_cndmask_b32_e64 v22, v8, v0, s[8:9]
	v_mov_b32_dpp v18, v17 quad_perm:[1,0,3,2] row_mask:0xf bank_mask:0xf
	v_mov_b32_e32 v17, 0
	v_cndmask_b32_e64 v21, v9, v1, s[8:9]
	v_cndmask_b32_e64 v23, v10, v2, s[8:9]
	v_mov_b32_dpp v17, v19 quad_perm:[1,0,3,2] row_mask:0xf bank_mask:0xf
	v_mov_b32_e32 v19, 0
	v_cndmask_b32_e64 v24, v11, v3, s[8:9]
	v_cndmask_b32_e64 v13, v18, v13, s[8:9]
	v_mov_b32_dpp v19, v20 quad_perm:[1,0,3,2] row_mask:0xf bank_mask:0xf
	v_mov_b32_e32 v20, 0
	v_cndmask_b32_e64 v12, v16, v12, s[8:9]
	v_cndmask_b32_e64 v15, v19, v15, s[8:9]
	v_mov_b32_dpp v20, v22 quad_perm:[1,0,3,2] row_mask:0xf bank_mask:0xf
	v_mov_b32_e32 v22, 0
	v_cndmask_b32_e64 v14, v17, v14, s[8:9]
	v_cndmask_b32_e64 v8, v20, v8, s[8:9]
	v_mov_b32_dpp v22, v21 quad_perm:[1,0,3,2] row_mask:0xf bank_mask:0xf
	v_mov_b32_e32 v21, 0
	v_cndmask_b32_e64 v9, v22, v9, s[8:9]
	s_waitcnt vmcnt(13)
	v_and_b32_e32 v25, 0xffff0000, v68
	v_mov_b32_dpp v21, v23 quad_perm:[1,0,3,2] row_mask:0xf bank_mask:0xf
	v_mov_b32_e32 v23, 0
	v_cndmask_b32_e64 v10, v21, v10, s[8:9]
	v_lshlrev_b32_e32 v26, 16, v69
	v_mov_b32_dpp v23, v24 quad_perm:[1,0,3,2] row_mask:0xf bank_mask:0xf
	v_cndmask_b32_e64 v11, v23, v11, s[8:9]
	v_lshlrev_b32_e32 v24, 16, v68
	v_and_b32_e32 v27, 0xffff0000, v69
	v_lshlrev_b32_e32 v28, 16, v70
	v_and_b32_e32 v29, 0xffff0000, v70
	v_lshlrev_b32_e32 v30, 16, v71
	v_and_b32_e32 v31, 0xffff0000, v71
	v_pk_fma_f32 v[14:15], v[26:27], s[18:19], v[14:15] op_sel_hi:[1,0,1]
	v_pk_fma_f32 v[12:13], v[24:25], s[18:19], v[12:13] op_sel_hi:[1,0,1]
	v_pk_fma_f32 v[10:11], v[30:31], s[18:19], v[10:11] op_sel_hi:[1,0,1]
	v_pk_fma_f32 v[8:9], v[28:29], s[18:19], v[8:9] op_sel_hi:[1,0,1]
	v_cvt_pk_bf16_f32 v24, v12, v13
	v_cvt_pk_bf16_f32 v25, v14, v15
	s_nop 0
	v_cvt_pk_bf16_f32 v26, v8, v9
	v_cvt_pk_bf16_f32 v27, v10, v11
	v_lshlrev_b32_e32 v8, 16, v24
	v_and_b32_e32 v10, 0xffff0000, v24
	v_lshlrev_b32_e32 v12, 16, v25
	v_and_b32_e32 v14, 0xffff0000, v25
	v_lshlrev_b32_e32 v28, 16, v26
	v_and_b32_e32 v30, 0xffff0000, v26
	v_lshlrev_b32_e32 v32, 16, v27
	v_and_b32_e32 v34, 0xffff0000, v27
	v_mul_f32_e32 v9, v8, v8
	v_mul_f32_e32 v11, v10, v10
	v_mul_f32_e32 v13, v12, v12
	v_mul_f32_e32 v15, v14, v14
	v_mul_f32_e32 v29, v28, v28
	v_mul_f32_e32 v31, v30, v30
	v_mul_f32_e32 v33, v32, v32
	v_mul_f32_e32 v35, v34, v34
	v_pk_add_f32 v[8:9], v[8:9], v[10:11]
	v_pk_add_f32 v[10:11], v[12:13], v[14:15]
	v_pk_add_f32 v[12:13], v[32:33], v[34:35]
	v_pk_add_f32 v[8:9], v[8:9], v[10:11]
	v_pk_add_f32 v[10:11], v[28:29], v[30:31]
	s_nop 0
	v_pk_add_f32 v[10:11], v[10:11], v[12:13]
	s_nop 0
	v_pk_add_f32 v[8:9], v[8:9], v[10:11]
	v_mov_b32_e32 v10, v165
	v_mov_b32_e32 v11, v165
	s_nop 0
	v_mov_b32_dpp v10, v8 quad_perm:[1,0,3,2] row_mask:0xf bank_mask:0xf
	v_mov_b32_dpp v11, v9 quad_perm:[1,0,3,2] row_mask:0xf bank_mask:0xf
	v_pk_add_f32 v[8:9], v[8:9], v[10:11]
	v_mov_b32_e32 v10, v8
	v_mov_b32_e32 v11, v9
	s_nop 1
	v_permlane16_swap_b32_e32 v8, v10
	v_permlane16_swap_b32_e32 v9, v11
	s_waitcnt lgkmcnt(0)
	v_pk_add_f32 v[10:11], v[8:9], v[10:11]
	v_mov_b32_e32 v12, v10
	v_mov_b32_e32 v13, v11
	s_nop 1
	v_permlane32_swap_b32_e32 v10, v12
	v_permlane32_swap_b32_e32 v11, v13
	v_lshl_add_u64 v[8:9], s[54:55], 0, v[164:165]
	global_store_dwordx4 v[8:9], v[24:27], off
	s_and_saveexec_b64 s[54:55], s[10:11]
	s_cbranch_execz .LBB0_612
	s_waitcnt lgkmcnt(0)
	v_pk_add_f32 v[10:11], v[10:11], v[12:13]
	v_add_co_u32_e32 v12, vcc, 0x16000, v124
	s_nop 1
	v_addc_co_u32_e32 v13, vcc, 0, v125, vcc
	global_store_dwordx2 v[12:13], v[10:11], off
.LBB0_612:
	s_or_b64 exec, exec, s[54:55]
	v_cndmask_b32_e64 v5, v5, v18, s[8:9]
	v_cndmask_b32_e64 v4, v4, v16, s[8:9]
	v_cndmask_b32_e64 v7, v7, v19, s[8:9]
	v_cndmask_b32_e64 v6, v6, v17, s[8:9]
	v_cndmask_b32_e64 v1, v1, v22, s[8:9]
	v_cndmask_b32_e64 v0, v0, v20, s[8:9]
	v_cndmask_b32_e64 v3, v3, v23, s[8:9]
	v_cndmask_b32_e64 v2, v2, v21, s[8:9]
	s_waitcnt vmcnt(14)
	v_lshlrev_b32_e32 v10, 16, v64
	v_and_b32_e32 v11, 0xffff0000, v64
	s_waitcnt lgkmcnt(0)
	v_lshlrev_b32_e32 v12, 16, v65
	s_waitcnt lgkmcnt(0)
	v_and_b32_e32 v13, 0xffff0000, v65
	v_lshlrev_b32_e32 v14, 16, v66
	v_and_b32_e32 v15, 0xffff0000, v66
	v_lshlrev_b32_e32 v16, 16, v67
	v_and_b32_e32 v17, 0xffff0000, v67
	v_pk_fma_f32 v[6:7], v[12:13], s[18:19], v[6:7] op_sel_hi:[1,0,1]
	v_pk_fma_f32 v[4:5], v[10:11], s[18:19], v[4:5] op_sel_hi:[1,0,1]
	v_pk_fma_f32 v[2:3], v[16:17], s[18:19], v[2:3] op_sel_hi:[1,0,1]
	v_pk_fma_f32 v[0:1], v[14:15], s[18:19], v[0:1] op_sel_hi:[1,0,1]
	v_cvt_pk_bf16_f32 v4, v4, v5
	v_cvt_pk_bf16_f32 v5, v6, v7
	s_nop 0
	v_cvt_pk_bf16_f32 v6, v0, v1
	v_cvt_pk_bf16_f32 v7, v2, v3
	v_lshlrev_b32_e32 v0, 16, v4
	v_and_b32_e32 v2, 0xffff0000, v4
	v_lshlrev_b32_e32 v10, 16, v5
	v_and_b32_e32 v12, 0xffff0000, v5
	v_lshlrev_b32_e32 v14, 16, v6
	v_and_b32_e32 v16, 0xffff0000, v6
	v_lshlrev_b32_e32 v18, 16, v7
	v_and_b32_e32 v20, 0xffff0000, v7
	v_mul_f32_e32 v1, v0, v0
	v_mul_f32_e32 v3, v2, v2
	v_mul_f32_e32 v11, v10, v10
	v_mul_f32_e32 v13, v12, v12
	v_mul_f32_e32 v15, v14, v14
	v_mul_f32_e32 v17, v16, v16
	v_mul_f32_e32 v19, v18, v18
	v_mul_f32_e32 v21, v20, v20
	v_pk_add_f32 v[0:1], v[0:1], v[2:3]
	v_pk_add_f32 v[2:3], v[10:11], v[12:13]
	v_pk_add_f32 v[10:11], v[18:19], v[20:21]
	v_pk_add_f32 v[0:1], v[0:1], v[2:3]
	v_pk_add_f32 v[2:3], v[14:15], v[16:17]
	global_store_dwordx4 v[8:9], v[4:7], off offset:128
	v_pk_add_f32 v[2:3], v[2:3], v[10:11]
	s_nop 0
	v_pk_add_f32 v[0:1], v[0:1], v[2:3]
	v_mov_b32_e32 v2, v165
	v_mov_b32_e32 v3, v165
	s_nop 0
	v_mov_b32_dpp v2, v0 quad_perm:[1,0,3,2] row_mask:0xf bank_mask:0xf
	v_mov_b32_dpp v3, v1 quad_perm:[1,0,3,2] row_mask:0xf bank_mask:0xf
	v_pk_add_f32 v[0:1], v[0:1], v[2:3]
	v_mov_b32_e32 v2, v0
	v_mov_b32_e32 v3, v1
	s_nop 1
	v_permlane16_swap_b32_e32 v0, v2
	v_permlane16_swap_b32_e32 v1, v3
	s_waitcnt lgkmcnt(0)
	v_pk_add_f32 v[0:1], v[0:1], v[2:3]
	v_mov_b32_e32 v2, v0
	v_mov_b32_e32 v3, v1
	s_nop 1
	v_permlane32_swap_b32_e32 v0, v2
	v_permlane32_swap_b32_e32 v1, v3
	s_and_saveexec_b64 s[54:55], s[10:11]
	s_cbranch_execz .LBB0_614
	s_waitcnt lgkmcnt(0)
	v_pk_add_f32 v[0:1], v[0:1], v[2:3]
	v_add_co_u32_e32 v2, vcc, 0x16000, v124
	s_nop 1
	v_addc_co_u32_e32 v3, vcc, 0, v125, vcc
	global_store_dwordx2 v[2:3], v[0:1], off offset:512

; #define LAS __attribute__((address_space(3)))
;     __device__ __forceinline__ void operator()(const f32x4 (&acc)[2][2][4][2], const Unit& u, int wr, int wc, int fr, int fq, const EpiCtx& X) const {
;     ...
;         char* yb = nullptr; char* xb = (char*)(XB + (size_t)u.pm * BM * DM + (size_t)(u.pn * 4 + wc) * (BM * 64));
;         unsigned lo = (unsigned)((wr * 64 + fe) * 64 + o32 + 8 * fq) * 2u; EPI_OPAQUE(lo);
;         const int col = u.pn * BM + wc * 64 + o32 + 8 * fq;
;         f32x4 g0, g1, b0, b1;
;         if (RESN) { ensure_tbl(PSp, sidp, u.pm, X);
;             g0 = *(const f32x4*)(gp + col); g1 = *(const f32x4*)(gp + col + 4); b0 = *(const f32x4*)(bp + col) * ALPHA; b1 = *(const f32x4*)(bp + col + 4) * ALPHA; }
;         const LAS f32x2* tbl = (const LAS f32x2*)(X.lds + TBL_OFF) + wr * 64 + fe;
;         f32x2* ps = PSn + ((size_t)u.pm * BM + wr * 64 + fe) * 64 + u.pn * 4 + wc;
; #pragma unroll
;         for (int ai = 0; ai < 2; ++ai) {
;             u32x4 raw[8];
; #pragma unroll
;             for (int m = 0; m < 4; ++m) { const unsigned off = lo + (unsigned)((ai * HALF + m * 16) * 64) * 2u; raw[2 * m] = *(const u32x4*)(xb + off); raw[2 * m + 1] = *(const u32x4*)(xb + off + 128); }
; #pragma unroll
;             for (int m = 0; m < 4; ++m) {
;                 const int rl = ai * HALF + m * 16; const unsigned off = lo + (unsigned)(rl * 64) * 2u;
;                 const f32x4 o0a = acc[ai][0][m][0], o0b = acc[ai][0][m][1], o1a = acc[ai][1][m][0], o1b = acc[ai][1][m][1];
;                 const f32x4 ra_ = dpp_swap1(odd ? o0a : o1a), rb_ = dpp_swap1(odd ? o0b : o1b);
;                 const f32x4 pa[2] = {odd ? ra_ : o0a, odd ? o1a : ra_}, pb[2] = {odd ? rb_ : o0b, odd ? o1b : rb_};
; #pragma unroll
;                 for (int q = 0; q < 2; ++q) {
;                     const u32x4 w0 = raw[2 * m + q];
;                     const f32x4 r0 = (f32x4){bf_lo(w0.x), bf_hi(w0.x), bf_lo(w0.y), bf_hi(w0.y)}, r1 = (f32x4){bf_lo(w0.z), bf_hi(w0.z), bf_lo(w0.w), bf_hi(w0.w)};
;                     f32x4 y0, y1;
;                     if (RESN) { const f32x2 t = tbl[rl + q]; const float mu = t.x, ra = t.y * ALPHA; y0 = (r0 - mu) * ra * g0 + b0 + pa[q]; y1 = (r1 - mu) * ra * g1 + b1 + pb[q]; }
;                     else { y0 = r0 * ALPHA + pa[q]; y1 = r1 * ALPHA + pb[q]; }
;                     { const u32x4 w = pack8f(y0, y1); *(u32x4*)(xb + off + q * 128) = w;
.LBB0_816:
	s_lshl_b64 s[4:5], s[70:71], 21
	s_add_u32 s20, s57, s4
	s_addc_u32 s21, s59, s5
	s_lshl_b32 s70, s68, 2
	s_or_b32 s4, s70, s41
	s_ashr_i32 s5, s4, 31
	v_lshl_add_u32 v72, s68, 8, v200
	v_ashrrev_i32_e32 v73, 31, v72
	s_lshl_b64 s[4:5], s[4:5], 15
	v_lshlrev_b64 v[72:73], 2, v[72:73]
	s_add_u32 s20, s20, s4
	v_lshl_add_u64 v[74:75], s[26:27], 0, v[72:73]
	s_addc_u32 s21, s21, s5
	global_load_dwordx4 v[194:197], v[74:75], off offset:16
	global_load_dwordx4 v[178:181], v[74:75], off
	global_load_dwordx4 v[214:217], v164, s[20:21]
	v_lshl_add_u64 v[72:73], s[24:25], 0, v[72:73]
	s_waitcnt lgkmcnt(0)
	global_load_dwordx4 v[76:79], v[72:73], off
	s_nop 0
	global_load_dwordx4 v[72:75], v[72:73], off offset:16
	v_cndmask_b32_e64 v136, v135, v127, s[10:11]
	v_cndmask_b32_e64 v137, v134, v126, s[10:11]
	v_cndmask_b32_e64 v138, v133, v125, s[10:11]
	v_cndmask_b32_e64 v139, v132, v124, s[10:11]
	v_mov_b32_e32 v189, 0
	v_mov_b32_e32 v193, 0
	v_mov_b32_e32 v191, 0
	v_mov_b32_e32 v209, 0
	v_cndmask_b32_e64 v140, v131, v123, s[10:11]
	v_cndmask_b32_e64 v141, v130, v122, s[10:11]
	v_cndmask_b32_e64 v142, v129, v121, s[10:11]
	v_cndmask_b32_e64 v143, v128, v120, s[10:11]
	v_mov_b32_e32 v210, 0
	v_mov_b32_e32 v212, 0
	v_mov_b32_e32 v211, 0
	v_mov_b32_e32 v213, 0
	v_mov_b32_dpp v189, v139 quad_perm:[1,0,3,2] row_mask:0xf bank_mask:0xf
	v_mov_b32_dpp v193, v138 quad_perm:[1,0,3,2] row_mask:0xf bank_mask:0xf
	v_mov_b32_dpp v191, v137 quad_perm:[1,0,3,2] row_mask:0xf bank_mask:0xf
	v_mov_b32_dpp v209, v136 quad_perm:[1,0,3,2] row_mask:0xf bank_mask:0xf
	v_mov_b32_dpp v210, v143 quad_perm:[1,0,3,2] row_mask:0xf bank_mask:0xf
	v_mov_b32_dpp v212, v142 quad_perm:[1,0,3,2] row_mask:0xf bank_mask:0xf
	v_mov_b32_dpp v211, v141 quad_perm:[1,0,3,2] row_mask:0xf bank_mask:0xf
	v_mov_b32_dpp v213, v140 quad_perm:[1,0,3,2] row_mask:0xf bank_mask:0xf
	v_add_u32_e32 v192, 0x800, v164
	v_add_u32_e32 v190, 0x1000, v164
	v_add_u32_e32 v188, 0x1800, v164
	ds_read_b64 v[218:219], v201
	v_cndmask_b32_e64 v221, v193, v133, s[10:11]
	v_cndmask_b32_e64 v220, v189, v132, s[10:11]
	v_cndmask_b32_e64 v223, v209, v135, s[10:11]
	v_cndmask_b32_e64 v222, v191, v134, s[10:11]
	v_cndmask_b32_e64 v225, v212, v129, s[10:11]
	v_cndmask_b32_e64 v224, v210, v128, s[10:11]
	v_cndmask_b32_e64 v227, v213, v131, s[10:11]
	v_cndmask_b32_e64 v226, v211, v130, s[10:11]
	global_load_dwordx4 v[152:155], v164, s[20:21] offset:128
	global_load_dwordx4 v[148:151], v192, s[20:21]
	global_load_dwordx4 v[144:147], v192, s[20:21] offset:128
	global_load_dwordx4 v[140:143], v190, s[20:21]
	global_load_dwordx4 v[136:139], v190, s[20:21] offset:128
	global_load_dwordx4 v[132:135], v188, s[20:21]
	global_load_dwordx4 v[128:131], v188, s[20:21] offset:128
	s_waitcnt lgkmcnt(0)
	v_mul_f32_e32 v208, 0x3fb504f3, v219
	v_lshl_add_u64 v[186:187], v[166:167], 0, s[72:73]
	s_ashr_i32 s71, s70, 31
	v_lshl_add_u64 v[186:187], s[70:71], 3, v[186:187]
	v_lshl_add_u64 v[186:187], v[186:187], 0, s[22:23]
	v_add_u32_e32 v246, 0x4000, v164
	v_add_u32_e32 v247, 0x4800, v164
	global_load_dwordx4 v[230:233], v246, s[20:21]
	global_load_dwordx4 v[234:237], v246, s[20:21] offset:128
	global_load_dwordx4 v[238:241], v247, s[20:21]
	global_load_dwordx4 v[242:245], v247, s[20:21] offset:128
	s_waitcnt vmcnt(14)
	v_pk_mul_f32 v[182:183], v[180:181], s[58:59] op_sel_hi:[1,0]
	v_pk_mul_f32 v[184:185], v[178:179], s[58:59] op_sel_hi:[1,0]
	v_pk_mul_f32 v[178:179], v[196:197], s[58:59] op_sel_hi:[1,0]
	v_pk_mul_f32 v[180:181], v[194:195], s[58:59] op_sel_hi:[1,0]
	s_waitcnt vmcnt(13)
	v_lshlrev_b32_e32 v194, 16, v214
	v_and_b32_e32 v195, 0xffff0000, v214
	v_lshlrev_b32_e32 v196, 16, v215
	v_and_b32_e32 v197, 0xffff0000, v215
	v_lshlrev_b32_e32 v207, 16, v216
	v_and_b32_e32 v214, 0xffff0000, v216
	v_lshlrev_b32_e32 v216, 16, v217
	v_and_b32_e32 v217, 0xffff0000, v217
	v_sub_f32_e32 v195, v195, v218
	v_sub_f32_e32 v194, v194, v218
	v_sub_f32_e32 v197, v197, v218
	v_sub_f32_e32 v196, v196, v218
	v_sub_f32_e32 v215, v214, v218
	v_sub_f32_e32 v214, v207, v218
	v_sub_f32_e32 v217, v217, v218
	v_sub_f32_e32 v216, v216, v218
	v_pk_mul_f32 v[196:197], v[196:197], v[208:209] op_sel_hi:[1,0]
	v_pk_mul_f32 v[194:195], v[194:195], v[208:209] op_sel_hi:[1,0]
	v_pk_mul_f32 v[216:217], v[216:217], v[208:209] op_sel_hi:[1,0]
	v_pk_mul_f32 v[214:215], v[214:215], v[208:209] op_sel_hi:[1,0]
	s_waitcnt vmcnt(12)
	v_pk_fma_f32 v[194:195], v[76:77], v[194:195], v[184:185]
	v_pk_fma_f32 v[196:197], v[78:79], v[196:197], v[182:183]
	s_waitcnt vmcnt(11)
	v_pk_fma_f32 v[214:215], v[72:73], v[214:215], v[180:181]
	v_pk_fma_f32 v[216:217], v[74:75], v[216:217], v[178:179]
	v_pk_add_f32 v[196:197], v[222:223], v[196:197]
	v_pk_add_f32 v[194:195], v[220:221], v[194:195]
	v_pk_add_f32 v[218:219], v[226:227], v[216:217]
	v_pk_add_f32 v[216:217], v[224:225], v[214:215]
	v_cvt_pk_bf16_f32 v214, v194, v195
	v_cvt_pk_bf16_f32 v215, v196, v197
	v_and_b32_e32 v208, 64, v206
	v_cvt_pk_bf16_f32 v216, v216, v217
	v_cvt_pk_bf16_f32 v217, v218, v219
	v_lshlrev_b32_e32 v194, 16, v214
	v_and_b32_e32 v196, 0xffff0000, v214
	v_lshlrev_b32_e32 v218, 16, v215
	v_and_b32_e32 v220, 0xffff0000, v215
	v_lshlrev_b32_e32 v222, 16, v216
	v_and_b32_e32 v224, 0xffff0000, v216
	v_lshlrev_b32_e32 v226, 16, v217
	v_and_b32_e32 v228, 0xffff0000, v217
	v_mul_f32_e32 v195, v194, v194
	v_mul_f32_e32 v197, v196, v196
	v_mul_f32_e32 v219, v218, v218
	v_mul_f32_e32 v221, v220, v220
	v_mul_f32_e32 v223, v222, v222
	v_mul_f32_e32 v225, v224, v224
	v_mul_f32_e32 v227, v226, v226
	v_mul_f32_e32 v229, v228, v228
	v_pk_add_f32 v[194:195], v[194:195], v[196:197]
	v_pk_add_f32 v[196:197], v[218:219], v[220:221]
	v_pk_add_f32 v[218:219], v[226:227], v[228:229]
	v_pk_add_f32 v[194:195], v[194:195], v[196:197]
	v_pk_add_f32 v[196:197], v[222:223], v[224:225]
	v_xor_b32_e32 v207, 16, v206
	v_add_u32_e32 v208, 64, v208
	v_pk_add_f32 v[196:197], v[196:197], v[218:219]
	v_cmp_lt_i32_e32 vcc, v207, v208
	v_pk_add_f32 v[194:195], v[194:195], v[196:197]
	v_mov_b32_e32 v196, 0
	v_mov_b32_e32 v197, 0
	v_cndmask_b32_e32 v207, v206, v207, vcc
	v_mov_b32_dpp v196, v194 quad_perm:[1,0,3,2] row_mask:0xf bank_mask:0xf
	v_mov_b32_dpp v197, v195 quad_perm:[1,0,3,2] row_mask:0xf bank_mask:0xf
	v_lshlrev_b32_e32 v207, 2, v207
	v_pk_add_f32 v[194:195], v[194:195], v[196:197]
	v_mov_b32_e32 v196, v194
	v_mov_b32_e32 v197, v195
	s_nop 1
	v_permlane16_swap_b32_e32 v194, v196
	v_permlane16_swap_b32_e32 v195, v197
	v_xor_b32_e32 v218, 32, v206
	v_cmp_lt_i32_e32 vcc, v218, v208
	global_store_dwordx4 v164, v[214:217], s[20:21]
	s_waitcnt lgkmcnt(0)
	v_pk_add_f32 v[194:195], v[194:195], v[196:197]
	v_cndmask_b32_e32 v208, v206, v218, vcc
	v_lshlrev_b32_e32 v208, 2, v208
	v_mov_b32_e32 v196, v194
	v_mov_b32_e32 v197, v195
	s_nop 1
	v_permlane32_swap_b32_e32 v194, v196
	v_permlane32_swap_b32_e32 v195, v197
	s_and_saveexec_b64 s[52:53], s[16:17]
	s_waitcnt lgkmcnt(0)
	v_pk_add_f32 v[194:195], v[194:195], v[196:197]
	global_store_dwordx2 v[186:187], v[194:195], off
;     __device__ __forceinline__ void operator()(const f32x4 (&acc)[2][2][4][2], const Unit& u, int wr, int wc, int fr, int fq, const EpiCtx& X) const {
;     ...
;             for (int m = 0; m < 4; ++m) { const unsigned off = lo + (unsigned)((ai * HALF + m * 16) * 64) * 2u; raw[2 * m] = *(const u32x4*)(xb + off); raw[2 * m + 1] = *(const u32x4*)(xb + off + 128); }
; #pragma unroll
;             for (int m = 0; m < 4; ++m) {
;                 const int rl = ai * HALF + m * 16; const unsigned off = lo + (unsigned)(rl * 64) * 2u;
;                 const f32x4 o0a = acc[ai][0][m][0], o0b = acc[ai][0][m][1], o1a = acc[ai][1][m][0], o1b = acc[ai][1][m][1];
;                 const f32x4 ra_ = dpp_swap1(odd ? o0a : o1a), rb_ = dpp_swap1(odd ? o0b : o1b);
;                 const f32x4 pa[2] = {odd ? ra_ : o0a, odd ? o1a : ra_}, pb[2] = {odd ? rb_ : o0b, odd ? o1b : rb_};
; #pragma unroll
;                 for (int q = 0; q < 2; ++q) {
;                     const u32x4 w0 = raw[2 * m + q];
;                     const f32x4 r0 = (f32x4){bf_lo(w0.x), bf_hi(w0.x), bf_lo(w0.y), bf_hi(w0.y)}, r1 = (f32x4){bf_lo(w0.z), bf_hi(w0.z), bf_lo(w0.w), bf_hi(w0.w)};
;                     f32x4 y0, y1;
;                     if (RESN) { const f32x2 t = tbl[rl + q]; const float mu = t.x, ra = t.y * ALPHA; y0 = (r0 - mu) * ra * g0 + b0 + pa[q]; y1 = (r1 - mu) * ra * g1 + b1 + pb[q]; }
;                     else { y0 = r0 * ALPHA + pa[q]; y1 = r1 * ALPHA + pb[q]; }
;                     { const u32x4 w = pack8f(y0, y1); *(u32x4*)(xb + off + q * 128) = w;
;                         y0 = (f32x4){bf_lo(w.x), bf_hi(w.x), bf_lo(w.y), bf_hi(w.y)}; y1 = (f32x4){bf_lo(w.z), bf_hi(w.z), bf_lo(w.w), bf_hi(w.w)}; }
;                     float sa = ((y0[0] + y0[1]) + (y0[2] + y0[3])) + ((y1[0] + y1[1]) + (y1[2] + y1[3]));
;                     float sb = ((y0[0] * y0[0] + y0[1] * y0[1]) + (y0[2] * y0[2] + y0[3] * y0[3])) + ((y1[0] * y1[0] + y1[1] * y1[1]) + (y1[2] * y1[2] + y1[3] * y1[3]));
;                     sa += dpp_x1(sa);
;                     sb += dpp_x1(sb);
;                     sa += __shfl_xor(sa, 16); sa += __shfl_xor(sa, 32); sb += __shfl_xor(sb, 16); sb += __shfl_xor(sb, 32);
;                     if (fq == 0 && !odd) ps[(size_t)(rl + q) * 64] = (f32x2){sa, sb};
;                 }
.LBB0_818:
	s_or_b64 exec, exec, s[52:53]
	v_cndmask_b32_e64 v125, v125, v193, s[10:11]
	v_cndmask_b32_e64 v124, v124, v189, s[10:11]
	v_cndmask_b32_e64 v126, v126, v191, s[10:11]
	s_waitcnt vmcnt(12)
	v_lshlrev_b32_e32 v189, 16, v152
	v_and_b32_e32 v191, 0xffff0000, v152
	v_lshlrev_b32_e32 v193, 16, v153
	s_waitcnt lgkmcnt(0)
	v_and_b32_e32 v196, 0xffff0000, v153
	ds_read_b64 v[152:153], v201 offset:8
	v_cndmask_b32_e64 v127, v127, v209, s[10:11]
	v_cndmask_b32_e64 v120, v120, v210, s[10:11]
	v_cndmask_b32_e64 v122, v122, v211, s[10:11]
	v_lshlrev_b32_e32 v209, 16, v154
	v_and_b32_e32 v210, 0xffff0000, v154
	v_lshlrev_b32_e32 v211, 16, v155
	v_and_b32_e32 v155, 0xffff0000, v155
	s_waitcnt lgkmcnt(0)
	v_mul_f32_e32 v154, 0x3fb504f3, v153
	v_sub_f32_e32 v195, v191, v152
	v_sub_f32_e32 v194, v189, v152
	v_pk_mul_f32 v[194:195], v[194:195], v[154:155] op_sel_hi:[1,0]
	v_sub_f32_e32 v197, v196, v152
	v_pk_fma_f32 v[194:195], v[76:77], v[194:195], v[184:185]
	v_sub_f32_e32 v196, v193, v152
	v_pk_add_f32 v[124:125], v[124:125], v[194:195]
	v_sub_f32_e32 v195, v210, v152
	v_sub_f32_e32 v194, v209, v152
	v_sub_f32_e32 v153, v155, v152
	v_sub_f32_e32 v152, v211, v152
	v_pk_mul_f32 v[196:197], v[196:197], v[154:155] op_sel_hi:[1,0]
	v_pk_mul_f32 v[152:153], v[152:153], v[154:155] op_sel_hi:[1,0]
	v_pk_mul_f32 v[154:155], v[194:195], v[154:155] op_sel_hi:[1,0]
	v_cndmask_b32_e64 v121, v121, v212, s[10:11]
	v_cndmask_b32_e64 v123, v123, v213, s[10:11]
	v_pk_fma_f32 v[196:197], v[78:79], v[196:197], v[182:183]
	v_pk_fma_f32 v[154:155], v[72:73], v[154:155], v[180:181]
	v_pk_fma_f32 v[152:153], v[74:75], v[152:153], v[178:179]
	v_pk_add_f32 v[126:127], v[126:127], v[196:197]
	v_pk_add_f32 v[122:123], v[122:123], v[152:153]
	v_pk_add_f32 v[120:121], v[120:121], v[154:155]
	v_cvt_pk_bf16_f32 v124, v124, v125
	v_cvt_pk_bf16_f32 v125, v126, v127
	s_nop 0
	v_cvt_pk_bf16_f32 v126, v120, v121
	v_cvt_pk_bf16_f32 v127, v122, v123
	v_lshlrev_b32_e32 v120, 16, v124
	v_and_b32_e32 v122, 0xffff0000, v124
	v_lshlrev_b32_e32 v152, 16, v125
	v_and_b32_e32 v154, 0xffff0000, v125
	v_lshlrev_b32_e32 v194, 16, v126
	v_and_b32_e32 v196, 0xffff0000, v126
	v_lshlrev_b32_e32 v210, 16, v127
	v_and_b32_e32 v212, 0xffff0000, v127
	v_mul_f32_e32 v121, v120, v120
	v_mul_f32_e32 v123, v122, v122
	v_mul_f32_e32 v153, v152, v152
	v_mul_f32_e32 v155, v154, v154
	v_mul_f32_e32 v195, v194, v194
	v_mul_f32_e32 v197, v196, v196
	v_mul_f32_e32 v211, v210, v210
	v_mul_f32_e32 v213, v212, v212
	v_pk_add_f32 v[120:121], v[120:121], v[122:123]
	v_pk_add_f32 v[122:123], v[152:153], v[154:155]
	v_pk_add_f32 v[152:153], v[210:211], v[212:213]
	v_pk_add_f32 v[120:121], v[120:121], v[122:123]
	v_pk_add_f32 v[122:123], v[194:195], v[196:197]
	s_nop 0
	v_pk_add_f32 v[122:123], v[122:123], v[152:153]
	v_lshl_add_u64 v[152:153], s[20:21], 0, v[164:165]
	v_pk_add_f32 v[120:121], v[120:121], v[122:123]
	v_mov_b32_e32 v122, v165
	v_mov_b32_e32 v123, v165
	global_store_dwordx4 v[152:153], v[124:127], off offset:128
	v_mov_b32_dpp v122, v120 quad_perm:[1,0,3,2] row_mask:0xf bank_mask:0xf
	v_mov_b32_dpp v123, v121 quad_perm:[1,0,3,2] row_mask:0xf bank_mask:0xf
	v_pk_add_f32 v[120:121], v[120:121], v[122:123]
	v_mov_b32_e32 v122, v120
	v_mov_b32_e32 v123, v121
	s_nop 1
	v_permlane16_swap_b32_e32 v120, v122
	v_permlane16_swap_b32_e32 v121, v123
	s_waitcnt lgkmcnt(0)
	v_pk_add_f32 v[120:121], v[120:121], v[122:123]
	v_mov_b32_e32 v122, v120
	v_mov_b32_e32 v123, v121
	s_nop 1
	v_permlane32_swap_b32_e32 v120, v122
	v_permlane32_swap_b32_e32 v121, v123
	s_and_saveexec_b64 s[52:53], s[16:17]
	s_waitcnt lgkmcnt(0)
	v_pk_add_f32 v[120:121], v[120:121], v[122:123]
	global_store_dwordx2 v[186:187], v[120:121], off offset:512
.LBB0_820:
	s_or_b64 exec, exec, s[52:53]
	s_waitcnt lgkmcnt(0)
	v_cndmask_b32_e64 v122, v116, v108, s[10:11]
	v_mov_b32_e32 v120, 0
	v_cndmask_b32_e64 v121, v117, v109, s[10:11]
	s_waitcnt lgkmcnt(0)
	v_cndmask_b32_e64 v123, v118, v110, s[10:11]
	v_mov_b32_dpp v120, v122 quad_perm:[1,0,3,2] row_mask:0xf bank_mask:0xf
	v_mov_b32_e32 v122, 0
	v_cndmask_b32_e64 v124, v119, v111, s[10:11]
	v_cndmask_b32_e64 v126, v112, v104, s[10:11]
	v_mov_b32_dpp v122, v121 quad_perm:[1,0,3,2] row_mask:0xf bank_mask:0xf
	v_mov_b32_e32 v121, 0
	v_cndmask_b32_e64 v125, v113, v105, s[10:11]
	v_cndmask_b32_e64 v127, v114, v106, s[10:11]
	v_mov_b32_dpp v121, v123 quad_perm:[1,0,3,2] row_mask:0xf bank_mask:0xf
	v_mov_b32_e32 v123, 0
	v_cndmask_b32_e64 v152, v115, v107, s[10:11]
	s_waitcnt vmcnt(13)
	v_and_b32_e32 v153, 0xffff0000, v148
	v_mov_b32_dpp v123, v124 quad_perm:[1,0,3,2] row_mask:0xf bank_mask:0xf
	v_mov_b32_e32 v124, 0
	v_lshlrev_b32_e32 v154, 16, v149
	v_and_b32_e32 v155, 0xffff0000, v149
	v_mov_b32_dpp v124, v126 quad_perm:[1,0,3,2] row_mask:0xf bank_mask:0xf
	v_mov_b32_e32 v126, 0
	v_lshlrev_b32_e32 v189, 16, v150
	v_and_b32_e32 v191, 0xffff0000, v150
	v_mov_b32_dpp v126, v125 quad_perm:[1,0,3,2] row_mask:0xf bank_mask:0xf
	v_mov_b32_e32 v125, 0
	v_lshlrev_b32_e32 v193, 16, v151
	v_and_b32_e32 v151, 0xffff0000, v151
	v_mov_b32_dpp v125, v127 quad_perm:[1,0,3,2] row_mask:0xf bank_mask:0xf
	v_mov_b32_e32 v127, 0
	v_cndmask_b32_e64 v117, v122, v117, s[10:11]
	v_cndmask_b32_e64 v116, v120, v116, s[10:11]
	v_mov_b32_dpp v127, v152 quad_perm:[1,0,3,2] row_mask:0xf bank_mask:0xf
	v_lshlrev_b32_e32 v152, 16, v148
	ds_read_b64 v[148:149], v201 offset:128
	v_cndmask_b32_e64 v119, v123, v119, s[10:11]
	v_cndmask_b32_e64 v118, v121, v118, s[10:11]
	v_cndmask_b32_e64 v113, v126, v113, s[10:11]
	v_cndmask_b32_e64 v112, v124, v112, s[10:11]
	s_waitcnt lgkmcnt(0)
;     __device__ __forceinline__ void operator()(const f32x4 (&acc)[2][2][4][2], const Unit& u, int wr, int wc, int fr, int fq, const EpiCtx& X) const {
;     ...
;             for (int m = 0; m < 4; ++m) { const unsigned off = lo + (unsigned)((ai * HALF + m * 16) * 64) * 2u; raw[2 * m] = *(const u32x4*)(xb + off); raw[2 * m + 1] = *(const u32x4*)(xb + off + 128); }
; #pragma unroll
;             for (int m = 0; m < 4; ++m) {
;                 const int rl = ai * HALF + m * 16; const unsigned off = lo + (unsigned)(rl * 64) * 2u;
;                 const f32x4 o0a = acc[ai][0][m][0], o0b = acc[ai][0][m][1], o1a = acc[ai][1][m][0], o1b = acc[ai][1][m][1];
;                 const f32x4 ra_ = dpp_swap1(odd ? o0a : o1a), rb_ = dpp_swap1(odd ? o0b : o1b);
;                 const f32x4 pa[2] = {odd ? ra_ : o0a, odd ? o1a : ra_}, pb[2] = {odd ? rb_ : o0b, odd ? o1b : rb_};
; #pragma unroll
;                 for (int q = 0; q < 2; ++q) {
;                     const u32x4 w0 = raw[2 * m + q];
;                     const f32x4 r0 = (f32x4){bf_lo(w0.x), bf_hi(w0.x), bf_lo(w0.y), bf_hi(w0.y)}, r1 = (f32x4){bf_lo(w0.z), bf_hi(w0.z), bf_lo(w0.w), bf_hi(w0.w)};
;                     f32x4 y0, y1;
;                     if (RESN) { const f32x2 t = tbl[rl + q]; const float mu = t.x, ra = t.y * ALPHA; y0 = (r0 - mu) * ra * g0 + b0 + pa[q]; y1 = (r1 - mu) * ra * g1 + b1 + pb[q]; }
;                     else { y0 = r0 * ALPHA + pa[q]; y1 = r1 * ALPHA + pb[q]; }
;                     { const u32x4 w = pack8f(y0, y1); *(u32x4*)(xb + off + q * 128) = w;
;                         y0 = (f32x4){bf_lo(w.x), bf_hi(w.x), bf_lo(w.y), bf_hi(w.y)}; y1 = (f32x4){bf_lo(w.z), bf_hi(w.z), bf_lo(w.w), bf_hi(w.w)}; }
;                     float sa = ((y0[0] + y0[1]) + (y0[2] + y0[3])) + ((y1[0] + y1[1]) + (y1[2] + y1[3]));
;                     float sb = ((y0[0] * y0[0] + y0[1] * y0[1]) + (y0[2] * y0[2] + y0[3] * y0[3])) + ((y1[0] * y1[0] + y1[1] * y1[1]) + (y1[2] * y1[2] + y1[3] * y1[3]));
;                     sa += dpp_x1(sa);
;                     sb += dpp_x1(sb);
;                     sa += __shfl_xor(sa, 16); sa += __shfl_xor(sa, 32); sb += __shfl_xor(sb, 16); sb += __shfl_xor(sb, 32);
;                     if (fq == 0 && !odd) ps[(size_t)(rl + q) * 64] = (f32x2){sa, sb};
;                 }
	v_mul_f32_e32 v150, 0x3fb504f3, v149
	v_sub_f32_e32 v153, v153, v148
	v_sub_f32_e32 v152, v152, v148
	v_pk_mul_f32 v[152:153], v[152:153], v[150:151] op_sel_hi:[1,0]
	v_sub_f32_e32 v155, v155, v148
	v_pk_fma_f32 v[152:153], v[76:77], v[152:153], v[184:185]
	v_sub_f32_e32 v154, v154, v148
	v_pk_add_f32 v[116:117], v[116:117], v[152:153]
	v_sub_f32_e32 v153, v191, v148
	v_sub_f32_e32 v152, v189, v148
	v_sub_f32_e32 v149, v151, v148
	v_sub_f32_e32 v148, v193, v148
	v_pk_mul_f32 v[154:155], v[154:155], v[150:151] op_sel_hi:[1,0]
	v_pk_mul_f32 v[148:149], v[148:149], v[150:151] op_sel_hi:[1,0]
	v_pk_mul_f32 v[150:151], v[152:153], v[150:151] op_sel_hi:[1,0]
	v_cndmask_b32_e64 v115, v127, v115, s[10:11]
	v_cndmask_b32_e64 v114, v125, v114, s[10:11]
	v_pk_fma_f32 v[154:155], v[78:79], v[154:155], v[182:183]
	v_pk_fma_f32 v[150:151], v[72:73], v[150:151], v[180:181]
	v_pk_fma_f32 v[148:149], v[74:75], v[148:149], v[178:179]
	v_pk_add_f32 v[118:119], v[118:119], v[154:155]
	v_pk_add_f32 v[114:115], v[114:115], v[148:149]
	v_pk_add_f32 v[112:113], v[112:113], v[150:151]
	v_cvt_pk_bf16_f32 v148, v116, v117
	v_cvt_pk_bf16_f32 v149, v118, v119
	v_mov_b32_e32 v193, v165
	v_cvt_pk_bf16_f32 v150, v112, v113
	v_cvt_pk_bf16_f32 v151, v114, v115
	v_lshlrev_b32_e32 v112, 16, v148
	v_and_b32_e32 v114, 0xffff0000, v148
	v_lshlrev_b32_e32 v116, 16, v149
	v_and_b32_e32 v118, 0xffff0000, v149
	v_lshlrev_b32_e32 v152, 16, v150
	v_and_b32_e32 v154, 0xffff0000, v150
	v_lshlrev_b32_e32 v194, 16, v151
	v_and_b32_e32 v196, 0xffff0000, v151
	v_mul_f32_e32 v113, v112, v112
	v_mul_f32_e32 v115, v114, v114
	v_mul_f32_e32 v117, v116, v116
	v_mul_f32_e32 v119, v118, v118
	v_mul_f32_e32 v153, v152, v152
	v_mul_f32_e32 v155, v154, v154
	v_mul_f32_e32 v195, v194, v194
	v_mul_f32_e32 v197, v196, v196
	v_pk_add_f32 v[112:113], v[112:113], v[114:115]
	v_pk_add_f32 v[114:115], v[116:117], v[118:119]
	v_pk_add_f32 v[116:117], v[194:195], v[196:197]
	v_pk_add_f32 v[112:113], v[112:113], v[114:115]
	v_pk_add_f32 v[114:115], v[152:153], v[154:155]
	s_nop 0
	v_pk_add_f32 v[114:115], v[114:115], v[116:117]
	s_nop 0
	v_pk_add_f32 v[112:113], v[112:113], v[114:115]
	v_mov_b32_e32 v114, v165
	v_mov_b32_e32 v115, v165
	s_nop 0
	v_mov_b32_dpp v114, v112 quad_perm:[1,0,3,2] row_mask:0xf bank_mask:0xf
	v_mov_b32_dpp v115, v113 quad_perm:[1,0,3,2] row_mask:0xf bank_mask:0xf
	v_pk_add_f32 v[112:113], v[112:113], v[114:115]
	v_mov_b32_e32 v114, v112
	v_mov_b32_e32 v115, v113
	s_nop 1
	v_permlane16_swap_b32_e32 v112, v114
	v_permlane16_swap_b32_e32 v113, v115
	s_waitcnt lgkmcnt(0)
	v_pk_add_f32 v[114:115], v[112:113], v[114:115]
	v_mov_b32_e32 v116, v114
	v_mov_b32_e32 v117, v115
	s_nop 1
	v_permlane32_swap_b32_e32 v114, v116
	v_permlane32_swap_b32_e32 v115, v117
	v_lshl_add_u64 v[112:113], s[20:21], 0, v[192:193]
	global_store_dwordx4 v[112:113], v[148:151], off
	s_and_saveexec_b64 s[68:69], s[16:17]
	s_waitcnt lgkmcnt(0)
	v_pk_add_f32 v[114:115], v[114:115], v[116:117]
	v_add_co_u32_e32 v116, vcc, 0x2000, v186
	s_nop 1
	v_addc_co_u32_e32 v117, vcc, 0, v187, vcc
	global_store_dwordx2 v[116:117], v[114:115], off
.LBB0_822:
	s_or_b64 exec, exec, s[68:69]
	ds_read_b64 v[114:115], v201 offset:136
	s_waitcnt lgkmcnt(1)
	s_waitcnt vmcnt(14)
	v_lshlrev_b32_e32 v117, 16, v144
	v_and_b32_e32 v118, 0xffff0000, v144
	v_cndmask_b32_e64 v109, v109, v122, s[10:11]
	v_cndmask_b32_e64 v108, v108, v120, s[10:11]
	s_waitcnt lgkmcnt(0)
	v_mul_f32_e32 v116, 0x3fb504f3, v115
	v_sub_f32_e32 v119, v118, v114
	v_sub_f32_e32 v118, v117, v114
	v_pk_mul_f32 v[118:119], v[118:119], v[116:117] op_sel_hi:[1,0]
	v_cndmask_b32_e64 v111, v111, v123, s[10:11]
	v_cndmask_b32_e64 v110, v110, v121, s[10:11]
	v_cndmask_b32_e64 v104, v104, v124, s[10:11]
	v_cndmask_b32_e64 v106, v106, v125, s[10:11]
	v_lshlrev_b32_e32 v120, 16, v145
	v_and_b32_e32 v121, 0xffff0000, v145
	v_lshlrev_b32_e32 v122, 16, v146
	v_and_b32_e32 v123, 0xffff0000, v146
	v_lshlrev_b32_e32 v124, 16, v147
	v_and_b32_e32 v125, 0xffff0000, v147
	v_pk_fma_f32 v[118:119], v[76:77], v[118:119], v[184:185]
	v_sub_f32_e32 v121, v121, v114
	v_sub_f32_e32 v120, v120, v114
	v_pk_add_f32 v[108:109], v[108:109], v[118:119]
	v_sub_f32_e32 v119, v123, v114
	v_sub_f32_e32 v118, v122, v114
	v_sub_f32_e32 v115, v125, v114
	v_sub_f32_e32 v114, v124, v114
	v_pk_mul_f32 v[120:121], v[120:121], v[116:117] op_sel_hi:[1,0]
	v_pk_mul_f32 v[114:115], v[114:115], v[116:117] op_sel_hi:[1,0]
	v_pk_mul_f32 v[116:117], v[118:119], v[116:117] op_sel_hi:[1,0]
	v_cndmask_b32_e64 v105, v105, v126, s[10:11]
	v_cndmask_b32_e64 v107, v107, v127, s[10:11]
	v_pk_fma_f32 v[120:121], v[78:79], v[120:121], v[182:183]
	v_pk_fma_f32 v[116:117], v[72:73], v[116:117], v[180:181]
	v_pk_fma_f32 v[114:115], v[74:75], v[114:115], v[178:179]
	v_pk_add_f32 v[110:111], v[110:111], v[120:121]
	v_pk_add_f32 v[106:107], v[106:107], v[114:115]
	v_pk_add_f32 v[104:105], v[104:105], v[116:117]
	v_cvt_pk_bf16_f32 v108, v108, v109
	v_cvt_pk_bf16_f32 v109, v110, v111
	s_nop 0
	v_cvt_pk_bf16_f32 v110, v104, v105
	v_cvt_pk_bf16_f32 v111, v106, v107
	v_lshlrev_b32_e32 v104, 16, v108
	v_and_b32_e32 v106, 0xffff0000, v108
	v_lshlrev_b32_e32 v114, 16, v109
	v_and_b32_e32 v116, 0xffff0000, v109
	v_lshlrev_b32_e32 v118, 16, v110
	v_and_b32_e32 v120, 0xffff0000, v110
	v_lshlrev_b32_e32 v122, 16, v111
	v_and_b32_e32 v124, 0xffff0000, v111
	v_mul_f32_e32 v105, v104, v104
	v_mul_f32_e32 v107, v106, v106
	v_mul_f32_e32 v115, v114, v114
	v_mul_f32_e32 v117, v116, v116
	v_mul_f32_e32 v119, v118, v118
	v_mul_f32_e32 v121, v120, v120
	v_mul_f32_e32 v123, v122, v122
	v_mul_f32_e32 v125, v124, v124
	v_pk_add_f32 v[104:105], v[104:105], v[106:107]
	v_pk_add_f32 v[106:107], v[114:115], v[116:117]
	v_pk_add_f32 v[114:115], v[122:123], v[124:125]
	v_pk_add_f32 v[104:105], v[104:105], v[106:107]
	v_pk_add_f32 v[106:107], v[118:119], v[120:121]
	global_store_dwordx4 v[112:113], v[108:111], off offset:128
	v_pk_add_f32 v[106:107], v[106:107], v[114:115]
	s_nop 0
	v_pk_add_f32 v[104:105], v[104:105], v[106:107]
	v_mov_b32_e32 v106, v165
	v_mov_b32_e32 v107, v165
	s_nop 0
	v_mov_b32_dpp v106, v104 quad_perm:[1,0,3,2] row_mask:0xf bank_mask:0xf
	v_mov_b32_dpp v107, v105 quad_perm:[1,0,3,2] row_mask:0xf bank_mask:0xf
	v_pk_add_f32 v[104:105], v[104:105], v[106:107]
	v_mov_b32_e32 v106, v104
	v_mov_b32_e32 v107, v105
	s_nop 1
	v_permlane16_swap_b32_e32 v104, v106
	v_permlane16_swap_b32_e32 v105, v107
	s_waitcnt lgkmcnt(0)
	v_pk_add_f32 v[104:105], v[104:105], v[106:107]
	v_mov_b32_e32 v106, v104
	v_mov_b32_e32 v107, v105
	s_nop 1
	v_permlane32_swap_b32_e32 v104, v106
	v_permlane32_swap_b32_e32 v105, v107
	s_and_saveexec_b64 s[68:69], s[16:17]
	s_waitcnt lgkmcnt(0)
	v_pk_add_f32 v[104:105], v[104:105], v[106:107]
	v_add_co_u32_e32 v106, vcc, 0x2000, v186
	s_nop 1
	v_addc_co_u32_e32 v107, vcc, 0, v187, vcc
	global_store_dwordx2 v[106:107], v[104:105], off offset:512
;     __device__ __forceinline__ void operator()(const f32x4 (&acc)[2][2][4][2], const Unit& u, int wr, int wc, int fr, int fq, const EpiCtx& X) const {
;     ...
;             for (int m = 0; m < 4; ++m) { const unsigned off = lo + (unsigned)((ai * HALF + m * 16) * 64) * 2u; raw[2 * m] = *(const u32x4*)(xb + off); raw[2 * m + 1] = *(const u32x4*)(xb + off + 128); }
; #pragma unroll
;             for (int m = 0; m < 4; ++m) {
;                 const int rl = ai * HALF + m * 16; const unsigned off = lo + (unsigned)(rl * 64) * 2u;
;                 const f32x4 o0a = acc[ai][0][m][0], o0b = acc[ai][0][m][1], o1a = acc[ai][1][m][0], o1b = acc[ai][1][m][1];
;                 const f32x4 ra_ = dpp_swap1(odd ? o0a : o1a), rb_ = dpp_swap1(odd ? o0b : o1b);
;                 const f32x4 pa[2] = {odd ? ra_ : o0a, odd ? o1a : ra_}, pb[2] = {odd ? rb_ : o0b, odd ? o1b : rb_};
; #pragma unroll
;                 for (int q = 0; q < 2; ++q) {
;                     const u32x4 w0 = raw[2 * m + q];
;                     const f32x4 r0 = (f32x4){bf_lo(w0.x), bf_hi(w0.x), bf_lo(w0.y), bf_hi(w0.y)}, r1 = (f32x4){bf_lo(w0.z), bf_hi(w0.z), bf_lo(w0.w), bf_hi(w0.w)};
;                     f32x4 y0, y1;
;                     if (RESN) { const f32x2 t = tbl[rl + q]; const float mu = t.x, ra = t.y * ALPHA; y0 = (r0 - mu) * ra * g0 + b0 + pa[q]; y1 = (r1 - mu) * ra * g1 + b1 + pb[q]; }
;                     else { y0 = r0 * ALPHA + pa[q]; y1 = r1 * ALPHA + pb[q]; }
;                     { const u32x4 w = pack8f(y0, y1); *(u32x4*)(xb + off + q * 128) = w;
;                         y0 = (f32x4){bf_lo(w.x), bf_hi(w.x), bf_lo(w.y), bf_hi(w.y)}; y1 = (f32x4){bf_lo(w.z), bf_hi(w.z), bf_lo(w.w), bf_hi(w.w)}; }
;                     float sa = ((y0[0] + y0[1]) + (y0[2] + y0[3])) + ((y1[0] + y1[1]) + (y1[2] + y1[3]));
;                     float sb = ((y0[0] * y0[0] + y0[1] * y0[1]) + (y0[2] * y0[2] + y0[3] * y0[3])) + ((y1[0] * y1[0] + y1[1] * y1[1]) + (y1[2] * y1[2] + y1[3] * y1[3]));
;                     sa += dpp_x1(sa);
;                     sb += dpp_x1(sb);
;                     sa += __shfl_xor(sa, 16); sa += __shfl_xor(sa, 32); sb += __shfl_xor(sb, 16); sb += __shfl_xor(sb, 32);
;                     if (fq == 0 && !odd) ps[(size_t)(rl + q) * 64] = (f32x2){sa, sb};
;                 }
.LBB0_824:
	s_or_b64 exec, exec, s[68:69]
	s_waitcnt lgkmcnt(0)
	v_cndmask_b32_e64 v106, v100, v92, s[10:11]
	v_mov_b32_e32 v104, 0
	v_cndmask_b32_e64 v105, v101, v93, s[10:11]
	s_waitcnt lgkmcnt(0)
	v_cndmask_b32_e64 v107, v102, v94, s[10:11]
	v_mov_b32_dpp v104, v106 quad_perm:[1,0,3,2] row_mask:0xf bank_mask:0xf
	v_mov_b32_e32 v106, 0
	v_cndmask_b32_e64 v108, v103, v95, s[10:11]
	v_cndmask_b32_e64 v110, v96, v88, s[10:11]
	v_mov_b32_dpp v106, v105 quad_perm:[1,0,3,2] row_mask:0xf bank_mask:0xf
	v_mov_b32_e32 v105, 0
	v_cndmask_b32_e64 v109, v97, v89, s[10:11]
	v_cndmask_b32_e64 v111, v98, v90, s[10:11]
	v_mov_b32_dpp v105, v107 quad_perm:[1,0,3,2] row_mask:0xf bank_mask:0xf
	v_mov_b32_e32 v107, 0
	v_cndmask_b32_e64 v112, v99, v91, s[10:11]
	s_waitcnt vmcnt(15)
	v_lshlrev_b32_e32 v115, 16, v140
	v_mov_b32_dpp v107, v108 quad_perm:[1,0,3,2] row_mask:0xf bank_mask:0xf
	v_mov_b32_e32 v108, 0
	v_and_b32_e32 v116, 0xffff0000, v140
	v_cndmask_b32_e64 v101, v106, v101, s[10:11]
	v_mov_b32_dpp v108, v110 quad_perm:[1,0,3,2] row_mask:0xf bank_mask:0xf
	v_mov_b32_e32 v110, 0
	v_cndmask_b32_e64 v100, v104, v100, s[10:11]
	v_lshlrev_b32_e32 v118, 16, v141
	v_mov_b32_dpp v110, v109 quad_perm:[1,0,3,2] row_mask:0xf bank_mask:0xf
	v_mov_b32_e32 v109, 0
	v_and_b32_e32 v119, 0xffff0000, v141
	v_lshlrev_b32_e32 v120, 16, v142
	v_mov_b32_dpp v109, v111 quad_perm:[1,0,3,2] row_mask:0xf bank_mask:0xf
	v_mov_b32_e32 v111, 0
	v_and_b32_e32 v121, 0xffff0000, v142
	v_lshlrev_b32_e32 v122, 16, v143
	v_mov_b32_dpp v111, v112 quad_perm:[1,0,3,2] row_mask:0xf bank_mask:0xf
	ds_read_b64 v[112:113], v201 offset:256
	v_and_b32_e32 v123, 0xffff0000, v143
	v_cndmask_b32_e64 v103, v107, v103, s[10:11]
	v_cndmask_b32_e64 v102, v105, v102, s[10:11]
	v_cndmask_b32_e64 v97, v110, v97, s[10:11]
	s_waitcnt lgkmcnt(0)
	v_mul_f32_e32 v114, 0x3fb504f3, v113
	v_sub_f32_e32 v117, v116, v112
	v_sub_f32_e32 v116, v115, v112
	v_pk_mul_f32 v[116:117], v[116:117], v[114:115] op_sel_hi:[1,0]
	v_sub_f32_e32 v119, v119, v112
	v_pk_fma_f32 v[116:117], v[76:77], v[116:117], v[184:185]
	v_sub_f32_e32 v118, v118, v112
	v_pk_add_f32 v[100:101], v[100:101], v[116:117]
	v_sub_f32_e32 v117, v121, v112
	v_sub_f32_e32 v116, v120, v112
	v_sub_f32_e32 v113, v123, v112
	v_sub_f32_e32 v112, v122, v112
	v_pk_mul_f32 v[118:119], v[118:119], v[114:115] op_sel_hi:[1,0]
	v_pk_mul_f32 v[112:113], v[112:113], v[114:115] op_sel_hi:[1,0]
	v_pk_mul_f32 v[114:115], v[116:117], v[114:115] op_sel_hi:[1,0]
	v_cndmask_b32_e64 v96, v108, v96, s[10:11]
	v_cndmask_b32_e64 v99, v111, v99, s[10:11]
	v_cndmask_b32_e64 v98, v109, v98, s[10:11]
	v_pk_fma_f32 v[118:119], v[78:79], v[118:119], v[182:183]
	v_pk_fma_f32 v[114:115], v[72:73], v[114:115], v[180:181]
	v_pk_fma_f32 v[112:113], v[74:75], v[112:113], v[178:179]
	v_pk_add_f32 v[102:103], v[102:103], v[118:119]
	v_pk_add_f32 v[98:99], v[98:99], v[112:113]
	v_pk_add_f32 v[96:97], v[96:97], v[114:115]
	v_cvt_pk_bf16_f32 v112, v100, v101
	v_cvt_pk_bf16_f32 v113, v102, v103
	v_mov_b32_e32 v191, v165
	v_cvt_pk_bf16_f32 v114, v96, v97
	v_cvt_pk_bf16_f32 v115, v98, v99
	v_lshlrev_b32_e32 v96, 16, v112
	v_and_b32_e32 v98, 0xffff0000, v112
	v_lshlrev_b32_e32 v100, 16, v113
	v_and_b32_e32 v102, 0xffff0000, v113
	v_lshlrev_b32_e32 v116, 16, v114
	v_and_b32_e32 v118, 0xffff0000, v114
	v_lshlrev_b32_e32 v120, 16, v115
	v_and_b32_e32 v122, 0xffff0000, v115
	v_mul_f32_e32 v97, v96, v96
	v_mul_f32_e32 v99, v98, v98
	v_mul_f32_e32 v101, v100, v100
	v_mul_f32_e32 v103, v102, v102
	v_mul_f32_e32 v117, v116, v116
	v_mul_f32_e32 v119, v118, v118
	v_mul_f32_e32 v121, v120, v120
	v_mul_f32_e32 v123, v122, v122
	v_pk_add_f32 v[96:97], v[96:97], v[98:99]
	v_pk_add_f32 v[98:99], v[100:101], v[102:103]
	v_pk_add_f32 v[100:101], v[120:121], v[122:123]
	v_pk_add_f32 v[96:97], v[96:97], v[98:99]
	v_pk_add_f32 v[98:99], v[116:117], v[118:119]
	s_nop 0
	v_pk_add_f32 v[98:99], v[98:99], v[100:101]
	s_nop 0
	v_pk_add_f32 v[96:97], v[96:97], v[98:99]
	v_mov_b32_e32 v98, v165
	v_mov_b32_e32 v99, v165
	s_nop 0
	v_mov_b32_dpp v98, v96 quad_perm:[1,0,3,2] row_mask:0xf bank_mask:0xf
	v_mov_b32_dpp v99, v97 quad_perm:[1,0,3,2] row_mask:0xf bank_mask:0xf
	v_pk_add_f32 v[96:97], v[96:97], v[98:99]
	v_mov_b32_e32 v98, v96
	v_mov_b32_e32 v99, v97
	s_nop 1
	v_permlane16_swap_b32_e32 v96, v98
	v_permlane16_swap_b32_e32 v97, v99
	s_waitcnt lgkmcnt(0)
	v_pk_add_f32 v[98:99], v[96:97], v[98:99]
	v_mov_b32_e32 v100, v98
	v_mov_b32_e32 v101, v99
	s_nop 1
	v_permlane32_swap_b32_e32 v98, v100
	v_permlane32_swap_b32_e32 v99, v101
	v_lshl_add_u64 v[96:97], s[20:21], 0, v[190:191]
	global_store_dwordx4 v[96:97], v[112:115], off
	s_and_saveexec_b64 s[68:69], s[16:17]
	s_waitcnt lgkmcnt(0)
	v_pk_add_f32 v[98:99], v[98:99], v[100:101]
	v_add_co_u32_e32 v100, vcc, 0x4000, v186
	s_nop 1
	v_addc_co_u32_e32 v101, vcc, 0, v187, vcc
	global_store_dwordx2 v[100:101], v[98:99], off
;     __device__ __forceinline__ void operator()(const f32x4 (&acc)[2][2][4][2], const Unit& u, int wr, int wc, int fr, int fq, const EpiCtx& X) const {
;     ...
;             for (int m = 0; m < 4; ++m) { const unsigned off = lo + (unsigned)((ai * HALF + m * 16) * 64) * 2u; raw[2 * m] = *(const u32x4*)(xb + off); raw[2 * m + 1] = *(const u32x4*)(xb + off + 128); }
; #pragma unroll
;             for (int m = 0; m < 4; ++m) {
;                 const int rl = ai * HALF + m * 16; const unsigned off = lo + (unsigned)(rl * 64) * 2u;
;                 const f32x4 o0a = acc[ai][0][m][0], o0b = acc[ai][0][m][1], o1a = acc[ai][1][m][0], o1b = acc[ai][1][m][1];
;                 const f32x4 ra_ = dpp_swap1(odd ? o0a : o1a), rb_ = dpp_swap1(odd ? o0b : o1b);
;                 const f32x4 pa[2] = {odd ? ra_ : o0a, odd ? o1a : ra_}, pb[2] = {odd ? rb_ : o0b, odd ? o1b : rb_};
; #pragma unroll
;                 for (int q = 0; q < 2; ++q) {
;                     const u32x4 w0 = raw[2 * m + q];
;                     const f32x4 r0 = (f32x4){bf_lo(w0.x), bf_hi(w0.x), bf_lo(w0.y), bf_hi(w0.y)}, r1 = (f32x4){bf_lo(w0.z), bf_hi(w0.z), bf_lo(w0.w), bf_hi(w0.w)};
;                     f32x4 y0, y1;
;                     if (RESN) { const f32x2 t = tbl[rl + q]; const float mu = t.x, ra = t.y * ALPHA; y0 = (r0 - mu) * ra * g0 + b0 + pa[q]; y1 = (r1 - mu) * ra * g1 + b1 + pb[q]; }
;                     else { y0 = r0 * ALPHA + pa[q]; y1 = r1 * ALPHA + pb[q]; }
;                     { const u32x4 w = pack8f(y0, y1); *(u32x4*)(xb + off + q * 128) = w;
;                         y0 = (f32x4){bf_lo(w.x), bf_hi(w.x), bf_lo(w.y), bf_hi(w.y)}; y1 = (f32x4){bf_lo(w.z), bf_hi(w.z), bf_lo(w.w), bf_hi(w.w)}; }
;                     float sa = ((y0[0] + y0[1]) + (y0[2] + y0[3])) + ((y1[0] + y1[1]) + (y1[2] + y1[3]));
;                     float sb = ((y0[0] * y0[0] + y0[1] * y0[1]) + (y0[2] * y0[2] + y0[3] * y0[3])) + ((y1[0] * y1[0] + y1[1] * y1[1]) + (y1[2] * y1[2] + y1[3] * y1[3]));
;                     sa += dpp_x1(sa);
;                     sb += dpp_x1(sb);
;                     sa += __shfl_xor(sa, 16); sa += __shfl_xor(sa, 32); sb += __shfl_xor(sb, 16); sb += __shfl_xor(sb, 32);
;                     if (fq == 0 && !odd) ps[(size_t)(rl + q) * 64] = (f32x2){sa, sb};
;                 }
.LBB0_826:
	s_or_b64 exec, exec, s[68:69]
	ds_read_b64 v[98:99], v201 offset:264
	s_waitcnt lgkmcnt(1)
	s_waitcnt vmcnt(16)
	v_lshlrev_b32_e32 v101, 16, v136
	v_and_b32_e32 v102, 0xffff0000, v136
	v_cndmask_b32_e64 v93, v93, v106, s[10:11]
	v_cndmask_b32_e64 v92, v92, v104, s[10:11]
	s_waitcnt lgkmcnt(0)
	v_mul_f32_e32 v100, 0x3fb504f3, v99
	v_sub_f32_e32 v103, v102, v98
	v_sub_f32_e32 v102, v101, v98
	v_pk_mul_f32 v[102:103], v[102:103], v[100:101] op_sel_hi:[1,0]
	v_cndmask_b32_e64 v95, v95, v107, s[10:11]
	v_cndmask_b32_e64 v94, v94, v105, s[10:11]
	v_cndmask_b32_e64 v88, v88, v108, s[10:11]
	v_cndmask_b32_e64 v90, v90, v109, s[10:11]
	v_lshlrev_b32_e32 v104, 16, v137
	v_and_b32_e32 v105, 0xffff0000, v137
	v_lshlrev_b32_e32 v106, 16, v138
	v_and_b32_e32 v107, 0xffff0000, v138
	v_lshlrev_b32_e32 v108, 16, v139
	v_and_b32_e32 v109, 0xffff0000, v139
	v_pk_fma_f32 v[102:103], v[76:77], v[102:103], v[184:185]
	v_sub_f32_e32 v105, v105, v98
	v_sub_f32_e32 v104, v104, v98
	v_pk_add_f32 v[92:93], v[92:93], v[102:103]
	v_sub_f32_e32 v103, v107, v98
	v_sub_f32_e32 v102, v106, v98
	v_sub_f32_e32 v99, v109, v98
	v_sub_f32_e32 v98, v108, v98
	v_pk_mul_f32 v[104:105], v[104:105], v[100:101] op_sel_hi:[1,0]
	v_pk_mul_f32 v[98:99], v[98:99], v[100:101] op_sel_hi:[1,0]
	v_pk_mul_f32 v[100:101], v[102:103], v[100:101] op_sel_hi:[1,0]
	v_cndmask_b32_e64 v89, v89, v110, s[10:11]
	v_cndmask_b32_e64 v91, v91, v111, s[10:11]
	v_pk_fma_f32 v[104:105], v[78:79], v[104:105], v[182:183]
	v_pk_fma_f32 v[100:101], v[72:73], v[100:101], v[180:181]
	v_pk_fma_f32 v[98:99], v[74:75], v[98:99], v[178:179]
	v_pk_add_f32 v[94:95], v[94:95], v[104:105]
	v_pk_add_f32 v[90:91], v[90:91], v[98:99]
	v_pk_add_f32 v[88:89], v[88:89], v[100:101]
	v_cvt_pk_bf16_f32 v92, v92, v93
	v_cvt_pk_bf16_f32 v93, v94, v95
	s_nop 0
	v_cvt_pk_bf16_f32 v94, v88, v89
	v_cvt_pk_bf16_f32 v95, v90, v91
	v_lshlrev_b32_e32 v88, 16, v92
	v_and_b32_e32 v90, 0xffff0000, v92
	v_lshlrev_b32_e32 v98, 16, v93
	v_and_b32_e32 v100, 0xffff0000, v93
	v_lshlrev_b32_e32 v102, 16, v94
	v_and_b32_e32 v104, 0xffff0000, v94
	v_lshlrev_b32_e32 v106, 16, v95
	v_and_b32_e32 v108, 0xffff0000, v95
	v_mul_f32_e32 v89, v88, v88
	v_mul_f32_e32 v91, v90, v90
	v_mul_f32_e32 v99, v98, v98
	v_mul_f32_e32 v101, v100, v100
	v_mul_f32_e32 v103, v102, v102
	v_mul_f32_e32 v105, v104, v104
	v_mul_f32_e32 v107, v106, v106
	v_mul_f32_e32 v109, v108, v108
	v_pk_add_f32 v[88:89], v[88:89], v[90:91]
	v_pk_add_f32 v[90:91], v[98:99], v[100:101]
	v_pk_add_f32 v[98:99], v[106:107], v[108:109]
	v_pk_add_f32 v[88:89], v[88:89], v[90:91]
	v_pk_add_f32 v[90:91], v[102:103], v[104:105]
	global_store_dwordx4 v[96:97], v[92:95], off offset:128
	v_pk_add_f32 v[90:91], v[90:91], v[98:99]
	s_nop 0
	v_pk_add_f32 v[88:89], v[88:89], v[90:91]
	v_mov_b32_e32 v90, v165
	v_mov_b32_e32 v91, v165
	s_nop 0
	v_mov_b32_dpp v90, v88 quad_perm:[1,0,3,2] row_mask:0xf bank_mask:0xf
	v_mov_b32_dpp v91, v89 quad_perm:[1,0,3,2] row_mask:0xf bank_mask:0xf
	v_pk_add_f32 v[88:89], v[88:89], v[90:91]
	v_mov_b32_e32 v90, v88
	v_mov_b32_e32 v91, v89
	s_nop 1
	v_permlane16_swap_b32_e32 v88, v90
	v_permlane16_swap_b32_e32 v89, v91
	s_waitcnt lgkmcnt(0)
	v_pk_add_f32 v[88:89], v[88:89], v[90:91]
	v_mov_b32_e32 v90, v88
	v_mov_b32_e32 v91, v89
	s_nop 1
	v_permlane32_swap_b32_e32 v88, v90
	v_permlane32_swap_b32_e32 v89, v91
	s_and_saveexec_b64 s[68:69], s[16:17]
	s_waitcnt lgkmcnt(0)
	v_pk_add_f32 v[88:89], v[88:89], v[90:91]
	v_add_co_u32_e32 v90, vcc, 0x4000, v186
	s_nop 1
	v_addc_co_u32_e32 v91, vcc, 0, v187, vcc
	global_store_dwordx2 v[90:91], v[88:89], off offset:512
.LBB0_828:
	s_or_b64 exec, exec, s[68:69]
	s_waitcnt lgkmcnt(0)
	v_cndmask_b32_e64 v90, v84, v68, s[10:11]
	v_mov_b32_e32 v88, 0
	v_cndmask_b32_e64 v89, v85, v69, s[10:11]
	s_waitcnt lgkmcnt(0)
	v_cndmask_b32_e64 v91, v86, v70, s[10:11]
	v_mov_b32_dpp v88, v90 quad_perm:[1,0,3,2] row_mask:0xf bank_mask:0xf
	v_mov_b32_e32 v90, 0
	v_cndmask_b32_e64 v92, v87, v71, s[10:11]
	v_cndmask_b32_e64 v94, v80, v64, s[10:11]
	v_mov_b32_dpp v90, v89 quad_perm:[1,0,3,2] row_mask:0xf bank_mask:0xf
	v_mov_b32_e32 v89, 0
	v_cndmask_b32_e64 v93, v81, v65, s[10:11]
	v_cndmask_b32_e64 v95, v82, v66, s[10:11]
	v_mov_b32_dpp v89, v91 quad_perm:[1,0,3,2] row_mask:0xf bank_mask:0xf
	v_mov_b32_e32 v91, 0
	v_cndmask_b32_e64 v96, v83, v67, s[10:11]
	s_waitcnt vmcnt(17)
	v_lshlrev_b32_e32 v99, 16, v132
	v_mov_b32_dpp v91, v92 quad_perm:[1,0,3,2] row_mask:0xf bank_mask:0xf
	v_mov_b32_e32 v92, 0
	v_and_b32_e32 v100, 0xffff0000, v132
	v_cndmask_b32_e64 v85, v90, v85, s[10:11]
	v_mov_b32_dpp v92, v94 quad_perm:[1,0,3,2] row_mask:0xf bank_mask:0xf
	v_mov_b32_e32 v94, 0
	v_cndmask_b32_e64 v84, v88, v84, s[10:11]
	v_lshlrev_b32_e32 v102, 16, v133
	v_mov_b32_dpp v94, v93 quad_perm:[1,0,3,2] row_mask:0xf bank_mask:0xf
	v_mov_b32_e32 v93, 0
	v_and_b32_e32 v103, 0xffff0000, v133
	v_lshlrev_b32_e32 v104, 16, v134
	v_mov_b32_dpp v93, v95 quad_perm:[1,0,3,2] row_mask:0xf bank_mask:0xf
	v_mov_b32_e32 v95, 0
	v_and_b32_e32 v105, 0xffff0000, v134
	v_lshlrev_b32_e32 v106, 16, v135
	v_mov_b32_dpp v95, v96 quad_perm:[1,0,3,2] row_mask:0xf bank_mask:0xf
	ds_read_b64 v[96:97], v201 offset:384
	v_and_b32_e32 v107, 0xffff0000, v135
	v_cndmask_b32_e64 v87, v91, v87, s[10:11]
	v_cndmask_b32_e64 v86, v89, v86, s[10:11]
	v_cndmask_b32_e64 v81, v94, v81, s[10:11]
	s_waitcnt lgkmcnt(0)
;     __device__ __forceinline__ void operator()(const f32x4 (&acc)[2][2][4][2], const Unit& u, int wr, int wc, int fr, int fq, const EpiCtx& X) const {
;     ...
;             for (int m = 0; m < 4; ++m) { const unsigned off = lo + (unsigned)((ai * HALF + m * 16) * 64) * 2u; raw[2 * m] = *(const u32x4*)(xb + off); raw[2 * m + 1] = *(const u32x4*)(xb + off + 128); }
; #pragma unroll
;             for (int m = 0; m < 4; ++m) {
;                 const int rl = ai * HALF + m * 16; const unsigned off = lo + (unsigned)(rl * 64) * 2u;
;                 const f32x4 o0a = acc[ai][0][m][0], o0b = acc[ai][0][m][1], o1a = acc[ai][1][m][0], o1b = acc[ai][1][m][1];
;                 const f32x4 ra_ = dpp_swap1(odd ? o0a : o1a), rb_ = dpp_swap1(odd ? o0b : o1b);
;                 const f32x4 pa[2] = {odd ? ra_ : o0a, odd ? o1a : ra_}, pb[2] = {odd ? rb_ : o0b, odd ? o1b : rb_};
; #pragma unroll
;                 for (int q = 0; q < 2; ++q) {
;                     const u32x4 w0 = raw[2 * m + q];
;                     const f32x4 r0 = (f32x4){bf_lo(w0.x), bf_hi(w0.x), bf_lo(w0.y), bf_hi(w0.y)}, r1 = (f32x4){bf_lo(w0.z), bf_hi(w0.z), bf_lo(w0.w), bf_hi(w0.w)};
;                     f32x4 y0, y1;
;                     if (RESN) { const f32x2 t = tbl[rl + q]; const float mu = t.x, ra = t.y * ALPHA; y0 = (r0 - mu) * ra * g0 + b0 + pa[q]; y1 = (r1 - mu) * ra * g1 + b1 + pb[q]; }
;                     else { y0 = r0 * ALPHA + pa[q]; y1 = r1 * ALPHA + pb[q]; }
;                     { const u32x4 w = pack8f(y0, y1); *(u32x4*)(xb + off + q * 128) = w;
;                         y0 = (f32x4){bf_lo(w.x), bf_hi(w.x), bf_lo(w.y), bf_hi(w.y)}; y1 = (f32x4){bf_lo(w.z), bf_hi(w.z), bf_lo(w.w), bf_hi(w.w)}; }
;                     float sa = ((y0[0] + y0[1]) + (y0[2] + y0[3])) + ((y1[0] + y1[1]) + (y1[2] + y1[3]));
;                     float sb = ((y0[0] * y0[0] + y0[1] * y0[1]) + (y0[2] * y0[2] + y0[3] * y0[3])) + ((y1[0] * y1[0] + y1[1] * y1[1]) + (y1[2] * y1[2] + y1[3] * y1[3]));
;                     sa += dpp_x1(sa);
;                     sb += dpp_x1(sb);
;                     sa += __shfl_xor(sa, 16); sa += __shfl_xor(sa, 32); sb += __shfl_xor(sb, 16); sb += __shfl_xor(sb, 32);
;                     if (fq == 0 && !odd) ps[(size_t)(rl + q) * 64] = (f32x2){sa, sb};
;                 }
	v_mul_f32_e32 v98, 0x3fb504f3, v97
	v_sub_f32_e32 v101, v100, v96
	v_sub_f32_e32 v100, v99, v96
	v_pk_mul_f32 v[100:101], v[100:101], v[98:99] op_sel_hi:[1,0]
	v_sub_f32_e32 v103, v103, v96
	v_pk_fma_f32 v[100:101], v[76:77], v[100:101], v[184:185]
	v_sub_f32_e32 v102, v102, v96
	v_pk_add_f32 v[84:85], v[84:85], v[100:101]
	v_sub_f32_e32 v101, v105, v96
	v_sub_f32_e32 v100, v104, v96
	v_sub_f32_e32 v97, v107, v96
	v_sub_f32_e32 v96, v106, v96
	v_pk_mul_f32 v[102:103], v[102:103], v[98:99] op_sel_hi:[1,0]
	v_pk_mul_f32 v[96:97], v[96:97], v[98:99] op_sel_hi:[1,0]
	v_pk_mul_f32 v[98:99], v[100:101], v[98:99] op_sel_hi:[1,0]
	v_cndmask_b32_e64 v80, v92, v80, s[10:11]
	v_cndmask_b32_e64 v83, v95, v83, s[10:11]
	v_cndmask_b32_e64 v82, v93, v82, s[10:11]
	v_pk_fma_f32 v[102:103], v[78:79], v[102:103], v[182:183]
	v_pk_fma_f32 v[98:99], v[72:73], v[98:99], v[180:181]
	v_pk_fma_f32 v[96:97], v[74:75], v[96:97], v[178:179]
	v_pk_add_f32 v[86:87], v[86:87], v[102:103]
	v_pk_add_f32 v[82:83], v[82:83], v[96:97]
	v_pk_add_f32 v[80:81], v[80:81], v[98:99]
	v_cvt_pk_bf16_f32 v96, v84, v85
	v_cvt_pk_bf16_f32 v97, v86, v87
	v_mov_b32_e32 v189, v165
	v_cvt_pk_bf16_f32 v98, v80, v81
	v_cvt_pk_bf16_f32 v99, v82, v83
	v_lshlrev_b32_e32 v80, 16, v96
	v_and_b32_e32 v82, 0xffff0000, v96
	v_lshlrev_b32_e32 v84, 16, v97
	v_and_b32_e32 v86, 0xffff0000, v97
	v_lshlrev_b32_e32 v100, 16, v98
	v_and_b32_e32 v102, 0xffff0000, v98
	v_lshlrev_b32_e32 v104, 16, v99
	v_and_b32_e32 v106, 0xffff0000, v99
	v_mul_f32_e32 v81, v80, v80
	v_mul_f32_e32 v83, v82, v82
	v_mul_f32_e32 v85, v84, v84
	v_mul_f32_e32 v87, v86, v86
	v_mul_f32_e32 v101, v100, v100
	v_mul_f32_e32 v103, v102, v102
	v_mul_f32_e32 v105, v104, v104
	v_mul_f32_e32 v107, v106, v106
	v_pk_add_f32 v[80:81], v[80:81], v[82:83]
	v_pk_add_f32 v[82:83], v[84:85], v[86:87]
	v_pk_add_f32 v[84:85], v[104:105], v[106:107]
	v_pk_add_f32 v[80:81], v[80:81], v[82:83]
	v_pk_add_f32 v[82:83], v[100:101], v[102:103]
	s_nop 0
	v_pk_add_f32 v[82:83], v[82:83], v[84:85]
	s_nop 0
	v_pk_add_f32 v[80:81], v[80:81], v[82:83]
	v_mov_b32_e32 v82, v165
	v_mov_b32_e32 v83, v165
	s_nop 0
	v_mov_b32_dpp v82, v80 quad_perm:[1,0,3,2] row_mask:0xf bank_mask:0xf
	v_mov_b32_dpp v83, v81 quad_perm:[1,0,3,2] row_mask:0xf bank_mask:0xf
	v_pk_add_f32 v[80:81], v[80:81], v[82:83]
	v_mov_b32_e32 v82, v80
	v_mov_b32_e32 v83, v81
	s_nop 1
	v_permlane16_swap_b32_e32 v80, v82
	v_permlane16_swap_b32_e32 v81, v83
	s_waitcnt lgkmcnt(0)
	v_pk_add_f32 v[82:83], v[80:81], v[82:83]
	v_mov_b32_e32 v84, v82
	v_mov_b32_e32 v85, v83
	s_nop 1
	v_permlane32_swap_b32_e32 v82, v84
	v_permlane32_swap_b32_e32 v83, v85
	v_lshl_add_u64 v[80:81], s[20:21], 0, v[188:189]
	global_store_dwordx4 v[80:81], v[96:99], off
	s_and_saveexec_b64 s[68:69], s[16:17]
	s_waitcnt lgkmcnt(0)
	v_pk_add_f32 v[82:83], v[82:83], v[84:85]
	v_add_co_u32_e32 v84, vcc, 0x6000, v186
	s_nop 1
	v_addc_co_u32_e32 v85, vcc, 0, v187, vcc
	global_store_dwordx2 v[84:85], v[82:83], off
.LBB0_830:
	s_or_b64 exec, exec, s[68:69]
	ds_read_b64 v[82:83], v201 offset:392
	s_waitcnt lgkmcnt(1)
	s_waitcnt vmcnt(18)
	v_lshlrev_b32_e32 v85, 16, v128
	v_and_b32_e32 v86, 0xffff0000, v128
	v_cndmask_b32_e64 v69, v69, v90, s[10:11]
	v_cndmask_b32_e64 v68, v68, v88, s[10:11]
	s_waitcnt lgkmcnt(0)
	v_mul_f32_e32 v84, 0x3fb504f3, v83
	v_sub_f32_e32 v87, v86, v82
	v_sub_f32_e32 v86, v85, v82
	v_pk_mul_f32 v[86:87], v[86:87], v[84:85] op_sel_hi:[1,0]
	v_cndmask_b32_e64 v71, v71, v91, s[10:11]
	v_cndmask_b32_e64 v70, v70, v89, s[10:11]
	v_cndmask_b32_e64 v64, v64, v92, s[10:11]
	v_cndmask_b32_e64 v66, v66, v93, s[10:11]
	v_lshlrev_b32_e32 v88, 16, v129
	v_and_b32_e32 v89, 0xffff0000, v129
	v_lshlrev_b32_e32 v90, 16, v130
	v_and_b32_e32 v91, 0xffff0000, v130
	v_lshlrev_b32_e32 v92, 16, v131
	v_and_b32_e32 v93, 0xffff0000, v131
	v_pk_fma_f32 v[86:87], v[76:77], v[86:87], v[184:185]
	v_sub_f32_e32 v89, v89, v82
	v_sub_f32_e32 v88, v88, v82
	v_pk_add_f32 v[68:69], v[68:69], v[86:87]
	v_sub_f32_e32 v87, v91, v82
	v_sub_f32_e32 v86, v90, v82
	v_sub_f32_e32 v83, v93, v82
	v_sub_f32_e32 v82, v92, v82
	v_pk_mul_f32 v[88:89], v[88:89], v[84:85] op_sel_hi:[1,0]
	v_pk_mul_f32 v[82:83], v[82:83], v[84:85] op_sel_hi:[1,0]
	v_pk_mul_f32 v[84:85], v[86:87], v[84:85] op_sel_hi:[1,0]
	v_cndmask_b32_e64 v65, v65, v94, s[10:11]
	v_cndmask_b32_e64 v67, v67, v95, s[10:11]
	v_pk_fma_f32 v[88:89], v[78:79], v[88:89], v[182:183]
	v_pk_fma_f32 v[84:85], v[72:73], v[84:85], v[180:181]
	v_pk_fma_f32 v[82:83], v[74:75], v[82:83], v[178:179]
	v_pk_add_f32 v[70:71], v[70:71], v[88:89]
	v_pk_add_f32 v[66:67], v[66:67], v[82:83]
	v_pk_add_f32 v[64:65], v[64:65], v[84:85]
	v_cvt_pk_bf16_f32 v68, v68, v69
	v_cvt_pk_bf16_f32 v69, v70, v71
	s_nop 0
	v_cvt_pk_bf16_f32 v70, v64, v65
	v_cvt_pk_bf16_f32 v71, v66, v67
	v_lshlrev_b32_e32 v64, 16, v68
	v_and_b32_e32 v66, 0xffff0000, v68
	v_lshlrev_b32_e32 v82, 16, v69
	v_and_b32_e32 v84, 0xffff0000, v69
	v_lshlrev_b32_e32 v86, 16, v70
	v_and_b32_e32 v88, 0xffff0000, v70
	v_lshlrev_b32_e32 v90, 16, v71
	v_and_b32_e32 v92, 0xffff0000, v71
	v_mul_f32_e32 v65, v64, v64
	v_mul_f32_e32 v67, v66, v66
	v_mul_f32_e32 v83, v82, v82
	v_mul_f32_e32 v85, v84, v84
	v_mul_f32_e32 v87, v86, v86
	v_mul_f32_e32 v89, v88, v88
	v_mul_f32_e32 v91, v90, v90
	v_mul_f32_e32 v93, v92, v92
	v_pk_add_f32 v[64:65], v[64:65], v[66:67]
	v_pk_add_f32 v[66:67], v[82:83], v[84:85]
	v_pk_add_f32 v[82:83], v[90:91], v[92:93]
	v_pk_add_f32 v[64:65], v[64:65], v[66:67]
	v_pk_add_f32 v[66:67], v[86:87], v[88:89]
	global_store_dwordx4 v[80:81], v[68:71], off offset:128
	v_pk_add_f32 v[66:67], v[66:67], v[82:83]
	s_nop 0
	v_pk_add_f32 v[64:65], v[64:65], v[66:67]
	v_mov_b32_e32 v66, v165
	v_mov_b32_e32 v67, v165
	s_nop 0
	v_mov_b32_dpp v66, v64 quad_perm:[1,0,3,2] row_mask:0xf bank_mask:0xf
	v_mov_b32_dpp v67, v65 quad_perm:[1,0,3,2] row_mask:0xf bank_mask:0xf
	v_pk_add_f32 v[64:65], v[64:65], v[66:67]
	v_mov_b32_e32 v66, v64
	v_mov_b32_e32 v67, v65
	s_nop 1
	v_permlane16_swap_b32_e32 v64, v66
	v_permlane16_swap_b32_e32 v65, v67
	s_waitcnt lgkmcnt(0)
	v_pk_add_f32 v[64:65], v[64:65], v[66:67]
	v_mov_b32_e32 v66, v64
	v_mov_b32_e32 v67, v65
	s_nop 1
	v_permlane32_swap_b32_e32 v64, v66
	v_permlane32_swap_b32_e32 v65, v67
	s_and_saveexec_b64 s[68:69], s[16:17]
	s_waitcnt lgkmcnt(0)
	v_pk_add_f32 v[64:65], v[64:65], v[66:67]
	v_add_co_u32_e32 v66, vcc, 0x6000, v186
	s_nop 1
	v_addc_co_u32_e32 v67, vcc, 0, v187, vcc
	global_store_dwordx2 v[66:67], v[64:65], off offset:512
;     __device__ __forceinline__ void operator()(const f32x4 (&acc)[2][2][4][2], const Unit& u, int wr, int wc, int fr, int fq, const EpiCtx& X) const {
;     ...
;             u32x4 raw[8];
; #pragma unroll
;             for (int m = 0; m < 4; ++m) { const unsigned off = lo + (unsigned)((ai * HALF + m * 16) * 64) * 2u; raw[2 * m] = *(const u32x4*)(xb + off); raw[2 * m + 1] = *(const u32x4*)(xb + off + 128); }
; #pragma unroll
;             for (int m = 0; m < 4; ++m) {
;                 const int rl = ai * HALF + m * 16; const unsigned off = lo + (unsigned)(rl * 64) * 2u;
;                 const f32x4 o0a = acc[ai][0][m][0], o0b = acc[ai][0][m][1], o1a = acc[ai][1][m][0], o1b = acc[ai][1][m][1];
;                 const f32x4 ra_ = dpp_swap1(odd ? o0a : o1a), rb_ = dpp_swap1(odd ? o0b : o1b);
;                 const f32x4 pa[2] = {odd ? ra_ : o0a, odd ? o1a : ra_}, pb[2] = {odd ? rb_ : o0b, odd ? o1b : rb_};
; #pragma unroll
;                 for (int q = 0; q < 2; ++q) {
;                     const u32x4 w0 = raw[2 * m + q];
;                     const f32x4 r0 = (f32x4){bf_lo(w0.x), bf_hi(w0.x), bf_lo(w0.y), bf_hi(w0.y)}, r1 = (f32x4){bf_lo(w0.z), bf_hi(w0.z), bf_lo(w0.w), bf_hi(w0.w)};
;                     f32x4 y0, y1;
;                     if (RESN) { const f32x2 t = tbl[rl + q]; const float mu = t.x, ra = t.y * ALPHA; y0 = (r0 - mu) * ra * g0 + b0 + pa[q]; y1 = (r1 - mu) * ra * g1 + b1 + pb[q]; }
;                     else { y0 = r0 * ALPHA + pa[q]; y1 = r1 * ALPHA + pb[q]; }
;                     { const u32x4 w = pack8f(y0, y1); *(u32x4*)(xb + off + q * 128) = w;
;                         y0 = (f32x4){bf_lo(w.x), bf_hi(w.x), bf_lo(w.y), bf_hi(w.y)}; y1 = (f32x4){bf_lo(w.z), bf_hi(w.z), bf_lo(w.w), bf_hi(w.w)}; }
;                     float sa = ((y0[0] + y0[1]) + (y0[2] + y0[3])) + ((y1[0] + y1[1]) + (y1[2] + y1[3]));
;                     float sb = ((y0[0] * y0[0] + y0[1] * y0[1]) + (y0[2] * y0[2] + y0[3] * y0[3])) + ((y1[0] * y1[0] + y1[1] * y1[1]) + (y1[2] * y1[2] + y1[3] * y1[3]));
;                     sa += dpp_x1(sa);
;                     sb += dpp_x1(sb);
;                     sa += __shfl_xor(sa, 16); sa += __shfl_xor(sa, 32); sb += __shfl_xor(sb, 16); sb += __shfl_xor(sb, 32);
;                     if (fq == 0 && !odd) ps[(size_t)(rl + q) * 64] = (f32x2){sa, sb};
;                 }
.LBB0_832:
	s_or_b64 exec, exec, s[68:69]
	v_add_u32_e32 v104, 0x4000, v164
	s_waitcnt vmcnt(16)
	v_mov_b32_e32 v112, v230
	v_mov_b32_e32 v113, v231
	v_mov_b32_e32 v114, v232
	v_mov_b32_e32 v115, v233
	v_add_u32_e32 v102, 0x4800, v164
	v_add_u32_e32 v100, 0x5000, v164
	v_add_u32_e32 v164, 0x5800, v164
	v_mov_b32_e32 v96, v234
	v_mov_b32_e32 v97, v235
	v_mov_b32_e32 v98, v236
	v_mov_b32_e32 v99, v237
	v_mov_b32_e32 v92, v238
	v_mov_b32_e32 v93, v239
	v_mov_b32_e32 v94, v240
	v_mov_b32_e32 v95, v241
	v_mov_b32_e32 v88, v242
	v_mov_b32_e32 v89, v243
	v_mov_b32_e32 v90, v244
	v_mov_b32_e32 v91, v245
	global_load_dwordx4 v[84:87], v100, s[20:21]
	global_load_dwordx4 v[80:83], v100, s[20:21] offset:128
	global_load_dwordx4 v[68:71], v164, s[20:21]
	s_waitcnt lgkmcnt(0)
	global_load_dwordx4 v[64:67], v164, s[20:21] offset:128
	v_cndmask_b32_e64 v116, v62, v54, s[10:11]
	v_cndmask_b32_e64 v117, v61, v53, s[10:11]
	v_mov_b32_e32 v105, 0
	v_mov_b32_e32 v103, 0
	v_cndmask_b32_e64 v111, v63, v55, s[10:11]
	v_mov_b32_dpp v105, v117 quad_perm:[1,0,3,2] row_mask:0xf bank_mask:0xf
	v_mov_b32_dpp v103, v116 quad_perm:[1,0,3,2] row_mask:0xf bank_mask:0xf
	ds_read_b64 v[116:117], v201 offset:1024
	v_cndmask_b32_e64 v118, v60, v52, s[10:11]
	v_mov_b32_e32 v101, 0
	v_mov_b32_e32 v106, 0
	v_cndmask_b32_e64 v119, v59, v51, s[10:11]
	v_cndmask_b32_e64 v120, v58, v50, s[10:11]
	v_cndmask_b32_e64 v121, v57, v49, s[10:11]
	v_cndmask_b32_e64 v122, v56, v48, s[10:11]
	v_mov_b32_e32 v107, 0
	v_mov_b32_e32 v109, 0
	v_mov_b32_e32 v108, 0
	v_mov_b32_e32 v110, 0
	v_mov_b32_dpp v101, v118 quad_perm:[1,0,3,2] row_mask:0xf bank_mask:0xf
	v_mov_b32_dpp v106, v111 quad_perm:[1,0,3,2] row_mask:0xf bank_mask:0xf
	v_mov_b32_dpp v107, v122 quad_perm:[1,0,3,2] row_mask:0xf bank_mask:0xf
	v_mov_b32_dpp v109, v121 quad_perm:[1,0,3,2] row_mask:0xf bank_mask:0xf
	v_mov_b32_dpp v108, v120 quad_perm:[1,0,3,2] row_mask:0xf bank_mask:0xf
	v_mov_b32_dpp v110, v119 quad_perm:[1,0,3,2] row_mask:0xf bank_mask:0xf
	s_waitcnt lgkmcnt(0)
	v_mul_f32_e32 v118, 0x3fb504f3, v117
	v_cndmask_b32_e64 v61, v105, v61, s[10:11]
	v_cndmask_b32_e64 v60, v101, v60, s[10:11]
	v_cndmask_b32_e64 v63, v106, v63, s[10:11]
	v_cndmask_b32_e64 v62, v103, v62, s[10:11]
	v_cndmask_b32_e64 v57, v109, v57, s[10:11]
	v_cndmask_b32_e64 v56, v107, v56, s[10:11]
	v_cndmask_b32_e64 v59, v110, v59, s[10:11]
	v_cndmask_b32_e64 v58, v108, v58, s[10:11]
	v_lshlrev_b32_e32 v111, 16, v112
	v_and_b32_e32 v112, 0xffff0000, v112
	v_lshlrev_b32_e32 v117, 16, v113
	v_and_b32_e32 v119, 0xffff0000, v113
	v_lshlrev_b32_e32 v120, 16, v114
	v_and_b32_e32 v121, 0xffff0000, v114
	v_lshlrev_b32_e32 v122, 16, v115
	v_and_b32_e32 v123, 0xffff0000, v115
	v_sub_f32_e32 v113, v112, v116
	v_sub_f32_e32 v112, v111, v116
	v_sub_f32_e32 v115, v119, v116
	v_sub_f32_e32 v114, v117, v116
	v_sub_f32_e32 v121, v121, v116
	v_sub_f32_e32 v120, v120, v116
	v_sub_f32_e32 v117, v123, v116
	v_sub_f32_e32 v116, v122, v116
	v_pk_mul_f32 v[114:115], v[114:115], v[118:119] op_sel_hi:[1,0]
	v_pk_mul_f32 v[112:113], v[112:113], v[118:119] op_sel_hi:[1,0]
	v_pk_mul_f32 v[116:117], v[116:117], v[118:119] op_sel_hi:[1,0]
	v_pk_mul_f32 v[118:119], v[120:121], v[118:119] op_sel_hi:[1,0]
	v_pk_fma_f32 v[112:113], v[76:77], v[112:113], v[184:185]
	v_pk_fma_f32 v[114:115], v[78:79], v[114:115], v[182:183]
	v_pk_fma_f32 v[118:119], v[72:73], v[118:119], v[180:181]
	v_pk_fma_f32 v[116:117], v[74:75], v[116:117], v[178:179]
	v_pk_add_f32 v[62:63], v[62:63], v[114:115]
	v_pk_add_f32 v[60:61], v[60:61], v[112:113]
	v_pk_add_f32 v[58:59], v[58:59], v[116:117]
	v_pk_add_f32 v[56:57], v[56:57], v[118:119]
	v_cvt_pk_bf16_f32 v60, v60, v61
	v_cvt_pk_bf16_f32 v61, v62, v63
	s_nop 0
	v_cvt_pk_bf16_f32 v62, v56, v57
	v_cvt_pk_bf16_f32 v63, v58, v59
	v_lshlrev_b32_e32 v56, 16, v60
	v_and_b32_e32 v58, 0xffff0000, v60
	v_lshlrev_b32_e32 v112, 16, v61
	v_and_b32_e32 v114, 0xffff0000, v61
	v_lshlrev_b32_e32 v116, 16, v62
	v_and_b32_e32 v118, 0xffff0000, v62
	v_lshlrev_b32_e32 v120, 16, v63
	v_and_b32_e32 v122, 0xffff0000, v63
	v_mul_f32_e32 v57, v56, v56
	v_mul_f32_e32 v59, v58, v58
	v_mul_f32_e32 v113, v112, v112
	v_mul_f32_e32 v115, v114, v114
	v_mul_f32_e32 v117, v116, v116
	v_mul_f32_e32 v119, v118, v118
	v_mul_f32_e32 v121, v120, v120
	v_mul_f32_e32 v123, v122, v122
	v_pk_add_f32 v[56:57], v[56:57], v[58:59]
	v_pk_add_f32 v[58:59], v[112:113], v[114:115]
	v_pk_add_f32 v[112:113], v[120:121], v[122:123]
	v_pk_add_f32 v[56:57], v[56:57], v[58:59]
	v_pk_add_f32 v[58:59], v[116:117], v[118:119]
	global_store_dwordx4 v104, v[60:63], s[20:21]
	v_pk_add_f32 v[58:59], v[58:59], v[112:113]
	s_nop 0
	v_pk_add_f32 v[56:57], v[56:57], v[58:59]
	v_mov_b32_e32 v58, v165
	v_mov_b32_e32 v59, v165
	s_nop 0
	v_mov_b32_dpp v58, v56 quad_perm:[1,0,3,2] row_mask:0xf bank_mask:0xf
	v_mov_b32_dpp v59, v57 quad_perm:[1,0,3,2] row_mask:0xf bank_mask:0xf
	v_pk_add_f32 v[56:57], v[56:57], v[58:59]
	v_mov_b32_e32 v58, v56
	v_mov_b32_e32 v59, v57
	s_nop 1
	v_permlane16_swap_b32_e32 v56, v58
	v_permlane16_swap_b32_e32 v57, v59
	s_waitcnt lgkmcnt(0)
	v_pk_add_f32 v[56:57], v[56:57], v[58:59]
	v_mov_b32_e32 v58, v56
	v_mov_b32_e32 v59, v57
	s_nop 1
	v_permlane32_swap_b32_e32 v56, v58
	v_permlane32_swap_b32_e32 v57, v59
	s_and_saveexec_b64 s[68:69], s[16:17]
	s_cbranch_execz .LBB0_834
	s_waitcnt lgkmcnt(0)
	v_pk_add_f32 v[56:57], v[56:57], v[58:59]
	v_add_co_u32_e32 v58, vcc, 0x10000, v186
	s_nop 1
	v_addc_co_u32_e32 v59, vcc, 0, v187, vcc
	global_store_dwordx2 v[58:59], v[56:57], off
;     __device__ __forceinline__ void operator()(const f32x4 (&acc)[2][2][4][2], const Unit& u, int wr, int wc, int fr, int fq, const EpiCtx& X) const {
;     ...
;             for (int m = 0; m < 4; ++m) { const unsigned off = lo + (unsigned)((ai * HALF + m * 16) * 64) * 2u; raw[2 * m] = *(const u32x4*)(xb + off); raw[2 * m + 1] = *(const u32x4*)(xb + off + 128); }
; #pragma unroll
;             for (int m = 0; m < 4; ++m) {
;                 const int rl = ai * HALF + m * 16; const unsigned off = lo + (unsigned)(rl * 64) * 2u;
;                 const f32x4 o0a = acc[ai][0][m][0], o0b = acc[ai][0][m][1], o1a = acc[ai][1][m][0], o1b = acc[ai][1][m][1];
;                 const f32x4 ra_ = dpp_swap1(odd ? o0a : o1a), rb_ = dpp_swap1(odd ? o0b : o1b);
;                 const f32x4 pa[2] = {odd ? ra_ : o0a, odd ? o1a : ra_}, pb[2] = {odd ? rb_ : o0b, odd ? o1b : rb_};
; #pragma unroll
;                 for (int q = 0; q < 2; ++q) {
;                     const u32x4 w0 = raw[2 * m + q];
;                     const f32x4 r0 = (f32x4){bf_lo(w0.x), bf_hi(w0.x), bf_lo(w0.y), bf_hi(w0.y)}, r1 = (f32x4){bf_lo(w0.z), bf_hi(w0.z), bf_lo(w0.w), bf_hi(w0.w)};
;                     f32x4 y0, y1;
;                     if (RESN) { const f32x2 t = tbl[rl + q]; const float mu = t.x, ra = t.y * ALPHA; y0 = (r0 - mu) * ra * g0 + b0 + pa[q]; y1 = (r1 - mu) * ra * g1 + b1 + pb[q]; }
;                     else { y0 = r0 * ALPHA + pa[q]; y1 = r1 * ALPHA + pb[q]; }
;                     { const u32x4 w = pack8f(y0, y1); *(u32x4*)(xb + off + q * 128) = w;
;                         y0 = (f32x4){bf_lo(w.x), bf_hi(w.x), bf_lo(w.y), bf_hi(w.y)}; y1 = (f32x4){bf_lo(w.z), bf_hi(w.z), bf_lo(w.w), bf_hi(w.w)}; }
;                     float sa = ((y0[0] + y0[1]) + (y0[2] + y0[3])) + ((y1[0] + y1[1]) + (y1[2] + y1[3]));
;                     float sb = ((y0[0] * y0[0] + y0[1] * y0[1]) + (y0[2] * y0[2] + y0[3] * y0[3])) + ((y1[0] * y1[0] + y1[1] * y1[1]) + (y1[2] * y1[2] + y1[3] * y1[3]));
;                     sa += dpp_x1(sa);
;                     sb += dpp_x1(sb);
;                     sa += __shfl_xor(sa, 16); sa += __shfl_xor(sa, 32); sb += __shfl_xor(sb, 16); sb += __shfl_xor(sb, 32);
;                     if (fq == 0 && !odd) ps[(size_t)(rl + q) * 64] = (f32x2){sa, sb};
;                 }
.LBB0_834:
	s_or_b64 exec, exec, s[68:69]
	ds_read_b64 v[56:57], v201 offset:1032
	s_waitcnt lgkmcnt(1)
	v_lshlrev_b32_e32 v59, 16, v96
	v_and_b32_e32 v60, 0xffff0000, v96
	v_cndmask_b32_e64 v53, v53, v105, s[10:11]
	v_cndmask_b32_e64 v52, v52, v101, s[10:11]
	s_waitcnt lgkmcnt(0)
	v_mul_f32_e32 v58, 0x3fb504f3, v57
	v_sub_f32_e32 v61, v60, v56
	v_sub_f32_e32 v60, v59, v56
	v_pk_mul_f32 v[60:61], v[60:61], v[58:59] op_sel_hi:[1,0]
	v_lshlrev_b32_e32 v62, 16, v97
	v_and_b32_e32 v63, 0xffff0000, v97
	v_lshlrev_b32_e32 v96, 16, v98
	v_and_b32_e32 v97, 0xffff0000, v98
	v_lshlrev_b32_e32 v98, 16, v99
	v_and_b32_e32 v99, 0xffff0000, v99
	v_pk_fma_f32 v[60:61], v[76:77], v[60:61], v[184:185]
	v_sub_f32_e32 v63, v63, v56
	v_sub_f32_e32 v62, v62, v56
	v_pk_add_f32 v[52:53], v[52:53], v[60:61]
	v_sub_f32_e32 v61, v97, v56
	v_sub_f32_e32 v60, v96, v56
	v_sub_f32_e32 v57, v99, v56
	v_sub_f32_e32 v56, v98, v56
	v_pk_mul_f32 v[62:63], v[62:63], v[58:59] op_sel_hi:[1,0]
	v_pk_mul_f32 v[56:57], v[56:57], v[58:59] op_sel_hi:[1,0]
	v_pk_mul_f32 v[58:59], v[60:61], v[58:59] op_sel_hi:[1,0]
	v_cndmask_b32_e64 v55, v55, v106, s[10:11]
	v_cndmask_b32_e64 v54, v54, v103, s[10:11]
	v_cndmask_b32_e64 v49, v49, v109, s[10:11]
	v_cndmask_b32_e64 v48, v48, v107, s[10:11]
	v_cndmask_b32_e64 v51, v51, v110, s[10:11]
	v_cndmask_b32_e64 v50, v50, v108, s[10:11]
	v_pk_fma_f32 v[62:63], v[78:79], v[62:63], v[182:183]
	v_pk_fma_f32 v[58:59], v[72:73], v[58:59], v[180:181]
	v_pk_fma_f32 v[56:57], v[74:75], v[56:57], v[178:179]
	v_pk_add_f32 v[54:55], v[54:55], v[62:63]
	v_pk_add_f32 v[50:51], v[50:51], v[56:57]
	v_pk_add_f32 v[48:49], v[48:49], v[58:59]
	v_cvt_pk_bf16_f32 v52, v52, v53
	v_cvt_pk_bf16_f32 v53, v54, v55
	v_mov_b32_e32 v105, v165
	v_cvt_pk_bf16_f32 v54, v48, v49
	v_cvt_pk_bf16_f32 v55, v50, v51
	v_lshlrev_b32_e32 v48, 16, v52
	v_and_b32_e32 v50, 0xffff0000, v52
	v_lshlrev_b32_e32 v56, 16, v53
	v_and_b32_e32 v58, 0xffff0000, v53
	v_lshlrev_b32_e32 v60, 16, v54
	v_and_b32_e32 v62, 0xffff0000, v54
	v_lshlrev_b32_e32 v96, 16, v55
	v_and_b32_e32 v98, 0xffff0000, v55
	v_mul_f32_e32 v49, v48, v48
	v_mul_f32_e32 v51, v50, v50
	v_mul_f32_e32 v57, v56, v56
	v_mul_f32_e32 v59, v58, v58
	v_mul_f32_e32 v61, v60, v60
	v_mul_f32_e32 v63, v62, v62
	v_mul_f32_e32 v97, v96, v96
	v_mul_f32_e32 v99, v98, v98
	v_pk_add_f32 v[48:49], v[48:49], v[50:51]
	v_pk_add_f32 v[50:51], v[56:57], v[58:59]
	v_pk_add_f32 v[56:57], v[96:97], v[98:99]
	v_pk_add_f32 v[48:49], v[48:49], v[50:51]
	v_pk_add_f32 v[50:51], v[60:61], v[62:63]
	s_nop 0
	v_pk_add_f32 v[50:51], v[50:51], v[56:57]
	v_lshl_add_u64 v[56:57], s[20:21], 0, v[104:105]
	v_pk_add_f32 v[48:49], v[48:49], v[50:51]
	v_mov_b32_e32 v50, v165
	v_mov_b32_e32 v51, v165
	global_store_dwordx4 v[56:57], v[52:55], off offset:128
	v_mov_b32_dpp v50, v48 quad_perm:[1,0,3,2] row_mask:0xf bank_mask:0xf
	v_mov_b32_dpp v51, v49 quad_perm:[1,0,3,2] row_mask:0xf bank_mask:0xf
	v_pk_add_f32 v[48:49], v[48:49], v[50:51]
	v_mov_b32_e32 v50, v48
	v_mov_b32_e32 v51, v49
	s_nop 1
	v_permlane16_swap_b32_e32 v48, v50
	v_permlane16_swap_b32_e32 v49, v51
	s_waitcnt lgkmcnt(0)
	v_pk_add_f32 v[48:49], v[48:49], v[50:51]
	v_mov_b32_e32 v50, v48
	v_mov_b32_e32 v51, v49
	s_nop 1
	v_permlane32_swap_b32_e32 v48, v50
	v_permlane32_swap_b32_e32 v49, v51
	s_and_saveexec_b64 s[68:69], s[16:17]
	s_cbranch_execz .LBB0_836
	s_waitcnt lgkmcnt(0)
	v_pk_add_f32 v[48:49], v[48:49], v[50:51]
	v_add_co_u32_e32 v50, vcc, 0x10000, v186
	s_nop 1
	v_addc_co_u32_e32 v51, vcc, 0, v187, vcc
	global_store_dwordx2 v[50:51], v[48:49], off offset:512
.LBB0_836:
	s_or_b64 exec, exec, s[68:69]
	s_waitcnt lgkmcnt(0)
	v_cndmask_b32_e64 v50, v44, v36, s[10:11]
	v_mov_b32_e32 v48, 0
	v_cndmask_b32_e64 v49, v45, v37, s[10:11]
	s_waitcnt lgkmcnt(0)
	v_cndmask_b32_e64 v51, v46, v38, s[10:11]
	v_mov_b32_dpp v48, v50 quad_perm:[1,0,3,2] row_mask:0xf bank_mask:0xf
	v_mov_b32_e32 v50, 0
	v_cndmask_b32_e64 v52, v47, v39, s[10:11]
	v_cndmask_b32_e64 v54, v40, v32, s[10:11]
	v_mov_b32_dpp v50, v49 quad_perm:[1,0,3,2] row_mask:0xf bank_mask:0xf
	v_mov_b32_e32 v49, 0
	v_cndmask_b32_e64 v53, v41, v33, s[10:11]
	v_cndmask_b32_e64 v55, v42, v34, s[10:11]
	v_mov_b32_dpp v49, v51 quad_perm:[1,0,3,2] row_mask:0xf bank_mask:0xf
	v_mov_b32_e32 v51, 0
	v_cndmask_b32_e64 v56, v43, v35, s[10:11]
	v_lshlrev_b32_e32 v59, 16, v92
	v_mov_b32_dpp v51, v52 quad_perm:[1,0,3,2] row_mask:0xf bank_mask:0xf
	v_mov_b32_e32 v52, 0
	v_and_b32_e32 v60, 0xffff0000, v92
	v_cndmask_b32_e64 v45, v50, v45, s[10:11]
	v_mov_b32_dpp v52, v54 quad_perm:[1,0,3,2] row_mask:0xf bank_mask:0xf
	v_mov_b32_e32 v54, 0
	v_cndmask_b32_e64 v44, v48, v44, s[10:11]
	v_lshlrev_b32_e32 v62, 16, v93
	v_mov_b32_dpp v54, v53 quad_perm:[1,0,3,2] row_mask:0xf bank_mask:0xf
	v_mov_b32_e32 v53, 0
	v_and_b32_e32 v63, 0xffff0000, v93
	v_lshlrev_b32_e32 v92, 16, v94
	v_mov_b32_dpp v53, v55 quad_perm:[1,0,3,2] row_mask:0xf bank_mask:0xf
	v_mov_b32_e32 v55, 0
	v_and_b32_e32 v93, 0xffff0000, v94
	v_lshlrev_b32_e32 v94, 16, v95
	v_mov_b32_dpp v55, v56 quad_perm:[1,0,3,2] row_mask:0xf bank_mask:0xf
	ds_read_b64 v[56:57], v201 offset:1152
	v_and_b32_e32 v95, 0xffff0000, v95
	v_cndmask_b32_e64 v47, v51, v47, s[10:11]
	v_cndmask_b32_e64 v46, v49, v46, s[10:11]
	v_cndmask_b32_e64 v41, v54, v41, s[10:11]
	s_waitcnt lgkmcnt(0)
;     __device__ __forceinline__ void operator()(const f32x4 (&acc)[2][2][4][2], const Unit& u, int wr, int wc, int fr, int fq, const EpiCtx& X) const {
;     ...
;             for (int m = 0; m < 4; ++m) { const unsigned off = lo + (unsigned)((ai * HALF + m * 16) * 64) * 2u; raw[2 * m] = *(const u32x4*)(xb + off); raw[2 * m + 1] = *(const u32x4*)(xb + off + 128); }
; #pragma unroll
;             for (int m = 0; m < 4; ++m) {
;                 const int rl = ai * HALF + m * 16; const unsigned off = lo + (unsigned)(rl * 64) * 2u;
;                 const f32x4 o0a = acc[ai][0][m][0], o0b = acc[ai][0][m][1], o1a = acc[ai][1][m][0], o1b = acc[ai][1][m][1];
;                 const f32x4 ra_ = dpp_swap1(odd ? o0a : o1a), rb_ = dpp_swap1(odd ? o0b : o1b);
;                 const f32x4 pa[2] = {odd ? ra_ : o0a, odd ? o1a : ra_}, pb[2] = {odd ? rb_ : o0b, odd ? o1b : rb_};
; #pragma unroll
;                 for (int q = 0; q < 2; ++q) {
;                     const u32x4 w0 = raw[2 * m + q];
;                     const f32x4 r0 = (f32x4){bf_lo(w0.x), bf_hi(w0.x), bf_lo(w0.y), bf_hi(w0.y)}, r1 = (f32x4){bf_lo(w0.z), bf_hi(w0.z), bf_lo(w0.w), bf_hi(w0.w)};
;                     f32x4 y0, y1;
;                     if (RESN) { const f32x2 t = tbl[rl + q]; const float mu = t.x, ra = t.y * ALPHA; y0 = (r0 - mu) * ra * g0 + b0 + pa[q]; y1 = (r1 - mu) * ra * g1 + b1 + pb[q]; }
;                     else { y0 = r0 * ALPHA + pa[q]; y1 = r1 * ALPHA + pb[q]; }
;                     { const u32x4 w = pack8f(y0, y1); *(u32x4*)(xb + off + q * 128) = w;
;                         y0 = (f32x4){bf_lo(w.x), bf_hi(w.x), bf_lo(w.y), bf_hi(w.y)}; y1 = (f32x4){bf_lo(w.z), bf_hi(w.z), bf_lo(w.w), bf_hi(w.w)}; }
;                     float sa = ((y0[0] + y0[1]) + (y0[2] + y0[3])) + ((y1[0] + y1[1]) + (y1[2] + y1[3]));
;                     float sb = ((y0[0] * y0[0] + y0[1] * y0[1]) + (y0[2] * y0[2] + y0[3] * y0[3])) + ((y1[0] * y1[0] + y1[1] * y1[1]) + (y1[2] * y1[2] + y1[3] * y1[3]));
;                     sa += dpp_x1(sa);
;                     sb += dpp_x1(sb);
;                     sa += __shfl_xor(sa, 16); sa += __shfl_xor(sa, 32); sb += __shfl_xor(sb, 16); sb += __shfl_xor(sb, 32);
;                     if (fq == 0 && !odd) ps[(size_t)(rl + q) * 64] = (f32x2){sa, sb};
;                 }
	v_mul_f32_e32 v58, 0x3fb504f3, v57
	v_sub_f32_e32 v61, v60, v56
	v_sub_f32_e32 v60, v59, v56
	v_pk_mul_f32 v[60:61], v[60:61], v[58:59] op_sel_hi:[1,0]
	v_sub_f32_e32 v63, v63, v56
	v_pk_fma_f32 v[60:61], v[76:77], v[60:61], v[184:185]
	v_sub_f32_e32 v62, v62, v56
	v_pk_add_f32 v[44:45], v[44:45], v[60:61]
	v_sub_f32_e32 v61, v93, v56
	v_sub_f32_e32 v60, v92, v56
	v_sub_f32_e32 v57, v95, v56
	v_sub_f32_e32 v56, v94, v56
	v_pk_mul_f32 v[62:63], v[62:63], v[58:59] op_sel_hi:[1,0]
	v_pk_mul_f32 v[56:57], v[56:57], v[58:59] op_sel_hi:[1,0]
	v_pk_mul_f32 v[58:59], v[60:61], v[58:59] op_sel_hi:[1,0]
	v_cndmask_b32_e64 v40, v52, v40, s[10:11]
	v_cndmask_b32_e64 v43, v55, v43, s[10:11]
	v_cndmask_b32_e64 v42, v53, v42, s[10:11]
	v_pk_fma_f32 v[62:63], v[78:79], v[62:63], v[182:183]
	v_pk_fma_f32 v[58:59], v[72:73], v[58:59], v[180:181]
	v_pk_fma_f32 v[56:57], v[74:75], v[56:57], v[178:179]
	v_pk_add_f32 v[46:47], v[46:47], v[62:63]
	v_pk_add_f32 v[42:43], v[42:43], v[56:57]
	v_pk_add_f32 v[40:41], v[40:41], v[58:59]
	v_cvt_pk_bf16_f32 v56, v44, v45
	v_cvt_pk_bf16_f32 v57, v46, v47
	v_mov_b32_e32 v103, v165
	v_cvt_pk_bf16_f32 v58, v40, v41
	v_cvt_pk_bf16_f32 v59, v42, v43
	v_lshlrev_b32_e32 v40, 16, v56
	v_and_b32_e32 v42, 0xffff0000, v56
	v_lshlrev_b32_e32 v44, 16, v57
	v_and_b32_e32 v46, 0xffff0000, v57
	v_lshlrev_b32_e32 v60, 16, v58
	v_and_b32_e32 v62, 0xffff0000, v58
	v_lshlrev_b32_e32 v92, 16, v59
	v_and_b32_e32 v94, 0xffff0000, v59
	v_mul_f32_e32 v41, v40, v40
	v_mul_f32_e32 v43, v42, v42
	v_mul_f32_e32 v45, v44, v44
	v_mul_f32_e32 v47, v46, v46
	v_mul_f32_e32 v61, v60, v60
	v_mul_f32_e32 v63, v62, v62
	v_mul_f32_e32 v93, v92, v92
	v_mul_f32_e32 v95, v94, v94
	v_pk_add_f32 v[40:41], v[40:41], v[42:43]
	v_pk_add_f32 v[42:43], v[44:45], v[46:47]
	v_pk_add_f32 v[44:45], v[92:93], v[94:95]
	v_pk_add_f32 v[40:41], v[40:41], v[42:43]
	v_pk_add_f32 v[42:43], v[60:61], v[62:63]
	s_nop 0
	v_pk_add_f32 v[42:43], v[42:43], v[44:45]
	s_nop 0
	v_pk_add_f32 v[40:41], v[40:41], v[42:43]
	v_mov_b32_e32 v42, v165
	v_mov_b32_e32 v43, v165
	s_nop 0
	v_mov_b32_dpp v42, v40 quad_perm:[1,0,3,2] row_mask:0xf bank_mask:0xf
	v_mov_b32_dpp v43, v41 quad_perm:[1,0,3,2] row_mask:0xf bank_mask:0xf
	v_pk_add_f32 v[40:41], v[40:41], v[42:43]
	v_mov_b32_e32 v42, v40
	v_mov_b32_e32 v43, v41
	s_nop 1
	v_permlane16_swap_b32_e32 v40, v42
	v_permlane16_swap_b32_e32 v41, v43
	s_waitcnt lgkmcnt(0)
	v_pk_add_f32 v[42:43], v[40:41], v[42:43]
	v_mov_b32_e32 v44, v42
	v_mov_b32_e32 v45, v43
	s_nop 1
	v_permlane32_swap_b32_e32 v42, v44
	v_permlane32_swap_b32_e32 v43, v45
	v_lshl_add_u64 v[40:41], s[20:21], 0, v[102:103]
	global_store_dwordx4 v[40:41], v[56:59], off
	s_and_saveexec_b64 s[68:69], s[16:17]
	s_cbranch_execz .LBB0_838
	s_waitcnt lgkmcnt(0)
	v_pk_add_f32 v[42:43], v[42:43], v[44:45]
	v_add_co_u32_e32 v44, vcc, 0x12000, v186
	s_nop 1
	v_addc_co_u32_e32 v45, vcc, 0, v187, vcc
	global_store_dwordx2 v[44:45], v[42:43], off
.LBB0_838:
	s_or_b64 exec, exec, s[68:69]
	ds_read_b64 v[42:43], v201 offset:1160
	s_waitcnt lgkmcnt(1)
	v_lshlrev_b32_e32 v45, 16, v88
	v_and_b32_e32 v46, 0xffff0000, v88
	v_cndmask_b32_e64 v37, v37, v50, s[10:11]
	v_cndmask_b32_e64 v36, v36, v48, s[10:11]
	s_waitcnt lgkmcnt(0)
	v_mul_f32_e32 v44, 0x3fb504f3, v43
	v_sub_f32_e32 v47, v46, v42
	v_sub_f32_e32 v46, v45, v42
	v_pk_mul_f32 v[46:47], v[46:47], v[44:45] op_sel_hi:[1,0]
	v_cndmask_b32_e64 v39, v39, v51, s[10:11]
	v_cndmask_b32_e64 v38, v38, v49, s[10:11]
	v_cndmask_b32_e64 v32, v32, v52, s[10:11]
	v_cndmask_b32_e64 v34, v34, v53, s[10:11]
	v_lshlrev_b32_e32 v48, 16, v89
	v_and_b32_e32 v49, 0xffff0000, v89
	v_lshlrev_b32_e32 v50, 16, v90
	v_and_b32_e32 v51, 0xffff0000, v90
	v_lshlrev_b32_e32 v52, 16, v91
	v_and_b32_e32 v53, 0xffff0000, v91
	v_pk_fma_f32 v[46:47], v[76:77], v[46:47], v[184:185]
	v_sub_f32_e32 v49, v49, v42
	v_sub_f32_e32 v48, v48, v42
	v_pk_add_f32 v[36:37], v[36:37], v[46:47]
	v_sub_f32_e32 v47, v51, v42
	v_sub_f32_e32 v46, v50, v42
	v_sub_f32_e32 v43, v53, v42
	v_sub_f32_e32 v42, v52, v42
	v_pk_mul_f32 v[48:49], v[48:49], v[44:45] op_sel_hi:[1,0]
	v_pk_mul_f32 v[42:43], v[42:43], v[44:45] op_sel_hi:[1,0]
	v_pk_mul_f32 v[44:45], v[46:47], v[44:45] op_sel_hi:[1,0]
	v_cndmask_b32_e64 v33, v33, v54, s[10:11]
	v_cndmask_b32_e64 v35, v35, v55, s[10:11]
	v_pk_fma_f32 v[48:49], v[78:79], v[48:49], v[182:183]
	v_pk_fma_f32 v[44:45], v[72:73], v[44:45], v[180:181]
	v_pk_fma_f32 v[42:43], v[74:75], v[42:43], v[178:179]
	v_pk_add_f32 v[38:39], v[38:39], v[48:49]
	v_pk_add_f32 v[34:35], v[34:35], v[42:43]
	v_pk_add_f32 v[32:33], v[32:33], v[44:45]
	v_cvt_pk_bf16_f32 v36, v36, v37
	v_cvt_pk_bf16_f32 v37, v38, v39
	s_nop 0
	v_cvt_pk_bf16_f32 v38, v32, v33
	v_cvt_pk_bf16_f32 v39, v34, v35
	v_lshlrev_b32_e32 v32, 16, v36
	v_and_b32_e32 v34, 0xffff0000, v36
	v_lshlrev_b32_e32 v42, 16, v37
	v_and_b32_e32 v44, 0xffff0000, v37
	v_lshlrev_b32_e32 v46, 16, v38
	v_and_b32_e32 v48, 0xffff0000, v38
	v_lshlrev_b32_e32 v50, 16, v39
	v_and_b32_e32 v52, 0xffff0000, v39
	v_mul_f32_e32 v33, v32, v32
	v_mul_f32_e32 v35, v34, v34
	v_mul_f32_e32 v43, v42, v42
	v_mul_f32_e32 v45, v44, v44
	v_mul_f32_e32 v47, v46, v46
	v_mul_f32_e32 v49, v48, v48
	v_mul_f32_e32 v51, v50, v50
	v_mul_f32_e32 v53, v52, v52
	v_pk_add_f32 v[32:33], v[32:33], v[34:35]
	v_pk_add_f32 v[34:35], v[42:43], v[44:45]
	v_pk_add_f32 v[42:43], v[50:51], v[52:53]
	v_pk_add_f32 v[32:33], v[32:33], v[34:35]
	v_pk_add_f32 v[34:35], v[46:47], v[48:49]
	global_store_dwordx4 v[40:41], v[36:39], off offset:128
	v_pk_add_f32 v[34:35], v[34:35], v[42:43]
	s_nop 0
	v_pk_add_f32 v[32:33], v[32:33], v[34:35]
	v_mov_b32_e32 v34, v165
	v_mov_b32_e32 v35, v165
	s_nop 0
	v_mov_b32_dpp v34, v32 quad_perm:[1,0,3,2] row_mask:0xf bank_mask:0xf
	v_mov_b32_dpp v35, v33 quad_perm:[1,0,3,2] row_mask:0xf bank_mask:0xf
	v_pk_add_f32 v[32:33], v[32:33], v[34:35]
	v_mov_b32_e32 v34, v32
	v_mov_b32_e32 v35, v33
	s_nop 1
	v_permlane16_swap_b32_e32 v32, v34
	v_permlane16_swap_b32_e32 v33, v35
	s_waitcnt lgkmcnt(0)
	v_pk_add_f32 v[32:33], v[32:33], v[34:35]
	v_mov_b32_e32 v34, v32
	v_mov_b32_e32 v35, v33
	s_nop 1
	v_permlane32_swap_b32_e32 v32, v34
	v_permlane32_swap_b32_e32 v33, v35
	s_and_saveexec_b64 s[68:69], s[16:17]
	s_cbranch_execz .LBB0_840
	s_waitcnt lgkmcnt(0)
	v_pk_add_f32 v[32:33], v[32:33], v[34:35]
	v_add_co_u32_e32 v34, vcc, 0x12000, v186
	s_nop 1
	v_addc_co_u32_e32 v35, vcc, 0, v187, vcc
	global_store_dwordx2 v[34:35], v[32:33], off offset:512
;     __device__ __forceinline__ void operator()(const f32x4 (&acc)[2][2][4][2], const Unit& u, int wr, int wc, int fr, int fq, const EpiCtx& X) const {
;     ...
;             for (int m = 0; m < 4; ++m) { const unsigned off = lo + (unsigned)((ai * HALF + m * 16) * 64) * 2u; raw[2 * m] = *(const u32x4*)(xb + off); raw[2 * m + 1] = *(const u32x4*)(xb + off + 128); }
; #pragma unroll
;             for (int m = 0; m < 4; ++m) {
;                 const int rl = ai * HALF + m * 16; const unsigned off = lo + (unsigned)(rl * 64) * 2u;
;                 const f32x4 o0a = acc[ai][0][m][0], o0b = acc[ai][0][m][1], o1a = acc[ai][1][m][0], o1b = acc[ai][1][m][1];
;                 const f32x4 ra_ = dpp_swap1(odd ? o0a : o1a), rb_ = dpp_swap1(odd ? o0b : o1b);
;                 const f32x4 pa[2] = {odd ? ra_ : o0a, odd ? o1a : ra_}, pb[2] = {odd ? rb_ : o0b, odd ? o1b : rb_};
; #pragma unroll
;                 for (int q = 0; q < 2; ++q) {
;                     const u32x4 w0 = raw[2 * m + q];
;                     const f32x4 r0 = (f32x4){bf_lo(w0.x), bf_hi(w0.x), bf_lo(w0.y), bf_hi(w0.y)}, r1 = (f32x4){bf_lo(w0.z), bf_hi(w0.z), bf_lo(w0.w), bf_hi(w0.w)};
;                     f32x4 y0, y1;
;                     if (RESN) { const f32x2 t = tbl[rl + q]; const float mu = t.x, ra = t.y * ALPHA; y0 = (r0 - mu) * ra * g0 + b0 + pa[q]; y1 = (r1 - mu) * ra * g1 + b1 + pb[q]; }
;                     else { y0 = r0 * ALPHA + pa[q]; y1 = r1 * ALPHA + pb[q]; }
;                     { const u32x4 w = pack8f(y0, y1); *(u32x4*)(xb + off + q * 128) = w;
;                         y0 = (f32x4){bf_lo(w.x), bf_hi(w.x), bf_lo(w.y), bf_hi(w.y)}; y1 = (f32x4){bf_lo(w.z), bf_hi(w.z), bf_lo(w.w), bf_hi(w.w)}; }
;                     float sa = ((y0[0] + y0[1]) + (y0[2] + y0[3])) + ((y1[0] + y1[1]) + (y1[2] + y1[3]));
;                     float sb = ((y0[0] * y0[0] + y0[1] * y0[1]) + (y0[2] * y0[2] + y0[3] * y0[3])) + ((y1[0] * y1[0] + y1[1] * y1[1]) + (y1[2] * y1[2] + y1[3] * y1[3]));
;                     sa += dpp_x1(sa);
;                     sb += dpp_x1(sb);
;                     sa += __shfl_xor(sa, 16); sa += __shfl_xor(sa, 32); sb += __shfl_xor(sb, 16); sb += __shfl_xor(sb, 32);
;                     if (fq == 0 && !odd) ps[(size_t)(rl + q) * 64] = (f32x2){sa, sb};
;                 }
.LBB0_840:
	s_or_b64 exec, exec, s[68:69]
	s_waitcnt lgkmcnt(0)
	v_cndmask_b32_e64 v34, v28, v20, s[10:11]
	v_mov_b32_e32 v32, 0
	v_cndmask_b32_e64 v33, v29, v21, s[10:11]
	s_waitcnt lgkmcnt(0)
	v_cndmask_b32_e64 v35, v30, v22, s[10:11]
	v_mov_b32_dpp v32, v34 quad_perm:[1,0,3,2] row_mask:0xf bank_mask:0xf
	v_mov_b32_e32 v34, 0
	v_cndmask_b32_e64 v36, v31, v23, s[10:11]
	v_cndmask_b32_e64 v38, v24, v16, s[10:11]
	v_mov_b32_dpp v34, v33 quad_perm:[1,0,3,2] row_mask:0xf bank_mask:0xf
	v_mov_b32_e32 v33, 0
	v_cndmask_b32_e64 v37, v25, v17, s[10:11]
	v_cndmask_b32_e64 v39, v26, v18, s[10:11]
	v_mov_b32_dpp v33, v35 quad_perm:[1,0,3,2] row_mask:0xf bank_mask:0xf
	v_mov_b32_e32 v35, 0
	v_cndmask_b32_e64 v40, v27, v19, s[10:11]
	s_waitcnt vmcnt(11)
	v_lshlrev_b32_e32 v43, 16, v84
	v_mov_b32_dpp v35, v36 quad_perm:[1,0,3,2] row_mask:0xf bank_mask:0xf
	v_mov_b32_e32 v36, 0
	v_and_b32_e32 v44, 0xffff0000, v84
	v_cndmask_b32_e64 v29, v34, v29, s[10:11]
	v_mov_b32_dpp v36, v38 quad_perm:[1,0,3,2] row_mask:0xf bank_mask:0xf
	v_mov_b32_e32 v38, 0
	v_cndmask_b32_e64 v28, v32, v28, s[10:11]
	v_lshlrev_b32_e32 v46, 16, v85
	v_mov_b32_dpp v38, v37 quad_perm:[1,0,3,2] row_mask:0xf bank_mask:0xf
	v_mov_b32_e32 v37, 0
	v_and_b32_e32 v47, 0xffff0000, v85
	v_lshlrev_b32_e32 v48, 16, v86
	v_mov_b32_dpp v37, v39 quad_perm:[1,0,3,2] row_mask:0xf bank_mask:0xf
	v_mov_b32_e32 v39, 0
	v_and_b32_e32 v49, 0xffff0000, v86
	v_lshlrev_b32_e32 v50, 16, v87
	v_mov_b32_dpp v39, v40 quad_perm:[1,0,3,2] row_mask:0xf bank_mask:0xf
	ds_read_b64 v[40:41], v201 offset:1280
	v_and_b32_e32 v51, 0xffff0000, v87
	v_cndmask_b32_e64 v31, v35, v31, s[10:11]
	v_cndmask_b32_e64 v30, v33, v30, s[10:11]
	v_cndmask_b32_e64 v25, v38, v25, s[10:11]
	s_waitcnt lgkmcnt(0)
	v_mul_f32_e32 v42, 0x3fb504f3, v41
	v_sub_f32_e32 v45, v44, v40
	v_sub_f32_e32 v44, v43, v40
	v_pk_mul_f32 v[44:45], v[44:45], v[42:43] op_sel_hi:[1,0]
	v_sub_f32_e32 v47, v47, v40
	v_pk_fma_f32 v[44:45], v[76:77], v[44:45], v[184:185]
	v_sub_f32_e32 v46, v46, v40
	v_pk_add_f32 v[28:29], v[28:29], v[44:45]
	v_sub_f32_e32 v45, v49, v40
	v_sub_f32_e32 v44, v48, v40
	v_sub_f32_e32 v41, v51, v40
	v_sub_f32_e32 v40, v50, v40
	v_pk_mul_f32 v[46:47], v[46:47], v[42:43] op_sel_hi:[1,0]
	v_pk_mul_f32 v[40:41], v[40:41], v[42:43] op_sel_hi:[1,0]
	v_pk_mul_f32 v[42:43], v[44:45], v[42:43] op_sel_hi:[1,0]
	v_cndmask_b32_e64 v24, v36, v24, s[10:11]
	v_cndmask_b32_e64 v27, v39, v27, s[10:11]
	v_cndmask_b32_e64 v26, v37, v26, s[10:11]
	v_pk_fma_f32 v[46:47], v[78:79], v[46:47], v[182:183]
	v_pk_fma_f32 v[42:43], v[72:73], v[42:43], v[180:181]
	v_pk_fma_f32 v[40:41], v[74:75], v[40:41], v[178:179]
	v_pk_add_f32 v[30:31], v[30:31], v[46:47]
	v_pk_add_f32 v[26:27], v[26:27], v[40:41]
	v_pk_add_f32 v[24:25], v[24:25], v[42:43]
	v_cvt_pk_bf16_f32 v40, v28, v29
	v_cvt_pk_bf16_f32 v41, v30, v31
	v_mov_b32_e32 v101, v165
	v_cvt_pk_bf16_f32 v42, v24, v25
	v_cvt_pk_bf16_f32 v43, v26, v27
	v_lshlrev_b32_e32 v24, 16, v40
	v_and_b32_e32 v26, 0xffff0000, v40
	v_lshlrev_b32_e32 v28, 16, v41
	v_and_b32_e32 v30, 0xffff0000, v41
	v_lshlrev_b32_e32 v44, 16, v42
	v_and_b32_e32 v46, 0xffff0000, v42
	v_lshlrev_b32_e32 v48, 16, v43
	v_and_b32_e32 v50, 0xffff0000, v43
	v_mul_f32_e32 v25, v24, v24
	v_mul_f32_e32 v27, v26, v26
	v_mul_f32_e32 v29, v28, v28
	v_mul_f32_e32 v31, v30, v30
	v_mul_f32_e32 v45, v44, v44
	v_mul_f32_e32 v47, v46, v46
	v_mul_f32_e32 v49, v48, v48
	v_mul_f32_e32 v51, v50, v50
	v_pk_add_f32 v[24:25], v[24:25], v[26:27]
	v_pk_add_f32 v[26:27], v[28:29], v[30:31]
	v_pk_add_f32 v[28:29], v[48:49], v[50:51]
	v_pk_add_f32 v[24:25], v[24:25], v[26:27]
	v_pk_add_f32 v[26:27], v[44:45], v[46:47]
	s_nop 0
	v_pk_add_f32 v[26:27], v[26:27], v[28:29]
	s_nop 0
	v_pk_add_f32 v[24:25], v[24:25], v[26:27]
	v_mov_b32_e32 v26, v165
	v_mov_b32_e32 v27, v165
	s_nop 0
	v_mov_b32_dpp v26, v24 quad_perm:[1,0,3,2] row_mask:0xf bank_mask:0xf
	v_mov_b32_dpp v27, v25 quad_perm:[1,0,3,2] row_mask:0xf bank_mask:0xf
	v_pk_add_f32 v[24:25], v[24:25], v[26:27]
	v_mov_b32_e32 v26, v24
	v_mov_b32_e32 v27, v25
	s_nop 1
	v_permlane16_swap_b32_e32 v24, v26
	v_permlane16_swap_b32_e32 v25, v27
	s_waitcnt lgkmcnt(0)
	v_pk_add_f32 v[26:27], v[24:25], v[26:27]
	v_mov_b32_e32 v28, v26
	v_mov_b32_e32 v29, v27
	s_nop 1
	v_permlane32_swap_b32_e32 v26, v28
	v_permlane32_swap_b32_e32 v27, v29
	v_lshl_add_u64 v[24:25], s[20:21], 0, v[100:101]
	global_store_dwordx4 v[24:25], v[40:43], off
	s_and_saveexec_b64 s[68:69], s[16:17]
	s_cbranch_execz .LBB0_842
	s_waitcnt lgkmcnt(0)
	v_pk_add_f32 v[26:27], v[26:27], v[28:29]
	v_add_co_u32_e32 v28, vcc, 0x14000, v186
	s_nop 1
	v_addc_co_u32_e32 v29, vcc, 0, v187, vcc
	global_store_dwordx2 v[28:29], v[26:27], off
;     __device__ __forceinline__ void operator()(const f32x4 (&acc)[2][2][4][2], const Unit& u, int wr, int wc, int fr, int fq, const EpiCtx& X) const {
;     ...
;             for (int m = 0; m < 4; ++m) { const unsigned off = lo + (unsigned)((ai * HALF + m * 16) * 64) * 2u; raw[2 * m] = *(const u32x4*)(xb + off); raw[2 * m + 1] = *(const u32x4*)(xb + off + 128); }
; #pragma unroll
;             for (int m = 0; m < 4; ++m) {
;                 const int rl = ai * HALF + m * 16; const unsigned off = lo + (unsigned)(rl * 64) * 2u;
;                 const f32x4 o0a = acc[ai][0][m][0], o0b = acc[ai][0][m][1], o1a = acc[ai][1][m][0], o1b = acc[ai][1][m][1];
;                 const f32x4 ra_ = dpp_swap1(odd ? o0a : o1a), rb_ = dpp_swap1(odd ? o0b : o1b);
;                 const f32x4 pa[2] = {odd ? ra_ : o0a, odd ? o1a : ra_}, pb[2] = {odd ? rb_ : o0b, odd ? o1b : rb_};
; #pragma unroll
;                 for (int q = 0; q < 2; ++q) {
;                     const u32x4 w0 = raw[2 * m + q];
;                     const f32x4 r0 = (f32x4){bf_lo(w0.x), bf_hi(w0.x), bf_lo(w0.y), bf_hi(w0.y)}, r1 = (f32x4){bf_lo(w0.z), bf_hi(w0.z), bf_lo(w0.w), bf_hi(w0.w)};
;                     f32x4 y0, y1;
;                     if (RESN) { const f32x2 t = tbl[rl + q]; const float mu = t.x, ra = t.y * ALPHA; y0 = (r0 - mu) * ra * g0 + b0 + pa[q]; y1 = (r1 - mu) * ra * g1 + b1 + pb[q]; }
;                     else { y0 = r0 * ALPHA + pa[q]; y1 = r1 * ALPHA + pb[q]; }
;                     { const u32x4 w = pack8f(y0, y1); *(u32x4*)(xb + off + q * 128) = w;
;                         y0 = (f32x4){bf_lo(w.x), bf_hi(w.x), bf_lo(w.y), bf_hi(w.y)}; y1 = (f32x4){bf_lo(w.z), bf_hi(w.z), bf_lo(w.w), bf_hi(w.w)}; }
;                     float sa = ((y0[0] + y0[1]) + (y0[2] + y0[3])) + ((y1[0] + y1[1]) + (y1[2] + y1[3]));
;                     float sb = ((y0[0] * y0[0] + y0[1] * y0[1]) + (y0[2] * y0[2] + y0[3] * y0[3])) + ((y1[0] * y1[0] + y1[1] * y1[1]) + (y1[2] * y1[2] + y1[3] * y1[3]));
;                     sa += dpp_x1(sa);
;                     sb += dpp_x1(sb);
;                     sa += __shfl_xor(sa, 16); sa += __shfl_xor(sa, 32); sb += __shfl_xor(sb, 16); sb += __shfl_xor(sb, 32);
;                     if (fq == 0 && !odd) ps[(size_t)(rl + q) * 64] = (f32x2){sa, sb};
;                 }
.LBB0_842:
	s_or_b64 exec, exec, s[68:69]
	ds_read_b64 v[26:27], v201 offset:1288
	s_waitcnt vmcnt(12) lgkmcnt(1)
	v_lshlrev_b32_e32 v29, 16, v80
	v_and_b32_e32 v30, 0xffff0000, v80
	v_cndmask_b32_e64 v21, v21, v34, s[10:11]
	v_cndmask_b32_e64 v20, v20, v32, s[10:11]
	s_waitcnt lgkmcnt(0)
	v_mul_f32_e32 v28, 0x3fb504f3, v27
	v_sub_f32_e32 v31, v30, v26
	v_sub_f32_e32 v30, v29, v26
	v_pk_mul_f32 v[30:31], v[30:31], v[28:29] op_sel_hi:[1,0]
	v_cndmask_b32_e64 v23, v23, v35, s[10:11]
	v_cndmask_b32_e64 v22, v22, v33, s[10:11]
	v_cndmask_b32_e64 v16, v16, v36, s[10:11]
	v_cndmask_b32_e64 v18, v18, v37, s[10:11]
	v_lshlrev_b32_e32 v32, 16, v81
	v_and_b32_e32 v33, 0xffff0000, v81
	v_lshlrev_b32_e32 v34, 16, v82
	v_and_b32_e32 v35, 0xffff0000, v82
	v_lshlrev_b32_e32 v36, 16, v83
	v_and_b32_e32 v37, 0xffff0000, v83
	v_pk_fma_f32 v[30:31], v[76:77], v[30:31], v[184:185]
	v_sub_f32_e32 v33, v33, v26
	v_sub_f32_e32 v32, v32, v26
	v_pk_add_f32 v[20:21], v[20:21], v[30:31]
	v_sub_f32_e32 v31, v35, v26
	v_sub_f32_e32 v30, v34, v26
	v_sub_f32_e32 v27, v37, v26
	v_sub_f32_e32 v26, v36, v26
	v_pk_mul_f32 v[32:33], v[32:33], v[28:29] op_sel_hi:[1,0]
	v_pk_mul_f32 v[26:27], v[26:27], v[28:29] op_sel_hi:[1,0]
	v_pk_mul_f32 v[28:29], v[30:31], v[28:29] op_sel_hi:[1,0]
	v_cndmask_b32_e64 v17, v17, v38, s[10:11]
	v_cndmask_b32_e64 v19, v19, v39, s[10:11]
	v_pk_fma_f32 v[32:33], v[78:79], v[32:33], v[182:183]
	v_pk_fma_f32 v[28:29], v[72:73], v[28:29], v[180:181]
	v_pk_fma_f32 v[26:27], v[74:75], v[26:27], v[178:179]
	v_pk_add_f32 v[22:23], v[22:23], v[32:33]
	v_pk_add_f32 v[18:19], v[18:19], v[26:27]
	v_pk_add_f32 v[16:17], v[16:17], v[28:29]
	v_cvt_pk_bf16_f32 v20, v20, v21
	v_cvt_pk_bf16_f32 v21, v22, v23
	s_nop 0
	v_cvt_pk_bf16_f32 v22, v16, v17
	v_cvt_pk_bf16_f32 v23, v18, v19
	v_lshlrev_b32_e32 v16, 16, v20
	v_and_b32_e32 v18, 0xffff0000, v20
	v_lshlrev_b32_e32 v26, 16, v21
	v_and_b32_e32 v28, 0xffff0000, v21
	v_lshlrev_b32_e32 v30, 16, v22
	v_and_b32_e32 v32, 0xffff0000, v22
	v_lshlrev_b32_e32 v34, 16, v23
	v_and_b32_e32 v36, 0xffff0000, v23
	v_mul_f32_e32 v17, v16, v16
	v_mul_f32_e32 v19, v18, v18
	v_mul_f32_e32 v27, v26, v26
	v_mul_f32_e32 v29, v28, v28
	v_mul_f32_e32 v31, v30, v30
	v_mul_f32_e32 v33, v32, v32
	v_mul_f32_e32 v35, v34, v34
	v_mul_f32_e32 v37, v36, v36
	v_pk_add_f32 v[16:17], v[16:17], v[18:19]
	v_pk_add_f32 v[18:19], v[26:27], v[28:29]
	v_pk_add_f32 v[26:27], v[34:35], v[36:37]
	v_pk_add_f32 v[16:17], v[16:17], v[18:19]
	v_pk_add_f32 v[18:19], v[30:31], v[32:33]
	global_store_dwordx4 v[24:25], v[20:23], off offset:128
	v_pk_add_f32 v[18:19], v[18:19], v[26:27]
	s_nop 0
	v_pk_add_f32 v[16:17], v[16:17], v[18:19]
	v_mov_b32_e32 v18, v165
	v_mov_b32_e32 v19, v165
	s_nop 0
	v_mov_b32_dpp v18, v16 quad_perm:[1,0,3,2] row_mask:0xf bank_mask:0xf
	v_mov_b32_dpp v19, v17 quad_perm:[1,0,3,2] row_mask:0xf bank_mask:0xf
	v_pk_add_f32 v[16:17], v[16:17], v[18:19]
	v_mov_b32_e32 v18, v16
	v_mov_b32_e32 v19, v17
	s_nop 1
	v_permlane16_swap_b32_e32 v16, v18
	v_permlane16_swap_b32_e32 v17, v19
	s_waitcnt lgkmcnt(0)
	v_pk_add_f32 v[16:17], v[16:17], v[18:19]
	v_mov_b32_e32 v18, v16
	v_mov_b32_e32 v19, v17
	s_nop 1
	v_permlane32_swap_b32_e32 v16, v18
	v_permlane32_swap_b32_e32 v17, v19
	s_and_saveexec_b64 s[68:69], s[16:17]
	s_cbranch_execz .LBB0_844
	s_waitcnt lgkmcnt(0)
	v_pk_add_f32 v[16:17], v[16:17], v[18:19]
	v_add_co_u32_e32 v18, vcc, 0x14000, v186
	s_nop 1
	v_addc_co_u32_e32 v19, vcc, 0, v187, vcc
	global_store_dwordx2 v[18:19], v[16:17], off offset:512
.LBB0_844:
	s_or_b64 exec, exec, s[68:69]
	s_waitcnt lgkmcnt(0)
	v_cndmask_b32_e64 v18, v12, v4, s[10:11]
	v_mov_b32_e32 v16, 0
	v_cndmask_b32_e64 v17, v13, v5, s[10:11]
	s_waitcnt lgkmcnt(0)
	v_cndmask_b32_e64 v19, v14, v6, s[10:11]
	v_mov_b32_dpp v16, v18 quad_perm:[1,0,3,2] row_mask:0xf bank_mask:0xf
	v_mov_b32_e32 v18, 0
	v_cndmask_b32_e64 v20, v15, v7, s[10:11]
	v_cndmask_b32_e64 v22, v8, v0, s[10:11]
	v_mov_b32_dpp v18, v17 quad_perm:[1,0,3,2] row_mask:0xf bank_mask:0xf
	v_mov_b32_e32 v17, 0
	v_cndmask_b32_e64 v21, v9, v1, s[10:11]
	v_cndmask_b32_e64 v23, v10, v2, s[10:11]
	v_mov_b32_dpp v17, v19 quad_perm:[1,0,3,2] row_mask:0xf bank_mask:0xf
	v_mov_b32_e32 v19, 0
	v_cndmask_b32_e64 v24, v11, v3, s[10:11]
	s_waitcnt vmcnt(13)
	v_lshlrev_b32_e32 v27, 16, v68
	v_mov_b32_dpp v19, v20 quad_perm:[1,0,3,2] row_mask:0xf bank_mask:0xf
	v_mov_b32_e32 v20, 0
	v_and_b32_e32 v28, 0xffff0000, v68
	v_cndmask_b32_e64 v13, v18, v13, s[10:11]
	v_mov_b32_dpp v20, v22 quad_perm:[1,0,3,2] row_mask:0xf bank_mask:0xf
	v_mov_b32_e32 v22, 0
	v_cndmask_b32_e64 v12, v16, v12, s[10:11]
	v_lshlrev_b32_e32 v30, 16, v69
	v_mov_b32_dpp v22, v21 quad_perm:[1,0,3,2] row_mask:0xf bank_mask:0xf
	v_mov_b32_e32 v21, 0
	v_and_b32_e32 v31, 0xffff0000, v69
	v_lshlrev_b32_e32 v32, 16, v70
	v_mov_b32_dpp v21, v23 quad_perm:[1,0,3,2] row_mask:0xf bank_mask:0xf
	v_mov_b32_e32 v23, 0
	v_and_b32_e32 v33, 0xffff0000, v70
	v_lshlrev_b32_e32 v34, 16, v71
	v_mov_b32_dpp v23, v24 quad_perm:[1,0,3,2] row_mask:0xf bank_mask:0xf
	ds_read_b64 v[24:25], v201 offset:1408
	v_and_b32_e32 v35, 0xffff0000, v71
	v_cndmask_b32_e64 v15, v19, v15, s[10:11]
	v_cndmask_b32_e64 v14, v17, v14, s[10:11]
	v_cndmask_b32_e64 v9, v22, v9, s[10:11]
	s_waitcnt lgkmcnt(0)
;     __device__ __forceinline__ void operator()(const f32x4 (&acc)[2][2][4][2], const Unit& u, int wr, int wc, int fr, int fq, const EpiCtx& X) const {
;     ...
;             for (int m = 0; m < 4; ++m) { const unsigned off = lo + (unsigned)((ai * HALF + m * 16) * 64) * 2u; raw[2 * m] = *(const u32x4*)(xb + off); raw[2 * m + 1] = *(const u32x4*)(xb + off + 128); }
; #pragma unroll
;             for (int m = 0; m < 4; ++m) {
;                 const int rl = ai * HALF + m * 16; const unsigned off = lo + (unsigned)(rl * 64) * 2u;
;                 const f32x4 o0a = acc[ai][0][m][0], o0b = acc[ai][0][m][1], o1a = acc[ai][1][m][0], o1b = acc[ai][1][m][1];
;                 const f32x4 ra_ = dpp_swap1(odd ? o0a : o1a), rb_ = dpp_swap1(odd ? o0b : o1b);
;                 const f32x4 pa[2] = {odd ? ra_ : o0a, odd ? o1a : ra_}, pb[2] = {odd ? rb_ : o0b, odd ? o1b : rb_};
; #pragma unroll
;                 for (int q = 0; q < 2; ++q) {
;                     const u32x4 w0 = raw[2 * m + q];
;                     const f32x4 r0 = (f32x4){bf_lo(w0.x), bf_hi(w0.x), bf_lo(w0.y), bf_hi(w0.y)}, r1 = (f32x4){bf_lo(w0.z), bf_hi(w0.z), bf_lo(w0.w), bf_hi(w0.w)};
;                     f32x4 y0, y1;
;                     if (RESN) { const f32x2 t = tbl[rl + q]; const float mu = t.x, ra = t.y * ALPHA; y0 = (r0 - mu) * ra * g0 + b0 + pa[q]; y1 = (r1 - mu) * ra * g1 + b1 + pb[q]; }
;                     else { y0 = r0 * ALPHA + pa[q]; y1 = r1 * ALPHA + pb[q]; }
;                     { const u32x4 w = pack8f(y0, y1); *(u32x4*)(xb + off + q * 128) = w;
;                         y0 = (f32x4){bf_lo(w.x), bf_hi(w.x), bf_lo(w.y), bf_hi(w.y)}; y1 = (f32x4){bf_lo(w.z), bf_hi(w.z), bf_lo(w.w), bf_hi(w.w)}; }
;                     float sa = ((y0[0] + y0[1]) + (y0[2] + y0[3])) + ((y1[0] + y1[1]) + (y1[2] + y1[3]));
;                     float sb = ((y0[0] * y0[0] + y0[1] * y0[1]) + (y0[2] * y0[2] + y0[3] * y0[3])) + ((y1[0] * y1[0] + y1[1] * y1[1]) + (y1[2] * y1[2] + y1[3] * y1[3]));
;                     sa += dpp_x1(sa);
;                     sb += dpp_x1(sb);
;                     sa += __shfl_xor(sa, 16); sa += __shfl_xor(sa, 32); sb += __shfl_xor(sb, 16); sb += __shfl_xor(sb, 32);
;                     if (fq == 0 && !odd) ps[(size_t)(rl + q) * 64] = (f32x2){sa, sb};
;                 }
	v_mul_f32_e32 v26, 0x3fb504f3, v25
	v_sub_f32_e32 v29, v28, v24
	v_sub_f32_e32 v28, v27, v24
	v_pk_mul_f32 v[28:29], v[28:29], v[26:27] op_sel_hi:[1,0]
	v_sub_f32_e32 v31, v31, v24
	v_pk_fma_f32 v[28:29], v[76:77], v[28:29], v[184:185]
	v_sub_f32_e32 v30, v30, v24
	v_pk_add_f32 v[12:13], v[12:13], v[28:29]
	v_sub_f32_e32 v29, v33, v24
	v_sub_f32_e32 v28, v32, v24
	v_sub_f32_e32 v25, v35, v24
	v_sub_f32_e32 v24, v34, v24
	v_pk_mul_f32 v[30:31], v[30:31], v[26:27] op_sel_hi:[1,0]
	v_pk_mul_f32 v[24:25], v[24:25], v[26:27] op_sel_hi:[1,0]
	v_pk_mul_f32 v[26:27], v[28:29], v[26:27] op_sel_hi:[1,0]
	v_cndmask_b32_e64 v8, v20, v8, s[10:11]
	v_cndmask_b32_e64 v11, v23, v11, s[10:11]
	v_cndmask_b32_e64 v10, v21, v10, s[10:11]
	v_pk_fma_f32 v[30:31], v[78:79], v[30:31], v[182:183]
	v_pk_fma_f32 v[26:27], v[72:73], v[26:27], v[180:181]
	v_pk_fma_f32 v[24:25], v[74:75], v[24:25], v[178:179]
	v_pk_add_f32 v[14:15], v[14:15], v[30:31]
	v_pk_add_f32 v[10:11], v[10:11], v[24:25]
	v_pk_add_f32 v[8:9], v[8:9], v[26:27]
	v_cvt_pk_bf16_f32 v24, v12, v13
	v_cvt_pk_bf16_f32 v25, v14, v15
	s_nop 0
	v_cvt_pk_bf16_f32 v26, v8, v9
	v_cvt_pk_bf16_f32 v27, v10, v11
	v_lshlrev_b32_e32 v8, 16, v24
	v_and_b32_e32 v10, 0xffff0000, v24
	v_lshlrev_b32_e32 v12, 16, v25
	v_and_b32_e32 v14, 0xffff0000, v25
	v_lshlrev_b32_e32 v28, 16, v26
	v_and_b32_e32 v30, 0xffff0000, v26
	v_lshlrev_b32_e32 v32, 16, v27
	v_and_b32_e32 v34, 0xffff0000, v27
	v_mul_f32_e32 v9, v8, v8
	v_mul_f32_e32 v11, v10, v10
	v_mul_f32_e32 v13, v12, v12
	v_mul_f32_e32 v15, v14, v14
	v_mul_f32_e32 v29, v28, v28
	v_mul_f32_e32 v31, v30, v30
	v_mul_f32_e32 v33, v32, v32
	v_mul_f32_e32 v35, v34, v34
	v_pk_add_f32 v[8:9], v[8:9], v[10:11]
	v_pk_add_f32 v[10:11], v[12:13], v[14:15]
	v_pk_add_f32 v[12:13], v[32:33], v[34:35]
	v_pk_add_f32 v[8:9], v[8:9], v[10:11]
	v_pk_add_f32 v[10:11], v[28:29], v[30:31]
	s_nop 0
	v_pk_add_f32 v[10:11], v[10:11], v[12:13]
	s_nop 0
	v_pk_add_f32 v[8:9], v[8:9], v[10:11]
	v_mov_b32_e32 v10, v165
	v_mov_b32_e32 v11, v165
	s_nop 0
	v_mov_b32_dpp v10, v8 quad_perm:[1,0,3,2] row_mask:0xf bank_mask:0xf
	v_mov_b32_dpp v11, v9 quad_perm:[1,0,3,2] row_mask:0xf bank_mask:0xf
	v_pk_add_f32 v[8:9], v[8:9], v[10:11]
	v_mov_b32_e32 v10, v8
	v_mov_b32_e32 v11, v9
	s_nop 1
	v_permlane16_swap_b32_e32 v8, v10
	v_permlane16_swap_b32_e32 v9, v11
	s_waitcnt lgkmcnt(0)
	v_pk_add_f32 v[10:11], v[8:9], v[10:11]
	v_mov_b32_e32 v12, v10
	v_mov_b32_e32 v13, v11
	s_nop 1
	v_permlane32_swap_b32_e32 v10, v12
	v_permlane32_swap_b32_e32 v11, v13
	v_lshl_add_u64 v[8:9], s[20:21], 0, v[164:165]
	global_store_dwordx4 v[8:9], v[24:27], off
	s_and_saveexec_b64 s[20:21], s[16:17]
	s_cbranch_execz .LBB0_846
	s_waitcnt lgkmcnt(0)
	v_pk_add_f32 v[10:11], v[10:11], v[12:13]
	v_add_co_u32_e32 v12, vcc, 0x16000, v186
	s_nop 1
	v_addc_co_u32_e32 v13, vcc, 0, v187, vcc
	global_store_dwordx2 v[12:13], v[10:11], off
.LBB0_846:
	s_or_b64 exec, exec, s[20:21]
	ds_read_b64 v[10:11], v201 offset:1416
	s_waitcnt vmcnt(14) lgkmcnt(1)
	v_lshlrev_b32_e32 v13, 16, v64
	v_and_b32_e32 v14, 0xffff0000, v64
	v_cndmask_b32_e64 v5, v5, v18, s[10:11]
	v_cndmask_b32_e64 v4, v4, v16, s[10:11]
	s_waitcnt lgkmcnt(0)
	v_mul_f32_e32 v12, 0x3fb504f3, v11
	v_sub_f32_e32 v15, v14, v10
	v_sub_f32_e32 v14, v13, v10
	v_pk_mul_f32 v[14:15], v[14:15], v[12:13] op_sel_hi:[1,0]
	v_cndmask_b32_e64 v7, v7, v19, s[10:11]
	v_cndmask_b32_e64 v6, v6, v17, s[10:11]
	v_cndmask_b32_e64 v0, v0, v20, s[10:11]
	v_cndmask_b32_e64 v2, v2, v21, s[10:11]
	v_lshlrev_b32_e32 v16, 16, v65
	v_and_b32_e32 v17, 0xffff0000, v65
	v_lshlrev_b32_e32 v18, 16, v66
	v_and_b32_e32 v19, 0xffff0000, v66
	v_lshlrev_b32_e32 v20, 16, v67
	v_and_b32_e32 v21, 0xffff0000, v67
	v_pk_fma_f32 v[14:15], v[76:77], v[14:15], v[184:185]
	v_sub_f32_e32 v17, v17, v10
	v_sub_f32_e32 v16, v16, v10
	v_pk_add_f32 v[4:5], v[4:5], v[14:15]
	v_sub_f32_e32 v15, v19, v10
	v_sub_f32_e32 v14, v18, v10
	v_sub_f32_e32 v11, v21, v10
	v_sub_f32_e32 v10, v20, v10
	v_pk_mul_f32 v[16:17], v[16:17], v[12:13] op_sel_hi:[1,0]
	v_pk_mul_f32 v[10:11], v[10:11], v[12:13] op_sel_hi:[1,0]
	v_pk_mul_f32 v[12:13], v[14:15], v[12:13] op_sel_hi:[1,0]
	v_cndmask_b32_e64 v1, v1, v22, s[10:11]
	v_cndmask_b32_e64 v3, v3, v23, s[10:11]
	v_pk_fma_f32 v[16:17], v[78:79], v[16:17], v[182:183]
	v_pk_fma_f32 v[12:13], v[72:73], v[12:13], v[180:181]
	v_pk_fma_f32 v[10:11], v[74:75], v[10:11], v[178:179]
	v_pk_add_f32 v[6:7], v[6:7], v[16:17]
	v_pk_add_f32 v[2:3], v[2:3], v[10:11]
	v_pk_add_f32 v[0:1], v[0:1], v[12:13]
	v_cvt_pk_bf16_f32 v4, v4, v5
	v_cvt_pk_bf16_f32 v5, v6, v7
	s_nop 0
	v_cvt_pk_bf16_f32 v6, v0, v1
	v_cvt_pk_bf16_f32 v7, v2, v3
	v_lshlrev_b32_e32 v0, 16, v4
	v_and_b32_e32 v2, 0xffff0000, v4
	v_lshlrev_b32_e32 v10, 16, v5
	v_and_b32_e32 v12, 0xffff0000, v5
	v_lshlrev_b32_e32 v14, 16, v6
	v_and_b32_e32 v16, 0xffff0000, v6
	v_lshlrev_b32_e32 v18, 16, v7
	v_and_b32_e32 v20, 0xffff0000, v7
	v_mul_f32_e32 v1, v0, v0
	v_mul_f32_e32 v3, v2, v2
	v_mul_f32_e32 v11, v10, v10
	v_mul_f32_e32 v13, v12, v12
	v_mul_f32_e32 v15, v14, v14
	v_mul_f32_e32 v17, v16, v16
	v_mul_f32_e32 v19, v18, v18
	v_mul_f32_e32 v21, v20, v20
	v_pk_add_f32 v[0:1], v[0:1], v[2:3]
	v_pk_add_f32 v[2:3], v[10:11], v[12:13]
	v_pk_add_f32 v[10:11], v[18:19], v[20:21]
	v_pk_add_f32 v[0:1], v[0:1], v[2:3]
	v_pk_add_f32 v[2:3], v[14:15], v[16:17]
	global_store_dwordx4 v[8:9], v[4:7], off offset:128
	v_pk_add_f32 v[2:3], v[2:3], v[10:11]
	s_nop 0
	v_pk_add_f32 v[0:1], v[0:1], v[2:3]
	v_mov_b32_e32 v2, v165
	v_mov_b32_e32 v3, v165
	s_nop 0
	v_mov_b32_dpp v2, v0 quad_perm:[1,0,3,2] row_mask:0xf bank_mask:0xf
	v_mov_b32_dpp v3, v1 quad_perm:[1,0,3,2] row_mask:0xf bank_mask:0xf
	v_pk_add_f32 v[0:1], v[0:1], v[2:3]
	v_mov_b32_e32 v2, v0
	v_mov_b32_e32 v3, v1
	s_nop 1
	v_permlane16_swap_b32_e32 v0, v2
	v_permlane16_swap_b32_e32 v1, v3
	s_waitcnt lgkmcnt(0)
	v_pk_add_f32 v[0:1], v[0:1], v[2:3]
	v_mov_b32_e32 v2, v0
	v_mov_b32_e32 v3, v1
	s_nop 1
	v_permlane32_swap_b32_e32 v0, v2
	v_permlane32_swap_b32_e32 v1, v3
	s_and_saveexec_b64 s[20:21], s[16:17]
	s_cbranch_execz .LBB0_848
	s_waitcnt lgkmcnt(0)
	v_pk_add_f32 v[0:1], v[0:1], v[2:3]
	v_add_co_u32_e32 v2, vcc, 0x16000, v186
	s_nop 1
	v_addc_co_u32_e32 v3, vcc, 0, v187, vcc
	global_store_dwordx2 v[2:3], v[0:1], off offset:512

; #define LAS __attribute__((address_space(3)))
;     __device__ __forceinline__ void operator()(const f32x4 (&acc)[2][2][4][2], const Unit& u, int wr, int wc, int fr, int fq, const EpiCtx& X) const {
;     ...
;         char* yb = nullptr; char* xb = (char*)(XB + (size_t)u.pm * BM * DM + (size_t)(u.pn * 4 + wc) * (BM * 64));
;         unsigned lo = (unsigned)((wr * 64 + fe) * 64 + o32 + 8 * fq) * 2u; EPI_OPAQUE(lo);
;         const int col = u.pn * BM + wc * 64 + o32 + 8 * fq;
;         f32x4 g0, g1, b0, b1;
;         if (RESN) { ensure_tbl(PSp, sidp, u.pm, X);
;             g0 = *(const f32x4*)(gp + col); g1 = *(const f32x4*)(gp + col + 4); b0 = *(const f32x4*)(bp + col) * ALPHA; b1 = *(const f32x4*)(bp + col + 4) * ALPHA; }
;         const LAS f32x2* tbl = (const LAS f32x2*)(X.lds + TBL_OFF) + wr * 64 + fe;
;         f32x2* ps = PSn + ((size_t)u.pm * BM + wr * 64 + fe) * 64 + u.pn * 4 + wc;
; #pragma unroll
;         for (int ai = 0; ai < 2; ++ai) {
;             u32x4 raw[8];
; #pragma unroll
;             for (int m = 0; m < 4; ++m) { const unsigned off = lo + (unsigned)((ai * HALF + m * 16) * 64) * 2u; raw[2 * m] = *(const u32x4*)(xb + off); raw[2 * m + 1] = *(const u32x4*)(xb + off + 128); }
; #pragma unroll
;             for (int m = 0; m < 4; ++m) {
;                 const int rl = ai * HALF + m * 16; const unsigned off = lo + (unsigned)(rl * 64) * 2u;
;                 const f32x4 o0a = acc[ai][0][m][0], o0b = acc[ai][0][m][1], o1a = acc[ai][1][m][0], o1b = acc[ai][1][m][1];
;                 const f32x4 ra_ = dpp_swap1(odd ? o0a : o1a), rb_ = dpp_swap1(odd ? o0b : o1b);
;                 const f32x4 pa[2] = {odd ? ra_ : o0a, odd ? o1a : ra_}, pb[2] = {odd ? rb_ : o0b, odd ? o1b : rb_};
; #pragma unroll
;                 for (int q = 0; q < 2; ++q) {
;                     const u32x4 w0 = raw[2 * m + q];
;                     const f32x4 r0 = (f32x4){bf_lo(w0.x), bf_hi(w0.x), bf_lo(w0.y), bf_hi(w0.y)}, r1 = (f32x4){bf_lo(w0.z), bf_hi(w0.z), bf_lo(w0.w), bf_hi(w0.w)};
;                     f32x4 y0, y1;
;                     if (RESN) { const f32x2 t = tbl[rl + q]; const float mu = t.x, ra = t.y * ALPHA; y0 = (r0 - mu) * ra * g0 + b0 + pa[q]; y1 = (r1 - mu) * ra * g1 + b1 + pb[q]; }
;                     else { y0 = r0 * ALPHA + pa[q]; y1 = r1 * ALPHA + pb[q]; }
;                     { const u32x4 w = pack8f(y0, y1); *(u32x4*)(xb + off + q * 128) = w;
.LBB0_1463:
	s_lshl_b64 s[4:5], s[66:67], 21
	s_add_u32 s20, s51, s4
	s_addc_u32 s21, s53, s5
	s_lshl_b32 s66, s64, 2
	s_or_b32 s4, s66, s41
	s_ashr_i32 s5, s4, 31
	v_lshl_add_u32 v72, s64, 8, v200
	v_ashrrev_i32_e32 v73, 31, v72
	s_lshl_b64 s[4:5], s[4:5], 15
	v_lshlrev_b64 v[72:73], 2, v[72:73]
	s_add_u32 s20, s20, s4
	v_lshl_add_u64 v[74:75], s[26:27], 0, v[72:73]
	s_addc_u32 s21, s21, s5
	global_load_dwordx4 v[194:197], v[74:75], off offset:16
	global_load_dwordx4 v[178:181], v[74:75], off
	global_load_dwordx4 v[214:217], v164, s[20:21]
	v_lshl_add_u64 v[72:73], s[24:25], 0, v[72:73]
	s_waitcnt lgkmcnt(0)
	global_load_dwordx4 v[76:79], v[72:73], off
	s_nop 0
	global_load_dwordx4 v[72:75], v[72:73], off offset:16
	v_cndmask_b32_e64 v136, v135, v127, s[10:11]
	v_cndmask_b32_e64 v137, v134, v126, s[10:11]
	v_cndmask_b32_e64 v138, v133, v125, s[10:11]
	v_cndmask_b32_e64 v139, v132, v124, s[10:11]
	v_mov_b32_e32 v189, 0
	v_mov_b32_e32 v193, 0
	v_mov_b32_e32 v191, 0
	v_mov_b32_e32 v209, 0
	v_cndmask_b32_e64 v140, v131, v123, s[10:11]
	v_cndmask_b32_e64 v141, v130, v122, s[10:11]
	v_cndmask_b32_e64 v142, v129, v121, s[10:11]
	v_cndmask_b32_e64 v143, v128, v120, s[10:11]
	v_mov_b32_e32 v210, 0
	v_mov_b32_e32 v212, 0
	v_mov_b32_e32 v211, 0
	v_mov_b32_e32 v213, 0
	v_mov_b32_dpp v189, v139 quad_perm:[1,0,3,2] row_mask:0xf bank_mask:0xf
	v_mov_b32_dpp v193, v138 quad_perm:[1,0,3,2] row_mask:0xf bank_mask:0xf
	v_mov_b32_dpp v191, v137 quad_perm:[1,0,3,2] row_mask:0xf bank_mask:0xf
	v_mov_b32_dpp v209, v136 quad_perm:[1,0,3,2] row_mask:0xf bank_mask:0xf
	v_mov_b32_dpp v210, v143 quad_perm:[1,0,3,2] row_mask:0xf bank_mask:0xf
	v_mov_b32_dpp v212, v142 quad_perm:[1,0,3,2] row_mask:0xf bank_mask:0xf
	v_mov_b32_dpp v211, v141 quad_perm:[1,0,3,2] row_mask:0xf bank_mask:0xf
	v_mov_b32_dpp v213, v140 quad_perm:[1,0,3,2] row_mask:0xf bank_mask:0xf
	v_add_u32_e32 v192, 0x800, v164
	v_add_u32_e32 v190, 0x1000, v164
	v_add_u32_e32 v188, 0x1800, v164
	ds_read_b64 v[218:219], v201
	v_cndmask_b32_e64 v221, v193, v133, s[10:11]
	v_cndmask_b32_e64 v220, v189, v132, s[10:11]
	v_cndmask_b32_e64 v223, v209, v135, s[10:11]
	v_cndmask_b32_e64 v222, v191, v134, s[10:11]
	v_cndmask_b32_e64 v225, v212, v129, s[10:11]
	v_cndmask_b32_e64 v224, v210, v128, s[10:11]
	v_cndmask_b32_e64 v227, v213, v131, s[10:11]
	v_cndmask_b32_e64 v226, v211, v130, s[10:11]
	global_load_dwordx4 v[152:155], v164, s[20:21] offset:128
	global_load_dwordx4 v[148:151], v192, s[20:21]
	global_load_dwordx4 v[144:147], v192, s[20:21] offset:128
	global_load_dwordx4 v[140:143], v190, s[20:21]
	global_load_dwordx4 v[136:139], v190, s[20:21] offset:128
	global_load_dwordx4 v[132:135], v188, s[20:21]
	global_load_dwordx4 v[128:131], v188, s[20:21] offset:128
	s_waitcnt lgkmcnt(0)
	v_mul_f32_e32 v208, 0x3fb504f3, v219
	v_lshl_add_u64 v[186:187], v[166:167], 0, s[68:69]
	s_ashr_i32 s67, s66, 31
	v_lshl_add_u64 v[186:187], s[66:67], 3, v[186:187]
	v_lshl_add_u64 v[186:187], v[186:187], 0, s[22:23]
	v_add_u32_e32 v246, 0x4000, v164
	v_add_u32_e32 v247, 0x4800, v164
	global_load_dwordx4 v[230:233], v246, s[20:21]
	global_load_dwordx4 v[234:237], v246, s[20:21] offset:128
	global_load_dwordx4 v[238:241], v247, s[20:21]
	global_load_dwordx4 v[242:245], v247, s[20:21] offset:128
	s_waitcnt vmcnt(14)
	v_pk_mul_f32 v[182:183], v[180:181], s[52:53] op_sel_hi:[1,0]
	v_pk_mul_f32 v[184:185], v[178:179], s[52:53] op_sel_hi:[1,0]
	v_pk_mul_f32 v[178:179], v[196:197], s[52:53] op_sel_hi:[1,0]
	v_pk_mul_f32 v[180:181], v[194:195], s[52:53] op_sel_hi:[1,0]
	s_waitcnt vmcnt(13)
	v_lshlrev_b32_e32 v194, 16, v214
	v_and_b32_e32 v195, 0xffff0000, v214
	v_lshlrev_b32_e32 v196, 16, v215
	v_and_b32_e32 v197, 0xffff0000, v215
	v_lshlrev_b32_e32 v207, 16, v216
	v_and_b32_e32 v214, 0xffff0000, v216
	v_lshlrev_b32_e32 v216, 16, v217
	v_and_b32_e32 v217, 0xffff0000, v217
	v_sub_f32_e32 v195, v195, v218
	v_sub_f32_e32 v194, v194, v218
	v_sub_f32_e32 v197, v197, v218
	v_sub_f32_e32 v196, v196, v218
	v_sub_f32_e32 v215, v214, v218
	v_sub_f32_e32 v214, v207, v218
	v_sub_f32_e32 v217, v217, v218
	v_sub_f32_e32 v216, v216, v218
	v_pk_mul_f32 v[196:197], v[196:197], v[208:209] op_sel_hi:[1,0]
	v_pk_mul_f32 v[194:195], v[194:195], v[208:209] op_sel_hi:[1,0]
	v_pk_mul_f32 v[216:217], v[216:217], v[208:209] op_sel_hi:[1,0]
	v_pk_mul_f32 v[214:215], v[214:215], v[208:209] op_sel_hi:[1,0]
	s_waitcnt vmcnt(12)
	v_pk_fma_f32 v[194:195], v[76:77], v[194:195], v[184:185]
	v_pk_fma_f32 v[196:197], v[78:79], v[196:197], v[182:183]
	s_waitcnt vmcnt(11)
	v_pk_fma_f32 v[214:215], v[72:73], v[214:215], v[180:181]
	v_pk_fma_f32 v[216:217], v[74:75], v[216:217], v[178:179]
	v_pk_add_f32 v[196:197], v[222:223], v[196:197]
	v_pk_add_f32 v[194:195], v[220:221], v[194:195]
	v_pk_add_f32 v[218:219], v[226:227], v[216:217]
	v_pk_add_f32 v[216:217], v[224:225], v[214:215]
	v_cvt_pk_bf16_f32 v214, v194, v195
	v_cvt_pk_bf16_f32 v215, v196, v197
	v_and_b32_e32 v208, 64, v206
	v_cvt_pk_bf16_f32 v216, v216, v217
	v_cvt_pk_bf16_f32 v217, v218, v219
	v_lshlrev_b32_e32 v194, 16, v214
	v_and_b32_e32 v196, 0xffff0000, v214
	v_lshlrev_b32_e32 v218, 16, v215
	v_and_b32_e32 v220, 0xffff0000, v215
	v_lshlrev_b32_e32 v222, 16, v216
	v_and_b32_e32 v224, 0xffff0000, v216
	v_lshlrev_b32_e32 v226, 16, v217
	v_and_b32_e32 v228, 0xffff0000, v217
	v_mul_f32_e32 v195, v194, v194
	v_mul_f32_e32 v197, v196, v196
	v_mul_f32_e32 v219, v218, v218
	v_mul_f32_e32 v221, v220, v220
	v_mul_f32_e32 v223, v222, v222
	v_mul_f32_e32 v225, v224, v224
	v_mul_f32_e32 v227, v226, v226
	v_mul_f32_e32 v229, v228, v228
	v_pk_add_f32 v[194:195], v[194:195], v[196:197]
	v_pk_add_f32 v[196:197], v[218:219], v[220:221]
	v_pk_add_f32 v[218:219], v[226:227], v[228:229]
	v_pk_add_f32 v[194:195], v[194:195], v[196:197]
	v_pk_add_f32 v[196:197], v[222:223], v[224:225]
	v_xor_b32_e32 v207, 16, v206
	v_add_u32_e32 v208, 64, v208
	v_pk_add_f32 v[196:197], v[196:197], v[218:219]
	v_cmp_lt_i32_e32 vcc, v207, v208
	v_pk_add_f32 v[194:195], v[194:195], v[196:197]
	v_mov_b32_e32 v196, 0
	v_mov_b32_e32 v197, 0
	v_cndmask_b32_e32 v207, v206, v207, vcc
	v_mov_b32_dpp v196, v194 quad_perm:[1,0,3,2] row_mask:0xf bank_mask:0xf
	v_mov_b32_dpp v197, v195 quad_perm:[1,0,3,2] row_mask:0xf bank_mask:0xf
	v_lshlrev_b32_e32 v207, 2, v207
	v_pk_add_f32 v[194:195], v[194:195], v[196:197]
	v_mov_b32_e32 v196, v194
	v_mov_b32_e32 v197, v195
	s_nop 1
	v_permlane16_swap_b32_e32 v194, v196
	v_permlane16_swap_b32_e32 v195, v197
	v_xor_b32_e32 v218, 32, v206
	v_cmp_lt_i32_e32 vcc, v218, v208
	global_store_dwordx4 v164, v[214:217], s[20:21]
	s_waitcnt lgkmcnt(0)
	v_pk_add_f32 v[194:195], v[194:195], v[196:197]
	v_cndmask_b32_e32 v208, v206, v218, vcc
	v_lshlrev_b32_e32 v208, 2, v208
	v_mov_b32_e32 v196, v194
	v_mov_b32_e32 v197, v195
	s_nop 1
	v_permlane32_swap_b32_e32 v194, v196
	v_permlane32_swap_b32_e32 v195, v197
	s_and_saveexec_b64 s[64:65], s[16:17]
	s_waitcnt lgkmcnt(0)
	v_pk_add_f32 v[194:195], v[194:195], v[196:197]
	global_store_dwordx2 v[186:187], v[194:195], off
;     __device__ __forceinline__ void operator()(const f32x4 (&acc)[2][2][4][2], const Unit& u, int wr, int wc, int fr, int fq, const EpiCtx& X) const {
;     ...
;             for (int m = 0; m < 4; ++m) { const unsigned off = lo + (unsigned)((ai * HALF + m * 16) * 64) * 2u; raw[2 * m] = *(const u32x4*)(xb + off); raw[2 * m + 1] = *(const u32x4*)(xb + off + 128); }
; #pragma unroll
;             for (int m = 0; m < 4; ++m) {
;                 const int rl = ai * HALF + m * 16; const unsigned off = lo + (unsigned)(rl * 64) * 2u;
;                 const f32x4 o0a = acc[ai][0][m][0], o0b = acc[ai][0][m][1], o1a = acc[ai][1][m][0], o1b = acc[ai][1][m][1];
;                 const f32x4 ra_ = dpp_swap1(odd ? o0a : o1a), rb_ = dpp_swap1(odd ? o0b : o1b);
;                 const f32x4 pa[2] = {odd ? ra_ : o0a, odd ? o1a : ra_}, pb[2] = {odd ? rb_ : o0b, odd ? o1b : rb_};
; #pragma unroll
;                 for (int q = 0; q < 2; ++q) {
;                     const u32x4 w0 = raw[2 * m + q];
;                     const f32x4 r0 = (f32x4){bf_lo(w0.x), bf_hi(w0.x), bf_lo(w0.y), bf_hi(w0.y)}, r1 = (f32x4){bf_lo(w0.z), bf_hi(w0.z), bf_lo(w0.w), bf_hi(w0.w)};
;                     f32x4 y0, y1;
;                     if (RESN) { const f32x2 t = tbl[rl + q]; const float mu = t.x, ra = t.y * ALPHA; y0 = (r0 - mu) * ra * g0 + b0 + pa[q]; y1 = (r1 - mu) * ra * g1 + b1 + pb[q]; }
;                     else { y0 = r0 * ALPHA + pa[q]; y1 = r1 * ALPHA + pb[q]; }
;                     { const u32x4 w = pack8f(y0, y1); *(u32x4*)(xb + off + q * 128) = w;
;                         y0 = (f32x4){bf_lo(w.x), bf_hi(w.x), bf_lo(w.y), bf_hi(w.y)}; y1 = (f32x4){bf_lo(w.z), bf_hi(w.z), bf_lo(w.w), bf_hi(w.w)}; }
;                     float sa = ((y0[0] + y0[1]) + (y0[2] + y0[3])) + ((y1[0] + y1[1]) + (y1[2] + y1[3]));
;                     float sb = ((y0[0] * y0[0] + y0[1] * y0[1]) + (y0[2] * y0[2] + y0[3] * y0[3])) + ((y1[0] * y1[0] + y1[1] * y1[1]) + (y1[2] * y1[2] + y1[3] * y1[3]));
;                     sa += dpp_x1(sa);
;                     sb += dpp_x1(sb);
;                     sa += __shfl_xor(sa, 16); sa += __shfl_xor(sa, 32); sb += __shfl_xor(sb, 16); sb += __shfl_xor(sb, 32);
;                     if (fq == 0 && !odd) ps[(size_t)(rl + q) * 64] = (f32x2){sa, sb};
;                 }
.LBB0_1465:
	s_or_b64 exec, exec, s[64:65]
	v_cndmask_b32_e64 v125, v125, v193, s[10:11]
	v_cndmask_b32_e64 v124, v124, v189, s[10:11]
	v_cndmask_b32_e64 v126, v126, v191, s[10:11]
	s_waitcnt vmcnt(12)
	v_lshlrev_b32_e32 v189, 16, v152
	v_and_b32_e32 v191, 0xffff0000, v152
	v_lshlrev_b32_e32 v193, 16, v153
	s_waitcnt lgkmcnt(0)
	v_and_b32_e32 v196, 0xffff0000, v153
	ds_read_b64 v[152:153], v201 offset:8
	v_cndmask_b32_e64 v127, v127, v209, s[10:11]
	v_cndmask_b32_e64 v120, v120, v210, s[10:11]
	v_cndmask_b32_e64 v122, v122, v211, s[10:11]
	v_lshlrev_b32_e32 v209, 16, v154
	v_and_b32_e32 v210, 0xffff0000, v154
	v_lshlrev_b32_e32 v211, 16, v155
	v_and_b32_e32 v155, 0xffff0000, v155
	s_waitcnt lgkmcnt(0)
	v_mul_f32_e32 v154, 0x3fb504f3, v153
	v_sub_f32_e32 v195, v191, v152
	v_sub_f32_e32 v194, v189, v152
	v_pk_mul_f32 v[194:195], v[194:195], v[154:155] op_sel_hi:[1,0]
	v_sub_f32_e32 v197, v196, v152
	v_pk_fma_f32 v[194:195], v[76:77], v[194:195], v[184:185]
	v_sub_f32_e32 v196, v193, v152
	v_pk_add_f32 v[124:125], v[124:125], v[194:195]
	v_sub_f32_e32 v195, v210, v152
	v_sub_f32_e32 v194, v209, v152
	v_sub_f32_e32 v153, v155, v152
	v_sub_f32_e32 v152, v211, v152
	v_pk_mul_f32 v[196:197], v[196:197], v[154:155] op_sel_hi:[1,0]
	v_pk_mul_f32 v[152:153], v[152:153], v[154:155] op_sel_hi:[1,0]
	v_pk_mul_f32 v[154:155], v[194:195], v[154:155] op_sel_hi:[1,0]
	v_cndmask_b32_e64 v121, v121, v212, s[10:11]
	v_cndmask_b32_e64 v123, v123, v213, s[10:11]
	v_pk_fma_f32 v[196:197], v[78:79], v[196:197], v[182:183]
	v_pk_fma_f32 v[154:155], v[72:73], v[154:155], v[180:181]
	v_pk_fma_f32 v[152:153], v[74:75], v[152:153], v[178:179]
	v_pk_add_f32 v[126:127], v[126:127], v[196:197]
	v_pk_add_f32 v[122:123], v[122:123], v[152:153]
	v_pk_add_f32 v[120:121], v[120:121], v[154:155]
	v_cvt_pk_bf16_f32 v124, v124, v125
	v_cvt_pk_bf16_f32 v125, v126, v127
	s_nop 0
	v_cvt_pk_bf16_f32 v126, v120, v121
	v_cvt_pk_bf16_f32 v127, v122, v123
	v_lshlrev_b32_e32 v120, 16, v124
	v_and_b32_e32 v122, 0xffff0000, v124
	v_lshlrev_b32_e32 v152, 16, v125
	v_and_b32_e32 v154, 0xffff0000, v125
	v_lshlrev_b32_e32 v194, 16, v126
	v_and_b32_e32 v196, 0xffff0000, v126
	v_lshlrev_b32_e32 v210, 16, v127
	v_and_b32_e32 v212, 0xffff0000, v127
	v_mul_f32_e32 v121, v120, v120
	v_mul_f32_e32 v123, v122, v122
	v_mul_f32_e32 v153, v152, v152
	v_mul_f32_e32 v155, v154, v154
	v_mul_f32_e32 v195, v194, v194
	v_mul_f32_e32 v197, v196, v196
	v_mul_f32_e32 v211, v210, v210
	v_mul_f32_e32 v213, v212, v212
	v_pk_add_f32 v[120:121], v[120:121], v[122:123]
	v_pk_add_f32 v[122:123], v[152:153], v[154:155]
	v_pk_add_f32 v[152:153], v[210:211], v[212:213]
	v_pk_add_f32 v[120:121], v[120:121], v[122:123]
	v_pk_add_f32 v[122:123], v[194:195], v[196:197]
	s_nop 0
	v_pk_add_f32 v[122:123], v[122:123], v[152:153]
	v_lshl_add_u64 v[152:153], s[20:21], 0, v[164:165]
	v_pk_add_f32 v[120:121], v[120:121], v[122:123]
	v_mov_b32_e32 v122, v165
	v_mov_b32_e32 v123, v165
	global_store_dwordx4 v[152:153], v[124:127], off offset:128
	v_mov_b32_dpp v122, v120 quad_perm:[1,0,3,2] row_mask:0xf bank_mask:0xf
	v_mov_b32_dpp v123, v121 quad_perm:[1,0,3,2] row_mask:0xf bank_mask:0xf
	v_pk_add_f32 v[120:121], v[120:121], v[122:123]
	v_mov_b32_e32 v122, v120
	v_mov_b32_e32 v123, v121
	s_nop 1
	v_permlane16_swap_b32_e32 v120, v122
	v_permlane16_swap_b32_e32 v121, v123
	s_waitcnt lgkmcnt(0)
	v_pk_add_f32 v[120:121], v[120:121], v[122:123]
	v_mov_b32_e32 v122, v120
	v_mov_b32_e32 v123, v121
	s_nop 1
	v_permlane32_swap_b32_e32 v120, v122
	v_permlane32_swap_b32_e32 v121, v123
	s_and_saveexec_b64 s[64:65], s[16:17]
	s_waitcnt lgkmcnt(0)
	v_pk_add_f32 v[120:121], v[120:121], v[122:123]
	global_store_dwordx2 v[186:187], v[120:121], off offset:512
.LBB0_1467:
	s_or_b64 exec, exec, s[64:65]
	s_waitcnt lgkmcnt(0)
	v_cndmask_b32_e64 v122, v116, v108, s[10:11]
	v_mov_b32_e32 v120, 0
	v_cndmask_b32_e64 v121, v117, v109, s[10:11]
	s_waitcnt lgkmcnt(0)
	v_cndmask_b32_e64 v123, v118, v110, s[10:11]
	v_mov_b32_dpp v120, v122 quad_perm:[1,0,3,2] row_mask:0xf bank_mask:0xf
	v_mov_b32_e32 v122, 0
	v_cndmask_b32_e64 v124, v119, v111, s[10:11]
	v_cndmask_b32_e64 v126, v112, v104, s[10:11]
	v_mov_b32_dpp v122, v121 quad_perm:[1,0,3,2] row_mask:0xf bank_mask:0xf
	v_mov_b32_e32 v121, 0
	v_cndmask_b32_e64 v125, v113, v105, s[10:11]
	v_cndmask_b32_e64 v127, v114, v106, s[10:11]
	v_mov_b32_dpp v121, v123 quad_perm:[1,0,3,2] row_mask:0xf bank_mask:0xf
	v_mov_b32_e32 v123, 0
	v_cndmask_b32_e64 v152, v115, v107, s[10:11]
	s_waitcnt vmcnt(13)
	v_and_b32_e32 v153, 0xffff0000, v148
	v_mov_b32_dpp v123, v124 quad_perm:[1,0,3,2] row_mask:0xf bank_mask:0xf
	v_mov_b32_e32 v124, 0
	v_lshlrev_b32_e32 v154, 16, v149
	v_and_b32_e32 v155, 0xffff0000, v149
	v_mov_b32_dpp v124, v126 quad_perm:[1,0,3,2] row_mask:0xf bank_mask:0xf
	v_mov_b32_e32 v126, 0
	v_lshlrev_b32_e32 v189, 16, v150
	v_and_b32_e32 v191, 0xffff0000, v150
	v_mov_b32_dpp v126, v125 quad_perm:[1,0,3,2] row_mask:0xf bank_mask:0xf
	v_mov_b32_e32 v125, 0
	v_lshlrev_b32_e32 v193, 16, v151
	v_and_b32_e32 v151, 0xffff0000, v151
	v_mov_b32_dpp v125, v127 quad_perm:[1,0,3,2] row_mask:0xf bank_mask:0xf
	v_mov_b32_e32 v127, 0
	v_cndmask_b32_e64 v117, v122, v117, s[10:11]
	v_cndmask_b32_e64 v116, v120, v116, s[10:11]
	v_mov_b32_dpp v127, v152 quad_perm:[1,0,3,2] row_mask:0xf bank_mask:0xf
	v_lshlrev_b32_e32 v152, 16, v148
	ds_read_b64 v[148:149], v201 offset:128
	v_cndmask_b32_e64 v119, v123, v119, s[10:11]
	v_cndmask_b32_e64 v118, v121, v118, s[10:11]
	v_cndmask_b32_e64 v113, v126, v113, s[10:11]
	v_cndmask_b32_e64 v112, v124, v112, s[10:11]
	s_waitcnt lgkmcnt(0)
;     __device__ __forceinline__ void operator()(const f32x4 (&acc)[2][2][4][2], const Unit& u, int wr, int wc, int fr, int fq, const EpiCtx& X) const {
;     ...
;             for (int m = 0; m < 4; ++m) { const unsigned off = lo + (unsigned)((ai * HALF + m * 16) * 64) * 2u; raw[2 * m] = *(const u32x4*)(xb + off); raw[2 * m + 1] = *(const u32x4*)(xb + off + 128); }
; #pragma unroll
;             for (int m = 0; m < 4; ++m) {
;                 const int rl = ai * HALF + m * 16; const unsigned off = lo + (unsigned)(rl * 64) * 2u;
;                 const f32x4 o0a = acc[ai][0][m][0], o0b = acc[ai][0][m][1], o1a = acc[ai][1][m][0], o1b = acc[ai][1][m][1];
;                 const f32x4 ra_ = dpp_swap1(odd ? o0a : o1a), rb_ = dpp_swap1(odd ? o0b : o1b);
;                 const f32x4 pa[2] = {odd ? ra_ : o0a, odd ? o1a : ra_}, pb[2] = {odd ? rb_ : o0b, odd ? o1b : rb_};
; #pragma unroll
;                 for (int q = 0; q < 2; ++q) {
;                     const u32x4 w0 = raw[2 * m + q];
;                     const f32x4 r0 = (f32x4){bf_lo(w0.x), bf_hi(w0.x), bf_lo(w0.y), bf_hi(w0.y)}, r1 = (f32x4){bf_lo(w0.z), bf_hi(w0.z), bf_lo(w0.w), bf_hi(w0.w)};
;                     f32x4 y0, y1;
;                     if (RESN) { const f32x2 t = tbl[rl + q]; const float mu = t.x, ra = t.y * ALPHA; y0 = (r0 - mu) * ra * g0 + b0 + pa[q]; y1 = (r1 - mu) * ra * g1 + b1 + pb[q]; }
;                     else { y0 = r0 * ALPHA + pa[q]; y1 = r1 * ALPHA + pb[q]; }
;                     { const u32x4 w = pack8f(y0, y1); *(u32x4*)(xb + off + q * 128) = w;
;                         y0 = (f32x4){bf_lo(w.x), bf_hi(w.x), bf_lo(w.y), bf_hi(w.y)}; y1 = (f32x4){bf_lo(w.z), bf_hi(w.z), bf_lo(w.w), bf_hi(w.w)}; }
;                     float sa = ((y0[0] + y0[1]) + (y0[2] + y0[3])) + ((y1[0] + y1[1]) + (y1[2] + y1[3]));
;                     float sb = ((y0[0] * y0[0] + y0[1] * y0[1]) + (y0[2] * y0[2] + y0[3] * y0[3])) + ((y1[0] * y1[0] + y1[1] * y1[1]) + (y1[2] * y1[2] + y1[3] * y1[3]));
;                     sa += dpp_x1(sa);
;                     sb += dpp_x1(sb);
;                     sa += __shfl_xor(sa, 16); sa += __shfl_xor(sa, 32); sb += __shfl_xor(sb, 16); sb += __shfl_xor(sb, 32);
;                     if (fq == 0 && !odd) ps[(size_t)(rl + q) * 64] = (f32x2){sa, sb};
;                 }
	v_mul_f32_e32 v150, 0x3fb504f3, v149
	v_sub_f32_e32 v153, v153, v148
	v_sub_f32_e32 v152, v152, v148
	v_pk_mul_f32 v[152:153], v[152:153], v[150:151] op_sel_hi:[1,0]
	v_sub_f32_e32 v155, v155, v148
	v_pk_fma_f32 v[152:153], v[76:77], v[152:153], v[184:185]
	v_sub_f32_e32 v154, v154, v148
	v_pk_add_f32 v[116:117], v[116:117], v[152:153]
	v_sub_f32_e32 v153, v191, v148
	v_sub_f32_e32 v152, v189, v148
	v_sub_f32_e32 v149, v151, v148
	v_sub_f32_e32 v148, v193, v148
	v_pk_mul_f32 v[154:155], v[154:155], v[150:151] op_sel_hi:[1,0]
	v_pk_mul_f32 v[148:149], v[148:149], v[150:151] op_sel_hi:[1,0]
	v_pk_mul_f32 v[150:151], v[152:153], v[150:151] op_sel_hi:[1,0]
	v_cndmask_b32_e64 v115, v127, v115, s[10:11]
	v_cndmask_b32_e64 v114, v125, v114, s[10:11]
	v_pk_fma_f32 v[154:155], v[78:79], v[154:155], v[182:183]
	v_pk_fma_f32 v[150:151], v[72:73], v[150:151], v[180:181]
	v_pk_fma_f32 v[148:149], v[74:75], v[148:149], v[178:179]
	v_pk_add_f32 v[118:119], v[118:119], v[154:155]
	v_pk_add_f32 v[114:115], v[114:115], v[148:149]
	v_pk_add_f32 v[112:113], v[112:113], v[150:151]
	v_cvt_pk_bf16_f32 v148, v116, v117
	v_cvt_pk_bf16_f32 v149, v118, v119
	v_mov_b32_e32 v193, v165
	v_cvt_pk_bf16_f32 v150, v112, v113
	v_cvt_pk_bf16_f32 v151, v114, v115
	v_lshlrev_b32_e32 v112, 16, v148
	v_and_b32_e32 v114, 0xffff0000, v148
	v_lshlrev_b32_e32 v116, 16, v149
	v_and_b32_e32 v118, 0xffff0000, v149
	v_lshlrev_b32_e32 v152, 16, v150
	v_and_b32_e32 v154, 0xffff0000, v150
	v_lshlrev_b32_e32 v194, 16, v151
	v_and_b32_e32 v196, 0xffff0000, v151
	v_mul_f32_e32 v113, v112, v112
	v_mul_f32_e32 v115, v114, v114
	v_mul_f32_e32 v117, v116, v116
	v_mul_f32_e32 v119, v118, v118
	v_mul_f32_e32 v153, v152, v152
	v_mul_f32_e32 v155, v154, v154
	v_mul_f32_e32 v195, v194, v194
	v_mul_f32_e32 v197, v196, v196
	v_pk_add_f32 v[112:113], v[112:113], v[114:115]
	v_pk_add_f32 v[114:115], v[116:117], v[118:119]
	v_pk_add_f32 v[116:117], v[194:195], v[196:197]
	v_pk_add_f32 v[112:113], v[112:113], v[114:115]
	v_pk_add_f32 v[114:115], v[152:153], v[154:155]
	s_nop 0
	v_pk_add_f32 v[114:115], v[114:115], v[116:117]
	s_nop 0
	v_pk_add_f32 v[112:113], v[112:113], v[114:115]
	v_mov_b32_e32 v114, v165
	v_mov_b32_e32 v115, v165
	s_nop 0
	v_mov_b32_dpp v114, v112 quad_perm:[1,0,3,2] row_mask:0xf bank_mask:0xf
	v_mov_b32_dpp v115, v113 quad_perm:[1,0,3,2] row_mask:0xf bank_mask:0xf
	v_pk_add_f32 v[112:113], v[112:113], v[114:115]
	v_mov_b32_e32 v114, v112
	v_mov_b32_e32 v115, v113
	s_nop 1
	v_permlane16_swap_b32_e32 v112, v114
	v_permlane16_swap_b32_e32 v113, v115
	s_waitcnt lgkmcnt(0)
	v_pk_add_f32 v[114:115], v[112:113], v[114:115]
	v_mov_b32_e32 v116, v114
	v_mov_b32_e32 v117, v115
	s_nop 1
	v_permlane32_swap_b32_e32 v114, v116
	v_permlane32_swap_b32_e32 v115, v117
	v_lshl_add_u64 v[112:113], s[20:21], 0, v[192:193]
	global_store_dwordx4 v[112:113], v[148:151], off
	s_and_saveexec_b64 s[64:65], s[16:17]
	s_waitcnt lgkmcnt(0)
	v_pk_add_f32 v[114:115], v[114:115], v[116:117]
	v_add_co_u32_e32 v116, vcc, 0x2000, v186
	s_nop 1
	v_addc_co_u32_e32 v117, vcc, 0, v187, vcc
	global_store_dwordx2 v[116:117], v[114:115], off
.LBB0_1469:
	s_or_b64 exec, exec, s[64:65]
	ds_read_b64 v[114:115], v201 offset:136
	s_waitcnt lgkmcnt(1)
	s_waitcnt vmcnt(14)
	v_lshlrev_b32_e32 v117, 16, v144
	v_and_b32_e32 v118, 0xffff0000, v144
	v_cndmask_b32_e64 v109, v109, v122, s[10:11]
	v_cndmask_b32_e64 v108, v108, v120, s[10:11]
	s_waitcnt lgkmcnt(0)
	v_mul_f32_e32 v116, 0x3fb504f3, v115
	v_sub_f32_e32 v119, v118, v114
	v_sub_f32_e32 v118, v117, v114
	v_pk_mul_f32 v[118:119], v[118:119], v[116:117] op_sel_hi:[1,0]
	v_cndmask_b32_e64 v111, v111, v123, s[10:11]
	v_cndmask_b32_e64 v110, v110, v121, s[10:11]
	v_cndmask_b32_e64 v104, v104, v124, s[10:11]
	v_cndmask_b32_e64 v106, v106, v125, s[10:11]
	v_lshlrev_b32_e32 v120, 16, v145
	v_and_b32_e32 v121, 0xffff0000, v145
	v_lshlrev_b32_e32 v122, 16, v146
	v_and_b32_e32 v123, 0xffff0000, v146
	v_lshlrev_b32_e32 v124, 16, v147
	v_and_b32_e32 v125, 0xffff0000, v147
	v_pk_fma_f32 v[118:119], v[76:77], v[118:119], v[184:185]
	v_sub_f32_e32 v121, v121, v114
	v_sub_f32_e32 v120, v120, v114
	v_pk_add_f32 v[108:109], v[108:109], v[118:119]
	v_sub_f32_e32 v119, v123, v114
	v_sub_f32_e32 v118, v122, v114
	v_sub_f32_e32 v115, v125, v114
	v_sub_f32_e32 v114, v124, v114
	v_pk_mul_f32 v[120:121], v[120:121], v[116:117] op_sel_hi:[1,0]
	v_pk_mul_f32 v[114:115], v[114:115], v[116:117] op_sel_hi:[1,0]
	v_pk_mul_f32 v[116:117], v[118:119], v[116:117] op_sel_hi:[1,0]
	v_cndmask_b32_e64 v105, v105, v126, s[10:11]
	v_cndmask_b32_e64 v107, v107, v127, s[10:11]
	v_pk_fma_f32 v[120:121], v[78:79], v[120:121], v[182:183]
	v_pk_fma_f32 v[116:117], v[72:73], v[116:117], v[180:181]
	v_pk_fma_f32 v[114:115], v[74:75], v[114:115], v[178:179]
	v_pk_add_f32 v[110:111], v[110:111], v[120:121]
	v_pk_add_f32 v[106:107], v[106:107], v[114:115]
	v_pk_add_f32 v[104:105], v[104:105], v[116:117]
	v_cvt_pk_bf16_f32 v108, v108, v109
	v_cvt_pk_bf16_f32 v109, v110, v111
	s_nop 0
	v_cvt_pk_bf16_f32 v110, v104, v105
	v_cvt_pk_bf16_f32 v111, v106, v107
	v_lshlrev_b32_e32 v104, 16, v108
	v_and_b32_e32 v106, 0xffff0000, v108
	v_lshlrev_b32_e32 v114, 16, v109
	v_and_b32_e32 v116, 0xffff0000, v109
	v_lshlrev_b32_e32 v118, 16, v110
	v_and_b32_e32 v120, 0xffff0000, v110
	v_lshlrev_b32_e32 v122, 16, v111
	v_and_b32_e32 v124, 0xffff0000, v111
	v_mul_f32_e32 v105, v104, v104
	v_mul_f32_e32 v107, v106, v106
	v_mul_f32_e32 v115, v114, v114
	v_mul_f32_e32 v117, v116, v116
	v_mul_f32_e32 v119, v118, v118
	v_mul_f32_e32 v121, v120, v120
	v_mul_f32_e32 v123, v122, v122
	v_mul_f32_e32 v125, v124, v124
	v_pk_add_f32 v[104:105], v[104:105], v[106:107]
	v_pk_add_f32 v[106:107], v[114:115], v[116:117]
	v_pk_add_f32 v[114:115], v[122:123], v[124:125]
	v_pk_add_f32 v[104:105], v[104:105], v[106:107]
	v_pk_add_f32 v[106:107], v[118:119], v[120:121]
	global_store_dwordx4 v[112:113], v[108:111], off offset:128
	v_pk_add_f32 v[106:107], v[106:107], v[114:115]
	s_nop 0
	v_pk_add_f32 v[104:105], v[104:105], v[106:107]
	v_mov_b32_e32 v106, v165
	v_mov_b32_e32 v107, v165
	s_nop 0
	v_mov_b32_dpp v106, v104 quad_perm:[1,0,3,2] row_mask:0xf bank_mask:0xf
	v_mov_b32_dpp v107, v105 quad_perm:[1,0,3,2] row_mask:0xf bank_mask:0xf
	v_pk_add_f32 v[104:105], v[104:105], v[106:107]
	v_mov_b32_e32 v106, v104
	v_mov_b32_e32 v107, v105
	s_nop 1
	v_permlane16_swap_b32_e32 v104, v106
	v_permlane16_swap_b32_e32 v105, v107
	s_waitcnt lgkmcnt(0)
	v_pk_add_f32 v[104:105], v[104:105], v[106:107]
	v_mov_b32_e32 v106, v104
	v_mov_b32_e32 v107, v105
	s_nop 1
	v_permlane32_swap_b32_e32 v104, v106
	v_permlane32_swap_b32_e32 v105, v107
	s_and_saveexec_b64 s[64:65], s[16:17]
	s_waitcnt lgkmcnt(0)
	v_pk_add_f32 v[104:105], v[104:105], v[106:107]
	v_add_co_u32_e32 v106, vcc, 0x2000, v186
	s_nop 1
	v_addc_co_u32_e32 v107, vcc, 0, v187, vcc
	global_store_dwordx2 v[106:107], v[104:105], off offset:512
;     __device__ __forceinline__ void operator()(const f32x4 (&acc)[2][2][4][2], const Unit& u, int wr, int wc, int fr, int fq, const EpiCtx& X) const {
;     ...
;             for (int m = 0; m < 4; ++m) { const unsigned off = lo + (unsigned)((ai * HALF + m * 16) * 64) * 2u; raw[2 * m] = *(const u32x4*)(xb + off); raw[2 * m + 1] = *(const u32x4*)(xb + off + 128); }
; #pragma unroll
;             for (int m = 0; m < 4; ++m) {
;                 const int rl = ai * HALF + m * 16; const unsigned off = lo + (unsigned)(rl * 64) * 2u;
;                 const f32x4 o0a = acc[ai][0][m][0], o0b = acc[ai][0][m][1], o1a = acc[ai][1][m][0], o1b = acc[ai][1][m][1];
;                 const f32x4 ra_ = dpp_swap1(odd ? o0a : o1a), rb_ = dpp_swap1(odd ? o0b : o1b);
;                 const f32x4 pa[2] = {odd ? ra_ : o0a, odd ? o1a : ra_}, pb[2] = {odd ? rb_ : o0b, odd ? o1b : rb_};
; #pragma unroll
;                 for (int q = 0; q < 2; ++q) {
;                     const u32x4 w0 = raw[2 * m + q];
;                     const f32x4 r0 = (f32x4){bf_lo(w0.x), bf_hi(w0.x), bf_lo(w0.y), bf_hi(w0.y)}, r1 = (f32x4){bf_lo(w0.z), bf_hi(w0.z), bf_lo(w0.w), bf_hi(w0.w)};
;                     f32x4 y0, y1;
;                     if (RESN) { const f32x2 t = tbl[rl + q]; const float mu = t.x, ra = t.y * ALPHA; y0 = (r0 - mu) * ra * g0 + b0 + pa[q]; y1 = (r1 - mu) * ra * g1 + b1 + pb[q]; }
;                     else { y0 = r0 * ALPHA + pa[q]; y1 = r1 * ALPHA + pb[q]; }
;                     { const u32x4 w = pack8f(y0, y1); *(u32x4*)(xb + off + q * 128) = w;
;                         y0 = (f32x4){bf_lo(w.x), bf_hi(w.x), bf_lo(w.y), bf_hi(w.y)}; y1 = (f32x4){bf_lo(w.z), bf_hi(w.z), bf_lo(w.w), bf_hi(w.w)}; }
;                     float sa = ((y0[0] + y0[1]) + (y0[2] + y0[3])) + ((y1[0] + y1[1]) + (y1[2] + y1[3]));
;                     float sb = ((y0[0] * y0[0] + y0[1] * y0[1]) + (y0[2] * y0[2] + y0[3] * y0[3])) + ((y1[0] * y1[0] + y1[1] * y1[1]) + (y1[2] * y1[2] + y1[3] * y1[3]));
;                     sa += dpp_x1(sa);
;                     sb += dpp_x1(sb);
;                     sa += __shfl_xor(sa, 16); sa += __shfl_xor(sa, 32); sb += __shfl_xor(sb, 16); sb += __shfl_xor(sb, 32);
;                     if (fq == 0 && !odd) ps[(size_t)(rl + q) * 64] = (f32x2){sa, sb};
;                 }
.LBB0_1471:
	s_or_b64 exec, exec, s[64:65]
	s_waitcnt lgkmcnt(0)
	v_cndmask_b32_e64 v106, v100, v92, s[10:11]
	v_mov_b32_e32 v104, 0
	v_cndmask_b32_e64 v105, v101, v93, s[10:11]
	s_waitcnt lgkmcnt(0)
	v_cndmask_b32_e64 v107, v102, v94, s[10:11]
	v_mov_b32_dpp v104, v106 quad_perm:[1,0,3,2] row_mask:0xf bank_mask:0xf
	v_mov_b32_e32 v106, 0
	v_cndmask_b32_e64 v108, v103, v95, s[10:11]
	v_cndmask_b32_e64 v110, v96, v88, s[10:11]
	v_mov_b32_dpp v106, v105 quad_perm:[1,0,3,2] row_mask:0xf bank_mask:0xf
	v_mov_b32_e32 v105, 0
	v_cndmask_b32_e64 v109, v97, v89, s[10:11]
	v_cndmask_b32_e64 v111, v98, v90, s[10:11]
	v_mov_b32_dpp v105, v107 quad_perm:[1,0,3,2] row_mask:0xf bank_mask:0xf
	v_mov_b32_e32 v107, 0
	v_cndmask_b32_e64 v112, v99, v91, s[10:11]
	s_waitcnt vmcnt(15)
	v_lshlrev_b32_e32 v115, 16, v140
	v_mov_b32_dpp v107, v108 quad_perm:[1,0,3,2] row_mask:0xf bank_mask:0xf
	v_mov_b32_e32 v108, 0
	v_and_b32_e32 v116, 0xffff0000, v140
	v_cndmask_b32_e64 v101, v106, v101, s[10:11]
	v_mov_b32_dpp v108, v110 quad_perm:[1,0,3,2] row_mask:0xf bank_mask:0xf
	v_mov_b32_e32 v110, 0
	v_cndmask_b32_e64 v100, v104, v100, s[10:11]
	v_lshlrev_b32_e32 v118, 16, v141
	v_mov_b32_dpp v110, v109 quad_perm:[1,0,3,2] row_mask:0xf bank_mask:0xf
	v_mov_b32_e32 v109, 0
	v_and_b32_e32 v119, 0xffff0000, v141
	v_lshlrev_b32_e32 v120, 16, v142
	v_mov_b32_dpp v109, v111 quad_perm:[1,0,3,2] row_mask:0xf bank_mask:0xf
	v_mov_b32_e32 v111, 0
	v_and_b32_e32 v121, 0xffff0000, v142
	v_lshlrev_b32_e32 v122, 16, v143
	v_mov_b32_dpp v111, v112 quad_perm:[1,0,3,2] row_mask:0xf bank_mask:0xf
	ds_read_b64 v[112:113], v201 offset:256
	v_and_b32_e32 v123, 0xffff0000, v143
	v_cndmask_b32_e64 v103, v107, v103, s[10:11]
	v_cndmask_b32_e64 v102, v105, v102, s[10:11]
	v_cndmask_b32_e64 v97, v110, v97, s[10:11]
	s_waitcnt lgkmcnt(0)
	v_mul_f32_e32 v114, 0x3fb504f3, v113
	v_sub_f32_e32 v117, v116, v112
	v_sub_f32_e32 v116, v115, v112
	v_pk_mul_f32 v[116:117], v[116:117], v[114:115] op_sel_hi:[1,0]
	v_sub_f32_e32 v119, v119, v112
	v_pk_fma_f32 v[116:117], v[76:77], v[116:117], v[184:185]
	v_sub_f32_e32 v118, v118, v112
	v_pk_add_f32 v[100:101], v[100:101], v[116:117]
	v_sub_f32_e32 v117, v121, v112
	v_sub_f32_e32 v116, v120, v112
	v_sub_f32_e32 v113, v123, v112
	v_sub_f32_e32 v112, v122, v112
	v_pk_mul_f32 v[118:119], v[118:119], v[114:115] op_sel_hi:[1,0]
	v_pk_mul_f32 v[112:113], v[112:113], v[114:115] op_sel_hi:[1,0]
	v_pk_mul_f32 v[114:115], v[116:117], v[114:115] op_sel_hi:[1,0]
	v_cndmask_b32_e64 v96, v108, v96, s[10:11]
	v_cndmask_b32_e64 v99, v111, v99, s[10:11]
	v_cndmask_b32_e64 v98, v109, v98, s[10:11]
	v_pk_fma_f32 v[118:119], v[78:79], v[118:119], v[182:183]
	v_pk_fma_f32 v[114:115], v[72:73], v[114:115], v[180:181]
	v_pk_fma_f32 v[112:113], v[74:75], v[112:113], v[178:179]
	v_pk_add_f32 v[102:103], v[102:103], v[118:119]
	v_pk_add_f32 v[98:99], v[98:99], v[112:113]
	v_pk_add_f32 v[96:97], v[96:97], v[114:115]
	v_cvt_pk_bf16_f32 v112, v100, v101
	v_cvt_pk_bf16_f32 v113, v102, v103
	v_mov_b32_e32 v191, v165
	v_cvt_pk_bf16_f32 v114, v96, v97
	v_cvt_pk_bf16_f32 v115, v98, v99
	v_lshlrev_b32_e32 v96, 16, v112
	v_and_b32_e32 v98, 0xffff0000, v112
	v_lshlrev_b32_e32 v100, 16, v113
	v_and_b32_e32 v102, 0xffff0000, v113
	v_lshlrev_b32_e32 v116, 16, v114
	v_and_b32_e32 v118, 0xffff0000, v114
	v_lshlrev_b32_e32 v120, 16, v115
	v_and_b32_e32 v122, 0xffff0000, v115
	v_mul_f32_e32 v97, v96, v96
	v_mul_f32_e32 v99, v98, v98
	v_mul_f32_e32 v101, v100, v100
	v_mul_f32_e32 v103, v102, v102
	v_mul_f32_e32 v117, v116, v116
	v_mul_f32_e32 v119, v118, v118
	v_mul_f32_e32 v121, v120, v120
	v_mul_f32_e32 v123, v122, v122
	v_pk_add_f32 v[96:97], v[96:97], v[98:99]
	v_pk_add_f32 v[98:99], v[100:101], v[102:103]
	v_pk_add_f32 v[100:101], v[120:121], v[122:123]
	v_pk_add_f32 v[96:97], v[96:97], v[98:99]
	v_pk_add_f32 v[98:99], v[116:117], v[118:119]
	s_nop 0
	v_pk_add_f32 v[98:99], v[98:99], v[100:101]
	s_nop 0
	v_pk_add_f32 v[96:97], v[96:97], v[98:99]
	v_mov_b32_e32 v98, v165
	v_mov_b32_e32 v99, v165
	s_nop 0
	v_mov_b32_dpp v98, v96 quad_perm:[1,0,3,2] row_mask:0xf bank_mask:0xf
	v_mov_b32_dpp v99, v97 quad_perm:[1,0,3,2] row_mask:0xf bank_mask:0xf
	v_pk_add_f32 v[96:97], v[96:97], v[98:99]
	v_mov_b32_e32 v98, v96
	v_mov_b32_e32 v99, v97
	s_nop 1
	v_permlane16_swap_b32_e32 v96, v98
	v_permlane16_swap_b32_e32 v97, v99
	s_waitcnt lgkmcnt(0)
	v_pk_add_f32 v[98:99], v[96:97], v[98:99]
	v_mov_b32_e32 v100, v98
	v_mov_b32_e32 v101, v99
	s_nop 1
	v_permlane32_swap_b32_e32 v98, v100
	v_permlane32_swap_b32_e32 v99, v101
	v_lshl_add_u64 v[96:97], s[20:21], 0, v[190:191]
	global_store_dwordx4 v[96:97], v[112:115], off
	s_and_saveexec_b64 s[64:65], s[16:17]
	s_waitcnt lgkmcnt(0)
	v_pk_add_f32 v[98:99], v[98:99], v[100:101]
	v_add_co_u32_e32 v100, vcc, 0x4000, v186
	s_nop 1
	v_addc_co_u32_e32 v101, vcc, 0, v187, vcc
	global_store_dwordx2 v[100:101], v[98:99], off
;     __device__ __forceinline__ void operator()(const f32x4 (&acc)[2][2][4][2], const Unit& u, int wr, int wc, int fr, int fq, const EpiCtx& X) const {
;     ...
;             for (int m = 0; m < 4; ++m) { const unsigned off = lo + (unsigned)((ai * HALF + m * 16) * 64) * 2u; raw[2 * m] = *(const u32x4*)(xb + off); raw[2 * m + 1] = *(const u32x4*)(xb + off + 128); }
; #pragma unroll
;             for (int m = 0; m < 4; ++m) {
;                 const int rl = ai * HALF + m * 16; const unsigned off = lo + (unsigned)(rl * 64) * 2u;
;                 const f32x4 o0a = acc[ai][0][m][0], o0b = acc[ai][0][m][1], o1a = acc[ai][1][m][0], o1b = acc[ai][1][m][1];
;                 const f32x4 ra_ = dpp_swap1(odd ? o0a : o1a), rb_ = dpp_swap1(odd ? o0b : o1b);
;                 const f32x4 pa[2] = {odd ? ra_ : o0a, odd ? o1a : ra_}, pb[2] = {odd ? rb_ : o0b, odd ? o1b : rb_};
; #pragma unroll
;                 for (int q = 0; q < 2; ++q) {
;                     const u32x4 w0 = raw[2 * m + q];
;                     const f32x4 r0 = (f32x4){bf_lo(w0.x), bf_hi(w0.x), bf_lo(w0.y), bf_hi(w0.y)}, r1 = (f32x4){bf_lo(w0.z), bf_hi(w0.z), bf_lo(w0.w), bf_hi(w0.w)};
;                     f32x4 y0, y1;
;                     if (RESN) { const f32x2 t = tbl[rl + q]; const float mu = t.x, ra = t.y * ALPHA; y0 = (r0 - mu) * ra * g0 + b0 + pa[q]; y1 = (r1 - mu) * ra * g1 + b1 + pb[q]; }
;                     else { y0 = r0 * ALPHA + pa[q]; y1 = r1 * ALPHA + pb[q]; }
;                     { const u32x4 w = pack8f(y0, y1); *(u32x4*)(xb + off + q * 128) = w;
;                         y0 = (f32x4){bf_lo(w.x), bf_hi(w.x), bf_lo(w.y), bf_hi(w.y)}; y1 = (f32x4){bf_lo(w.z), bf_hi(w.z), bf_lo(w.w), bf_hi(w.w)}; }
;                     float sa = ((y0[0] + y0[1]) + (y0[2] + y0[3])) + ((y1[0] + y1[1]) + (y1[2] + y1[3]));
;                     float sb = ((y0[0] * y0[0] + y0[1] * y0[1]) + (y0[2] * y0[2] + y0[3] * y0[3])) + ((y1[0] * y1[0] + y1[1] * y1[1]) + (y1[2] * y1[2] + y1[3] * y1[3]));
;                     sa += dpp_x1(sa);
;                     sb += dpp_x1(sb);
;                     sa += __shfl_xor(sa, 16); sa += __shfl_xor(sa, 32); sb += __shfl_xor(sb, 16); sb += __shfl_xor(sb, 32);
;                     if (fq == 0 && !odd) ps[(size_t)(rl + q) * 64] = (f32x2){sa, sb};
;                 }
.LBB0_1473:
	s_or_b64 exec, exec, s[64:65]
	ds_read_b64 v[98:99], v201 offset:264
	s_waitcnt lgkmcnt(1)
	s_waitcnt vmcnt(16)
	v_lshlrev_b32_e32 v101, 16, v136
	v_and_b32_e32 v102, 0xffff0000, v136
	v_cndmask_b32_e64 v93, v93, v106, s[10:11]
	v_cndmask_b32_e64 v92, v92, v104, s[10:11]
	s_waitcnt lgkmcnt(0)
	v_mul_f32_e32 v100, 0x3fb504f3, v99
	v_sub_f32_e32 v103, v102, v98
	v_sub_f32_e32 v102, v101, v98
	v_pk_mul_f32 v[102:103], v[102:103], v[100:101] op_sel_hi:[1,0]
	v_cndmask_b32_e64 v95, v95, v107, s[10:11]
	v_cndmask_b32_e64 v94, v94, v105, s[10:11]
	v_cndmask_b32_e64 v88, v88, v108, s[10:11]
	v_cndmask_b32_e64 v90, v90, v109, s[10:11]
	v_lshlrev_b32_e32 v104, 16, v137
	v_and_b32_e32 v105, 0xffff0000, v137
	v_lshlrev_b32_e32 v106, 16, v138
	v_and_b32_e32 v107, 0xffff0000, v138
	v_lshlrev_b32_e32 v108, 16, v139
	v_and_b32_e32 v109, 0xffff0000, v139
	v_pk_fma_f32 v[102:103], v[76:77], v[102:103], v[184:185]
	v_sub_f32_e32 v105, v105, v98
	v_sub_f32_e32 v104, v104, v98
	v_pk_add_f32 v[92:93], v[92:93], v[102:103]
	v_sub_f32_e32 v103, v107, v98
	v_sub_f32_e32 v102, v106, v98
	v_sub_f32_e32 v99, v109, v98
	v_sub_f32_e32 v98, v108, v98
	v_pk_mul_f32 v[104:105], v[104:105], v[100:101] op_sel_hi:[1,0]
	v_pk_mul_f32 v[98:99], v[98:99], v[100:101] op_sel_hi:[1,0]
	v_pk_mul_f32 v[100:101], v[102:103], v[100:101] op_sel_hi:[1,0]
	v_cndmask_b32_e64 v89, v89, v110, s[10:11]
	v_cndmask_b32_e64 v91, v91, v111, s[10:11]
	v_pk_fma_f32 v[104:105], v[78:79], v[104:105], v[182:183]
	v_pk_fma_f32 v[100:101], v[72:73], v[100:101], v[180:181]
	v_pk_fma_f32 v[98:99], v[74:75], v[98:99], v[178:179]
	v_pk_add_f32 v[94:95], v[94:95], v[104:105]
	v_pk_add_f32 v[90:91], v[90:91], v[98:99]
	v_pk_add_f32 v[88:89], v[88:89], v[100:101]
	v_cvt_pk_bf16_f32 v92, v92, v93
	v_cvt_pk_bf16_f32 v93, v94, v95
	s_nop 0
	v_cvt_pk_bf16_f32 v94, v88, v89
	v_cvt_pk_bf16_f32 v95, v90, v91
	v_lshlrev_b32_e32 v88, 16, v92
	v_and_b32_e32 v90, 0xffff0000, v92
	v_lshlrev_b32_e32 v98, 16, v93
	v_and_b32_e32 v100, 0xffff0000, v93
	v_lshlrev_b32_e32 v102, 16, v94
	v_and_b32_e32 v104, 0xffff0000, v94
	v_lshlrev_b32_e32 v106, 16, v95
	v_and_b32_e32 v108, 0xffff0000, v95
	v_mul_f32_e32 v89, v88, v88
	v_mul_f32_e32 v91, v90, v90
	v_mul_f32_e32 v99, v98, v98
	v_mul_f32_e32 v101, v100, v100
	v_mul_f32_e32 v103, v102, v102
	v_mul_f32_e32 v105, v104, v104
	v_mul_f32_e32 v107, v106, v106
	v_mul_f32_e32 v109, v108, v108
	v_pk_add_f32 v[88:89], v[88:89], v[90:91]
	v_pk_add_f32 v[90:91], v[98:99], v[100:101]
	v_pk_add_f32 v[98:99], v[106:107], v[108:109]
	v_pk_add_f32 v[88:89], v[88:89], v[90:91]
	v_pk_add_f32 v[90:91], v[102:103], v[104:105]
	global_store_dwordx4 v[96:97], v[92:95], off offset:128
	v_pk_add_f32 v[90:91], v[90:91], v[98:99]
	s_nop 0
	v_pk_add_f32 v[88:89], v[88:89], v[90:91]
	v_mov_b32_e32 v90, v165
	v_mov_b32_e32 v91, v165
	s_nop 0
	v_mov_b32_dpp v90, v88 quad_perm:[1,0,3,2] row_mask:0xf bank_mask:0xf
	v_mov_b32_dpp v91, v89 quad_perm:[1,0,3,2] row_mask:0xf bank_mask:0xf
	v_pk_add_f32 v[88:89], v[88:89], v[90:91]
	v_mov_b32_e32 v90, v88
	v_mov_b32_e32 v91, v89
	s_nop 1
	v_permlane16_swap_b32_e32 v88, v90
	v_permlane16_swap_b32_e32 v89, v91
	s_waitcnt lgkmcnt(0)
	v_pk_add_f32 v[88:89], v[88:89], v[90:91]
	v_mov_b32_e32 v90, v88
	v_mov_b32_e32 v91, v89
	s_nop 1
	v_permlane32_swap_b32_e32 v88, v90
	v_permlane32_swap_b32_e32 v89, v91
	s_and_saveexec_b64 s[64:65], s[16:17]
	s_waitcnt lgkmcnt(0)
	v_pk_add_f32 v[88:89], v[88:89], v[90:91]
	v_add_co_u32_e32 v90, vcc, 0x4000, v186
	s_nop 1
	v_addc_co_u32_e32 v91, vcc, 0, v187, vcc
	global_store_dwordx2 v[90:91], v[88:89], off offset:512
.LBB0_1475:
	s_or_b64 exec, exec, s[64:65]
	s_waitcnt lgkmcnt(0)
	v_cndmask_b32_e64 v90, v84, v68, s[10:11]
	v_mov_b32_e32 v88, 0
	v_cndmask_b32_e64 v89, v85, v69, s[10:11]
	s_waitcnt lgkmcnt(0)
	v_cndmask_b32_e64 v91, v86, v70, s[10:11]
	v_mov_b32_dpp v88, v90 quad_perm:[1,0,3,2] row_mask:0xf bank_mask:0xf
	v_mov_b32_e32 v90, 0
	v_cndmask_b32_e64 v92, v87, v71, s[10:11]
	v_cndmask_b32_e64 v94, v80, v64, s[10:11]
	v_mov_b32_dpp v90, v89 quad_perm:[1,0,3,2] row_mask:0xf bank_mask:0xf
	v_mov_b32_e32 v89, 0
	v_cndmask_b32_e64 v93, v81, v65, s[10:11]
	v_cndmask_b32_e64 v95, v82, v66, s[10:11]
	v_mov_b32_dpp v89, v91 quad_perm:[1,0,3,2] row_mask:0xf bank_mask:0xf
	v_mov_b32_e32 v91, 0
	v_cndmask_b32_e64 v96, v83, v67, s[10:11]
	s_waitcnt vmcnt(17)
	v_lshlrev_b32_e32 v99, 16, v132
	v_mov_b32_dpp v91, v92 quad_perm:[1,0,3,2] row_mask:0xf bank_mask:0xf
	v_mov_b32_e32 v92, 0
	v_and_b32_e32 v100, 0xffff0000, v132
	v_cndmask_b32_e64 v85, v90, v85, s[10:11]
	v_mov_b32_dpp v92, v94 quad_perm:[1,0,3,2] row_mask:0xf bank_mask:0xf
	v_mov_b32_e32 v94, 0
	v_cndmask_b32_e64 v84, v88, v84, s[10:11]
	v_lshlrev_b32_e32 v102, 16, v133
	v_mov_b32_dpp v94, v93 quad_perm:[1,0,3,2] row_mask:0xf bank_mask:0xf
	v_mov_b32_e32 v93, 0
	v_and_b32_e32 v103, 0xffff0000, v133
	v_lshlrev_b32_e32 v104, 16, v134
	v_mov_b32_dpp v93, v95 quad_perm:[1,0,3,2] row_mask:0xf bank_mask:0xf
	v_mov_b32_e32 v95, 0
	v_and_b32_e32 v105, 0xffff0000, v134
	v_lshlrev_b32_e32 v106, 16, v135
	v_mov_b32_dpp v95, v96 quad_perm:[1,0,3,2] row_mask:0xf bank_mask:0xf
	ds_read_b64 v[96:97], v201 offset:384
	v_and_b32_e32 v107, 0xffff0000, v135
	v_cndmask_b32_e64 v87, v91, v87, s[10:11]
	v_cndmask_b32_e64 v86, v89, v86, s[10:11]
	v_cndmask_b32_e64 v81, v94, v81, s[10:11]
	s_waitcnt lgkmcnt(0)
; __device__ __forceinline__ u32x4 pack8f(f32x4 a, f32x4 b) { u32x4 w; w.x = cvt_pk_bf16(a[0], a[1]); w.y = cvt_pk_bf16(a[2], a[3]); w.z = cvt_pk_bf16(b[0], b[1]); w.w = cvt_pk_bf16(b[2], b[3]); return w; }
;     __device__ __forceinline__ void operator()(const f32x4 (&acc)[2][2][4][2], const Unit& u, int wr, int wc, int fr, int fq, const EpiCtx& X) const {
;     ...
;             for (int m = 0; m < 4; ++m) {
;                 const int rl = ai * HALF + m * 16; const unsigned off = lo + (unsigned)(rl * 64) * 2u;
;                 const f32x4 o0a = acc[ai][0][m][0], o0b = acc[ai][0][m][1], o1a = acc[ai][1][m][0], o1b = acc[ai][1][m][1];
;                 const f32x4 ra_ = dpp_swap1(odd ? o0a : o1a), rb_ = dpp_swap1(odd ? o0b : o1b);
;                 const f32x4 pa[2] = {odd ? ra_ : o0a, odd ? o1a : ra_}, pb[2] = {odd ? rb_ : o0b, odd ? o1b : rb_};
; #pragma unroll
;                 for (int q = 0; q < 2; ++q) {
;                     const u32x4 w0 = raw[2 * m + q];
;                     const f32x4 r0 = (f32x4){bf_lo(w0.x), bf_hi(w0.x), bf_lo(w0.y), bf_hi(w0.y)}, r1 = (f32x4){bf_lo(w0.z), bf_hi(w0.z), bf_lo(w0.w), bf_hi(w0.w)};
;                     f32x4 y0, y1;
;                     if (RESN) { const f32x2 t = tbl[rl + q]; const float mu = t.x, ra = t.y * ALPHA; y0 = (r0 - mu) * ra * g0 + b0 + pa[q]; y1 = (r1 - mu) * ra * g1 + b1 + pb[q]; }
;                     else { y0 = r0 * ALPHA + pa[q]; y1 = r1 * ALPHA + pb[q]; }
;                     { const u32x4 w = pack8f(y0, y1); *(u32x4*)(xb + off + q * 128) = w;
;                         y0 = (f32x4){bf_lo(w.x), bf_hi(w.x), bf_lo(w.y), bf_hi(w.y)}; y1 = (f32x4){bf_lo(w.z), bf_hi(w.z), bf_lo(w.w), bf_hi(w.w)}; }
;                     float sa = ((y0[0] + y0[1]) + (y0[2] + y0[3])) + ((y1[0] + y1[1]) + (y1[2] + y1[3]));
;                     float sb = ((y0[0] * y0[0] + y0[1] * y0[1]) + (y0[2] * y0[2] + y0[3] * y0[3])) + ((y1[0] * y1[0] + y1[1] * y1[1]) + (y1[2] * y1[2] + y1[3] * y1[3]));
;                     sa += dpp_x1(sa);
;                     sb += dpp_x1(sb);
;                     sa += __shfl_xor(sa, 16); sa += __shfl_xor(sa, 32); sb += __shfl_xor(sb, 16); sb += __shfl_xor(sb, 32);
;                     if (fq == 0 && !odd) ps[(size_t)(rl + q) * 64] = (f32x2){sa, sb};
;                 }
	v_mul_f32_e32 v98, 0x3fb504f3, v97
	v_sub_f32_e32 v101, v100, v96
	v_sub_f32_e32 v100, v99, v96
	v_pk_mul_f32 v[100:101], v[100:101], v[98:99] op_sel_hi:[1,0]
	v_sub_f32_e32 v103, v103, v96
	v_pk_fma_f32 v[100:101], v[76:77], v[100:101], v[184:185]
	v_sub_f32_e32 v102, v102, v96
	v_pk_add_f32 v[84:85], v[84:85], v[100:101]
	v_sub_f32_e32 v101, v105, v96
	v_sub_f32_e32 v100, v104, v96
	v_sub_f32_e32 v97, v107, v96
	v_sub_f32_e32 v96, v106, v96
	v_pk_mul_f32 v[102:103], v[102:103], v[98:99] op_sel_hi:[1,0]
	v_pk_mul_f32 v[96:97], v[96:97], v[98:99] op_sel_hi:[1,0]
	v_pk_mul_f32 v[98:99], v[100:101], v[98:99] op_sel_hi:[1,0]
	v_cndmask_b32_e64 v80, v92, v80, s[10:11]
	v_cndmask_b32_e64 v83, v95, v83, s[10:11]
	v_cndmask_b32_e64 v82, v93, v82, s[10:11]
	v_pk_fma_f32 v[102:103], v[78:79], v[102:103], v[182:183]
	v_pk_fma_f32 v[98:99], v[72:73], v[98:99], v[180:181]
	v_pk_fma_f32 v[96:97], v[74:75], v[96:97], v[178:179]
	v_pk_add_f32 v[86:87], v[86:87], v[102:103]
	v_pk_add_f32 v[82:83], v[82:83], v[96:97]
	v_pk_add_f32 v[80:81], v[80:81], v[98:99]
	v_cvt_pk_bf16_f32 v96, v84, v85
	v_cvt_pk_bf16_f32 v97, v86, v87
	v_mov_b32_e32 v189, v165
	v_cvt_pk_bf16_f32 v98, v80, v81
	v_cvt_pk_bf16_f32 v99, v82, v83
	v_lshlrev_b32_e32 v80, 16, v96
	v_and_b32_e32 v82, 0xffff0000, v96
	v_lshlrev_b32_e32 v84, 16, v97
	v_and_b32_e32 v86, 0xffff0000, v97
	v_lshlrev_b32_e32 v100, 16, v98
	v_and_b32_e32 v102, 0xffff0000, v98
	v_lshlrev_b32_e32 v104, 16, v99
	v_and_b32_e32 v106, 0xffff0000, v99
	v_mul_f32_e32 v81, v80, v80
	v_mul_f32_e32 v83, v82, v82
	v_mul_f32_e32 v85, v84, v84
	v_mul_f32_e32 v87, v86, v86
	v_mul_f32_e32 v101, v100, v100
	v_mul_f32_e32 v103, v102, v102
	v_mul_f32_e32 v105, v104, v104
	v_mul_f32_e32 v107, v106, v106
	v_pk_add_f32 v[80:81], v[80:81], v[82:83]
	v_pk_add_f32 v[82:83], v[84:85], v[86:87]
	v_pk_add_f32 v[84:85], v[104:105], v[106:107]
	v_pk_add_f32 v[80:81], v[80:81], v[82:83]
	v_pk_add_f32 v[82:83], v[100:101], v[102:103]
	s_nop 0
	v_pk_add_f32 v[82:83], v[82:83], v[84:85]
	s_nop 0
	v_pk_add_f32 v[80:81], v[80:81], v[82:83]
	v_mov_b32_e32 v82, v165
	v_mov_b32_e32 v83, v165
	s_nop 0
	v_mov_b32_dpp v82, v80 quad_perm:[1,0,3,2] row_mask:0xf bank_mask:0xf
	v_mov_b32_dpp v83, v81 quad_perm:[1,0,3,2] row_mask:0xf bank_mask:0xf
	v_pk_add_f32 v[80:81], v[80:81], v[82:83]
	v_mov_b32_e32 v82, v80
	v_mov_b32_e32 v83, v81
	s_nop 1
	v_permlane16_swap_b32_e32 v80, v82
	v_permlane16_swap_b32_e32 v81, v83
	s_waitcnt lgkmcnt(0)
	v_pk_add_f32 v[82:83], v[80:81], v[82:83]
	v_mov_b32_e32 v84, v82
	v_mov_b32_e32 v85, v83
	s_nop 1
	v_permlane32_swap_b32_e32 v82, v84
	v_permlane32_swap_b32_e32 v83, v85
	v_lshl_add_u64 v[80:81], s[20:21], 0, v[188:189]
	global_store_dwordx4 v[80:81], v[96:99], off
	s_and_saveexec_b64 s[64:65], s[16:17]
	s_waitcnt lgkmcnt(0)
	v_pk_add_f32 v[82:83], v[82:83], v[84:85]
	v_add_co_u32_e32 v84, vcc, 0x6000, v186
	s_nop 1
	v_addc_co_u32_e32 v85, vcc, 0, v187, vcc
	global_store_dwordx2 v[84:85], v[82:83], off
.LBB0_1477:
	s_or_b64 exec, exec, s[64:65]
	ds_read_b64 v[82:83], v201 offset:392
	s_waitcnt lgkmcnt(1)
	s_waitcnt vmcnt(18)
	v_lshlrev_b32_e32 v85, 16, v128
	v_and_b32_e32 v86, 0xffff0000, v128
	v_cndmask_b32_e64 v69, v69, v90, s[10:11]
	v_cndmask_b32_e64 v68, v68, v88, s[10:11]
	s_waitcnt lgkmcnt(0)
	v_mul_f32_e32 v84, 0x3fb504f3, v83
	v_sub_f32_e32 v87, v86, v82
	v_sub_f32_e32 v86, v85, v82
	v_pk_mul_f32 v[86:87], v[86:87], v[84:85] op_sel_hi:[1,0]
	v_cndmask_b32_e64 v71, v71, v91, s[10:11]
	v_cndmask_b32_e64 v70, v70, v89, s[10:11]
	v_cndmask_b32_e64 v64, v64, v92, s[10:11]
	v_cndmask_b32_e64 v66, v66, v93, s[10:11]
	v_lshlrev_b32_e32 v88, 16, v129
	v_and_b32_e32 v89, 0xffff0000, v129
	v_lshlrev_b32_e32 v90, 16, v130
	v_and_b32_e32 v91, 0xffff0000, v130
	v_lshlrev_b32_e32 v92, 16, v131
	v_and_b32_e32 v93, 0xffff0000, v131
	v_pk_fma_f32 v[86:87], v[76:77], v[86:87], v[184:185]
	v_sub_f32_e32 v89, v89, v82
	v_sub_f32_e32 v88, v88, v82
	v_pk_add_f32 v[68:69], v[68:69], v[86:87]
	v_sub_f32_e32 v87, v91, v82
	v_sub_f32_e32 v86, v90, v82
	v_sub_f32_e32 v83, v93, v82
	v_sub_f32_e32 v82, v92, v82
	v_pk_mul_f32 v[88:89], v[88:89], v[84:85] op_sel_hi:[1,0]
	v_pk_mul_f32 v[82:83], v[82:83], v[84:85] op_sel_hi:[1,0]
	v_pk_mul_f32 v[84:85], v[86:87], v[84:85] op_sel_hi:[1,0]
	v_cndmask_b32_e64 v65, v65, v94, s[10:11]
	v_cndmask_b32_e64 v67, v67, v95, s[10:11]
	v_pk_fma_f32 v[88:89], v[78:79], v[88:89], v[182:183]
	v_pk_fma_f32 v[84:85], v[72:73], v[84:85], v[180:181]
	v_pk_fma_f32 v[82:83], v[74:75], v[82:83], v[178:179]
	v_pk_add_f32 v[70:71], v[70:71], v[88:89]
	v_pk_add_f32 v[66:67], v[66:67], v[82:83]
	v_pk_add_f32 v[64:65], v[64:65], v[84:85]
	v_cvt_pk_bf16_f32 v68, v68, v69
	v_cvt_pk_bf16_f32 v69, v70, v71
	s_nop 0
	v_cvt_pk_bf16_f32 v70, v64, v65
	v_cvt_pk_bf16_f32 v71, v66, v67
	v_lshlrev_b32_e32 v64, 16, v68
	v_and_b32_e32 v66, 0xffff0000, v68
	v_lshlrev_b32_e32 v82, 16, v69
	v_and_b32_e32 v84, 0xffff0000, v69
	v_lshlrev_b32_e32 v86, 16, v70
	v_and_b32_e32 v88, 0xffff0000, v70
	v_lshlrev_b32_e32 v90, 16, v71
	v_and_b32_e32 v92, 0xffff0000, v71
	v_mul_f32_e32 v65, v64, v64
	v_mul_f32_e32 v67, v66, v66
	v_mul_f32_e32 v83, v82, v82
	v_mul_f32_e32 v85, v84, v84
	v_mul_f32_e32 v87, v86, v86
	v_mul_f32_e32 v89, v88, v88
	v_mul_f32_e32 v91, v90, v90
	v_mul_f32_e32 v93, v92, v92
	v_pk_add_f32 v[64:65], v[64:65], v[66:67]
	v_pk_add_f32 v[66:67], v[82:83], v[84:85]
	v_pk_add_f32 v[82:83], v[90:91], v[92:93]
	v_pk_add_f32 v[64:65], v[64:65], v[66:67]
	v_pk_add_f32 v[66:67], v[86:87], v[88:89]
	global_store_dwordx4 v[80:81], v[68:71], off offset:128
	v_pk_add_f32 v[66:67], v[66:67], v[82:83]
	s_nop 0
	v_pk_add_f32 v[64:65], v[64:65], v[66:67]
	v_mov_b32_e32 v66, v165
	v_mov_b32_e32 v67, v165
	s_nop 0
	v_mov_b32_dpp v66, v64 quad_perm:[1,0,3,2] row_mask:0xf bank_mask:0xf
	v_mov_b32_dpp v67, v65 quad_perm:[1,0,3,2] row_mask:0xf bank_mask:0xf
	v_pk_add_f32 v[64:65], v[64:65], v[66:67]
	v_mov_b32_e32 v66, v64
	v_mov_b32_e32 v67, v65
	s_nop 1
	v_permlane16_swap_b32_e32 v64, v66
	v_permlane16_swap_b32_e32 v65, v67
	s_waitcnt lgkmcnt(0)
	v_pk_add_f32 v[64:65], v[64:65], v[66:67]
	v_mov_b32_e32 v66, v64
	v_mov_b32_e32 v67, v65
	s_nop 1
	v_permlane32_swap_b32_e32 v64, v66
	v_permlane32_swap_b32_e32 v65, v67
	s_and_saveexec_b64 s[64:65], s[16:17]
	s_waitcnt lgkmcnt(0)
	v_pk_add_f32 v[64:65], v[64:65], v[66:67]
	v_add_co_u32_e32 v66, vcc, 0x6000, v186
	s_nop 1
	v_addc_co_u32_e32 v67, vcc, 0, v187, vcc
	global_store_dwordx2 v[66:67], v[64:65], off offset:512
;     __device__ __forceinline__ void operator()(const f32x4 (&acc)[2][2][4][2], const Unit& u, int wr, int wc, int fr, int fq, const EpiCtx& X) const {
;     ...
;         for (int ai = 0; ai < 2; ++ai) {
;             u32x4 raw[8];
; #pragma unroll
;             for (int m = 0; m < 4; ++m) { const unsigned off = lo + (unsigned)((ai * HALF + m * 16) * 64) * 2u; raw[2 * m] = *(const u32x4*)(xb + off); raw[2 * m + 1] = *(const u32x4*)(xb + off + 128); }
; #pragma unroll
;             for (int m = 0; m < 4; ++m) {
;                 const int rl = ai * HALF + m * 16; const unsigned off = lo + (unsigned)(rl * 64) * 2u;
;                 const f32x4 o0a = acc[ai][0][m][0], o0b = acc[ai][0][m][1], o1a = acc[ai][1][m][0], o1b = acc[ai][1][m][1];
;                 const f32x4 ra_ = dpp_swap1(odd ? o0a : o1a), rb_ = dpp_swap1(odd ? o0b : o1b);
;                 const f32x4 pa[2] = {odd ? ra_ : o0a, odd ? o1a : ra_}, pb[2] = {odd ? rb_ : o0b, odd ? o1b : rb_};
; #pragma unroll
;                 for (int q = 0; q < 2; ++q) {
;                     const u32x4 w0 = raw[2 * m + q];
;                     const f32x4 r0 = (f32x4){bf_lo(w0.x), bf_hi(w0.x), bf_lo(w0.y), bf_hi(w0.y)}, r1 = (f32x4){bf_lo(w0.z), bf_hi(w0.z), bf_lo(w0.w), bf_hi(w0.w)};
;                     f32x4 y0, y1;
;                     if (RESN) { const f32x2 t = tbl[rl + q]; const float mu = t.x, ra = t.y * ALPHA; y0 = (r0 - mu) * ra * g0 + b0 + pa[q]; y1 = (r1 - mu) * ra * g1 + b1 + pb[q]; }
;                     else { y0 = r0 * ALPHA + pa[q]; y1 = r1 * ALPHA + pb[q]; }
;                     { const u32x4 w = pack8f(y0, y1); *(u32x4*)(xb + off + q * 128) = w;
;                         y0 = (f32x4){bf_lo(w.x), bf_hi(w.x), bf_lo(w.y), bf_hi(w.y)}; y1 = (f32x4){bf_lo(w.z), bf_hi(w.z), bf_lo(w.w), bf_hi(w.w)}; }
;                     float sa = ((y0[0] + y0[1]) + (y0[2] + y0[3])) + ((y1[0] + y1[1]) + (y1[2] + y1[3]));
;                     float sb = ((y0[0] * y0[0] + y0[1] * y0[1]) + (y0[2] * y0[2] + y0[3] * y0[3])) + ((y1[0] * y1[0] + y1[1] * y1[1]) + (y1[2] * y1[2] + y1[3] * y1[3]));
;                     sa += dpp_x1(sa);
;                     sb += dpp_x1(sb);
;                     sa += __shfl_xor(sa, 16); sa += __shfl_xor(sa, 32); sb += __shfl_xor(sb, 16); sb += __shfl_xor(sb, 32);
;                     if (fq == 0 && !odd) ps[(size_t)(rl + q) * 64] = (f32x2){sa, sb};
;                 }
.LBB0_1479:
	s_or_b64 exec, exec, s[64:65]
	v_add_u32_e32 v104, 0x4000, v164
	s_waitcnt vmcnt(16)
	v_mov_b32_e32 v112, v230
	v_mov_b32_e32 v113, v231
	v_mov_b32_e32 v114, v232
	v_mov_b32_e32 v115, v233
	v_add_u32_e32 v102, 0x4800, v164
	v_add_u32_e32 v100, 0x5000, v164
	v_add_u32_e32 v164, 0x5800, v164
	v_mov_b32_e32 v96, v234
	v_mov_b32_e32 v97, v235
	v_mov_b32_e32 v98, v236
	v_mov_b32_e32 v99, v237
	v_mov_b32_e32 v92, v238
	v_mov_b32_e32 v93, v239
	v_mov_b32_e32 v94, v240
	v_mov_b32_e32 v95, v241
	v_mov_b32_e32 v88, v242
	v_mov_b32_e32 v89, v243
	v_mov_b32_e32 v90, v244
	v_mov_b32_e32 v91, v245
	global_load_dwordx4 v[84:87], v100, s[20:21]
	global_load_dwordx4 v[80:83], v100, s[20:21] offset:128
	global_load_dwordx4 v[68:71], v164, s[20:21]
	s_waitcnt lgkmcnt(0)
	global_load_dwordx4 v[64:67], v164, s[20:21] offset:128
	v_cndmask_b32_e64 v116, v62, v54, s[10:11]
	v_cndmask_b32_e64 v117, v61, v53, s[10:11]
	v_mov_b32_e32 v105, 0
	v_mov_b32_e32 v103, 0
	v_cndmask_b32_e64 v111, v63, v55, s[10:11]
	v_mov_b32_dpp v105, v117 quad_perm:[1,0,3,2] row_mask:0xf bank_mask:0xf
	v_mov_b32_dpp v103, v116 quad_perm:[1,0,3,2] row_mask:0xf bank_mask:0xf
	ds_read_b64 v[116:117], v201 offset:1024
	v_cndmask_b32_e64 v118, v60, v52, s[10:11]
	v_mov_b32_e32 v101, 0
	v_mov_b32_e32 v106, 0
	v_cndmask_b32_e64 v119, v59, v51, s[10:11]
	v_cndmask_b32_e64 v120, v58, v50, s[10:11]
	v_cndmask_b32_e64 v121, v57, v49, s[10:11]
	v_cndmask_b32_e64 v122, v56, v48, s[10:11]
	v_mov_b32_e32 v107, 0
	v_mov_b32_e32 v109, 0
	v_mov_b32_e32 v108, 0
	v_mov_b32_e32 v110, 0
	v_mov_b32_dpp v101, v118 quad_perm:[1,0,3,2] row_mask:0xf bank_mask:0xf
	v_mov_b32_dpp v106, v111 quad_perm:[1,0,3,2] row_mask:0xf bank_mask:0xf
	v_mov_b32_dpp v107, v122 quad_perm:[1,0,3,2] row_mask:0xf bank_mask:0xf
	v_mov_b32_dpp v109, v121 quad_perm:[1,0,3,2] row_mask:0xf bank_mask:0xf
	v_mov_b32_dpp v108, v120 quad_perm:[1,0,3,2] row_mask:0xf bank_mask:0xf
	v_mov_b32_dpp v110, v119 quad_perm:[1,0,3,2] row_mask:0xf bank_mask:0xf
	s_waitcnt lgkmcnt(0)
	v_mul_f32_e32 v118, 0x3fb504f3, v117
	v_cndmask_b32_e64 v61, v105, v61, s[10:11]
	v_cndmask_b32_e64 v60, v101, v60, s[10:11]
	v_cndmask_b32_e64 v63, v106, v63, s[10:11]
	v_cndmask_b32_e64 v62, v103, v62, s[10:11]
	v_cndmask_b32_e64 v57, v109, v57, s[10:11]
	v_cndmask_b32_e64 v56, v107, v56, s[10:11]
	v_cndmask_b32_e64 v59, v110, v59, s[10:11]
	v_cndmask_b32_e64 v58, v108, v58, s[10:11]
	v_lshlrev_b32_e32 v111, 16, v112
	v_and_b32_e32 v112, 0xffff0000, v112
	v_lshlrev_b32_e32 v117, 16, v113
	v_and_b32_e32 v119, 0xffff0000, v113
	v_lshlrev_b32_e32 v120, 16, v114
	v_and_b32_e32 v121, 0xffff0000, v114
	v_lshlrev_b32_e32 v122, 16, v115
	v_and_b32_e32 v123, 0xffff0000, v115
	v_sub_f32_e32 v113, v112, v116
	v_sub_f32_e32 v112, v111, v116
	v_sub_f32_e32 v115, v119, v116
	v_sub_f32_e32 v114, v117, v116
	v_sub_f32_e32 v121, v121, v116
	v_sub_f32_e32 v120, v120, v116
	v_sub_f32_e32 v117, v123, v116
	v_sub_f32_e32 v116, v122, v116
	v_pk_mul_f32 v[114:115], v[114:115], v[118:119] op_sel_hi:[1,0]
	v_pk_mul_f32 v[112:113], v[112:113], v[118:119] op_sel_hi:[1,0]
	v_pk_mul_f32 v[116:117], v[116:117], v[118:119] op_sel_hi:[1,0]
	v_pk_mul_f32 v[118:119], v[120:121], v[118:119] op_sel_hi:[1,0]
	v_pk_fma_f32 v[112:113], v[76:77], v[112:113], v[184:185]
	v_pk_fma_f32 v[114:115], v[78:79], v[114:115], v[182:183]
	v_pk_fma_f32 v[118:119], v[72:73], v[118:119], v[180:181]
	v_pk_fma_f32 v[116:117], v[74:75], v[116:117], v[178:179]
	v_pk_add_f32 v[62:63], v[62:63], v[114:115]
	v_pk_add_f32 v[60:61], v[60:61], v[112:113]
	v_pk_add_f32 v[58:59], v[58:59], v[116:117]
	v_pk_add_f32 v[56:57], v[56:57], v[118:119]
	v_cvt_pk_bf16_f32 v60, v60, v61
	v_cvt_pk_bf16_f32 v61, v62, v63
	s_nop 0
	v_cvt_pk_bf16_f32 v62, v56, v57
	v_cvt_pk_bf16_f32 v63, v58, v59
	v_lshlrev_b32_e32 v56, 16, v60
	v_and_b32_e32 v58, 0xffff0000, v60
	v_lshlrev_b32_e32 v112, 16, v61
	v_and_b32_e32 v114, 0xffff0000, v61
	v_lshlrev_b32_e32 v116, 16, v62
	v_and_b32_e32 v118, 0xffff0000, v62
	v_lshlrev_b32_e32 v120, 16, v63
	v_and_b32_e32 v122, 0xffff0000, v63
	v_mul_f32_e32 v57, v56, v56
	v_mul_f32_e32 v59, v58, v58
	v_mul_f32_e32 v113, v112, v112
	v_mul_f32_e32 v115, v114, v114
	v_mul_f32_e32 v117, v116, v116
	v_mul_f32_e32 v119, v118, v118
	v_mul_f32_e32 v121, v120, v120
	v_mul_f32_e32 v123, v122, v122
	v_pk_add_f32 v[56:57], v[56:57], v[58:59]
	v_pk_add_f32 v[58:59], v[112:113], v[114:115]
	v_pk_add_f32 v[112:113], v[120:121], v[122:123]
	v_pk_add_f32 v[56:57], v[56:57], v[58:59]
	v_pk_add_f32 v[58:59], v[116:117], v[118:119]
	global_store_dwordx4 v104, v[60:63], s[20:21]
	v_pk_add_f32 v[58:59], v[58:59], v[112:113]
	s_nop 0
	v_pk_add_f32 v[56:57], v[56:57], v[58:59]
	v_mov_b32_e32 v58, v165
	v_mov_b32_e32 v59, v165
	s_nop 0
	v_mov_b32_dpp v58, v56 quad_perm:[1,0,3,2] row_mask:0xf bank_mask:0xf
	v_mov_b32_dpp v59, v57 quad_perm:[1,0,3,2] row_mask:0xf bank_mask:0xf
	v_pk_add_f32 v[56:57], v[56:57], v[58:59]
	v_mov_b32_e32 v58, v56
	v_mov_b32_e32 v59, v57
	s_nop 1
	v_permlane16_swap_b32_e32 v56, v58
	v_permlane16_swap_b32_e32 v57, v59
	s_waitcnt lgkmcnt(0)
	v_pk_add_f32 v[56:57], v[56:57], v[58:59]
	v_mov_b32_e32 v58, v56
	v_mov_b32_e32 v59, v57
	s_nop 1
	v_permlane32_swap_b32_e32 v56, v58
	v_permlane32_swap_b32_e32 v57, v59
	s_and_saveexec_b64 s[64:65], s[16:17]
	s_cbranch_execz .LBB0_1481
	s_waitcnt lgkmcnt(0)
	v_pk_add_f32 v[56:57], v[56:57], v[58:59]
	v_add_co_u32_e32 v58, vcc, 0x10000, v186
	s_nop 1
	v_addc_co_u32_e32 v59, vcc, 0, v187, vcc
	global_store_dwordx2 v[58:59], v[56:57], off
; __device__ __forceinline__ u32x4 pack8f(f32x4 a, f32x4 b) { u32x4 w; w.x = cvt_pk_bf16(a[0], a[1]); w.y = cvt_pk_bf16(a[2], a[3]); w.z = cvt_pk_bf16(b[0], b[1]); w.w = cvt_pk_bf16(b[2], b[3]); return w; }
;     __device__ __forceinline__ void operator()(const f32x4 (&acc)[2][2][4][2], const Unit& u, int wr, int wc, int fr, int fq, const EpiCtx& X) const {
;     ...
;             for (int m = 0; m < 4; ++m) {
;                 const int rl = ai * HALF + m * 16; const unsigned off = lo + (unsigned)(rl * 64) * 2u;
;                 const f32x4 o0a = acc[ai][0][m][0], o0b = acc[ai][0][m][1], o1a = acc[ai][1][m][0], o1b = acc[ai][1][m][1];
;                 const f32x4 ra_ = dpp_swap1(odd ? o0a : o1a), rb_ = dpp_swap1(odd ? o0b : o1b);
;                 const f32x4 pa[2] = {odd ? ra_ : o0a, odd ? o1a : ra_}, pb[2] = {odd ? rb_ : o0b, odd ? o1b : rb_};
; #pragma unroll
;                 for (int q = 0; q < 2; ++q) {
;                     const u32x4 w0 = raw[2 * m + q];
;                     const f32x4 r0 = (f32x4){bf_lo(w0.x), bf_hi(w0.x), bf_lo(w0.y), bf_hi(w0.y)}, r1 = (f32x4){bf_lo(w0.z), bf_hi(w0.z), bf_lo(w0.w), bf_hi(w0.w)};
;                     f32x4 y0, y1;
;                     if (RESN) { const f32x2 t = tbl[rl + q]; const float mu = t.x, ra = t.y * ALPHA; y0 = (r0 - mu) * ra * g0 + b0 + pa[q]; y1 = (r1 - mu) * ra * g1 + b1 + pb[q]; }
;                     else { y0 = r0 * ALPHA + pa[q]; y1 = r1 * ALPHA + pb[q]; }
;                     { const u32x4 w = pack8f(y0, y1); *(u32x4*)(xb + off + q * 128) = w;
;                         y0 = (f32x4){bf_lo(w.x), bf_hi(w.x), bf_lo(w.y), bf_hi(w.y)}; y1 = (f32x4){bf_lo(w.z), bf_hi(w.z), bf_lo(w.w), bf_hi(w.w)}; }
;                     float sa = ((y0[0] + y0[1]) + (y0[2] + y0[3])) + ((y1[0] + y1[1]) + (y1[2] + y1[3]));
;                     float sb = ((y0[0] * y0[0] + y0[1] * y0[1]) + (y0[2] * y0[2] + y0[3] * y0[3])) + ((y1[0] * y1[0] + y1[1] * y1[1]) + (y1[2] * y1[2] + y1[3] * y1[3]));
;                     sa += dpp_x1(sa);
;                     sb += dpp_x1(sb);
;                     sa += __shfl_xor(sa, 16); sa += __shfl_xor(sa, 32); sb += __shfl_xor(sb, 16); sb += __shfl_xor(sb, 32);
;                     if (fq == 0 && !odd) ps[(size_t)(rl + q) * 64] = (f32x2){sa, sb};
;                 }
.LBB0_1481:
	s_or_b64 exec, exec, s[64:65]
	ds_read_b64 v[56:57], v201 offset:1032
	s_waitcnt lgkmcnt(1)
	v_lshlrev_b32_e32 v59, 16, v96
	v_and_b32_e32 v60, 0xffff0000, v96
	v_cndmask_b32_e64 v53, v53, v105, s[10:11]
	v_cndmask_b32_e64 v52, v52, v101, s[10:11]
	s_waitcnt lgkmcnt(0)
	v_mul_f32_e32 v58, 0x3fb504f3, v57
	v_sub_f32_e32 v61, v60, v56
	v_sub_f32_e32 v60, v59, v56
	v_pk_mul_f32 v[60:61], v[60:61], v[58:59] op_sel_hi:[1,0]
	v_lshlrev_b32_e32 v62, 16, v97
	v_and_b32_e32 v63, 0xffff0000, v97
	v_lshlrev_b32_e32 v96, 16, v98
	v_and_b32_e32 v97, 0xffff0000, v98
	v_lshlrev_b32_e32 v98, 16, v99
	v_and_b32_e32 v99, 0xffff0000, v99
	v_pk_fma_f32 v[60:61], v[76:77], v[60:61], v[184:185]
	v_sub_f32_e32 v63, v63, v56
	v_sub_f32_e32 v62, v62, v56
	v_pk_add_f32 v[52:53], v[52:53], v[60:61]
	v_sub_f32_e32 v61, v97, v56
	v_sub_f32_e32 v60, v96, v56
	v_sub_f32_e32 v57, v99, v56
	v_sub_f32_e32 v56, v98, v56
	v_pk_mul_f32 v[62:63], v[62:63], v[58:59] op_sel_hi:[1,0]
	v_pk_mul_f32 v[56:57], v[56:57], v[58:59] op_sel_hi:[1,0]
	v_pk_mul_f32 v[58:59], v[60:61], v[58:59] op_sel_hi:[1,0]
	v_cndmask_b32_e64 v55, v55, v106, s[10:11]
	v_cndmask_b32_e64 v54, v54, v103, s[10:11]
	v_cndmask_b32_e64 v49, v49, v109, s[10:11]
	v_cndmask_b32_e64 v48, v48, v107, s[10:11]
	v_cndmask_b32_e64 v51, v51, v110, s[10:11]
	v_cndmask_b32_e64 v50, v50, v108, s[10:11]
	v_pk_fma_f32 v[62:63], v[78:79], v[62:63], v[182:183]
	v_pk_fma_f32 v[58:59], v[72:73], v[58:59], v[180:181]
	v_pk_fma_f32 v[56:57], v[74:75], v[56:57], v[178:179]
	v_pk_add_f32 v[54:55], v[54:55], v[62:63]
	v_pk_add_f32 v[50:51], v[50:51], v[56:57]
	v_pk_add_f32 v[48:49], v[48:49], v[58:59]
	v_cvt_pk_bf16_f32 v52, v52, v53
	v_cvt_pk_bf16_f32 v53, v54, v55
	v_mov_b32_e32 v105, v165
	v_cvt_pk_bf16_f32 v54, v48, v49
	v_cvt_pk_bf16_f32 v55, v50, v51
	v_lshlrev_b32_e32 v48, 16, v52
	v_and_b32_e32 v50, 0xffff0000, v52
	v_lshlrev_b32_e32 v56, 16, v53
	v_and_b32_e32 v58, 0xffff0000, v53
	v_lshlrev_b32_e32 v60, 16, v54
	v_and_b32_e32 v62, 0xffff0000, v54
	v_lshlrev_b32_e32 v96, 16, v55
	v_and_b32_e32 v98, 0xffff0000, v55
	v_mul_f32_e32 v49, v48, v48
	v_mul_f32_e32 v51, v50, v50
	v_mul_f32_e32 v57, v56, v56
	v_mul_f32_e32 v59, v58, v58
	v_mul_f32_e32 v61, v60, v60
	v_mul_f32_e32 v63, v62, v62
	v_mul_f32_e32 v97, v96, v96
	v_mul_f32_e32 v99, v98, v98
	v_pk_add_f32 v[48:49], v[48:49], v[50:51]
	v_pk_add_f32 v[50:51], v[56:57], v[58:59]
	v_pk_add_f32 v[56:57], v[96:97], v[98:99]
	v_pk_add_f32 v[48:49], v[48:49], v[50:51]
	v_pk_add_f32 v[50:51], v[60:61], v[62:63]
	s_nop 0
	v_pk_add_f32 v[50:51], v[50:51], v[56:57]
	v_lshl_add_u64 v[56:57], s[20:21], 0, v[104:105]
	v_pk_add_f32 v[48:49], v[48:49], v[50:51]
	v_mov_b32_e32 v50, v165
	v_mov_b32_e32 v51, v165
	global_store_dwordx4 v[56:57], v[52:55], off offset:128
	v_mov_b32_dpp v50, v48 quad_perm:[1,0,3,2] row_mask:0xf bank_mask:0xf
	v_mov_b32_dpp v51, v49 quad_perm:[1,0,3,2] row_mask:0xf bank_mask:0xf
	v_pk_add_f32 v[48:49], v[48:49], v[50:51]
	v_mov_b32_e32 v50, v48
	v_mov_b32_e32 v51, v49
	s_nop 1
	v_permlane16_swap_b32_e32 v48, v50
	v_permlane16_swap_b32_e32 v49, v51
	s_waitcnt lgkmcnt(0)
	v_pk_add_f32 v[48:49], v[48:49], v[50:51]
	v_mov_b32_e32 v50, v48
	v_mov_b32_e32 v51, v49
	s_nop 1
	v_permlane32_swap_b32_e32 v48, v50
	v_permlane32_swap_b32_e32 v49, v51
	s_and_saveexec_b64 s[64:65], s[16:17]
	s_cbranch_execz .LBB0_1483
	s_waitcnt lgkmcnt(0)
	v_pk_add_f32 v[48:49], v[48:49], v[50:51]
	v_add_co_u32_e32 v50, vcc, 0x10000, v186
	s_nop 1
	v_addc_co_u32_e32 v51, vcc, 0, v187, vcc
	global_store_dwordx2 v[50:51], v[48:49], off offset:512
.LBB0_1483:
	s_or_b64 exec, exec, s[64:65]
	s_waitcnt lgkmcnt(0)
	v_cndmask_b32_e64 v50, v44, v36, s[10:11]
	v_mov_b32_e32 v48, 0
	v_cndmask_b32_e64 v49, v45, v37, s[10:11]
	s_waitcnt lgkmcnt(0)
	v_cndmask_b32_e64 v51, v46, v38, s[10:11]
	v_mov_b32_dpp v48, v50 quad_perm:[1,0,3,2] row_mask:0xf bank_mask:0xf
	v_mov_b32_e32 v50, 0
	v_cndmask_b32_e64 v52, v47, v39, s[10:11]
	v_cndmask_b32_e64 v54, v40, v32, s[10:11]
	v_mov_b32_dpp v50, v49 quad_perm:[1,0,3,2] row_mask:0xf bank_mask:0xf
	v_mov_b32_e32 v49, 0
	v_cndmask_b32_e64 v53, v41, v33, s[10:11]
	v_cndmask_b32_e64 v55, v42, v34, s[10:11]
	v_mov_b32_dpp v49, v51 quad_perm:[1,0,3,2] row_mask:0xf bank_mask:0xf
	v_mov_b32_e32 v51, 0
	v_cndmask_b32_e64 v56, v43, v35, s[10:11]
	v_lshlrev_b32_e32 v59, 16, v92
	v_mov_b32_dpp v51, v52 quad_perm:[1,0,3,2] row_mask:0xf bank_mask:0xf
	v_mov_b32_e32 v52, 0
	v_and_b32_e32 v60, 0xffff0000, v92
	v_cndmask_b32_e64 v45, v50, v45, s[10:11]
	v_mov_b32_dpp v52, v54 quad_perm:[1,0,3,2] row_mask:0xf bank_mask:0xf
	v_mov_b32_e32 v54, 0
	v_cndmask_b32_e64 v44, v48, v44, s[10:11]
	v_lshlrev_b32_e32 v62, 16, v93
	v_mov_b32_dpp v54, v53 quad_perm:[1,0,3,2] row_mask:0xf bank_mask:0xf
	v_mov_b32_e32 v53, 0
	v_and_b32_e32 v63, 0xffff0000, v93
	v_lshlrev_b32_e32 v92, 16, v94
	v_mov_b32_dpp v53, v55 quad_perm:[1,0,3,2] row_mask:0xf bank_mask:0xf
	v_mov_b32_e32 v55, 0
	v_and_b32_e32 v93, 0xffff0000, v94
	v_lshlrev_b32_e32 v94, 16, v95
	v_mov_b32_dpp v55, v56 quad_perm:[1,0,3,2] row_mask:0xf bank_mask:0xf
	ds_read_b64 v[56:57], v201 offset:1152
	v_and_b32_e32 v95, 0xffff0000, v95
	v_cndmask_b32_e64 v47, v51, v47, s[10:11]
	v_cndmask_b32_e64 v46, v49, v46, s[10:11]
	v_cndmask_b32_e64 v41, v54, v41, s[10:11]
	s_waitcnt lgkmcnt(0)
; __device__ __forceinline__ u32x4 pack8f(f32x4 a, f32x4 b) { u32x4 w; w.x = cvt_pk_bf16(a[0], a[1]); w.y = cvt_pk_bf16(a[2], a[3]); w.z = cvt_pk_bf16(b[0], b[1]); w.w = cvt_pk_bf16(b[2], b[3]); return w; }
;     __device__ __forceinline__ void operator()(const f32x4 (&acc)[2][2][4][2], const Unit& u, int wr, int wc, int fr, int fq, const EpiCtx& X) const {
;     ...
;             for (int m = 0; m < 4; ++m) {
;                 const int rl = ai * HALF + m * 16; const unsigned off = lo + (unsigned)(rl * 64) * 2u;
;                 const f32x4 o0a = acc[ai][0][m][0], o0b = acc[ai][0][m][1], o1a = acc[ai][1][m][0], o1b = acc[ai][1][m][1];
;                 const f32x4 ra_ = dpp_swap1(odd ? o0a : o1a), rb_ = dpp_swap1(odd ? o0b : o1b);
;                 const f32x4 pa[2] = {odd ? ra_ : o0a, odd ? o1a : ra_}, pb[2] = {odd ? rb_ : o0b, odd ? o1b : rb_};
; #pragma unroll
;                 for (int q = 0; q < 2; ++q) {
;                     const u32x4 w0 = raw[2 * m + q];
;                     const f32x4 r0 = (f32x4){bf_lo(w0.x), bf_hi(w0.x), bf_lo(w0.y), bf_hi(w0.y)}, r1 = (f32x4){bf_lo(w0.z), bf_hi(w0.z), bf_lo(w0.w), bf_hi(w0.w)};
;                     f32x4 y0, y1;
;                     if (RESN) { const f32x2 t = tbl[rl + q]; const float mu = t.x, ra = t.y * ALPHA; y0 = (r0 - mu) * ra * g0 + b0 + pa[q]; y1 = (r1 - mu) * ra * g1 + b1 + pb[q]; }
;                     else { y0 = r0 * ALPHA + pa[q]; y1 = r1 * ALPHA + pb[q]; }
;                     { const u32x4 w = pack8f(y0, y1); *(u32x4*)(xb + off + q * 128) = w;
;                         y0 = (f32x4){bf_lo(w.x), bf_hi(w.x), bf_lo(w.y), bf_hi(w.y)}; y1 = (f32x4){bf_lo(w.z), bf_hi(w.z), bf_lo(w.w), bf_hi(w.w)}; }
;                     float sa = ((y0[0] + y0[1]) + (y0[2] + y0[3])) + ((y1[0] + y1[1]) + (y1[2] + y1[3]));
;                     float sb = ((y0[0] * y0[0] + y0[1] * y0[1]) + (y0[2] * y0[2] + y0[3] * y0[3])) + ((y1[0] * y1[0] + y1[1] * y1[1]) + (y1[2] * y1[2] + y1[3] * y1[3]));
;                     sa += dpp_x1(sa);
;                     sb += dpp_x1(sb);
;                     sa += __shfl_xor(sa, 16); sa += __shfl_xor(sa, 32); sb += __shfl_xor(sb, 16); sb += __shfl_xor(sb, 32);
;                     if (fq == 0 && !odd) ps[(size_t)(rl + q) * 64] = (f32x2){sa, sb};
;                 }
	v_mul_f32_e32 v58, 0x3fb504f3, v57
	v_sub_f32_e32 v61, v60, v56
	v_sub_f32_e32 v60, v59, v56
	v_pk_mul_f32 v[60:61], v[60:61], v[58:59] op_sel_hi:[1,0]
	v_sub_f32_e32 v63, v63, v56
	v_pk_fma_f32 v[60:61], v[76:77], v[60:61], v[184:185]
	v_sub_f32_e32 v62, v62, v56
	v_pk_add_f32 v[44:45], v[44:45], v[60:61]
	v_sub_f32_e32 v61, v93, v56
	v_sub_f32_e32 v60, v92, v56
	v_sub_f32_e32 v57, v95, v56
	v_sub_f32_e32 v56, v94, v56
	v_pk_mul_f32 v[62:63], v[62:63], v[58:59] op_sel_hi:[1,0]
	v_pk_mul_f32 v[56:57], v[56:57], v[58:59] op_sel_hi:[1,0]
	v_pk_mul_f32 v[58:59], v[60:61], v[58:59] op_sel_hi:[1,0]
	v_cndmask_b32_e64 v40, v52, v40, s[10:11]
	v_cndmask_b32_e64 v43, v55, v43, s[10:11]
	v_cndmask_b32_e64 v42, v53, v42, s[10:11]
	v_pk_fma_f32 v[62:63], v[78:79], v[62:63], v[182:183]
	v_pk_fma_f32 v[58:59], v[72:73], v[58:59], v[180:181]
	v_pk_fma_f32 v[56:57], v[74:75], v[56:57], v[178:179]
	v_pk_add_f32 v[46:47], v[46:47], v[62:63]
	v_pk_add_f32 v[42:43], v[42:43], v[56:57]
	v_pk_add_f32 v[40:41], v[40:41], v[58:59]
	v_cvt_pk_bf16_f32 v56, v44, v45
	v_cvt_pk_bf16_f32 v57, v46, v47
	v_mov_b32_e32 v103, v165
	v_cvt_pk_bf16_f32 v58, v40, v41
	v_cvt_pk_bf16_f32 v59, v42, v43
	v_lshlrev_b32_e32 v40, 16, v56
	v_and_b32_e32 v42, 0xffff0000, v56
	v_lshlrev_b32_e32 v44, 16, v57
	v_and_b32_e32 v46, 0xffff0000, v57
	v_lshlrev_b32_e32 v60, 16, v58
	v_and_b32_e32 v62, 0xffff0000, v58
	v_lshlrev_b32_e32 v92, 16, v59
	v_and_b32_e32 v94, 0xffff0000, v59
	v_mul_f32_e32 v41, v40, v40
	v_mul_f32_e32 v43, v42, v42
	v_mul_f32_e32 v45, v44, v44
	v_mul_f32_e32 v47, v46, v46
	v_mul_f32_e32 v61, v60, v60
	v_mul_f32_e32 v63, v62, v62
	v_mul_f32_e32 v93, v92, v92
	v_mul_f32_e32 v95, v94, v94
	v_pk_add_f32 v[40:41], v[40:41], v[42:43]
	v_pk_add_f32 v[42:43], v[44:45], v[46:47]
	v_pk_add_f32 v[44:45], v[92:93], v[94:95]
	v_pk_add_f32 v[40:41], v[40:41], v[42:43]
	v_pk_add_f32 v[42:43], v[60:61], v[62:63]
	s_nop 0
	v_pk_add_f32 v[42:43], v[42:43], v[44:45]
	s_nop 0
	v_pk_add_f32 v[40:41], v[40:41], v[42:43]
	v_mov_b32_e32 v42, v165
	v_mov_b32_e32 v43, v165
	s_nop 0
	v_mov_b32_dpp v42, v40 quad_perm:[1,0,3,2] row_mask:0xf bank_mask:0xf
	v_mov_b32_dpp v43, v41 quad_perm:[1,0,3,2] row_mask:0xf bank_mask:0xf
	v_pk_add_f32 v[40:41], v[40:41], v[42:43]
	v_mov_b32_e32 v42, v40
	v_mov_b32_e32 v43, v41
	s_nop 1
	v_permlane16_swap_b32_e32 v40, v42
	v_permlane16_swap_b32_e32 v41, v43
	s_waitcnt lgkmcnt(0)
	v_pk_add_f32 v[42:43], v[40:41], v[42:43]
	v_mov_b32_e32 v44, v42
	v_mov_b32_e32 v45, v43
	s_nop 1
	v_permlane32_swap_b32_e32 v42, v44
	v_permlane32_swap_b32_e32 v43, v45
	v_lshl_add_u64 v[40:41], s[20:21], 0, v[102:103]
	global_store_dwordx4 v[40:41], v[56:59], off
	s_and_saveexec_b64 s[64:65], s[16:17]
	s_cbranch_execz .LBB0_1485
	s_waitcnt lgkmcnt(0)
	v_pk_add_f32 v[42:43], v[42:43], v[44:45]
	v_add_co_u32_e32 v44, vcc, 0x12000, v186
	s_nop 1
	v_addc_co_u32_e32 v45, vcc, 0, v187, vcc
	global_store_dwordx2 v[44:45], v[42:43], off
.LBB0_1485:
	s_or_b64 exec, exec, s[64:65]
	ds_read_b64 v[42:43], v201 offset:1160
	s_waitcnt lgkmcnt(1)
	v_lshlrev_b32_e32 v45, 16, v88
	v_and_b32_e32 v46, 0xffff0000, v88
	v_cndmask_b32_e64 v37, v37, v50, s[10:11]
	v_cndmask_b32_e64 v36, v36, v48, s[10:11]
	s_waitcnt lgkmcnt(0)
	v_mul_f32_e32 v44, 0x3fb504f3, v43
	v_sub_f32_e32 v47, v46, v42
	v_sub_f32_e32 v46, v45, v42
	v_pk_mul_f32 v[46:47], v[46:47], v[44:45] op_sel_hi:[1,0]
	v_cndmask_b32_e64 v39, v39, v51, s[10:11]
	v_cndmask_b32_e64 v38, v38, v49, s[10:11]
	v_cndmask_b32_e64 v32, v32, v52, s[10:11]
	v_cndmask_b32_e64 v34, v34, v53, s[10:11]
	v_lshlrev_b32_e32 v48, 16, v89
	v_and_b32_e32 v49, 0xffff0000, v89
	v_lshlrev_b32_e32 v50, 16, v90
	v_and_b32_e32 v51, 0xffff0000, v90
	v_lshlrev_b32_e32 v52, 16, v91
	v_and_b32_e32 v53, 0xffff0000, v91
	v_pk_fma_f32 v[46:47], v[76:77], v[46:47], v[184:185]
	v_sub_f32_e32 v49, v49, v42
	v_sub_f32_e32 v48, v48, v42
	v_pk_add_f32 v[36:37], v[36:37], v[46:47]
	v_sub_f32_e32 v47, v51, v42
	v_sub_f32_e32 v46, v50, v42
	v_sub_f32_e32 v43, v53, v42
	v_sub_f32_e32 v42, v52, v42
	v_pk_mul_f32 v[48:49], v[48:49], v[44:45] op_sel_hi:[1,0]
	v_pk_mul_f32 v[42:43], v[42:43], v[44:45] op_sel_hi:[1,0]
	v_pk_mul_f32 v[44:45], v[46:47], v[44:45] op_sel_hi:[1,0]
	v_cndmask_b32_e64 v33, v33, v54, s[10:11]
	v_cndmask_b32_e64 v35, v35, v55, s[10:11]
	v_pk_fma_f32 v[48:49], v[78:79], v[48:49], v[182:183]
	v_pk_fma_f32 v[44:45], v[72:73], v[44:45], v[180:181]
	v_pk_fma_f32 v[42:43], v[74:75], v[42:43], v[178:179]
	v_pk_add_f32 v[38:39], v[38:39], v[48:49]
	v_pk_add_f32 v[34:35], v[34:35], v[42:43]
	v_pk_add_f32 v[32:33], v[32:33], v[44:45]
	v_cvt_pk_bf16_f32 v36, v36, v37
	v_cvt_pk_bf16_f32 v37, v38, v39
	s_nop 0
	v_cvt_pk_bf16_f32 v38, v32, v33
	v_cvt_pk_bf16_f32 v39, v34, v35
	v_lshlrev_b32_e32 v32, 16, v36
	v_and_b32_e32 v34, 0xffff0000, v36
	v_lshlrev_b32_e32 v42, 16, v37
	v_and_b32_e32 v44, 0xffff0000, v37
	v_lshlrev_b32_e32 v46, 16, v38
	v_and_b32_e32 v48, 0xffff0000, v38
	v_lshlrev_b32_e32 v50, 16, v39
	v_and_b32_e32 v52, 0xffff0000, v39
	v_mul_f32_e32 v33, v32, v32
	v_mul_f32_e32 v35, v34, v34
	v_mul_f32_e32 v43, v42, v42
	v_mul_f32_e32 v45, v44, v44
	v_mul_f32_e32 v47, v46, v46
	v_mul_f32_e32 v49, v48, v48
	v_mul_f32_e32 v51, v50, v50
	v_mul_f32_e32 v53, v52, v52
	v_pk_add_f32 v[32:33], v[32:33], v[34:35]
	v_pk_add_f32 v[34:35], v[42:43], v[44:45]
	v_pk_add_f32 v[42:43], v[50:51], v[52:53]
	v_pk_add_f32 v[32:33], v[32:33], v[34:35]
	v_pk_add_f32 v[34:35], v[46:47], v[48:49]
	global_store_dwordx4 v[40:41], v[36:39], off offset:128
	v_pk_add_f32 v[34:35], v[34:35], v[42:43]
	s_nop 0
	v_pk_add_f32 v[32:33], v[32:33], v[34:35]
	v_mov_b32_e32 v34, v165
	v_mov_b32_e32 v35, v165
	s_nop 0
	v_mov_b32_dpp v34, v32 quad_perm:[1,0,3,2] row_mask:0xf bank_mask:0xf
	v_mov_b32_dpp v35, v33 quad_perm:[1,0,3,2] row_mask:0xf bank_mask:0xf
	v_pk_add_f32 v[32:33], v[32:33], v[34:35]
	v_mov_b32_e32 v34, v32
	v_mov_b32_e32 v35, v33
	s_nop 1
	v_permlane16_swap_b32_e32 v32, v34
	v_permlane16_swap_b32_e32 v33, v35
	s_waitcnt lgkmcnt(0)
	v_pk_add_f32 v[32:33], v[32:33], v[34:35]
	v_mov_b32_e32 v34, v32
	v_mov_b32_e32 v35, v33
	s_nop 1
	v_permlane32_swap_b32_e32 v32, v34
	v_permlane32_swap_b32_e32 v33, v35
	s_and_saveexec_b64 s[64:65], s[16:17]
	s_cbranch_execz .LBB0_1487
	s_waitcnt lgkmcnt(0)
	v_pk_add_f32 v[32:33], v[32:33], v[34:35]
	v_add_co_u32_e32 v34, vcc, 0x12000, v186
	s_nop 1
	v_addc_co_u32_e32 v35, vcc, 0, v187, vcc
	global_store_dwordx2 v[34:35], v[32:33], off offset:512
; __device__ __forceinline__ u32x4 pack8f(f32x4 a, f32x4 b) { u32x4 w; w.x = cvt_pk_bf16(a[0], a[1]); w.y = cvt_pk_bf16(a[2], a[3]); w.z = cvt_pk_bf16(b[0], b[1]); w.w = cvt_pk_bf16(b[2], b[3]); return w; }
;     __device__ __forceinline__ void operator()(const f32x4 (&acc)[2][2][4][2], const Unit& u, int wr, int wc, int fr, int fq, const EpiCtx& X) const {
;     ...
;             for (int m = 0; m < 4; ++m) {
;                 const int rl = ai * HALF + m * 16; const unsigned off = lo + (unsigned)(rl * 64) * 2u;
;                 const f32x4 o0a = acc[ai][0][m][0], o0b = acc[ai][0][m][1], o1a = acc[ai][1][m][0], o1b = acc[ai][1][m][1];
;                 const f32x4 ra_ = dpp_swap1(odd ? o0a : o1a), rb_ = dpp_swap1(odd ? o0b : o1b);
;                 const f32x4 pa[2] = {odd ? ra_ : o0a, odd ? o1a : ra_}, pb[2] = {odd ? rb_ : o0b, odd ? o1b : rb_};
; #pragma unroll
;                 for (int q = 0; q < 2; ++q) {
;                     const u32x4 w0 = raw[2 * m + q];
;                     const f32x4 r0 = (f32x4){bf_lo(w0.x), bf_hi(w0.x), bf_lo(w0.y), bf_hi(w0.y)}, r1 = (f32x4){bf_lo(w0.z), bf_hi(w0.z), bf_lo(w0.w), bf_hi(w0.w)};
;                     f32x4 y0, y1;
;                     if (RESN) { const f32x2 t = tbl[rl + q]; const float mu = t.x, ra = t.y * ALPHA; y0 = (r0 - mu) * ra * g0 + b0 + pa[q]; y1 = (r1 - mu) * ra * g1 + b1 + pb[q]; }
;                     else { y0 = r0 * ALPHA + pa[q]; y1 = r1 * ALPHA + pb[q]; }
;                     { const u32x4 w = pack8f(y0, y1); *(u32x4*)(xb + off + q * 128) = w;
;                         y0 = (f32x4){bf_lo(w.x), bf_hi(w.x), bf_lo(w.y), bf_hi(w.y)}; y1 = (f32x4){bf_lo(w.z), bf_hi(w.z), bf_lo(w.w), bf_hi(w.w)}; }
;                     float sa = ((y0[0] + y0[1]) + (y0[2] + y0[3])) + ((y1[0] + y1[1]) + (y1[2] + y1[3]));
;                     float sb = ((y0[0] * y0[0] + y0[1] * y0[1]) + (y0[2] * y0[2] + y0[3] * y0[3])) + ((y1[0] * y1[0] + y1[1] * y1[1]) + (y1[2] * y1[2] + y1[3] * y1[3]));
;                     sa += dpp_x1(sa);
;                     sb += dpp_x1(sb);
;                     sa += __shfl_xor(sa, 16); sa += __shfl_xor(sa, 32); sb += __shfl_xor(sb, 16); sb += __shfl_xor(sb, 32);
;                     if (fq == 0 && !odd) ps[(size_t)(rl + q) * 64] = (f32x2){sa, sb};
;                 }
.LBB0_1487:
	s_or_b64 exec, exec, s[64:65]
	s_waitcnt lgkmcnt(0)
	v_cndmask_b32_e64 v34, v28, v20, s[10:11]
	v_mov_b32_e32 v32, 0
	v_cndmask_b32_e64 v33, v29, v21, s[10:11]
	s_waitcnt lgkmcnt(0)
	v_cndmask_b32_e64 v35, v30, v22, s[10:11]
	v_mov_b32_dpp v32, v34 quad_perm:[1,0,3,2] row_mask:0xf bank_mask:0xf
	v_mov_b32_e32 v34, 0
	v_cndmask_b32_e64 v36, v31, v23, s[10:11]
	v_cndmask_b32_e64 v38, v24, v16, s[10:11]
	v_mov_b32_dpp v34, v33 quad_perm:[1,0,3,2] row_mask:0xf bank_mask:0xf
	v_mov_b32_e32 v33, 0
	v_cndmask_b32_e64 v37, v25, v17, s[10:11]
	v_cndmask_b32_e64 v39, v26, v18, s[10:11]
	v_mov_b32_dpp v33, v35 quad_perm:[1,0,3,2] row_mask:0xf bank_mask:0xf
	v_mov_b32_e32 v35, 0
	v_cndmask_b32_e64 v40, v27, v19, s[10:11]
	s_waitcnt vmcnt(11)
	v_lshlrev_b32_e32 v43, 16, v84
	v_mov_b32_dpp v35, v36 quad_perm:[1,0,3,2] row_mask:0xf bank_mask:0xf
	v_mov_b32_e32 v36, 0
	v_and_b32_e32 v44, 0xffff0000, v84
	v_cndmask_b32_e64 v29, v34, v29, s[10:11]
	v_mov_b32_dpp v36, v38 quad_perm:[1,0,3,2] row_mask:0xf bank_mask:0xf
	v_mov_b32_e32 v38, 0
	v_cndmask_b32_e64 v28, v32, v28, s[10:11]
	v_lshlrev_b32_e32 v46, 16, v85
	v_mov_b32_dpp v38, v37 quad_perm:[1,0,3,2] row_mask:0xf bank_mask:0xf
	v_mov_b32_e32 v37, 0
	v_and_b32_e32 v47, 0xffff0000, v85
	v_lshlrev_b32_e32 v48, 16, v86
	v_mov_b32_dpp v37, v39 quad_perm:[1,0,3,2] row_mask:0xf bank_mask:0xf
	v_mov_b32_e32 v39, 0
	v_and_b32_e32 v49, 0xffff0000, v86
	v_lshlrev_b32_e32 v50, 16, v87
	v_mov_b32_dpp v39, v40 quad_perm:[1,0,3,2] row_mask:0xf bank_mask:0xf
	ds_read_b64 v[40:41], v201 offset:1280
	v_and_b32_e32 v51, 0xffff0000, v87
	v_cndmask_b32_e64 v31, v35, v31, s[10:11]
	v_cndmask_b32_e64 v30, v33, v30, s[10:11]
	v_cndmask_b32_e64 v25, v38, v25, s[10:11]
	s_waitcnt lgkmcnt(0)
	v_mul_f32_e32 v42, 0x3fb504f3, v41
	v_sub_f32_e32 v45, v44, v40
	v_sub_f32_e32 v44, v43, v40
	v_pk_mul_f32 v[44:45], v[44:45], v[42:43] op_sel_hi:[1,0]
	v_sub_f32_e32 v47, v47, v40
	v_pk_fma_f32 v[44:45], v[76:77], v[44:45], v[184:185]
	v_sub_f32_e32 v46, v46, v40
	v_pk_add_f32 v[28:29], v[28:29], v[44:45]
	v_sub_f32_e32 v45, v49, v40
	v_sub_f32_e32 v44, v48, v40
	v_sub_f32_e32 v41, v51, v40
	v_sub_f32_e32 v40, v50, v40
	v_pk_mul_f32 v[46:47], v[46:47], v[42:43] op_sel_hi:[1,0]
	v_pk_mul_f32 v[40:41], v[40:41], v[42:43] op_sel_hi:[1,0]
	v_pk_mul_f32 v[42:43], v[44:45], v[42:43] op_sel_hi:[1,0]
	v_cndmask_b32_e64 v24, v36, v24, s[10:11]
	v_cndmask_b32_e64 v27, v39, v27, s[10:11]
	v_cndmask_b32_e64 v26, v37, v26, s[10:11]
	v_pk_fma_f32 v[46:47], v[78:79], v[46:47], v[182:183]
	v_pk_fma_f32 v[42:43], v[72:73], v[42:43], v[180:181]
	v_pk_fma_f32 v[40:41], v[74:75], v[40:41], v[178:179]
	v_pk_add_f32 v[30:31], v[30:31], v[46:47]
	v_pk_add_f32 v[26:27], v[26:27], v[40:41]
	v_pk_add_f32 v[24:25], v[24:25], v[42:43]
	v_cvt_pk_bf16_f32 v40, v28, v29
	v_cvt_pk_bf16_f32 v41, v30, v31
	v_mov_b32_e32 v101, v165
	v_cvt_pk_bf16_f32 v42, v24, v25
	v_cvt_pk_bf16_f32 v43, v26, v27
	v_lshlrev_b32_e32 v24, 16, v40
	v_and_b32_e32 v26, 0xffff0000, v40
	v_lshlrev_b32_e32 v28, 16, v41
	v_and_b32_e32 v30, 0xffff0000, v41
	v_lshlrev_b32_e32 v44, 16, v42
	v_and_b32_e32 v46, 0xffff0000, v42
	v_lshlrev_b32_e32 v48, 16, v43
	v_and_b32_e32 v50, 0xffff0000, v43
	v_mul_f32_e32 v25, v24, v24
	v_mul_f32_e32 v27, v26, v26
	v_mul_f32_e32 v29, v28, v28
	v_mul_f32_e32 v31, v30, v30
	v_mul_f32_e32 v45, v44, v44
	v_mul_f32_e32 v47, v46, v46
	v_mul_f32_e32 v49, v48, v48
	v_mul_f32_e32 v51, v50, v50
	v_pk_add_f32 v[24:25], v[24:25], v[26:27]
	v_pk_add_f32 v[26:27], v[28:29], v[30:31]
	v_pk_add_f32 v[28:29], v[48:49], v[50:51]
	v_pk_add_f32 v[24:25], v[24:25], v[26:27]
	v_pk_add_f32 v[26:27], v[44:45], v[46:47]
	s_nop 0
	v_pk_add_f32 v[26:27], v[26:27], v[28:29]
	s_nop 0
	v_pk_add_f32 v[24:25], v[24:25], v[26:27]
	v_mov_b32_e32 v26, v165
	v_mov_b32_e32 v27, v165
	s_nop 0
	v_mov_b32_dpp v26, v24 quad_perm:[1,0,3,2] row_mask:0xf bank_mask:0xf
	v_mov_b32_dpp v27, v25 quad_perm:[1,0,3,2] row_mask:0xf bank_mask:0xf
	v_pk_add_f32 v[24:25], v[24:25], v[26:27]
	v_mov_b32_e32 v26, v24
	v_mov_b32_e32 v27, v25
	s_nop 1
	v_permlane16_swap_b32_e32 v24, v26
	v_permlane16_swap_b32_e32 v25, v27
	s_waitcnt lgkmcnt(0)
	v_pk_add_f32 v[26:27], v[24:25], v[26:27]
	v_mov_b32_e32 v28, v26
	v_mov_b32_e32 v29, v27
	s_nop 1
	v_permlane32_swap_b32_e32 v26, v28
	v_permlane32_swap_b32_e32 v27, v29
	v_lshl_add_u64 v[24:25], s[20:21], 0, v[100:101]
	global_store_dwordx4 v[24:25], v[40:43], off
	s_and_saveexec_b64 s[64:65], s[16:17]
	s_cbranch_execz .LBB0_1489
	s_waitcnt lgkmcnt(0)
	v_pk_add_f32 v[26:27], v[26:27], v[28:29]
	v_add_co_u32_e32 v28, vcc, 0x14000, v186
	s_nop 1
	v_addc_co_u32_e32 v29, vcc, 0, v187, vcc
	global_store_dwordx2 v[28:29], v[26:27], off
; __device__ __forceinline__ u32x4 pack8f(f32x4 a, f32x4 b) { u32x4 w; w.x = cvt_pk_bf16(a[0], a[1]); w.y = cvt_pk_bf16(a[2], a[3]); w.z = cvt_pk_bf16(b[0], b[1]); w.w = cvt_pk_bf16(b[2], b[3]); return w; }
;     __device__ __forceinline__ void operator()(const f32x4 (&acc)[2][2][4][2], const Unit& u, int wr, int wc, int fr, int fq, const EpiCtx& X) const {
;     ...
;             for (int m = 0; m < 4; ++m) {
;                 const int rl = ai * HALF + m * 16; const unsigned off = lo + (unsigned)(rl * 64) * 2u;
;                 const f32x4 o0a = acc[ai][0][m][0], o0b = acc[ai][0][m][1], o1a = acc[ai][1][m][0], o1b = acc[ai][1][m][1];
;                 const f32x4 ra_ = dpp_swap1(odd ? o0a : o1a), rb_ = dpp_swap1(odd ? o0b : o1b);
;                 const f32x4 pa[2] = {odd ? ra_ : o0a, odd ? o1a : ra_}, pb[2] = {odd ? rb_ : o0b, odd ? o1b : rb_};
; #pragma unroll
;                 for (int q = 0; q < 2; ++q) {
;                     const u32x4 w0 = raw[2 * m + q];
;                     const f32x4 r0 = (f32x4){bf_lo(w0.x), bf_hi(w0.x), bf_lo(w0.y), bf_hi(w0.y)}, r1 = (f32x4){bf_lo(w0.z), bf_hi(w0.z), bf_lo(w0.w), bf_hi(w0.w)};
;                     f32x4 y0, y1;
;                     if (RESN) { const f32x2 t = tbl[rl + q]; const float mu = t.x, ra = t.y * ALPHA; y0 = (r0 - mu) * ra * g0 + b0 + pa[q]; y1 = (r1 - mu) * ra * g1 + b1 + pb[q]; }
;                     else { y0 = r0 * ALPHA + pa[q]; y1 = r1 * ALPHA + pb[q]; }
;                     { const u32x4 w = pack8f(y0, y1); *(u32x4*)(xb + off + q * 128) = w;
;                         y0 = (f32x4){bf_lo(w.x), bf_hi(w.x), bf_lo(w.y), bf_hi(w.y)}; y1 = (f32x4){bf_lo(w.z), bf_hi(w.z), bf_lo(w.w), bf_hi(w.w)}; }
;                     float sa = ((y0[0] + y0[1]) + (y0[2] + y0[3])) + ((y1[0] + y1[1]) + (y1[2] + y1[3]));
;                     float sb = ((y0[0] * y0[0] + y0[1] * y0[1]) + (y0[2] * y0[2] + y0[3] * y0[3])) + ((y1[0] * y1[0] + y1[1] * y1[1]) + (y1[2] * y1[2] + y1[3] * y1[3]));
;                     sa += dpp_x1(sa);
;                     sb += dpp_x1(sb);
;                     sa += __shfl_xor(sa, 16); sa += __shfl_xor(sa, 32); sb += __shfl_xor(sb, 16); sb += __shfl_xor(sb, 32);
;                     if (fq == 0 && !odd) ps[(size_t)(rl + q) * 64] = (f32x2){sa, sb};
;                 }
.LBB0_1489:
	s_or_b64 exec, exec, s[64:65]
	ds_read_b64 v[26:27], v201 offset:1288
	s_waitcnt vmcnt(12) lgkmcnt(1)
	v_lshlrev_b32_e32 v29, 16, v80
	v_and_b32_e32 v30, 0xffff0000, v80
	v_cndmask_b32_e64 v21, v21, v34, s[10:11]
	v_cndmask_b32_e64 v20, v20, v32, s[10:11]
	s_waitcnt lgkmcnt(0)
	v_mul_f32_e32 v28, 0x3fb504f3, v27
	v_sub_f32_e32 v31, v30, v26
	v_sub_f32_e32 v30, v29, v26
	v_pk_mul_f32 v[30:31], v[30:31], v[28:29] op_sel_hi:[1,0]
	v_cndmask_b32_e64 v23, v23, v35, s[10:11]
	v_cndmask_b32_e64 v22, v22, v33, s[10:11]
	v_cndmask_b32_e64 v16, v16, v36, s[10:11]
	v_cndmask_b32_e64 v18, v18, v37, s[10:11]
	v_lshlrev_b32_e32 v32, 16, v81
	v_and_b32_e32 v33, 0xffff0000, v81
	v_lshlrev_b32_e32 v34, 16, v82
	v_and_b32_e32 v35, 0xffff0000, v82
	v_lshlrev_b32_e32 v36, 16, v83
	v_and_b32_e32 v37, 0xffff0000, v83
	v_pk_fma_f32 v[30:31], v[76:77], v[30:31], v[184:185]
	v_sub_f32_e32 v33, v33, v26
	v_sub_f32_e32 v32, v32, v26
	v_pk_add_f32 v[20:21], v[20:21], v[30:31]
	v_sub_f32_e32 v31, v35, v26
	v_sub_f32_e32 v30, v34, v26
	v_sub_f32_e32 v27, v37, v26
	v_sub_f32_e32 v26, v36, v26
	v_pk_mul_f32 v[32:33], v[32:33], v[28:29] op_sel_hi:[1,0]
	v_pk_mul_f32 v[26:27], v[26:27], v[28:29] op_sel_hi:[1,0]
	v_pk_mul_f32 v[28:29], v[30:31], v[28:29] op_sel_hi:[1,0]
	v_cndmask_b32_e64 v17, v17, v38, s[10:11]
	v_cndmask_b32_e64 v19, v19, v39, s[10:11]
	v_pk_fma_f32 v[32:33], v[78:79], v[32:33], v[182:183]
	v_pk_fma_f32 v[28:29], v[72:73], v[28:29], v[180:181]
	v_pk_fma_f32 v[26:27], v[74:75], v[26:27], v[178:179]
	v_pk_add_f32 v[22:23], v[22:23], v[32:33]
	v_pk_add_f32 v[18:19], v[18:19], v[26:27]
	v_pk_add_f32 v[16:17], v[16:17], v[28:29]
	v_cvt_pk_bf16_f32 v20, v20, v21
	v_cvt_pk_bf16_f32 v21, v22, v23
	s_nop 0
	v_cvt_pk_bf16_f32 v22, v16, v17
	v_cvt_pk_bf16_f32 v23, v18, v19
	v_lshlrev_b32_e32 v16, 16, v20
	v_and_b32_e32 v18, 0xffff0000, v20
	v_lshlrev_b32_e32 v26, 16, v21
	v_and_b32_e32 v28, 0xffff0000, v21
	v_lshlrev_b32_e32 v30, 16, v22
	v_and_b32_e32 v32, 0xffff0000, v22
	v_lshlrev_b32_e32 v34, 16, v23
	v_and_b32_e32 v36, 0xffff0000, v23
	v_mul_f32_e32 v17, v16, v16
	v_mul_f32_e32 v19, v18, v18
	v_mul_f32_e32 v27, v26, v26
	v_mul_f32_e32 v29, v28, v28
	v_mul_f32_e32 v31, v30, v30
	v_mul_f32_e32 v33, v32, v32
	v_mul_f32_e32 v35, v34, v34
	v_mul_f32_e32 v37, v36, v36
	v_pk_add_f32 v[16:17], v[16:17], v[18:19]
	v_pk_add_f32 v[18:19], v[26:27], v[28:29]
	v_pk_add_f32 v[26:27], v[34:35], v[36:37]
	v_pk_add_f32 v[16:17], v[16:17], v[18:19]
	v_pk_add_f32 v[18:19], v[30:31], v[32:33]
	global_store_dwordx4 v[24:25], v[20:23], off offset:128
	v_pk_add_f32 v[18:19], v[18:19], v[26:27]
	s_nop 0
	v_pk_add_f32 v[16:17], v[16:17], v[18:19]
	v_mov_b32_e32 v18, v165
	v_mov_b32_e32 v19, v165
	s_nop 0
	v_mov_b32_dpp v18, v16 quad_perm:[1,0,3,2] row_mask:0xf bank_mask:0xf
	v_mov_b32_dpp v19, v17 quad_perm:[1,0,3,2] row_mask:0xf bank_mask:0xf
	v_pk_add_f32 v[16:17], v[16:17], v[18:19]
	v_mov_b32_e32 v18, v16
	v_mov_b32_e32 v19, v17
	s_nop 1
	v_permlane16_swap_b32_e32 v16, v18
	v_permlane16_swap_b32_e32 v17, v19
	s_waitcnt lgkmcnt(0)
	v_pk_add_f32 v[16:17], v[16:17], v[18:19]
	v_mov_b32_e32 v18, v16
	v_mov_b32_e32 v19, v17
	s_nop 1
	v_permlane32_swap_b32_e32 v16, v18
	v_permlane32_swap_b32_e32 v17, v19
	s_and_saveexec_b64 s[64:65], s[16:17]
	s_cbranch_execz .LBB0_1491
	s_waitcnt lgkmcnt(0)
	v_pk_add_f32 v[16:17], v[16:17], v[18:19]
	v_add_co_u32_e32 v18, vcc, 0x14000, v186
	s_nop 1
	v_addc_co_u32_e32 v19, vcc, 0, v187, vcc
	global_store_dwordx2 v[18:19], v[16:17], off offset:512
; __device__ __forceinline__ u32x4 pack8f(f32x4 a, f32x4 b) { u32x4 w; w.x = cvt_pk_bf16(a[0], a[1]); w.y = cvt_pk_bf16(a[2], a[3]); w.z = cvt_pk_bf16(b[0], b[1]); w.w = cvt_pk_bf16(b[2], b[3]); return w; }
;     __device__ __forceinline__ void operator()(const f32x4 (&acc)[2][2][4][2], const Unit& u, int wr, int wc, int fr, int fq, const EpiCtx& X) const {
;     ...
;             for (int m = 0; m < 4; ++m) {
;                 const int rl = ai * HALF + m * 16; const unsigned off = lo + (unsigned)(rl * 64) * 2u;
;                 const f32x4 o0a = acc[ai][0][m][0], o0b = acc[ai][0][m][1], o1a = acc[ai][1][m][0], o1b = acc[ai][1][m][1];
;                 const f32x4 ra_ = dpp_swap1(odd ? o0a : o1a), rb_ = dpp_swap1(odd ? o0b : o1b);
;                 const f32x4 pa[2] = {odd ? ra_ : o0a, odd ? o1a : ra_}, pb[2] = {odd ? rb_ : o0b, odd ? o1b : rb_};
; #pragma unroll
;                 for (int q = 0; q < 2; ++q) {
;                     const u32x4 w0 = raw[2 * m + q];
;                     const f32x4 r0 = (f32x4){bf_lo(w0.x), bf_hi(w0.x), bf_lo(w0.y), bf_hi(w0.y)}, r1 = (f32x4){bf_lo(w0.z), bf_hi(w0.z), bf_lo(w0.w), bf_hi(w0.w)};
;                     f32x4 y0, y1;
;                     if (RESN) { const f32x2 t = tbl[rl + q]; const float mu = t.x, ra = t.y * ALPHA; y0 = (r0 - mu) * ra * g0 + b0 + pa[q]; y1 = (r1 - mu) * ra * g1 + b1 + pb[q]; }
;                     else { y0 = r0 * ALPHA + pa[q]; y1 = r1 * ALPHA + pb[q]; }
;                     { const u32x4 w = pack8f(y0, y1); *(u32x4*)(xb + off + q * 128) = w;
;                         y0 = (f32x4){bf_lo(w.x), bf_hi(w.x), bf_lo(w.y), bf_hi(w.y)}; y1 = (f32x4){bf_lo(w.z), bf_hi(w.z), bf_lo(w.w), bf_hi(w.w)}; }
;                     float sa = ((y0[0] + y0[1]) + (y0[2] + y0[3])) + ((y1[0] + y1[1]) + (y1[2] + y1[3]));
;                     float sb = ((y0[0] * y0[0] + y0[1] * y0[1]) + (y0[2] * y0[2] + y0[3] * y0[3])) + ((y1[0] * y1[0] + y1[1] * y1[1]) + (y1[2] * y1[2] + y1[3] * y1[3]));
;                     sa += dpp_x1(sa);
;                     sb += dpp_x1(sb);
;                     sa += __shfl_xor(sa, 16); sa += __shfl_xor(sa, 32); sb += __shfl_xor(sb, 16); sb += __shfl_xor(sb, 32);
;                     if (fq == 0 && !odd) ps[(size_t)(rl + q) * 64] = (f32x2){sa, sb};
;                 }
.LBB0_1491:
	s_or_b64 exec, exec, s[64:65]
	s_waitcnt lgkmcnt(0)
	v_cndmask_b32_e64 v18, v12, v4, s[10:11]
	v_mov_b32_e32 v16, 0
	v_cndmask_b32_e64 v17, v13, v5, s[10:11]
	s_waitcnt lgkmcnt(0)
	v_cndmask_b32_e64 v19, v14, v6, s[10:11]
	v_mov_b32_dpp v16, v18 quad_perm:[1,0,3,2] row_mask:0xf bank_mask:0xf
	v_mov_b32_e32 v18, 0
	v_cndmask_b32_e64 v20, v15, v7, s[10:11]
	v_cndmask_b32_e64 v22, v8, v0, s[10:11]
	v_mov_b32_dpp v18, v17 quad_perm:[1,0,3,2] row_mask:0xf bank_mask:0xf
	v_mov_b32_e32 v17, 0
	v_cndmask_b32_e64 v21, v9, v1, s[10:11]
	v_cndmask_b32_e64 v23, v10, v2, s[10:11]
	v_mov_b32_dpp v17, v19 quad_perm:[1,0,3,2] row_mask:0xf bank_mask:0xf
	v_mov_b32_e32 v19, 0
	v_cndmask_b32_e64 v24, v11, v3, s[10:11]
	s_waitcnt vmcnt(13)
	v_lshlrev_b32_e32 v27, 16, v68
	v_mov_b32_dpp v19, v20 quad_perm:[1,0,3,2] row_mask:0xf bank_mask:0xf
	v_mov_b32_e32 v20, 0
	v_and_b32_e32 v28, 0xffff0000, v68
	v_cndmask_b32_e64 v13, v18, v13, s[10:11]
	v_mov_b32_dpp v20, v22 quad_perm:[1,0,3,2] row_mask:0xf bank_mask:0xf
	v_mov_b32_e32 v22, 0
	v_cndmask_b32_e64 v12, v16, v12, s[10:11]
	v_lshlrev_b32_e32 v30, 16, v69
	v_mov_b32_dpp v22, v21 quad_perm:[1,0,3,2] row_mask:0xf bank_mask:0xf
	v_mov_b32_e32 v21, 0
	v_and_b32_e32 v31, 0xffff0000, v69
	v_lshlrev_b32_e32 v32, 16, v70
	v_mov_b32_dpp v21, v23 quad_perm:[1,0,3,2] row_mask:0xf bank_mask:0xf
	v_mov_b32_e32 v23, 0
	v_and_b32_e32 v33, 0xffff0000, v70
	v_lshlrev_b32_e32 v34, 16, v71
	v_mov_b32_dpp v23, v24 quad_perm:[1,0,3,2] row_mask:0xf bank_mask:0xf
	ds_read_b64 v[24:25], v201 offset:1408
	v_and_b32_e32 v35, 0xffff0000, v71
	v_cndmask_b32_e64 v15, v19, v15, s[10:11]
	v_cndmask_b32_e64 v14, v17, v14, s[10:11]
	v_cndmask_b32_e64 v9, v22, v9, s[10:11]
	s_waitcnt lgkmcnt(0)
	v_mul_f32_e32 v26, 0x3fb504f3, v25
	v_sub_f32_e32 v29, v28, v24
	v_sub_f32_e32 v28, v27, v24
	v_pk_mul_f32 v[28:29], v[28:29], v[26:27] op_sel_hi:[1,0]
	v_sub_f32_e32 v31, v31, v24
	v_pk_fma_f32 v[28:29], v[76:77], v[28:29], v[184:185]
	v_sub_f32_e32 v30, v30, v24
	v_pk_add_f32 v[12:13], v[12:13], v[28:29]
	v_sub_f32_e32 v29, v33, v24
	v_sub_f32_e32 v28, v32, v24
	v_sub_f32_e32 v25, v35, v24
	v_sub_f32_e32 v24, v34, v24
	v_pk_mul_f32 v[30:31], v[30:31], v[26:27] op_sel_hi:[1,0]
	v_pk_mul_f32 v[24:25], v[24:25], v[26:27] op_sel_hi:[1,0]
	v_pk_mul_f32 v[26:27], v[28:29], v[26:27] op_sel_hi:[1,0]
	v_cndmask_b32_e64 v8, v20, v8, s[10:11]
	v_cndmask_b32_e64 v11, v23, v11, s[10:11]
	v_cndmask_b32_e64 v10, v21, v10, s[10:11]
	v_pk_fma_f32 v[30:31], v[78:79], v[30:31], v[182:183]
	v_pk_fma_f32 v[26:27], v[72:73], v[26:27], v[180:181]
	v_pk_fma_f32 v[24:25], v[74:75], v[24:25], v[178:179]
	v_pk_add_f32 v[14:15], v[14:15], v[30:31]
	v_pk_add_f32 v[10:11], v[10:11], v[24:25]
	v_pk_add_f32 v[8:9], v[8:9], v[26:27]
	v_cvt_pk_bf16_f32 v24, v12, v13
	v_cvt_pk_bf16_f32 v25, v14, v15
	s_nop 0
	v_cvt_pk_bf16_f32 v26, v8, v9
	v_cvt_pk_bf16_f32 v27, v10, v11
	v_lshlrev_b32_e32 v8, 16, v24
	v_and_b32_e32 v10, 0xffff0000, v24
	v_lshlrev_b32_e32 v12, 16, v25
	v_and_b32_e32 v14, 0xffff0000, v25
	v_lshlrev_b32_e32 v28, 16, v26
	v_and_b32_e32 v30, 0xffff0000, v26
	v_lshlrev_b32_e32 v32, 16, v27
	v_and_b32_e32 v34, 0xffff0000, v27
	v_mul_f32_e32 v9, v8, v8
	v_mul_f32_e32 v11, v10, v10
	v_mul_f32_e32 v13, v12, v12
	v_mul_f32_e32 v15, v14, v14
	v_mul_f32_e32 v29, v28, v28
	v_mul_f32_e32 v31, v30, v30
	v_mul_f32_e32 v33, v32, v32
	v_mul_f32_e32 v35, v34, v34
	v_pk_add_f32 v[8:9], v[8:9], v[10:11]
	v_pk_add_f32 v[10:11], v[12:13], v[14:15]
	v_pk_add_f32 v[12:13], v[32:33], v[34:35]
	v_pk_add_f32 v[8:9], v[8:9], v[10:11]
	v_pk_add_f32 v[10:11], v[28:29], v[30:31]
	s_nop 0
	v_pk_add_f32 v[10:11], v[10:11], v[12:13]
	s_nop 0
	v_pk_add_f32 v[8:9], v[8:9], v[10:11]
	v_mov_b32_e32 v10, v165
	v_mov_b32_e32 v11, v165
	s_nop 0
	v_mov_b32_dpp v10, v8 quad_perm:[1,0,3,2] row_mask:0xf bank_mask:0xf
	v_mov_b32_dpp v11, v9 quad_perm:[1,0,3,2] row_mask:0xf bank_mask:0xf
	v_pk_add_f32 v[8:9], v[8:9], v[10:11]
	v_mov_b32_e32 v10, v8
	v_mov_b32_e32 v11, v9
	s_nop 1
	v_permlane16_swap_b32_e32 v8, v10
	v_permlane16_swap_b32_e32 v9, v11
	s_waitcnt lgkmcnt(0)
	v_pk_add_f32 v[10:11], v[8:9], v[10:11]
	v_mov_b32_e32 v12, v10
	v_mov_b32_e32 v13, v11
	s_nop 1
	v_permlane32_swap_b32_e32 v10, v12
	v_permlane32_swap_b32_e32 v11, v13
	v_lshl_add_u64 v[8:9], s[20:21], 0, v[164:165]
	global_store_dwordx4 v[8:9], v[24:27], off
	s_and_saveexec_b64 s[20:21], s[16:17]
	s_cbranch_execz .LBB0_1493
	s_waitcnt lgkmcnt(0)
	v_pk_add_f32 v[10:11], v[10:11], v[12:13]
	v_add_co_u32_e32 v12, vcc, 0x16000, v186
	s_nop 1
	v_addc_co_u32_e32 v13, vcc, 0, v187, vcc
	global_store_dwordx2 v[12:13], v[10:11], off

; #define LAS __attribute__((address_space(3)))
;     __device__ __forceinline__ void operator()(const f32x4 (&acc)[2][2][4][2], const Unit& u, int wr, int wc, int fr, int fq, const EpiCtx& X) const {
;     ...
;         char* yb = nullptr; char* xb = (char*)(XB + (size_t)u.pm * BM * DM + (size_t)(u.pn * 4 + wc) * (BM * 64));
;         unsigned lo = (unsigned)((wr * 64 + fe) * 64 + o32 + 8 * fq) * 2u; EPI_OPAQUE(lo);
;         const int col = u.pn * BM + wc * 64 + o32 + 8 * fq;
;         f32x4 g0, g1, b0, b1;
;         if (RESN) { ensure_tbl(PSp, sidp, u.pm, X);
;             g0 = *(const f32x4*)(gp + col); g1 = *(const f32x4*)(gp + col + 4); b0 = *(const f32x4*)(bp + col) * ALPHA; b1 = *(const f32x4*)(bp + col + 4) * ALPHA; }
;         const LAS f32x2* tbl = (const LAS f32x2*)(X.lds + TBL_OFF) + wr * 64 + fe;
;         f32x2* ps = PSn + ((size_t)u.pm * BM + wr * 64 + fe) * 64 + u.pn * 4 + wc;
; #pragma unroll
;         for (int ai = 0; ai < 2; ++ai) {
;             u32x4 raw[8];
; #pragma unroll
;             for (int m = 0; m < 4; ++m) { const unsigned off = lo + (unsigned)((ai * HALF + m * 16) * 64) * 2u; raw[2 * m] = *(const u32x4*)(xb + off); raw[2 * m + 1] = *(const u32x4*)(xb + off + 128); }
; #pragma unroll
;             for (int m = 0; m < 4; ++m) {
;                 const int rl = ai * HALF + m * 16; const unsigned off = lo + (unsigned)(rl * 64) * 2u;
;                 const f32x4 o0a = acc[ai][0][m][0], o0b = acc[ai][0][m][1], o1a = acc[ai][1][m][0], o1b = acc[ai][1][m][1];
;                 const f32x4 ra_ = dpp_swap1(odd ? o0a : o1a), rb_ = dpp_swap1(odd ? o0b : o1b);
;                 const f32x4 pa[2] = {odd ? ra_ : o0a, odd ? o1a : ra_}, pb[2] = {odd ? rb_ : o0b, odd ? o1b : rb_};
; #pragma unroll
;                 for (int q = 0; q < 2; ++q) {
;                     const u32x4 w0 = raw[2 * m + q];
;                     const f32x4 r0 = (f32x4){bf_lo(w0.x), bf_hi(w0.x), bf_lo(w0.y), bf_hi(w0.y)}, r1 = (f32x4){bf_lo(w0.z), bf_hi(w0.z), bf_lo(w0.w), bf_hi(w0.w)};
;                     f32x4 y0, y1;
;                     if (RESN) { const f32x2 t = tbl[rl + q]; const float mu = t.x, ra = t.y * ALPHA; y0 = (r0 - mu) * ra * g0 + b0 + pa[q]; y1 = (r1 - mu) * ra * g1 + b1 + pb[q]; }
;                     else { y0 = r0 * ALPHA + pa[q]; y1 = r1 * ALPHA + pb[q]; }
;                     { const u32x4 w = pack8f(y0, y1); *(u32x4*)(xb + off + q * 128) = w;
.LBB0_1697:
	s_lshl_b64 s[16:17], s[58:59], 21
	s_add_u32 s35, s31, s16
	s_addc_u32 s38, s68, s17
	s_lshl_b32 s58, s56, 2
	s_or_b32 s16, s58, s41
	s_ashr_i32 s17, s16, 31
	v_lshl_add_u32 v72, s56, 8, v200
	v_ashrrev_i32_e32 v73, 31, v72
	s_lshl_b64 s[16:17], s[16:17], 15
	v_lshlrev_b64 v[72:73], 2, v[72:73]
	s_add_u32 s16, s35, s16
	v_lshl_add_u64 v[74:75], s[26:27], 0, v[72:73]
	s_addc_u32 s17, s38, s17
	global_load_dwordx4 v[194:197], v[74:75], off offset:16
	global_load_dwordx4 v[178:181], v[74:75], off
	global_load_dwordx4 v[214:217], v164, s[16:17]
	v_lshl_add_u64 v[72:73], s[24:25], 0, v[72:73]
	s_waitcnt lgkmcnt(0)
	global_load_dwordx4 v[76:79], v[72:73], off
	s_nop 0
	global_load_dwordx4 v[72:75], v[72:73], off offset:16
	v_cndmask_b32_e64 v136, v135, v127, s[6:7]
	v_cndmask_b32_e64 v137, v134, v126, s[6:7]
	v_cndmask_b32_e64 v138, v133, v125, s[6:7]
	v_cndmask_b32_e64 v139, v132, v124, s[6:7]
	v_mov_b32_e32 v189, 0
	v_mov_b32_e32 v193, 0
	v_mov_b32_e32 v191, 0
	v_mov_b32_e32 v209, 0
	v_cndmask_b32_e64 v140, v131, v123, s[6:7]
	v_cndmask_b32_e64 v141, v130, v122, s[6:7]
	v_cndmask_b32_e64 v142, v129, v121, s[6:7]
	v_cndmask_b32_e64 v143, v128, v120, s[6:7]
	v_mov_b32_e32 v210, 0
	v_mov_b32_e32 v212, 0
	v_mov_b32_e32 v211, 0
	v_mov_b32_e32 v213, 0
	v_mov_b32_dpp v189, v139 quad_perm:[1,0,3,2] row_mask:0xf bank_mask:0xf
	v_mov_b32_dpp v193, v138 quad_perm:[1,0,3,2] row_mask:0xf bank_mask:0xf
	v_mov_b32_dpp v191, v137 quad_perm:[1,0,3,2] row_mask:0xf bank_mask:0xf
	v_mov_b32_dpp v209, v136 quad_perm:[1,0,3,2] row_mask:0xf bank_mask:0xf
	v_mov_b32_dpp v210, v143 quad_perm:[1,0,3,2] row_mask:0xf bank_mask:0xf
	v_mov_b32_dpp v212, v142 quad_perm:[1,0,3,2] row_mask:0xf bank_mask:0xf
	v_mov_b32_dpp v211, v141 quad_perm:[1,0,3,2] row_mask:0xf bank_mask:0xf
	v_mov_b32_dpp v213, v140 quad_perm:[1,0,3,2] row_mask:0xf bank_mask:0xf
	v_add_u32_e32 v192, 0x800, v164
	v_add_u32_e32 v190, 0x1000, v164
	v_add_u32_e32 v188, 0x1800, v164
	ds_read_b64 v[218:219], v201
	v_cndmask_b32_e64 v221, v193, v133, s[6:7]
	v_cndmask_b32_e64 v220, v189, v132, s[6:7]
	v_cndmask_b32_e64 v223, v209, v135, s[6:7]
	v_cndmask_b32_e64 v222, v191, v134, s[6:7]
	v_cndmask_b32_e64 v225, v212, v129, s[6:7]
	v_cndmask_b32_e64 v224, v210, v128, s[6:7]
	v_cndmask_b32_e64 v227, v213, v131, s[6:7]
	v_cndmask_b32_e64 v226, v211, v130, s[6:7]
	global_load_dwordx4 v[152:155], v164, s[16:17] offset:128
	global_load_dwordx4 v[148:151], v192, s[16:17]
	global_load_dwordx4 v[144:147], v192, s[16:17] offset:128
	global_load_dwordx4 v[140:143], v190, s[16:17]
	global_load_dwordx4 v[136:139], v190, s[16:17] offset:128
	global_load_dwordx4 v[132:135], v188, s[16:17]
	global_load_dwordx4 v[128:131], v188, s[16:17] offset:128
	s_waitcnt lgkmcnt(0)
	v_mul_f32_e32 v208, 0x3fb504f3, v219
	v_lshl_add_u64 v[186:187], v[166:167], 0, s[60:61]
	s_ashr_i32 s59, s58, 31
	v_lshl_add_u64 v[186:187], s[58:59], 3, v[186:187]
	v_lshl_add_u64 v[186:187], v[186:187], 0, s[20:21]
	v_add_u32_e32 v246, 0x4000, v164
	v_add_u32_e32 v247, 0x4800, v164
	global_load_dwordx4 v[230:233], v246, s[16:17]
	global_load_dwordx4 v[234:237], v246, s[16:17] offset:128
	global_load_dwordx4 v[238:241], v247, s[16:17]
	global_load_dwordx4 v[242:245], v247, s[16:17] offset:128
	s_waitcnt vmcnt(14)
	v_pk_mul_f32 v[182:183], v[180:181], s[46:47] op_sel_hi:[1,0]
	v_pk_mul_f32 v[184:185], v[178:179], s[46:47] op_sel_hi:[1,0]
	v_pk_mul_f32 v[178:179], v[196:197], s[46:47] op_sel_hi:[1,0]
	v_pk_mul_f32 v[180:181], v[194:195], s[46:47] op_sel_hi:[1,0]
	s_waitcnt vmcnt(13)
	v_lshlrev_b32_e32 v194, 16, v214
	v_and_b32_e32 v195, 0xffff0000, v214
	v_lshlrev_b32_e32 v196, 16, v215
	v_and_b32_e32 v197, 0xffff0000, v215
	v_lshlrev_b32_e32 v207, 16, v216
	v_and_b32_e32 v214, 0xffff0000, v216
	v_lshlrev_b32_e32 v216, 16, v217
	v_and_b32_e32 v217, 0xffff0000, v217
	v_sub_f32_e32 v195, v195, v218
	v_sub_f32_e32 v194, v194, v218
	v_sub_f32_e32 v197, v197, v218
	v_sub_f32_e32 v196, v196, v218
	v_sub_f32_e32 v215, v214, v218
	v_sub_f32_e32 v214, v207, v218
	v_sub_f32_e32 v217, v217, v218
	v_sub_f32_e32 v216, v216, v218
	v_pk_mul_f32 v[196:197], v[196:197], v[208:209] op_sel_hi:[1,0]
	v_pk_mul_f32 v[194:195], v[194:195], v[208:209] op_sel_hi:[1,0]
	v_pk_mul_f32 v[216:217], v[216:217], v[208:209] op_sel_hi:[1,0]
	v_pk_mul_f32 v[214:215], v[214:215], v[208:209] op_sel_hi:[1,0]
	s_waitcnt vmcnt(12)
	v_pk_fma_f32 v[194:195], v[76:77], v[194:195], v[184:185]
	v_pk_fma_f32 v[196:197], v[78:79], v[196:197], v[182:183]
	s_waitcnt vmcnt(11)
	v_pk_fma_f32 v[214:215], v[72:73], v[214:215], v[180:181]
	v_pk_fma_f32 v[216:217], v[74:75], v[216:217], v[178:179]
	v_pk_add_f32 v[196:197], v[222:223], v[196:197]
	v_pk_add_f32 v[194:195], v[220:221], v[194:195]
	v_pk_add_f32 v[218:219], v[226:227], v[216:217]
	v_pk_add_f32 v[216:217], v[224:225], v[214:215]
	v_cvt_pk_bf16_f32 v214, v194, v195
	v_cvt_pk_bf16_f32 v215, v196, v197
	v_and_b32_e32 v208, 64, v206
	v_cvt_pk_bf16_f32 v216, v216, v217
	v_cvt_pk_bf16_f32 v217, v218, v219
	v_lshlrev_b32_e32 v194, 16, v214
	v_and_b32_e32 v196, 0xffff0000, v214
	v_lshlrev_b32_e32 v218, 16, v215
	v_and_b32_e32 v220, 0xffff0000, v215
	v_lshlrev_b32_e32 v222, 16, v216
	v_and_b32_e32 v224, 0xffff0000, v216
	v_lshlrev_b32_e32 v226, 16, v217
	v_and_b32_e32 v228, 0xffff0000, v217
	v_mul_f32_e32 v195, v194, v194
	v_mul_f32_e32 v197, v196, v196
	v_mul_f32_e32 v219, v218, v218
	v_mul_f32_e32 v221, v220, v220
	v_mul_f32_e32 v223, v222, v222
	v_mul_f32_e32 v225, v224, v224
	v_mul_f32_e32 v227, v226, v226
	v_mul_f32_e32 v229, v228, v228
	v_pk_add_f32 v[194:195], v[194:195], v[196:197]
	v_pk_add_f32 v[196:197], v[218:219], v[220:221]
	v_pk_add_f32 v[218:219], v[226:227], v[228:229]
	v_pk_add_f32 v[194:195], v[194:195], v[196:197]
	v_pk_add_f32 v[196:197], v[222:223], v[224:225]
	v_xor_b32_e32 v207, 16, v206
	v_add_u32_e32 v208, 64, v208
	v_pk_add_f32 v[196:197], v[196:197], v[218:219]
	v_cmp_lt_i32_e32 vcc, v207, v208
	v_pk_add_f32 v[194:195], v[194:195], v[196:197]
	v_mov_b32_e32 v196, 0
	v_mov_b32_e32 v197, 0
	v_cndmask_b32_e32 v207, v206, v207, vcc
	v_mov_b32_dpp v196, v194 quad_perm:[1,0,3,2] row_mask:0xf bank_mask:0xf
	v_mov_b32_dpp v197, v195 quad_perm:[1,0,3,2] row_mask:0xf bank_mask:0xf
	v_lshlrev_b32_e32 v207, 2, v207
	v_pk_add_f32 v[194:195], v[194:195], v[196:197]
	v_mov_b32_e32 v196, v194
	v_mov_b32_e32 v197, v195
	s_nop 1
	v_permlane16_swap_b32_e32 v194, v196
	v_permlane16_swap_b32_e32 v195, v197
	v_xor_b32_e32 v218, 32, v206
	v_cmp_lt_i32_e32 vcc, v218, v208
	global_store_dwordx4 v164, v[214:217], s[16:17]
	s_waitcnt lgkmcnt(0)
	v_pk_add_f32 v[194:195], v[194:195], v[196:197]
	v_cndmask_b32_e32 v208, v206, v218, vcc
	v_lshlrev_b32_e32 v208, 2, v208
	v_mov_b32_e32 v196, v194
	v_mov_b32_e32 v197, v195
	s_nop 1
	v_permlane32_swap_b32_e32 v194, v196
	v_permlane32_swap_b32_e32 v195, v197
	s_and_saveexec_b64 s[56:57], s[12:13]
	s_waitcnt lgkmcnt(0)
	v_pk_add_f32 v[194:195], v[194:195], v[196:197]
	global_store_dwordx2 v[186:187], v[194:195], off
; __device__ __forceinline__ u32x4 pack8f(f32x4 a, f32x4 b) { u32x4 w; w.x = cvt_pk_bf16(a[0], a[1]); w.y = cvt_pk_bf16(a[2], a[3]); w.z = cvt_pk_bf16(b[0], b[1]); w.w = cvt_pk_bf16(b[2], b[3]); return w; }
;     __device__ __forceinline__ void operator()(const f32x4 (&acc)[2][2][4][2], const Unit& u, int wr, int wc, int fr, int fq, const EpiCtx& X) const {
;     ...
;             for (int m = 0; m < 4; ++m) {
;                 const int rl = ai * HALF + m * 16; const unsigned off = lo + (unsigned)(rl * 64) * 2u;
;                 const f32x4 o0a = acc[ai][0][m][0], o0b = acc[ai][0][m][1], o1a = acc[ai][1][m][0], o1b = acc[ai][1][m][1];
;                 const f32x4 ra_ = dpp_swap1(odd ? o0a : o1a), rb_ = dpp_swap1(odd ? o0b : o1b);
;                 const f32x4 pa[2] = {odd ? ra_ : o0a, odd ? o1a : ra_}, pb[2] = {odd ? rb_ : o0b, odd ? o1b : rb_};
; #pragma unroll
;                 for (int q = 0; q < 2; ++q) {
;                     const u32x4 w0 = raw[2 * m + q];
;                     const f32x4 r0 = (f32x4){bf_lo(w0.x), bf_hi(w0.x), bf_lo(w0.y), bf_hi(w0.y)}, r1 = (f32x4){bf_lo(w0.z), bf_hi(w0.z), bf_lo(w0.w), bf_hi(w0.w)};
;                     f32x4 y0, y1;
;                     if (RESN) { const f32x2 t = tbl[rl + q]; const float mu = t.x, ra = t.y * ALPHA; y0 = (r0 - mu) * ra * g0 + b0 + pa[q]; y1 = (r1 - mu) * ra * g1 + b1 + pb[q]; }
;                     else { y0 = r0 * ALPHA + pa[q]; y1 = r1 * ALPHA + pb[q]; }
;                     { const u32x4 w = pack8f(y0, y1); *(u32x4*)(xb + off + q * 128) = w;
;                         y0 = (f32x4){bf_lo(w.x), bf_hi(w.x), bf_lo(w.y), bf_hi(w.y)}; y1 = (f32x4){bf_lo(w.z), bf_hi(w.z), bf_lo(w.w), bf_hi(w.w)}; }
;                     float sa = ((y0[0] + y0[1]) + (y0[2] + y0[3])) + ((y1[0] + y1[1]) + (y1[2] + y1[3]));
;                     float sb = ((y0[0] * y0[0] + y0[1] * y0[1]) + (y0[2] * y0[2] + y0[3] * y0[3])) + ((y1[0] * y1[0] + y1[1] * y1[1]) + (y1[2] * y1[2] + y1[3] * y1[3]));
;                     sa += dpp_x1(sa);
;                     sb += dpp_x1(sb);
;                     sa += __shfl_xor(sa, 16); sa += __shfl_xor(sa, 32); sb += __shfl_xor(sb, 16); sb += __shfl_xor(sb, 32);
;                     if (fq == 0 && !odd) ps[(size_t)(rl + q) * 64] = (f32x2){sa, sb};
;                 }
.LBB0_1699:
	s_or_b64 exec, exec, s[56:57]
	v_cndmask_b32_e64 v125, v125, v193, s[6:7]
	v_cndmask_b32_e64 v124, v124, v189, s[6:7]
	v_cndmask_b32_e64 v126, v126, v191, s[6:7]
	s_waitcnt vmcnt(12)
	v_lshlrev_b32_e32 v189, 16, v152
	v_and_b32_e32 v191, 0xffff0000, v152
	v_lshlrev_b32_e32 v193, 16, v153
	s_waitcnt lgkmcnt(0)
	v_and_b32_e32 v196, 0xffff0000, v153
	ds_read_b64 v[152:153], v201 offset:8
	v_cndmask_b32_e64 v127, v127, v209, s[6:7]
	v_cndmask_b32_e64 v120, v120, v210, s[6:7]
	v_cndmask_b32_e64 v122, v122, v211, s[6:7]
	v_lshlrev_b32_e32 v209, 16, v154
	v_and_b32_e32 v210, 0xffff0000, v154
	v_lshlrev_b32_e32 v211, 16, v155
	v_and_b32_e32 v155, 0xffff0000, v155
	s_waitcnt lgkmcnt(0)
	v_mul_f32_e32 v154, 0x3fb504f3, v153
	v_sub_f32_e32 v195, v191, v152
	v_sub_f32_e32 v194, v189, v152
	v_pk_mul_f32 v[194:195], v[194:195], v[154:155] op_sel_hi:[1,0]
	v_sub_f32_e32 v197, v196, v152
	v_pk_fma_f32 v[194:195], v[76:77], v[194:195], v[184:185]
	v_sub_f32_e32 v196, v193, v152
	v_pk_add_f32 v[124:125], v[124:125], v[194:195]
	v_sub_f32_e32 v195, v210, v152
	v_sub_f32_e32 v194, v209, v152
	v_sub_f32_e32 v153, v155, v152
	v_sub_f32_e32 v152, v211, v152
	v_pk_mul_f32 v[196:197], v[196:197], v[154:155] op_sel_hi:[1,0]
	v_pk_mul_f32 v[152:153], v[152:153], v[154:155] op_sel_hi:[1,0]
	v_pk_mul_f32 v[154:155], v[194:195], v[154:155] op_sel_hi:[1,0]
	v_cndmask_b32_e64 v121, v121, v212, s[6:7]
	v_cndmask_b32_e64 v123, v123, v213, s[6:7]
	v_pk_fma_f32 v[196:197], v[78:79], v[196:197], v[182:183]
	v_pk_fma_f32 v[154:155], v[72:73], v[154:155], v[180:181]
	v_pk_fma_f32 v[152:153], v[74:75], v[152:153], v[178:179]
	v_pk_add_f32 v[126:127], v[126:127], v[196:197]
	v_pk_add_f32 v[122:123], v[122:123], v[152:153]
	v_pk_add_f32 v[120:121], v[120:121], v[154:155]
	v_cvt_pk_bf16_f32 v124, v124, v125
	v_cvt_pk_bf16_f32 v125, v126, v127
	s_nop 0
	v_cvt_pk_bf16_f32 v126, v120, v121
	v_cvt_pk_bf16_f32 v127, v122, v123
	v_lshlrev_b32_e32 v120, 16, v124
	v_and_b32_e32 v122, 0xffff0000, v124
	v_lshlrev_b32_e32 v152, 16, v125
	v_and_b32_e32 v154, 0xffff0000, v125
	v_lshlrev_b32_e32 v194, 16, v126
	v_and_b32_e32 v196, 0xffff0000, v126
	v_lshlrev_b32_e32 v210, 16, v127
	v_and_b32_e32 v212, 0xffff0000, v127
	v_mul_f32_e32 v121, v120, v120
	v_mul_f32_e32 v123, v122, v122
	v_mul_f32_e32 v153, v152, v152
	v_mul_f32_e32 v155, v154, v154
	v_mul_f32_e32 v195, v194, v194
	v_mul_f32_e32 v197, v196, v196
	v_mul_f32_e32 v211, v210, v210
	v_mul_f32_e32 v213, v212, v212
	v_pk_add_f32 v[120:121], v[120:121], v[122:123]
	v_pk_add_f32 v[122:123], v[152:153], v[154:155]
	v_pk_add_f32 v[152:153], v[210:211], v[212:213]
	v_pk_add_f32 v[120:121], v[120:121], v[122:123]
	v_pk_add_f32 v[122:123], v[194:195], v[196:197]
	s_nop 0
	v_pk_add_f32 v[122:123], v[122:123], v[152:153]
	v_lshl_add_u64 v[152:153], s[16:17], 0, v[164:165]
	v_pk_add_f32 v[120:121], v[120:121], v[122:123]
	v_mov_b32_e32 v122, v165
	v_mov_b32_e32 v123, v165
	global_store_dwordx4 v[152:153], v[124:127], off offset:128
	v_mov_b32_dpp v122, v120 quad_perm:[1,0,3,2] row_mask:0xf bank_mask:0xf
	v_mov_b32_dpp v123, v121 quad_perm:[1,0,3,2] row_mask:0xf bank_mask:0xf
	v_pk_add_f32 v[120:121], v[120:121], v[122:123]
	v_mov_b32_e32 v122, v120
	v_mov_b32_e32 v123, v121
	s_nop 1
	v_permlane16_swap_b32_e32 v120, v122
	v_permlane16_swap_b32_e32 v121, v123
	s_waitcnt lgkmcnt(0)
	v_pk_add_f32 v[120:121], v[120:121], v[122:123]
	v_mov_b32_e32 v122, v120
	v_mov_b32_e32 v123, v121
	s_nop 1
	v_permlane32_swap_b32_e32 v120, v122
	v_permlane32_swap_b32_e32 v121, v123
	s_and_saveexec_b64 s[56:57], s[12:13]
	s_waitcnt lgkmcnt(0)
	v_pk_add_f32 v[120:121], v[120:121], v[122:123]
	global_store_dwordx2 v[186:187], v[120:121], off offset:512
.LBB0_1701:
	s_or_b64 exec, exec, s[56:57]
	s_waitcnt lgkmcnt(0)
	v_cndmask_b32_e64 v122, v116, v108, s[6:7]
	v_mov_b32_e32 v120, 0
	v_cndmask_b32_e64 v121, v117, v109, s[6:7]
	s_waitcnt lgkmcnt(0)
	v_cndmask_b32_e64 v123, v118, v110, s[6:7]
	v_mov_b32_dpp v120, v122 quad_perm:[1,0,3,2] row_mask:0xf bank_mask:0xf
	v_mov_b32_e32 v122, 0
	v_cndmask_b32_e64 v124, v119, v111, s[6:7]
	v_cndmask_b32_e64 v126, v112, v104, s[6:7]
	v_mov_b32_dpp v122, v121 quad_perm:[1,0,3,2] row_mask:0xf bank_mask:0xf
	v_mov_b32_e32 v121, 0
	v_cndmask_b32_e64 v125, v113, v105, s[6:7]
	v_cndmask_b32_e64 v127, v114, v106, s[6:7]
	v_mov_b32_dpp v121, v123 quad_perm:[1,0,3,2] row_mask:0xf bank_mask:0xf
	v_mov_b32_e32 v123, 0
	v_cndmask_b32_e64 v152, v115, v107, s[6:7]
	s_waitcnt vmcnt(13)
	v_and_b32_e32 v153, 0xffff0000, v148
	v_mov_b32_dpp v123, v124 quad_perm:[1,0,3,2] row_mask:0xf bank_mask:0xf
	v_mov_b32_e32 v124, 0
	v_lshlrev_b32_e32 v154, 16, v149
	v_and_b32_e32 v155, 0xffff0000, v149
	v_mov_b32_dpp v124, v126 quad_perm:[1,0,3,2] row_mask:0xf bank_mask:0xf
	v_mov_b32_e32 v126, 0
	v_lshlrev_b32_e32 v189, 16, v150
	v_and_b32_e32 v191, 0xffff0000, v150
	v_mov_b32_dpp v126, v125 quad_perm:[1,0,3,2] row_mask:0xf bank_mask:0xf
	v_mov_b32_e32 v125, 0
	v_lshlrev_b32_e32 v193, 16, v151
	v_and_b32_e32 v151, 0xffff0000, v151
	v_mov_b32_dpp v125, v127 quad_perm:[1,0,3,2] row_mask:0xf bank_mask:0xf
	v_mov_b32_e32 v127, 0
	v_cndmask_b32_e64 v117, v122, v117, s[6:7]
	v_cndmask_b32_e64 v116, v120, v116, s[6:7]
	v_mov_b32_dpp v127, v152 quad_perm:[1,0,3,2] row_mask:0xf bank_mask:0xf
	v_lshlrev_b32_e32 v152, 16, v148
	ds_read_b64 v[148:149], v201 offset:128
	v_cndmask_b32_e64 v119, v123, v119, s[6:7]
	v_cndmask_b32_e64 v118, v121, v118, s[6:7]
	v_cndmask_b32_e64 v113, v126, v113, s[6:7]
	v_cndmask_b32_e64 v112, v124, v112, s[6:7]
	s_waitcnt lgkmcnt(0)
; __device__ __forceinline__ u32x4 pack8f(f32x4 a, f32x4 b) { u32x4 w; w.x = cvt_pk_bf16(a[0], a[1]); w.y = cvt_pk_bf16(a[2], a[3]); w.z = cvt_pk_bf16(b[0], b[1]); w.w = cvt_pk_bf16(b[2], b[3]); return w; }
;     __device__ __forceinline__ void operator()(const f32x4 (&acc)[2][2][4][2], const Unit& u, int wr, int wc, int fr, int fq, const EpiCtx& X) const {
;     ...
;             for (int m = 0; m < 4; ++m) {
;                 const int rl = ai * HALF + m * 16; const unsigned off = lo + (unsigned)(rl * 64) * 2u;
;                 const f32x4 o0a = acc[ai][0][m][0], o0b = acc[ai][0][m][1], o1a = acc[ai][1][m][0], o1b = acc[ai][1][m][1];
;                 const f32x4 ra_ = dpp_swap1(odd ? o0a : o1a), rb_ = dpp_swap1(odd ? o0b : o1b);
;                 const f32x4 pa[2] = {odd ? ra_ : o0a, odd ? o1a : ra_}, pb[2] = {odd ? rb_ : o0b, odd ? o1b : rb_};
; #pragma unroll
;                 for (int q = 0; q < 2; ++q) {
;                     const u32x4 w0 = raw[2 * m + q];
;                     const f32x4 r0 = (f32x4){bf_lo(w0.x), bf_hi(w0.x), bf_lo(w0.y), bf_hi(w0.y)}, r1 = (f32x4){bf_lo(w0.z), bf_hi(w0.z), bf_lo(w0.w), bf_hi(w0.w)};
;                     f32x4 y0, y1;
;                     if (RESN) { const f32x2 t = tbl[rl + q]; const float mu = t.x, ra = t.y * ALPHA; y0 = (r0 - mu) * ra * g0 + b0 + pa[q]; y1 = (r1 - mu) * ra * g1 + b1 + pb[q]; }
;                     else { y0 = r0 * ALPHA + pa[q]; y1 = r1 * ALPHA + pb[q]; }
;                     { const u32x4 w = pack8f(y0, y1); *(u32x4*)(xb + off + q * 128) = w;
;                         y0 = (f32x4){bf_lo(w.x), bf_hi(w.x), bf_lo(w.y), bf_hi(w.y)}; y1 = (f32x4){bf_lo(w.z), bf_hi(w.z), bf_lo(w.w), bf_hi(w.w)}; }
;                     float sa = ((y0[0] + y0[1]) + (y0[2] + y0[3])) + ((y1[0] + y1[1]) + (y1[2] + y1[3]));
;                     float sb = ((y0[0] * y0[0] + y0[1] * y0[1]) + (y0[2] * y0[2] + y0[3] * y0[3])) + ((y1[0] * y1[0] + y1[1] * y1[1]) + (y1[2] * y1[2] + y1[3] * y1[3]));
;                     sa += dpp_x1(sa);
;                     sb += dpp_x1(sb);
;                     sa += __shfl_xor(sa, 16); sa += __shfl_xor(sa, 32); sb += __shfl_xor(sb, 16); sb += __shfl_xor(sb, 32);
;                     if (fq == 0 && !odd) ps[(size_t)(rl + q) * 64] = (f32x2){sa, sb};
;                 }
	v_mul_f32_e32 v150, 0x3fb504f3, v149
	v_sub_f32_e32 v153, v153, v148
	v_sub_f32_e32 v152, v152, v148
	v_pk_mul_f32 v[152:153], v[152:153], v[150:151] op_sel_hi:[1,0]
	v_sub_f32_e32 v155, v155, v148
	v_pk_fma_f32 v[152:153], v[76:77], v[152:153], v[184:185]
	v_sub_f32_e32 v154, v154, v148
	v_pk_add_f32 v[116:117], v[116:117], v[152:153]
	v_sub_f32_e32 v153, v191, v148
	v_sub_f32_e32 v152, v189, v148
	v_sub_f32_e32 v149, v151, v148
	v_sub_f32_e32 v148, v193, v148
	v_pk_mul_f32 v[154:155], v[154:155], v[150:151] op_sel_hi:[1,0]
	v_pk_mul_f32 v[148:149], v[148:149], v[150:151] op_sel_hi:[1,0]
	v_pk_mul_f32 v[150:151], v[152:153], v[150:151] op_sel_hi:[1,0]
	v_cndmask_b32_e64 v115, v127, v115, s[6:7]
	v_cndmask_b32_e64 v114, v125, v114, s[6:7]
	v_pk_fma_f32 v[154:155], v[78:79], v[154:155], v[182:183]
	v_pk_fma_f32 v[150:151], v[72:73], v[150:151], v[180:181]
	v_pk_fma_f32 v[148:149], v[74:75], v[148:149], v[178:179]
	v_pk_add_f32 v[118:119], v[118:119], v[154:155]
	v_pk_add_f32 v[114:115], v[114:115], v[148:149]
	v_pk_add_f32 v[112:113], v[112:113], v[150:151]
	v_cvt_pk_bf16_f32 v148, v116, v117
	v_cvt_pk_bf16_f32 v149, v118, v119
	v_mov_b32_e32 v193, v165
	v_cvt_pk_bf16_f32 v150, v112, v113
	v_cvt_pk_bf16_f32 v151, v114, v115
	v_lshlrev_b32_e32 v112, 16, v148
	v_and_b32_e32 v114, 0xffff0000, v148
	v_lshlrev_b32_e32 v116, 16, v149
	v_and_b32_e32 v118, 0xffff0000, v149
	v_lshlrev_b32_e32 v152, 16, v150
	v_and_b32_e32 v154, 0xffff0000, v150
	v_lshlrev_b32_e32 v194, 16, v151
	v_and_b32_e32 v196, 0xffff0000, v151
	v_mul_f32_e32 v113, v112, v112
	v_mul_f32_e32 v115, v114, v114
	v_mul_f32_e32 v117, v116, v116
	v_mul_f32_e32 v119, v118, v118
	v_mul_f32_e32 v153, v152, v152
	v_mul_f32_e32 v155, v154, v154
	v_mul_f32_e32 v195, v194, v194
	v_mul_f32_e32 v197, v196, v196
	v_pk_add_f32 v[112:113], v[112:113], v[114:115]
	v_pk_add_f32 v[114:115], v[116:117], v[118:119]
	v_pk_add_f32 v[116:117], v[194:195], v[196:197]
	v_pk_add_f32 v[112:113], v[112:113], v[114:115]
	v_pk_add_f32 v[114:115], v[152:153], v[154:155]
	s_nop 0
	v_pk_add_f32 v[114:115], v[114:115], v[116:117]
	s_nop 0
	v_pk_add_f32 v[112:113], v[112:113], v[114:115]
	v_mov_b32_e32 v114, v165
	v_mov_b32_e32 v115, v165
	s_nop 0
	v_mov_b32_dpp v114, v112 quad_perm:[1,0,3,2] row_mask:0xf bank_mask:0xf
	v_mov_b32_dpp v115, v113 quad_perm:[1,0,3,2] row_mask:0xf bank_mask:0xf
	v_pk_add_f32 v[112:113], v[112:113], v[114:115]
	v_mov_b32_e32 v114, v112
	v_mov_b32_e32 v115, v113
	s_nop 1
	v_permlane16_swap_b32_e32 v112, v114
	v_permlane16_swap_b32_e32 v113, v115
	s_waitcnt lgkmcnt(0)
	v_pk_add_f32 v[114:115], v[112:113], v[114:115]
	v_mov_b32_e32 v116, v114
	v_mov_b32_e32 v117, v115
	s_nop 1
	v_permlane32_swap_b32_e32 v114, v116
	v_permlane32_swap_b32_e32 v115, v117
	v_lshl_add_u64 v[112:113], s[16:17], 0, v[192:193]
	global_store_dwordx4 v[112:113], v[148:151], off
	s_and_saveexec_b64 s[56:57], s[12:13]
	s_waitcnt lgkmcnt(0)
	v_pk_add_f32 v[114:115], v[114:115], v[116:117]
	v_add_co_u32_e32 v116, vcc, 0x2000, v186
	s_nop 1
	v_addc_co_u32_e32 v117, vcc, 0, v187, vcc
	global_store_dwordx2 v[116:117], v[114:115], off
.LBB0_1703:
	s_or_b64 exec, exec, s[56:57]
	ds_read_b64 v[114:115], v201 offset:136
	s_waitcnt lgkmcnt(1)
	s_waitcnt vmcnt(14)
	v_lshlrev_b32_e32 v117, 16, v144
	v_and_b32_e32 v118, 0xffff0000, v144
	v_cndmask_b32_e64 v109, v109, v122, s[6:7]
	v_cndmask_b32_e64 v108, v108, v120, s[6:7]
	s_waitcnt lgkmcnt(0)
	v_mul_f32_e32 v116, 0x3fb504f3, v115
	v_sub_f32_e32 v119, v118, v114
	v_sub_f32_e32 v118, v117, v114
	v_pk_mul_f32 v[118:119], v[118:119], v[116:117] op_sel_hi:[1,0]
	v_cndmask_b32_e64 v111, v111, v123, s[6:7]
	v_cndmask_b32_e64 v110, v110, v121, s[6:7]
	v_cndmask_b32_e64 v104, v104, v124, s[6:7]
	v_cndmask_b32_e64 v106, v106, v125, s[6:7]
	v_lshlrev_b32_e32 v120, 16, v145
	v_and_b32_e32 v121, 0xffff0000, v145
	v_lshlrev_b32_e32 v122, 16, v146
	v_and_b32_e32 v123, 0xffff0000, v146
	v_lshlrev_b32_e32 v124, 16, v147
	v_and_b32_e32 v125, 0xffff0000, v147
	v_pk_fma_f32 v[118:119], v[76:77], v[118:119], v[184:185]
	v_sub_f32_e32 v121, v121, v114
	v_sub_f32_e32 v120, v120, v114
	v_pk_add_f32 v[108:109], v[108:109], v[118:119]
	v_sub_f32_e32 v119, v123, v114
	v_sub_f32_e32 v118, v122, v114
	v_sub_f32_e32 v115, v125, v114
	v_sub_f32_e32 v114, v124, v114
	v_pk_mul_f32 v[120:121], v[120:121], v[116:117] op_sel_hi:[1,0]
	v_pk_mul_f32 v[114:115], v[114:115], v[116:117] op_sel_hi:[1,0]
	v_pk_mul_f32 v[116:117], v[118:119], v[116:117] op_sel_hi:[1,0]
	v_cndmask_b32_e64 v105, v105, v126, s[6:7]
	v_cndmask_b32_e64 v107, v107, v127, s[6:7]
	v_pk_fma_f32 v[120:121], v[78:79], v[120:121], v[182:183]
	v_pk_fma_f32 v[116:117], v[72:73], v[116:117], v[180:181]
	v_pk_fma_f32 v[114:115], v[74:75], v[114:115], v[178:179]
	v_pk_add_f32 v[110:111], v[110:111], v[120:121]
	v_pk_add_f32 v[106:107], v[106:107], v[114:115]
	v_pk_add_f32 v[104:105], v[104:105], v[116:117]
	v_cvt_pk_bf16_f32 v108, v108, v109
	v_cvt_pk_bf16_f32 v109, v110, v111
	s_nop 0
	v_cvt_pk_bf16_f32 v110, v104, v105
	v_cvt_pk_bf16_f32 v111, v106, v107
	v_lshlrev_b32_e32 v104, 16, v108
	v_and_b32_e32 v106, 0xffff0000, v108
	v_lshlrev_b32_e32 v114, 16, v109
	v_and_b32_e32 v116, 0xffff0000, v109
	v_lshlrev_b32_e32 v118, 16, v110
	v_and_b32_e32 v120, 0xffff0000, v110
	v_lshlrev_b32_e32 v122, 16, v111
	v_and_b32_e32 v124, 0xffff0000, v111
	v_mul_f32_e32 v105, v104, v104
	v_mul_f32_e32 v107, v106, v106
	v_mul_f32_e32 v115, v114, v114
	v_mul_f32_e32 v117, v116, v116
	v_mul_f32_e32 v119, v118, v118
	v_mul_f32_e32 v121, v120, v120
	v_mul_f32_e32 v123, v122, v122
	v_mul_f32_e32 v125, v124, v124
	v_pk_add_f32 v[104:105], v[104:105], v[106:107]
	v_pk_add_f32 v[106:107], v[114:115], v[116:117]
	v_pk_add_f32 v[114:115], v[122:123], v[124:125]
	v_pk_add_f32 v[104:105], v[104:105], v[106:107]
	v_pk_add_f32 v[106:107], v[118:119], v[120:121]
	global_store_dwordx4 v[112:113], v[108:111], off offset:128
	v_pk_add_f32 v[106:107], v[106:107], v[114:115]
	s_nop 0
	v_pk_add_f32 v[104:105], v[104:105], v[106:107]
	v_mov_b32_e32 v106, v165
	v_mov_b32_e32 v107, v165
	s_nop 0
	v_mov_b32_dpp v106, v104 quad_perm:[1,0,3,2] row_mask:0xf bank_mask:0xf
	v_mov_b32_dpp v107, v105 quad_perm:[1,0,3,2] row_mask:0xf bank_mask:0xf
	v_pk_add_f32 v[104:105], v[104:105], v[106:107]
	v_mov_b32_e32 v106, v104
	v_mov_b32_e32 v107, v105
	s_nop 1
	v_permlane16_swap_b32_e32 v104, v106
	v_permlane16_swap_b32_e32 v105, v107
	s_waitcnt lgkmcnt(0)
	v_pk_add_f32 v[104:105], v[104:105], v[106:107]
	v_mov_b32_e32 v106, v104
	v_mov_b32_e32 v107, v105
	s_nop 1
	v_permlane32_swap_b32_e32 v104, v106
	v_permlane32_swap_b32_e32 v105, v107
	s_and_saveexec_b64 s[56:57], s[12:13]
	s_waitcnt lgkmcnt(0)
	v_pk_add_f32 v[104:105], v[104:105], v[106:107]
	v_add_co_u32_e32 v106, vcc, 0x2000, v186
	s_nop 1
	v_addc_co_u32_e32 v107, vcc, 0, v187, vcc
	global_store_dwordx2 v[106:107], v[104:105], off offset:512
; __device__ __forceinline__ u32x4 pack8f(f32x4 a, f32x4 b) { u32x4 w; w.x = cvt_pk_bf16(a[0], a[1]); w.y = cvt_pk_bf16(a[2], a[3]); w.z = cvt_pk_bf16(b[0], b[1]); w.w = cvt_pk_bf16(b[2], b[3]); return w; }
;     __device__ __forceinline__ void operator()(const f32x4 (&acc)[2][2][4][2], const Unit& u, int wr, int wc, int fr, int fq, const EpiCtx& X) const {
;     ...
;             for (int m = 0; m < 4; ++m) {
;                 const int rl = ai * HALF + m * 16; const unsigned off = lo + (unsigned)(rl * 64) * 2u;
;                 const f32x4 o0a = acc[ai][0][m][0], o0b = acc[ai][0][m][1], o1a = acc[ai][1][m][0], o1b = acc[ai][1][m][1];
;                 const f32x4 ra_ = dpp_swap1(odd ? o0a : o1a), rb_ = dpp_swap1(odd ? o0b : o1b);
;                 const f32x4 pa[2] = {odd ? ra_ : o0a, odd ? o1a : ra_}, pb[2] = {odd ? rb_ : o0b, odd ? o1b : rb_};
; #pragma unroll
;                 for (int q = 0; q < 2; ++q) {
;                     const u32x4 w0 = raw[2 * m + q];
;                     const f32x4 r0 = (f32x4){bf_lo(w0.x), bf_hi(w0.x), bf_lo(w0.y), bf_hi(w0.y)}, r1 = (f32x4){bf_lo(w0.z), bf_hi(w0.z), bf_lo(w0.w), bf_hi(w0.w)};
;                     f32x4 y0, y1;
;                     if (RESN) { const f32x2 t = tbl[rl + q]; const float mu = t.x, ra = t.y * ALPHA; y0 = (r0 - mu) * ra * g0 + b0 + pa[q]; y1 = (r1 - mu) * ra * g1 + b1 + pb[q]; }
;                     else { y0 = r0 * ALPHA + pa[q]; y1 = r1 * ALPHA + pb[q]; }
;                     { const u32x4 w = pack8f(y0, y1); *(u32x4*)(xb + off + q * 128) = w;
;                         y0 = (f32x4){bf_lo(w.x), bf_hi(w.x), bf_lo(w.y), bf_hi(w.y)}; y1 = (f32x4){bf_lo(w.z), bf_hi(w.z), bf_lo(w.w), bf_hi(w.w)}; }
;                     float sa = ((y0[0] + y0[1]) + (y0[2] + y0[3])) + ((y1[0] + y1[1]) + (y1[2] + y1[3]));
;                     float sb = ((y0[0] * y0[0] + y0[1] * y0[1]) + (y0[2] * y0[2] + y0[3] * y0[3])) + ((y1[0] * y1[0] + y1[1] * y1[1]) + (y1[2] * y1[2] + y1[3] * y1[3]));
;                     sa += dpp_x1(sa);
;                     sb += dpp_x1(sb);
;                     sa += __shfl_xor(sa, 16); sa += __shfl_xor(sa, 32); sb += __shfl_xor(sb, 16); sb += __shfl_xor(sb, 32);
;                     if (fq == 0 && !odd) ps[(size_t)(rl + q) * 64] = (f32x2){sa, sb};
;                 }
.LBB0_1705:
	s_or_b64 exec, exec, s[56:57]
	s_waitcnt lgkmcnt(0)
	v_cndmask_b32_e64 v106, v100, v92, s[6:7]
	v_mov_b32_e32 v104, 0
	v_cndmask_b32_e64 v105, v101, v93, s[6:7]
	s_waitcnt lgkmcnt(0)
	v_cndmask_b32_e64 v107, v102, v94, s[6:7]
	v_mov_b32_dpp v104, v106 quad_perm:[1,0,3,2] row_mask:0xf bank_mask:0xf
	v_mov_b32_e32 v106, 0
	v_cndmask_b32_e64 v108, v103, v95, s[6:7]
	v_cndmask_b32_e64 v110, v96, v88, s[6:7]
	v_mov_b32_dpp v106, v105 quad_perm:[1,0,3,2] row_mask:0xf bank_mask:0xf
	v_mov_b32_e32 v105, 0
	v_cndmask_b32_e64 v109, v97, v89, s[6:7]
	v_cndmask_b32_e64 v111, v98, v90, s[6:7]
	v_mov_b32_dpp v105, v107 quad_perm:[1,0,3,2] row_mask:0xf bank_mask:0xf
	v_mov_b32_e32 v107, 0
	v_cndmask_b32_e64 v112, v99, v91, s[6:7]
	s_waitcnt vmcnt(15)
	v_lshlrev_b32_e32 v115, 16, v140
	v_mov_b32_dpp v107, v108 quad_perm:[1,0,3,2] row_mask:0xf bank_mask:0xf
	v_mov_b32_e32 v108, 0
	v_and_b32_e32 v116, 0xffff0000, v140
	v_cndmask_b32_e64 v101, v106, v101, s[6:7]
	v_mov_b32_dpp v108, v110 quad_perm:[1,0,3,2] row_mask:0xf bank_mask:0xf
	v_mov_b32_e32 v110, 0
	v_cndmask_b32_e64 v100, v104, v100, s[6:7]
	v_lshlrev_b32_e32 v118, 16, v141
	v_mov_b32_dpp v110, v109 quad_perm:[1,0,3,2] row_mask:0xf bank_mask:0xf
	v_mov_b32_e32 v109, 0
	v_and_b32_e32 v119, 0xffff0000, v141
	v_lshlrev_b32_e32 v120, 16, v142
	v_mov_b32_dpp v109, v111 quad_perm:[1,0,3,2] row_mask:0xf bank_mask:0xf
	v_mov_b32_e32 v111, 0
	v_and_b32_e32 v121, 0xffff0000, v142
	v_lshlrev_b32_e32 v122, 16, v143
	v_mov_b32_dpp v111, v112 quad_perm:[1,0,3,2] row_mask:0xf bank_mask:0xf
	ds_read_b64 v[112:113], v201 offset:256
	v_and_b32_e32 v123, 0xffff0000, v143
	v_cndmask_b32_e64 v103, v107, v103, s[6:7]
	v_cndmask_b32_e64 v102, v105, v102, s[6:7]
	v_cndmask_b32_e64 v97, v110, v97, s[6:7]
	s_waitcnt lgkmcnt(0)
	v_mul_f32_e32 v114, 0x3fb504f3, v113
	v_sub_f32_e32 v117, v116, v112
	v_sub_f32_e32 v116, v115, v112
	v_pk_mul_f32 v[116:117], v[116:117], v[114:115] op_sel_hi:[1,0]
	v_sub_f32_e32 v119, v119, v112
	v_pk_fma_f32 v[116:117], v[76:77], v[116:117], v[184:185]
	v_sub_f32_e32 v118, v118, v112
	v_pk_add_f32 v[100:101], v[100:101], v[116:117]
	v_sub_f32_e32 v117, v121, v112
	v_sub_f32_e32 v116, v120, v112
	v_sub_f32_e32 v113, v123, v112
	v_sub_f32_e32 v112, v122, v112
	v_pk_mul_f32 v[118:119], v[118:119], v[114:115] op_sel_hi:[1,0]
	v_pk_mul_f32 v[112:113], v[112:113], v[114:115] op_sel_hi:[1,0]
	v_pk_mul_f32 v[114:115], v[116:117], v[114:115] op_sel_hi:[1,0]
	v_cndmask_b32_e64 v96, v108, v96, s[6:7]
	v_cndmask_b32_e64 v99, v111, v99, s[6:7]
	v_cndmask_b32_e64 v98, v109, v98, s[6:7]
	v_pk_fma_f32 v[118:119], v[78:79], v[118:119], v[182:183]
	v_pk_fma_f32 v[114:115], v[72:73], v[114:115], v[180:181]
	v_pk_fma_f32 v[112:113], v[74:75], v[112:113], v[178:179]
	v_pk_add_f32 v[102:103], v[102:103], v[118:119]
	v_pk_add_f32 v[98:99], v[98:99], v[112:113]
	v_pk_add_f32 v[96:97], v[96:97], v[114:115]
	v_cvt_pk_bf16_f32 v112, v100, v101
	v_cvt_pk_bf16_f32 v113, v102, v103
	v_mov_b32_e32 v191, v165
	v_cvt_pk_bf16_f32 v114, v96, v97
	v_cvt_pk_bf16_f32 v115, v98, v99
	v_lshlrev_b32_e32 v96, 16, v112
	v_and_b32_e32 v98, 0xffff0000, v112
	v_lshlrev_b32_e32 v100, 16, v113
	v_and_b32_e32 v102, 0xffff0000, v113
	v_lshlrev_b32_e32 v116, 16, v114
	v_and_b32_e32 v118, 0xffff0000, v114
	v_lshlrev_b32_e32 v120, 16, v115
	v_and_b32_e32 v122, 0xffff0000, v115
	v_mul_f32_e32 v97, v96, v96
	v_mul_f32_e32 v99, v98, v98
	v_mul_f32_e32 v101, v100, v100
	v_mul_f32_e32 v103, v102, v102
	v_mul_f32_e32 v117, v116, v116
	v_mul_f32_e32 v119, v118, v118
	v_mul_f32_e32 v121, v120, v120
	v_mul_f32_e32 v123, v122, v122
	v_pk_add_f32 v[96:97], v[96:97], v[98:99]
	v_pk_add_f32 v[98:99], v[100:101], v[102:103]
	v_pk_add_f32 v[100:101], v[120:121], v[122:123]
	v_pk_add_f32 v[96:97], v[96:97], v[98:99]
	v_pk_add_f32 v[98:99], v[116:117], v[118:119]
	s_nop 0
	v_pk_add_f32 v[98:99], v[98:99], v[100:101]
	s_nop 0
	v_pk_add_f32 v[96:97], v[96:97], v[98:99]
	v_mov_b32_e32 v98, v165
	v_mov_b32_e32 v99, v165
	s_nop 0
	v_mov_b32_dpp v98, v96 quad_perm:[1,0,3,2] row_mask:0xf bank_mask:0xf
	v_mov_b32_dpp v99, v97 quad_perm:[1,0,3,2] row_mask:0xf bank_mask:0xf
	v_pk_add_f32 v[96:97], v[96:97], v[98:99]
	v_mov_b32_e32 v98, v96
	v_mov_b32_e32 v99, v97
	s_nop 1
	v_permlane16_swap_b32_e32 v96, v98
	v_permlane16_swap_b32_e32 v97, v99
	s_waitcnt lgkmcnt(0)
	v_pk_add_f32 v[98:99], v[96:97], v[98:99]
	v_mov_b32_e32 v100, v98
	v_mov_b32_e32 v101, v99
	s_nop 1
	v_permlane32_swap_b32_e32 v98, v100
	v_permlane32_swap_b32_e32 v99, v101
	v_lshl_add_u64 v[96:97], s[16:17], 0, v[190:191]
	global_store_dwordx4 v[96:97], v[112:115], off
	s_and_saveexec_b64 s[56:57], s[12:13]
	s_waitcnt lgkmcnt(0)
	v_pk_add_f32 v[98:99], v[98:99], v[100:101]
	v_add_co_u32_e32 v100, vcc, 0x4000, v186
	s_nop 1
	v_addc_co_u32_e32 v101, vcc, 0, v187, vcc
	global_store_dwordx2 v[100:101], v[98:99], off
; __device__ __forceinline__ u32x4 pack8f(f32x4 a, f32x4 b) { u32x4 w; w.x = cvt_pk_bf16(a[0], a[1]); w.y = cvt_pk_bf16(a[2], a[3]); w.z = cvt_pk_bf16(b[0], b[1]); w.w = cvt_pk_bf16(b[2], b[3]); return w; }
;     __device__ __forceinline__ void operator()(const f32x4 (&acc)[2][2][4][2], const Unit& u, int wr, int wc, int fr, int fq, const EpiCtx& X) const {
;     ...
;             for (int m = 0; m < 4; ++m) {
;                 const int rl = ai * HALF + m * 16; const unsigned off = lo + (unsigned)(rl * 64) * 2u;
;                 const f32x4 o0a = acc[ai][0][m][0], o0b = acc[ai][0][m][1], o1a = acc[ai][1][m][0], o1b = acc[ai][1][m][1];
;                 const f32x4 ra_ = dpp_swap1(odd ? o0a : o1a), rb_ = dpp_swap1(odd ? o0b : o1b);
;                 const f32x4 pa[2] = {odd ? ra_ : o0a, odd ? o1a : ra_}, pb[2] = {odd ? rb_ : o0b, odd ? o1b : rb_};
; #pragma unroll
;                 for (int q = 0; q < 2; ++q) {
;                     const u32x4 w0 = raw[2 * m + q];
;                     const f32x4 r0 = (f32x4){bf_lo(w0.x), bf_hi(w0.x), bf_lo(w0.y), bf_hi(w0.y)}, r1 = (f32x4){bf_lo(w0.z), bf_hi(w0.z), bf_lo(w0.w), bf_hi(w0.w)};
;                     f32x4 y0, y1;
;                     if (RESN) { const f32x2 t = tbl[rl + q]; const float mu = t.x, ra = t.y * ALPHA; y0 = (r0 - mu) * ra * g0 + b0 + pa[q]; y1 = (r1 - mu) * ra * g1 + b1 + pb[q]; }
;                     else { y0 = r0 * ALPHA + pa[q]; y1 = r1 * ALPHA + pb[q]; }
;                     { const u32x4 w = pack8f(y0, y1); *(u32x4*)(xb + off + q * 128) = w;
;                         y0 = (f32x4){bf_lo(w.x), bf_hi(w.x), bf_lo(w.y), bf_hi(w.y)}; y1 = (f32x4){bf_lo(w.z), bf_hi(w.z), bf_lo(w.w), bf_hi(w.w)}; }
;                     float sa = ((y0[0] + y0[1]) + (y0[2] + y0[3])) + ((y1[0] + y1[1]) + (y1[2] + y1[3]));
;                     float sb = ((y0[0] * y0[0] + y0[1] * y0[1]) + (y0[2] * y0[2] + y0[3] * y0[3])) + ((y1[0] * y1[0] + y1[1] * y1[1]) + (y1[2] * y1[2] + y1[3] * y1[3]));
;                     sa += dpp_x1(sa);
;                     sb += dpp_x1(sb);
;                     sa += __shfl_xor(sa, 16); sa += __shfl_xor(sa, 32); sb += __shfl_xor(sb, 16); sb += __shfl_xor(sb, 32);
;                     if (fq == 0 && !odd) ps[(size_t)(rl + q) * 64] = (f32x2){sa, sb};
;                 }
.LBB0_1707:
	s_or_b64 exec, exec, s[56:57]
	ds_read_b64 v[98:99], v201 offset:264
	s_waitcnt lgkmcnt(1)
	s_waitcnt vmcnt(16)
	v_lshlrev_b32_e32 v101, 16, v136
	v_and_b32_e32 v102, 0xffff0000, v136
	v_cndmask_b32_e64 v93, v93, v106, s[6:7]
	v_cndmask_b32_e64 v92, v92, v104, s[6:7]
	s_waitcnt lgkmcnt(0)
	v_mul_f32_e32 v100, 0x3fb504f3, v99
	v_sub_f32_e32 v103, v102, v98
	v_sub_f32_e32 v102, v101, v98
	v_pk_mul_f32 v[102:103], v[102:103], v[100:101] op_sel_hi:[1,0]
	v_cndmask_b32_e64 v95, v95, v107, s[6:7]
	v_cndmask_b32_e64 v94, v94, v105, s[6:7]
	v_cndmask_b32_e64 v88, v88, v108, s[6:7]
	v_cndmask_b32_e64 v90, v90, v109, s[6:7]
	v_lshlrev_b32_e32 v104, 16, v137
	v_and_b32_e32 v105, 0xffff0000, v137
	v_lshlrev_b32_e32 v106, 16, v138
	v_and_b32_e32 v107, 0xffff0000, v138
	v_lshlrev_b32_e32 v108, 16, v139
	v_and_b32_e32 v109, 0xffff0000, v139
	v_pk_fma_f32 v[102:103], v[76:77], v[102:103], v[184:185]
	v_sub_f32_e32 v105, v105, v98
	v_sub_f32_e32 v104, v104, v98
	v_pk_add_f32 v[92:93], v[92:93], v[102:103]
	v_sub_f32_e32 v103, v107, v98
	v_sub_f32_e32 v102, v106, v98
	v_sub_f32_e32 v99, v109, v98
	v_sub_f32_e32 v98, v108, v98
	v_pk_mul_f32 v[104:105], v[104:105], v[100:101] op_sel_hi:[1,0]
	v_pk_mul_f32 v[98:99], v[98:99], v[100:101] op_sel_hi:[1,0]
	v_pk_mul_f32 v[100:101], v[102:103], v[100:101] op_sel_hi:[1,0]
	v_cndmask_b32_e64 v89, v89, v110, s[6:7]
	v_cndmask_b32_e64 v91, v91, v111, s[6:7]
	v_pk_fma_f32 v[104:105], v[78:79], v[104:105], v[182:183]
	v_pk_fma_f32 v[100:101], v[72:73], v[100:101], v[180:181]
	v_pk_fma_f32 v[98:99], v[74:75], v[98:99], v[178:179]
	v_pk_add_f32 v[94:95], v[94:95], v[104:105]
	v_pk_add_f32 v[90:91], v[90:91], v[98:99]
	v_pk_add_f32 v[88:89], v[88:89], v[100:101]
	v_cvt_pk_bf16_f32 v92, v92, v93
	v_cvt_pk_bf16_f32 v93, v94, v95
	s_nop 0
	v_cvt_pk_bf16_f32 v94, v88, v89
	v_cvt_pk_bf16_f32 v95, v90, v91
	v_lshlrev_b32_e32 v88, 16, v92
	v_and_b32_e32 v90, 0xffff0000, v92
	v_lshlrev_b32_e32 v98, 16, v93
	v_and_b32_e32 v100, 0xffff0000, v93
	v_lshlrev_b32_e32 v102, 16, v94
	v_and_b32_e32 v104, 0xffff0000, v94
	v_lshlrev_b32_e32 v106, 16, v95
	v_and_b32_e32 v108, 0xffff0000, v95
	v_mul_f32_e32 v89, v88, v88
	v_mul_f32_e32 v91, v90, v90
	v_mul_f32_e32 v99, v98, v98
	v_mul_f32_e32 v101, v100, v100
	v_mul_f32_e32 v103, v102, v102
	v_mul_f32_e32 v105, v104, v104
	v_mul_f32_e32 v107, v106, v106
	v_mul_f32_e32 v109, v108, v108
	v_pk_add_f32 v[88:89], v[88:89], v[90:91]
	v_pk_add_f32 v[90:91], v[98:99], v[100:101]
	v_pk_add_f32 v[98:99], v[106:107], v[108:109]
	v_pk_add_f32 v[88:89], v[88:89], v[90:91]
	v_pk_add_f32 v[90:91], v[102:103], v[104:105]
	global_store_dwordx4 v[96:97], v[92:95], off offset:128
	v_pk_add_f32 v[90:91], v[90:91], v[98:99]
	s_nop 0
	v_pk_add_f32 v[88:89], v[88:89], v[90:91]
	v_mov_b32_e32 v90, v165
	v_mov_b32_e32 v91, v165
	s_nop 0
	v_mov_b32_dpp v90, v88 quad_perm:[1,0,3,2] row_mask:0xf bank_mask:0xf
	v_mov_b32_dpp v91, v89 quad_perm:[1,0,3,2] row_mask:0xf bank_mask:0xf
	v_pk_add_f32 v[88:89], v[88:89], v[90:91]
	v_mov_b32_e32 v90, v88
	v_mov_b32_e32 v91, v89
	s_nop 1
	v_permlane16_swap_b32_e32 v88, v90
	v_permlane16_swap_b32_e32 v89, v91
	s_waitcnt lgkmcnt(0)
	v_pk_add_f32 v[88:89], v[88:89], v[90:91]
	v_mov_b32_e32 v90, v88
	v_mov_b32_e32 v91, v89
	s_nop 1
	v_permlane32_swap_b32_e32 v88, v90
	v_permlane32_swap_b32_e32 v89, v91
	s_and_saveexec_b64 s[56:57], s[12:13]
	s_waitcnt lgkmcnt(0)
	v_pk_add_f32 v[88:89], v[88:89], v[90:91]
	v_add_co_u32_e32 v90, vcc, 0x4000, v186
	s_nop 1
	v_addc_co_u32_e32 v91, vcc, 0, v187, vcc
	global_store_dwordx2 v[90:91], v[88:89], off offset:512
.LBB0_1709:
	s_or_b64 exec, exec, s[56:57]
	s_waitcnt lgkmcnt(0)
	v_cndmask_b32_e64 v90, v84, v68, s[6:7]
	v_mov_b32_e32 v88, 0
	v_cndmask_b32_e64 v89, v85, v69, s[6:7]
	s_waitcnt lgkmcnt(0)
	v_cndmask_b32_e64 v91, v86, v70, s[6:7]
	v_mov_b32_dpp v88, v90 quad_perm:[1,0,3,2] row_mask:0xf bank_mask:0xf
	v_mov_b32_e32 v90, 0
	v_cndmask_b32_e64 v92, v87, v71, s[6:7]
	v_cndmask_b32_e64 v94, v80, v64, s[6:7]
	v_mov_b32_dpp v90, v89 quad_perm:[1,0,3,2] row_mask:0xf bank_mask:0xf
	v_mov_b32_e32 v89, 0
	v_cndmask_b32_e64 v93, v81, v65, s[6:7]
	v_cndmask_b32_e64 v95, v82, v66, s[6:7]
	v_mov_b32_dpp v89, v91 quad_perm:[1,0,3,2] row_mask:0xf bank_mask:0xf
	v_mov_b32_e32 v91, 0
	v_cndmask_b32_e64 v96, v83, v67, s[6:7]
	s_waitcnt vmcnt(17)
	v_lshlrev_b32_e32 v99, 16, v132
	v_mov_b32_dpp v91, v92 quad_perm:[1,0,3,2] row_mask:0xf bank_mask:0xf
	v_mov_b32_e32 v92, 0
	v_and_b32_e32 v100, 0xffff0000, v132
	v_cndmask_b32_e64 v85, v90, v85, s[6:7]
	v_mov_b32_dpp v92, v94 quad_perm:[1,0,3,2] row_mask:0xf bank_mask:0xf
	v_mov_b32_e32 v94, 0
	v_cndmask_b32_e64 v84, v88, v84, s[6:7]
	v_lshlrev_b32_e32 v102, 16, v133
	v_mov_b32_dpp v94, v93 quad_perm:[1,0,3,2] row_mask:0xf bank_mask:0xf
	v_mov_b32_e32 v93, 0
	v_and_b32_e32 v103, 0xffff0000, v133
	v_lshlrev_b32_e32 v104, 16, v134
	v_mov_b32_dpp v93, v95 quad_perm:[1,0,3,2] row_mask:0xf bank_mask:0xf
	v_mov_b32_e32 v95, 0
	v_and_b32_e32 v105, 0xffff0000, v134
	v_lshlrev_b32_e32 v106, 16, v135
	v_mov_b32_dpp v95, v96 quad_perm:[1,0,3,2] row_mask:0xf bank_mask:0xf
	ds_read_b64 v[96:97], v201 offset:384
	v_and_b32_e32 v107, 0xffff0000, v135
	v_cndmask_b32_e64 v87, v91, v87, s[6:7]
	v_cndmask_b32_e64 v86, v89, v86, s[6:7]
	v_cndmask_b32_e64 v81, v94, v81, s[6:7]
	s_waitcnt lgkmcnt(0)
; __device__ __forceinline__ u32x4 pack8f(f32x4 a, f32x4 b) { u32x4 w; w.x = cvt_pk_bf16(a[0], a[1]); w.y = cvt_pk_bf16(a[2], a[3]); w.z = cvt_pk_bf16(b[0], b[1]); w.w = cvt_pk_bf16(b[2], b[3]); return w; }
;     __device__ __forceinline__ void operator()(const f32x4 (&acc)[2][2][4][2], const Unit& u, int wr, int wc, int fr, int fq, const EpiCtx& X) const {
;     ...
;             for (int m = 0; m < 4; ++m) {
;                 const int rl = ai * HALF + m * 16; const unsigned off = lo + (unsigned)(rl * 64) * 2u;
;                 const f32x4 o0a = acc[ai][0][m][0], o0b = acc[ai][0][m][1], o1a = acc[ai][1][m][0], o1b = acc[ai][1][m][1];
;                 const f32x4 ra_ = dpp_swap1(odd ? o0a : o1a), rb_ = dpp_swap1(odd ? o0b : o1b);
;                 const f32x4 pa[2] = {odd ? ra_ : o0a, odd ? o1a : ra_}, pb[2] = {odd ? rb_ : o0b, odd ? o1b : rb_};
; #pragma unroll
;                 for (int q = 0; q < 2; ++q) {
;                     const u32x4 w0 = raw[2 * m + q];
;                     const f32x4 r0 = (f32x4){bf_lo(w0.x), bf_hi(w0.x), bf_lo(w0.y), bf_hi(w0.y)}, r1 = (f32x4){bf_lo(w0.z), bf_hi(w0.z), bf_lo(w0.w), bf_hi(w0.w)};
;                     f32x4 y0, y1;
;                     if (RESN) { const f32x2 t = tbl[rl + q]; const float mu = t.x, ra = t.y * ALPHA; y0 = (r0 - mu) * ra * g0 + b0 + pa[q]; y1 = (r1 - mu) * ra * g1 + b1 + pb[q]; }
;                     else { y0 = r0 * ALPHA + pa[q]; y1 = r1 * ALPHA + pb[q]; }
;                     { const u32x4 w = pack8f(y0, y1); *(u32x4*)(xb + off + q * 128) = w;
;                         y0 = (f32x4){bf_lo(w.x), bf_hi(w.x), bf_lo(w.y), bf_hi(w.y)}; y1 = (f32x4){bf_lo(w.z), bf_hi(w.z), bf_lo(w.w), bf_hi(w.w)}; }
;                     float sa = ((y0[0] + y0[1]) + (y0[2] + y0[3])) + ((y1[0] + y1[1]) + (y1[2] + y1[3]));
;                     float sb = ((y0[0] * y0[0] + y0[1] * y0[1]) + (y0[2] * y0[2] + y0[3] * y0[3])) + ((y1[0] * y1[0] + y1[1] * y1[1]) + (y1[2] * y1[2] + y1[3] * y1[3]));
;                     sa += dpp_x1(sa);
;                     sb += dpp_x1(sb);
;                     sa += __shfl_xor(sa, 16); sa += __shfl_xor(sa, 32); sb += __shfl_xor(sb, 16); sb += __shfl_xor(sb, 32);
;                     if (fq == 0 && !odd) ps[(size_t)(rl + q) * 64] = (f32x2){sa, sb};
;                 }
	v_mul_f32_e32 v98, 0x3fb504f3, v97
	v_sub_f32_e32 v101, v100, v96
	v_sub_f32_e32 v100, v99, v96
	v_pk_mul_f32 v[100:101], v[100:101], v[98:99] op_sel_hi:[1,0]
	v_sub_f32_e32 v103, v103, v96
	v_pk_fma_f32 v[100:101], v[76:77], v[100:101], v[184:185]
	v_sub_f32_e32 v102, v102, v96
	v_pk_add_f32 v[84:85], v[84:85], v[100:101]
	v_sub_f32_e32 v101, v105, v96
	v_sub_f32_e32 v100, v104, v96
	v_sub_f32_e32 v97, v107, v96
	v_sub_f32_e32 v96, v106, v96
	v_pk_mul_f32 v[102:103], v[102:103], v[98:99] op_sel_hi:[1,0]
	v_pk_mul_f32 v[96:97], v[96:97], v[98:99] op_sel_hi:[1,0]
	v_pk_mul_f32 v[98:99], v[100:101], v[98:99] op_sel_hi:[1,0]
	v_cndmask_b32_e64 v80, v92, v80, s[6:7]
	v_cndmask_b32_e64 v83, v95, v83, s[6:7]
	v_cndmask_b32_e64 v82, v93, v82, s[6:7]
	v_pk_fma_f32 v[102:103], v[78:79], v[102:103], v[182:183]
	v_pk_fma_f32 v[98:99], v[72:73], v[98:99], v[180:181]
	v_pk_fma_f32 v[96:97], v[74:75], v[96:97], v[178:179]
	v_pk_add_f32 v[86:87], v[86:87], v[102:103]
	v_pk_add_f32 v[82:83], v[82:83], v[96:97]
	v_pk_add_f32 v[80:81], v[80:81], v[98:99]
	v_cvt_pk_bf16_f32 v96, v84, v85
	v_cvt_pk_bf16_f32 v97, v86, v87
	v_mov_b32_e32 v189, v165
	v_cvt_pk_bf16_f32 v98, v80, v81
	v_cvt_pk_bf16_f32 v99, v82, v83
	v_lshlrev_b32_e32 v80, 16, v96
	v_and_b32_e32 v82, 0xffff0000, v96
	v_lshlrev_b32_e32 v84, 16, v97
	v_and_b32_e32 v86, 0xffff0000, v97
	v_lshlrev_b32_e32 v100, 16, v98
	v_and_b32_e32 v102, 0xffff0000, v98
	v_lshlrev_b32_e32 v104, 16, v99
	v_and_b32_e32 v106, 0xffff0000, v99
	v_mul_f32_e32 v81, v80, v80
	v_mul_f32_e32 v83, v82, v82
	v_mul_f32_e32 v85, v84, v84
	v_mul_f32_e32 v87, v86, v86
	v_mul_f32_e32 v101, v100, v100
	v_mul_f32_e32 v103, v102, v102
	v_mul_f32_e32 v105, v104, v104
	v_mul_f32_e32 v107, v106, v106
	v_pk_add_f32 v[80:81], v[80:81], v[82:83]
	v_pk_add_f32 v[82:83], v[84:85], v[86:87]
	v_pk_add_f32 v[84:85], v[104:105], v[106:107]
	v_pk_add_f32 v[80:81], v[80:81], v[82:83]
	v_pk_add_f32 v[82:83], v[100:101], v[102:103]
	s_nop 0
	v_pk_add_f32 v[82:83], v[82:83], v[84:85]
	s_nop 0
	v_pk_add_f32 v[80:81], v[80:81], v[82:83]
	v_mov_b32_e32 v82, v165
	v_mov_b32_e32 v83, v165
	s_nop 0
	v_mov_b32_dpp v82, v80 quad_perm:[1,0,3,2] row_mask:0xf bank_mask:0xf
	v_mov_b32_dpp v83, v81 quad_perm:[1,0,3,2] row_mask:0xf bank_mask:0xf
	v_pk_add_f32 v[80:81], v[80:81], v[82:83]
	v_mov_b32_e32 v82, v80
	v_mov_b32_e32 v83, v81
	s_nop 1
	v_permlane16_swap_b32_e32 v80, v82
	v_permlane16_swap_b32_e32 v81, v83
	s_waitcnt lgkmcnt(0)
	v_pk_add_f32 v[82:83], v[80:81], v[82:83]
	v_mov_b32_e32 v84, v82
	v_mov_b32_e32 v85, v83
	s_nop 1
	v_permlane32_swap_b32_e32 v82, v84
	v_permlane32_swap_b32_e32 v83, v85
	v_lshl_add_u64 v[80:81], s[16:17], 0, v[188:189]
	global_store_dwordx4 v[80:81], v[96:99], off
	s_and_saveexec_b64 s[56:57], s[12:13]
	s_waitcnt lgkmcnt(0)
	v_pk_add_f32 v[82:83], v[82:83], v[84:85]
	v_add_co_u32_e32 v84, vcc, 0x6000, v186
	s_nop 1
	v_addc_co_u32_e32 v85, vcc, 0, v187, vcc
	global_store_dwordx2 v[84:85], v[82:83], off
.LBB0_1711:
	s_or_b64 exec, exec, s[56:57]
	ds_read_b64 v[82:83], v201 offset:392
	s_waitcnt lgkmcnt(1)
	s_waitcnt vmcnt(18)
	v_lshlrev_b32_e32 v85, 16, v128
	v_and_b32_e32 v86, 0xffff0000, v128
	v_cndmask_b32_e64 v69, v69, v90, s[6:7]
	v_cndmask_b32_e64 v68, v68, v88, s[6:7]
	s_waitcnt lgkmcnt(0)
	v_mul_f32_e32 v84, 0x3fb504f3, v83
	v_sub_f32_e32 v87, v86, v82
	v_sub_f32_e32 v86, v85, v82
	v_pk_mul_f32 v[86:87], v[86:87], v[84:85] op_sel_hi:[1,0]
	v_cndmask_b32_e64 v71, v71, v91, s[6:7]
	v_cndmask_b32_e64 v70, v70, v89, s[6:7]
	v_cndmask_b32_e64 v64, v64, v92, s[6:7]
	v_cndmask_b32_e64 v66, v66, v93, s[6:7]
	v_lshlrev_b32_e32 v88, 16, v129
	v_and_b32_e32 v89, 0xffff0000, v129
	v_lshlrev_b32_e32 v90, 16, v130
	v_and_b32_e32 v91, 0xffff0000, v130
	v_lshlrev_b32_e32 v92, 16, v131
	v_and_b32_e32 v93, 0xffff0000, v131
	v_pk_fma_f32 v[86:87], v[76:77], v[86:87], v[184:185]
	v_sub_f32_e32 v89, v89, v82
	v_sub_f32_e32 v88, v88, v82
	v_pk_add_f32 v[68:69], v[68:69], v[86:87]
	v_sub_f32_e32 v87, v91, v82
	v_sub_f32_e32 v86, v90, v82
	v_sub_f32_e32 v83, v93, v82
	v_sub_f32_e32 v82, v92, v82
	v_pk_mul_f32 v[88:89], v[88:89], v[84:85] op_sel_hi:[1,0]
	v_pk_mul_f32 v[82:83], v[82:83], v[84:85] op_sel_hi:[1,0]
	v_pk_mul_f32 v[84:85], v[86:87], v[84:85] op_sel_hi:[1,0]
	v_cndmask_b32_e64 v65, v65, v94, s[6:7]
	v_cndmask_b32_e64 v67, v67, v95, s[6:7]
	v_pk_fma_f32 v[88:89], v[78:79], v[88:89], v[182:183]
	v_pk_fma_f32 v[84:85], v[72:73], v[84:85], v[180:181]
	v_pk_fma_f32 v[82:83], v[74:75], v[82:83], v[178:179]
	v_pk_add_f32 v[70:71], v[70:71], v[88:89]
	v_pk_add_f32 v[66:67], v[66:67], v[82:83]
	v_pk_add_f32 v[64:65], v[64:65], v[84:85]
	v_cvt_pk_bf16_f32 v68, v68, v69
	v_cvt_pk_bf16_f32 v69, v70, v71
	s_nop 0
	v_cvt_pk_bf16_f32 v70, v64, v65
	v_cvt_pk_bf16_f32 v71, v66, v67
	v_lshlrev_b32_e32 v64, 16, v68
	v_and_b32_e32 v66, 0xffff0000, v68
	v_lshlrev_b32_e32 v82, 16, v69
	v_and_b32_e32 v84, 0xffff0000, v69
	v_lshlrev_b32_e32 v86, 16, v70
	v_and_b32_e32 v88, 0xffff0000, v70
	v_lshlrev_b32_e32 v90, 16, v71
	v_and_b32_e32 v92, 0xffff0000, v71
	v_mul_f32_e32 v65, v64, v64
	v_mul_f32_e32 v67, v66, v66
	v_mul_f32_e32 v83, v82, v82
	v_mul_f32_e32 v85, v84, v84
	v_mul_f32_e32 v87, v86, v86
	v_mul_f32_e32 v89, v88, v88
	v_mul_f32_e32 v91, v90, v90
	v_mul_f32_e32 v93, v92, v92
	v_pk_add_f32 v[64:65], v[64:65], v[66:67]
	v_pk_add_f32 v[66:67], v[82:83], v[84:85]
	v_pk_add_f32 v[82:83], v[90:91], v[92:93]
	v_pk_add_f32 v[64:65], v[64:65], v[66:67]
	v_pk_add_f32 v[66:67], v[86:87], v[88:89]
	global_store_dwordx4 v[80:81], v[68:71], off offset:128
	v_pk_add_f32 v[66:67], v[66:67], v[82:83]
	s_nop 0
	v_pk_add_f32 v[64:65], v[64:65], v[66:67]
	v_mov_b32_e32 v66, v165
	v_mov_b32_e32 v67, v165
	s_nop 0
	v_mov_b32_dpp v66, v64 quad_perm:[1,0,3,2] row_mask:0xf bank_mask:0xf
	v_mov_b32_dpp v67, v65 quad_perm:[1,0,3,2] row_mask:0xf bank_mask:0xf
	v_pk_add_f32 v[64:65], v[64:65], v[66:67]
	v_mov_b32_e32 v66, v64
	v_mov_b32_e32 v67, v65
	s_nop 1
	v_permlane16_swap_b32_e32 v64, v66
	v_permlane16_swap_b32_e32 v65, v67
	s_waitcnt lgkmcnt(0)
	v_pk_add_f32 v[64:65], v[64:65], v[66:67]
	v_mov_b32_e32 v66, v64
	v_mov_b32_e32 v67, v65
	s_nop 1
	v_permlane32_swap_b32_e32 v64, v66
	v_permlane32_swap_b32_e32 v65, v67
	s_and_saveexec_b64 s[56:57], s[12:13]
	s_waitcnt lgkmcnt(0)
	v_pk_add_f32 v[64:65], v[64:65], v[66:67]
	v_add_co_u32_e32 v66, vcc, 0x6000, v186
	s_nop 1
	v_addc_co_u32_e32 v67, vcc, 0, v187, vcc
	global_store_dwordx2 v[66:67], v[64:65], off offset:512
;     __device__ __forceinline__ void operator()(const f32x4 (&acc)[2][2][4][2], const Unit& u, int wr, int wc, int fr, int fq, const EpiCtx& X) const {
;     ...
;         for (int ai = 0; ai < 2; ++ai) {
;             u32x4 raw[8];
; #pragma unroll
;             for (int m = 0; m < 4; ++m) { const unsigned off = lo + (unsigned)((ai * HALF + m * 16) * 64) * 2u; raw[2 * m] = *(const u32x4*)(xb + off); raw[2 * m + 1] = *(const u32x4*)(xb + off + 128); }
; #pragma unroll
;             for (int m = 0; m < 4; ++m) {
;                 const int rl = ai * HALF + m * 16; const unsigned off = lo + (unsigned)(rl * 64) * 2u;
;                 const f32x4 o0a = acc[ai][0][m][0], o0b = acc[ai][0][m][1], o1a = acc[ai][1][m][0], o1b = acc[ai][1][m][1];
;                 const f32x4 ra_ = dpp_swap1(odd ? o0a : o1a), rb_ = dpp_swap1(odd ? o0b : o1b);
;                 const f32x4 pa[2] = {odd ? ra_ : o0a, odd ? o1a : ra_}, pb[2] = {odd ? rb_ : o0b, odd ? o1b : rb_};
; #pragma unroll
;                 for (int q = 0; q < 2; ++q) {
;                     const u32x4 w0 = raw[2 * m + q];
;                     const f32x4 r0 = (f32x4){bf_lo(w0.x), bf_hi(w0.x), bf_lo(w0.y), bf_hi(w0.y)}, r1 = (f32x4){bf_lo(w0.z), bf_hi(w0.z), bf_lo(w0.w), bf_hi(w0.w)};
;                     f32x4 y0, y1;
;                     if (RESN) { const f32x2 t = tbl[rl + q]; const float mu = t.x, ra = t.y * ALPHA; y0 = (r0 - mu) * ra * g0 + b0 + pa[q]; y1 = (r1 - mu) * ra * g1 + b1 + pb[q]; }
;                     else { y0 = r0 * ALPHA + pa[q]; y1 = r1 * ALPHA + pb[q]; }
;                     { const u32x4 w = pack8f(y0, y1); *(u32x4*)(xb + off + q * 128) = w;
;                         y0 = (f32x4){bf_lo(w.x), bf_hi(w.x), bf_lo(w.y), bf_hi(w.y)}; y1 = (f32x4){bf_lo(w.z), bf_hi(w.z), bf_lo(w.w), bf_hi(w.w)}; }
;                     float sa = ((y0[0] + y0[1]) + (y0[2] + y0[3])) + ((y1[0] + y1[1]) + (y1[2] + y1[3]));
;                     float sb = ((y0[0] * y0[0] + y0[1] * y0[1]) + (y0[2] * y0[2] + y0[3] * y0[3])) + ((y1[0] * y1[0] + y1[1] * y1[1]) + (y1[2] * y1[2] + y1[3] * y1[3]));
;                     sa += dpp_x1(sa);
;                     sb += dpp_x1(sb);
;                     sa += __shfl_xor(sa, 16); sa += __shfl_xor(sa, 32); sb += __shfl_xor(sb, 16); sb += __shfl_xor(sb, 32);
;                     if (fq == 0 && !odd) ps[(size_t)(rl + q) * 64] = (f32x2){sa, sb};
;                 }
.LBB0_1713:
	s_or_b64 exec, exec, s[56:57]
	v_add_u32_e32 v104, 0x4000, v164
	s_waitcnt vmcnt(16)
	v_mov_b32_e32 v112, v230
	v_mov_b32_e32 v113, v231
	v_mov_b32_e32 v114, v232
	v_mov_b32_e32 v115, v233
	v_add_u32_e32 v102, 0x4800, v164
	v_add_u32_e32 v100, 0x5000, v164
	v_add_u32_e32 v164, 0x5800, v164
	v_mov_b32_e32 v96, v234
	v_mov_b32_e32 v97, v235
	v_mov_b32_e32 v98, v236
	v_mov_b32_e32 v99, v237
	v_mov_b32_e32 v92, v238
	v_mov_b32_e32 v93, v239
	v_mov_b32_e32 v94, v240
	v_mov_b32_e32 v95, v241
	v_mov_b32_e32 v88, v242
	v_mov_b32_e32 v89, v243
	v_mov_b32_e32 v90, v244
	v_mov_b32_e32 v91, v245
	global_load_dwordx4 v[84:87], v100, s[16:17]
	global_load_dwordx4 v[80:83], v100, s[16:17] offset:128
	global_load_dwordx4 v[68:71], v164, s[16:17]
	s_waitcnt lgkmcnt(0)
	global_load_dwordx4 v[64:67], v164, s[16:17] offset:128
	v_cndmask_b32_e64 v116, v62, v54, s[6:7]
	v_cndmask_b32_e64 v117, v61, v53, s[6:7]
	v_mov_b32_e32 v105, 0
	v_mov_b32_e32 v103, 0
	v_cndmask_b32_e64 v111, v63, v55, s[6:7]
	v_mov_b32_dpp v105, v117 quad_perm:[1,0,3,2] row_mask:0xf bank_mask:0xf
	v_mov_b32_dpp v103, v116 quad_perm:[1,0,3,2] row_mask:0xf bank_mask:0xf
	ds_read_b64 v[116:117], v201 offset:1024
	v_cndmask_b32_e64 v118, v60, v52, s[6:7]
	v_mov_b32_e32 v101, 0
	v_mov_b32_e32 v106, 0
	v_cndmask_b32_e64 v119, v59, v51, s[6:7]
	v_cndmask_b32_e64 v120, v58, v50, s[6:7]
	v_cndmask_b32_e64 v121, v57, v49, s[6:7]
	v_cndmask_b32_e64 v122, v56, v48, s[6:7]
	v_mov_b32_e32 v107, 0
	v_mov_b32_e32 v109, 0
	v_mov_b32_e32 v108, 0
	v_mov_b32_e32 v110, 0
	v_mov_b32_dpp v101, v118 quad_perm:[1,0,3,2] row_mask:0xf bank_mask:0xf
	v_mov_b32_dpp v106, v111 quad_perm:[1,0,3,2] row_mask:0xf bank_mask:0xf
	v_mov_b32_dpp v107, v122 quad_perm:[1,0,3,2] row_mask:0xf bank_mask:0xf
	v_mov_b32_dpp v109, v121 quad_perm:[1,0,3,2] row_mask:0xf bank_mask:0xf
	v_mov_b32_dpp v108, v120 quad_perm:[1,0,3,2] row_mask:0xf bank_mask:0xf
	v_mov_b32_dpp v110, v119 quad_perm:[1,0,3,2] row_mask:0xf bank_mask:0xf
	s_waitcnt lgkmcnt(0)
	v_mul_f32_e32 v118, 0x3fb504f3, v117
	v_cndmask_b32_e64 v61, v105, v61, s[6:7]
	v_cndmask_b32_e64 v60, v101, v60, s[6:7]
	v_cndmask_b32_e64 v63, v106, v63, s[6:7]
	v_cndmask_b32_e64 v62, v103, v62, s[6:7]
	v_cndmask_b32_e64 v57, v109, v57, s[6:7]
	v_cndmask_b32_e64 v56, v107, v56, s[6:7]
	v_cndmask_b32_e64 v59, v110, v59, s[6:7]
	v_cndmask_b32_e64 v58, v108, v58, s[6:7]
	v_lshlrev_b32_e32 v111, 16, v112
	v_and_b32_e32 v112, 0xffff0000, v112
	v_lshlrev_b32_e32 v117, 16, v113
	v_and_b32_e32 v119, 0xffff0000, v113
	v_lshlrev_b32_e32 v120, 16, v114
	v_and_b32_e32 v121, 0xffff0000, v114
	v_lshlrev_b32_e32 v122, 16, v115
	v_and_b32_e32 v123, 0xffff0000, v115
	v_sub_f32_e32 v113, v112, v116
	v_sub_f32_e32 v112, v111, v116
	v_sub_f32_e32 v115, v119, v116
	v_sub_f32_e32 v114, v117, v116
	v_sub_f32_e32 v121, v121, v116
	v_sub_f32_e32 v120, v120, v116
	v_sub_f32_e32 v117, v123, v116
	v_sub_f32_e32 v116, v122, v116
	v_pk_mul_f32 v[114:115], v[114:115], v[118:119] op_sel_hi:[1,0]
	v_pk_mul_f32 v[112:113], v[112:113], v[118:119] op_sel_hi:[1,0]
	v_pk_mul_f32 v[116:117], v[116:117], v[118:119] op_sel_hi:[1,0]
	v_pk_mul_f32 v[118:119], v[120:121], v[118:119] op_sel_hi:[1,0]
	v_pk_fma_f32 v[112:113], v[76:77], v[112:113], v[184:185]
	v_pk_fma_f32 v[114:115], v[78:79], v[114:115], v[182:183]
	v_pk_fma_f32 v[118:119], v[72:73], v[118:119], v[180:181]
	v_pk_fma_f32 v[116:117], v[74:75], v[116:117], v[178:179]
	v_pk_add_f32 v[62:63], v[62:63], v[114:115]
	v_pk_add_f32 v[60:61], v[60:61], v[112:113]
	v_pk_add_f32 v[58:59], v[58:59], v[116:117]
	v_pk_add_f32 v[56:57], v[56:57], v[118:119]
	v_cvt_pk_bf16_f32 v60, v60, v61
	v_cvt_pk_bf16_f32 v61, v62, v63
	s_nop 0
	v_cvt_pk_bf16_f32 v62, v56, v57
	v_cvt_pk_bf16_f32 v63, v58, v59
	v_lshlrev_b32_e32 v56, 16, v60
	v_and_b32_e32 v58, 0xffff0000, v60
	v_lshlrev_b32_e32 v112, 16, v61
	v_and_b32_e32 v114, 0xffff0000, v61
	v_lshlrev_b32_e32 v116, 16, v62
	v_and_b32_e32 v118, 0xffff0000, v62
	v_lshlrev_b32_e32 v120, 16, v63
	v_and_b32_e32 v122, 0xffff0000, v63
	v_mul_f32_e32 v57, v56, v56
	v_mul_f32_e32 v59, v58, v58
	v_mul_f32_e32 v113, v112, v112
	v_mul_f32_e32 v115, v114, v114
	v_mul_f32_e32 v117, v116, v116
	v_mul_f32_e32 v119, v118, v118
	v_mul_f32_e32 v121, v120, v120
	v_mul_f32_e32 v123, v122, v122
	v_pk_add_f32 v[56:57], v[56:57], v[58:59]
	v_pk_add_f32 v[58:59], v[112:113], v[114:115]
	v_pk_add_f32 v[112:113], v[120:121], v[122:123]
	v_pk_add_f32 v[56:57], v[56:57], v[58:59]
	v_pk_add_f32 v[58:59], v[116:117], v[118:119]
	global_store_dwordx4 v104, v[60:63], s[16:17]
	v_pk_add_f32 v[58:59], v[58:59], v[112:113]
	s_nop 0
	v_pk_add_f32 v[56:57], v[56:57], v[58:59]
	v_mov_b32_e32 v58, v165
	v_mov_b32_e32 v59, v165
	s_nop 0
	v_mov_b32_dpp v58, v56 quad_perm:[1,0,3,2] row_mask:0xf bank_mask:0xf
	v_mov_b32_dpp v59, v57 quad_perm:[1,0,3,2] row_mask:0xf bank_mask:0xf
	v_pk_add_f32 v[56:57], v[56:57], v[58:59]
	v_mov_b32_e32 v58, v56
	v_mov_b32_e32 v59, v57
	s_nop 1
	v_permlane16_swap_b32_e32 v56, v58
	v_permlane16_swap_b32_e32 v57, v59
	s_waitcnt lgkmcnt(0)
	v_pk_add_f32 v[56:57], v[56:57], v[58:59]
	v_mov_b32_e32 v58, v56
	v_mov_b32_e32 v59, v57
	s_nop 1
	v_permlane32_swap_b32_e32 v56, v58
	v_permlane32_swap_b32_e32 v57, v59
	s_and_saveexec_b64 s[56:57], s[12:13]
	s_cbranch_execz .LBB0_1715
	s_waitcnt lgkmcnt(0)
	v_pk_add_f32 v[56:57], v[56:57], v[58:59]
	v_add_co_u32_e32 v58, vcc, 0x10000, v186
	s_nop 1
	v_addc_co_u32_e32 v59, vcc, 0, v187, vcc
	global_store_dwordx2 v[58:59], v[56:57], off
; __device__ __forceinline__ u32x4 pack8f(f32x4 a, f32x4 b) { u32x4 w; w.x = cvt_pk_bf16(a[0], a[1]); w.y = cvt_pk_bf16(a[2], a[3]); w.z = cvt_pk_bf16(b[0], b[1]); w.w = cvt_pk_bf16(b[2], b[3]); return w; }
;     __device__ __forceinline__ void operator()(const f32x4 (&acc)[2][2][4][2], const Unit& u, int wr, int wc, int fr, int fq, const EpiCtx& X) const {
;     ...
;             for (int m = 0; m < 4; ++m) {
;                 const int rl = ai * HALF + m * 16; const unsigned off = lo + (unsigned)(rl * 64) * 2u;
;                 const f32x4 o0a = acc[ai][0][m][0], o0b = acc[ai][0][m][1], o1a = acc[ai][1][m][0], o1b = acc[ai][1][m][1];
;                 const f32x4 ra_ = dpp_swap1(odd ? o0a : o1a), rb_ = dpp_swap1(odd ? o0b : o1b);
;                 const f32x4 pa[2] = {odd ? ra_ : o0a, odd ? o1a : ra_}, pb[2] = {odd ? rb_ : o0b, odd ? o1b : rb_};
; #pragma unroll
;                 for (int q = 0; q < 2; ++q) {
;                     const u32x4 w0 = raw[2 * m + q];
;                     const f32x4 r0 = (f32x4){bf_lo(w0.x), bf_hi(w0.x), bf_lo(w0.y), bf_hi(w0.y)}, r1 = (f32x4){bf_lo(w0.z), bf_hi(w0.z), bf_lo(w0.w), bf_hi(w0.w)};
;                     f32x4 y0, y1;
;                     if (RESN) { const f32x2 t = tbl[rl + q]; const float mu = t.x, ra = t.y * ALPHA; y0 = (r0 - mu) * ra * g0 + b0 + pa[q]; y1 = (r1 - mu) * ra * g1 + b1 + pb[q]; }
;                     else { y0 = r0 * ALPHA + pa[q]; y1 = r1 * ALPHA + pb[q]; }
;                     { const u32x4 w = pack8f(y0, y1); *(u32x4*)(xb + off + q * 128) = w;
;                         y0 = (f32x4){bf_lo(w.x), bf_hi(w.x), bf_lo(w.y), bf_hi(w.y)}; y1 = (f32x4){bf_lo(w.z), bf_hi(w.z), bf_lo(w.w), bf_hi(w.w)}; }
;                     float sa = ((y0[0] + y0[1]) + (y0[2] + y0[3])) + ((y1[0] + y1[1]) + (y1[2] + y1[3]));
;                     float sb = ((y0[0] * y0[0] + y0[1] * y0[1]) + (y0[2] * y0[2] + y0[3] * y0[3])) + ((y1[0] * y1[0] + y1[1] * y1[1]) + (y1[2] * y1[2] + y1[3] * y1[3]));
;                     sa += dpp_x1(sa);
;                     sb += dpp_x1(sb);
;                     sa += __shfl_xor(sa, 16); sa += __shfl_xor(sa, 32); sb += __shfl_xor(sb, 16); sb += __shfl_xor(sb, 32);
;                     if (fq == 0 && !odd) ps[(size_t)(rl + q) * 64] = (f32x2){sa, sb};
;                 }
.LBB0_1715:
	s_or_b64 exec, exec, s[56:57]
	ds_read_b64 v[56:57], v201 offset:1032
	s_waitcnt lgkmcnt(1)
	v_lshlrev_b32_e32 v59, 16, v96
	v_and_b32_e32 v60, 0xffff0000, v96
	v_cndmask_b32_e64 v53, v53, v105, s[6:7]
	v_cndmask_b32_e64 v52, v52, v101, s[6:7]
	s_waitcnt lgkmcnt(0)
	v_mul_f32_e32 v58, 0x3fb504f3, v57
	v_sub_f32_e32 v61, v60, v56
	v_sub_f32_e32 v60, v59, v56
	v_pk_mul_f32 v[60:61], v[60:61], v[58:59] op_sel_hi:[1,0]
	v_lshlrev_b32_e32 v62, 16, v97
	v_and_b32_e32 v63, 0xffff0000, v97
	v_lshlrev_b32_e32 v96, 16, v98
	v_and_b32_e32 v97, 0xffff0000, v98
	v_lshlrev_b32_e32 v98, 16, v99
	v_and_b32_e32 v99, 0xffff0000, v99
	v_pk_fma_f32 v[60:61], v[76:77], v[60:61], v[184:185]
	v_sub_f32_e32 v63, v63, v56
	v_sub_f32_e32 v62, v62, v56
	v_pk_add_f32 v[52:53], v[52:53], v[60:61]
	v_sub_f32_e32 v61, v97, v56
	v_sub_f32_e32 v60, v96, v56
	v_sub_f32_e32 v57, v99, v56
	v_sub_f32_e32 v56, v98, v56
	v_pk_mul_f32 v[62:63], v[62:63], v[58:59] op_sel_hi:[1,0]
	v_pk_mul_f32 v[56:57], v[56:57], v[58:59] op_sel_hi:[1,0]
	v_pk_mul_f32 v[58:59], v[60:61], v[58:59] op_sel_hi:[1,0]
	v_cndmask_b32_e64 v55, v55, v106, s[6:7]
	v_cndmask_b32_e64 v54, v54, v103, s[6:7]
	v_cndmask_b32_e64 v49, v49, v109, s[6:7]
	v_cndmask_b32_e64 v48, v48, v107, s[6:7]
	v_cndmask_b32_e64 v51, v51, v110, s[6:7]
	v_cndmask_b32_e64 v50, v50, v108, s[6:7]
	v_pk_fma_f32 v[62:63], v[78:79], v[62:63], v[182:183]
	v_pk_fma_f32 v[58:59], v[72:73], v[58:59], v[180:181]
	v_pk_fma_f32 v[56:57], v[74:75], v[56:57], v[178:179]
	v_pk_add_f32 v[54:55], v[54:55], v[62:63]
	v_pk_add_f32 v[50:51], v[50:51], v[56:57]
	v_pk_add_f32 v[48:49], v[48:49], v[58:59]
	v_cvt_pk_bf16_f32 v52, v52, v53
	v_cvt_pk_bf16_f32 v53, v54, v55
	v_mov_b32_e32 v105, v165
	v_cvt_pk_bf16_f32 v54, v48, v49
	v_cvt_pk_bf16_f32 v55, v50, v51
	v_lshlrev_b32_e32 v48, 16, v52
	v_and_b32_e32 v50, 0xffff0000, v52
	v_lshlrev_b32_e32 v56, 16, v53
	v_and_b32_e32 v58, 0xffff0000, v53
	v_lshlrev_b32_e32 v60, 16, v54
	v_and_b32_e32 v62, 0xffff0000, v54
	v_lshlrev_b32_e32 v96, 16, v55
	v_and_b32_e32 v98, 0xffff0000, v55
	v_mul_f32_e32 v49, v48, v48
	v_mul_f32_e32 v51, v50, v50
	v_mul_f32_e32 v57, v56, v56
	v_mul_f32_e32 v59, v58, v58
	v_mul_f32_e32 v61, v60, v60
	v_mul_f32_e32 v63, v62, v62
	v_mul_f32_e32 v97, v96, v96
	v_mul_f32_e32 v99, v98, v98
	v_pk_add_f32 v[48:49], v[48:49], v[50:51]
	v_pk_add_f32 v[50:51], v[56:57], v[58:59]
	v_pk_add_f32 v[56:57], v[96:97], v[98:99]
	v_pk_add_f32 v[48:49], v[48:49], v[50:51]
	v_pk_add_f32 v[50:51], v[60:61], v[62:63]
	s_nop 0
	v_pk_add_f32 v[50:51], v[50:51], v[56:57]
	v_lshl_add_u64 v[56:57], s[16:17], 0, v[104:105]
	v_pk_add_f32 v[48:49], v[48:49], v[50:51]
	v_mov_b32_e32 v50, v165
	v_mov_b32_e32 v51, v165
	global_store_dwordx4 v[56:57], v[52:55], off offset:128
	v_mov_b32_dpp v50, v48 quad_perm:[1,0,3,2] row_mask:0xf bank_mask:0xf
	v_mov_b32_dpp v51, v49 quad_perm:[1,0,3,2] row_mask:0xf bank_mask:0xf
	v_pk_add_f32 v[48:49], v[48:49], v[50:51]
	v_mov_b32_e32 v50, v48
	v_mov_b32_e32 v51, v49
	s_nop 1
	v_permlane16_swap_b32_e32 v48, v50
	v_permlane16_swap_b32_e32 v49, v51
	s_waitcnt lgkmcnt(0)
	v_pk_add_f32 v[48:49], v[48:49], v[50:51]
	v_mov_b32_e32 v50, v48
	v_mov_b32_e32 v51, v49
	s_nop 1
	v_permlane32_swap_b32_e32 v48, v50
	v_permlane32_swap_b32_e32 v49, v51
	s_and_saveexec_b64 s[56:57], s[12:13]
	s_cbranch_execz .LBB0_1717
	s_waitcnt lgkmcnt(0)
	v_pk_add_f32 v[48:49], v[48:49], v[50:51]
	v_add_co_u32_e32 v50, vcc, 0x10000, v186
	s_nop 1
	v_addc_co_u32_e32 v51, vcc, 0, v187, vcc
	global_store_dwordx2 v[50:51], v[48:49], off offset:512
.LBB0_1717:
	s_or_b64 exec, exec, s[56:57]
	s_waitcnt lgkmcnt(0)
	v_cndmask_b32_e64 v50, v44, v36, s[6:7]
	v_mov_b32_e32 v48, 0
	v_cndmask_b32_e64 v49, v45, v37, s[6:7]
	s_waitcnt lgkmcnt(0)
	v_cndmask_b32_e64 v51, v46, v38, s[6:7]
	v_mov_b32_dpp v48, v50 quad_perm:[1,0,3,2] row_mask:0xf bank_mask:0xf
	v_mov_b32_e32 v50, 0
	v_cndmask_b32_e64 v52, v47, v39, s[6:7]
	v_cndmask_b32_e64 v54, v40, v32, s[6:7]
	v_mov_b32_dpp v50, v49 quad_perm:[1,0,3,2] row_mask:0xf bank_mask:0xf
	v_mov_b32_e32 v49, 0
	v_cndmask_b32_e64 v53, v41, v33, s[6:7]
	v_cndmask_b32_e64 v55, v42, v34, s[6:7]
	v_mov_b32_dpp v49, v51 quad_perm:[1,0,3,2] row_mask:0xf bank_mask:0xf
	v_mov_b32_e32 v51, 0
	v_cndmask_b32_e64 v56, v43, v35, s[6:7]
	v_lshlrev_b32_e32 v59, 16, v92
	v_mov_b32_dpp v51, v52 quad_perm:[1,0,3,2] row_mask:0xf bank_mask:0xf
	v_mov_b32_e32 v52, 0
	v_and_b32_e32 v60, 0xffff0000, v92
	v_cndmask_b32_e64 v45, v50, v45, s[6:7]
	v_mov_b32_dpp v52, v54 quad_perm:[1,0,3,2] row_mask:0xf bank_mask:0xf
	v_mov_b32_e32 v54, 0
	v_cndmask_b32_e64 v44, v48, v44, s[6:7]
	v_lshlrev_b32_e32 v62, 16, v93
	v_mov_b32_dpp v54, v53 quad_perm:[1,0,3,2] row_mask:0xf bank_mask:0xf
	v_mov_b32_e32 v53, 0
	v_and_b32_e32 v63, 0xffff0000, v93
	v_lshlrev_b32_e32 v92, 16, v94
	v_mov_b32_dpp v53, v55 quad_perm:[1,0,3,2] row_mask:0xf bank_mask:0xf
	v_mov_b32_e32 v55, 0
	v_and_b32_e32 v93, 0xffff0000, v94
	v_lshlrev_b32_e32 v94, 16, v95
	v_mov_b32_dpp v55, v56 quad_perm:[1,0,3,2] row_mask:0xf bank_mask:0xf
	ds_read_b64 v[56:57], v201 offset:1152
	v_and_b32_e32 v95, 0xffff0000, v95
	v_cndmask_b32_e64 v47, v51, v47, s[6:7]
	v_cndmask_b32_e64 v46, v49, v46, s[6:7]
	v_cndmask_b32_e64 v41, v54, v41, s[6:7]
	s_waitcnt lgkmcnt(0)
; __device__ __forceinline__ u32x4 pack8f(f32x4 a, f32x4 b) { u32x4 w; w.x = cvt_pk_bf16(a[0], a[1]); w.y = cvt_pk_bf16(a[2], a[3]); w.z = cvt_pk_bf16(b[0], b[1]); w.w = cvt_pk_bf16(b[2], b[3]); return w; }
;     __device__ __forceinline__ void operator()(const f32x4 (&acc)[2][2][4][2], const Unit& u, int wr, int wc, int fr, int fq, const EpiCtx& X) const {
;     ...
;             for (int m = 0; m < 4; ++m) {
;                 const int rl = ai * HALF + m * 16; const unsigned off = lo + (unsigned)(rl * 64) * 2u;
;                 const f32x4 o0a = acc[ai][0][m][0], o0b = acc[ai][0][m][1], o1a = acc[ai][1][m][0], o1b = acc[ai][1][m][1];
;                 const f32x4 ra_ = dpp_swap1(odd ? o0a : o1a), rb_ = dpp_swap1(odd ? o0b : o1b);
;                 const f32x4 pa[2] = {odd ? ra_ : o0a, odd ? o1a : ra_}, pb[2] = {odd ? rb_ : o0b, odd ? o1b : rb_};
; #pragma unroll
;                 for (int q = 0; q < 2; ++q) {
;                     const u32x4 w0 = raw[2 * m + q];
;                     const f32x4 r0 = (f32x4){bf_lo(w0.x), bf_hi(w0.x), bf_lo(w0.y), bf_hi(w0.y)}, r1 = (f32x4){bf_lo(w0.z), bf_hi(w0.z), bf_lo(w0.w), bf_hi(w0.w)};
;                     f32x4 y0, y1;
;                     if (RESN) { const f32x2 t = tbl[rl + q]; const float mu = t.x, ra = t.y * ALPHA; y0 = (r0 - mu) * ra * g0 + b0 + pa[q]; y1 = (r1 - mu) * ra * g1 + b1 + pb[q]; }
;                     else { y0 = r0 * ALPHA + pa[q]; y1 = r1 * ALPHA + pb[q]; }
;                     { const u32x4 w = pack8f(y0, y1); *(u32x4*)(xb + off + q * 128) = w;
;                         y0 = (f32x4){bf_lo(w.x), bf_hi(w.x), bf_lo(w.y), bf_hi(w.y)}; y1 = (f32x4){bf_lo(w.z), bf_hi(w.z), bf_lo(w.w), bf_hi(w.w)}; }
;                     float sa = ((y0[0] + y0[1]) + (y0[2] + y0[3])) + ((y1[0] + y1[1]) + (y1[2] + y1[3]));
;                     float sb = ((y0[0] * y0[0] + y0[1] * y0[1]) + (y0[2] * y0[2] + y0[3] * y0[3])) + ((y1[0] * y1[0] + y1[1] * y1[1]) + (y1[2] * y1[2] + y1[3] * y1[3]));
;                     sa += dpp_x1(sa);
;                     sb += dpp_x1(sb);
;                     sa += __shfl_xor(sa, 16); sa += __shfl_xor(sa, 32); sb += __shfl_xor(sb, 16); sb += __shfl_xor(sb, 32);
;                     if (fq == 0 && !odd) ps[(size_t)(rl + q) * 64] = (f32x2){sa, sb};
;                 }
	v_mul_f32_e32 v58, 0x3fb504f3, v57
	v_sub_f32_e32 v61, v60, v56
	v_sub_f32_e32 v60, v59, v56
	v_pk_mul_f32 v[60:61], v[60:61], v[58:59] op_sel_hi:[1,0]
	v_sub_f32_e32 v63, v63, v56
	v_pk_fma_f32 v[60:61], v[76:77], v[60:61], v[184:185]
	v_sub_f32_e32 v62, v62, v56
	v_pk_add_f32 v[44:45], v[44:45], v[60:61]
	v_sub_f32_e32 v61, v93, v56
	v_sub_f32_e32 v60, v92, v56
	v_sub_f32_e32 v57, v95, v56
	v_sub_f32_e32 v56, v94, v56
	v_pk_mul_f32 v[62:63], v[62:63], v[58:59] op_sel_hi:[1,0]
	v_pk_mul_f32 v[56:57], v[56:57], v[58:59] op_sel_hi:[1,0]
	v_pk_mul_f32 v[58:59], v[60:61], v[58:59] op_sel_hi:[1,0]
	v_cndmask_b32_e64 v40, v52, v40, s[6:7]
	v_cndmask_b32_e64 v43, v55, v43, s[6:7]
	v_cndmask_b32_e64 v42, v53, v42, s[6:7]
	v_pk_fma_f32 v[62:63], v[78:79], v[62:63], v[182:183]
	v_pk_fma_f32 v[58:59], v[72:73], v[58:59], v[180:181]
	v_pk_fma_f32 v[56:57], v[74:75], v[56:57], v[178:179]
	v_pk_add_f32 v[46:47], v[46:47], v[62:63]
	v_pk_add_f32 v[42:43], v[42:43], v[56:57]
	v_pk_add_f32 v[40:41], v[40:41], v[58:59]
	v_cvt_pk_bf16_f32 v56, v44, v45
	v_cvt_pk_bf16_f32 v57, v46, v47
	v_mov_b32_e32 v103, v165
	v_cvt_pk_bf16_f32 v58, v40, v41
	v_cvt_pk_bf16_f32 v59, v42, v43
	v_lshlrev_b32_e32 v40, 16, v56
	v_and_b32_e32 v42, 0xffff0000, v56
	v_lshlrev_b32_e32 v44, 16, v57
	v_and_b32_e32 v46, 0xffff0000, v57
	v_lshlrev_b32_e32 v60, 16, v58
	v_and_b32_e32 v62, 0xffff0000, v58
	v_lshlrev_b32_e32 v92, 16, v59
	v_and_b32_e32 v94, 0xffff0000, v59
	v_mul_f32_e32 v41, v40, v40
	v_mul_f32_e32 v43, v42, v42
	v_mul_f32_e32 v45, v44, v44
	v_mul_f32_e32 v47, v46, v46
	v_mul_f32_e32 v61, v60, v60
	v_mul_f32_e32 v63, v62, v62
	v_mul_f32_e32 v93, v92, v92
	v_mul_f32_e32 v95, v94, v94
	v_pk_add_f32 v[40:41], v[40:41], v[42:43]
	v_pk_add_f32 v[42:43], v[44:45], v[46:47]
	v_pk_add_f32 v[44:45], v[92:93], v[94:95]
	v_pk_add_f32 v[40:41], v[40:41], v[42:43]
	v_pk_add_f32 v[42:43], v[60:61], v[62:63]
	s_nop 0
	v_pk_add_f32 v[42:43], v[42:43], v[44:45]
	s_nop 0
	v_pk_add_f32 v[40:41], v[40:41], v[42:43]
	v_mov_b32_e32 v42, v165
	v_mov_b32_e32 v43, v165
	s_nop 0
	v_mov_b32_dpp v42, v40 quad_perm:[1,0,3,2] row_mask:0xf bank_mask:0xf
	v_mov_b32_dpp v43, v41 quad_perm:[1,0,3,2] row_mask:0xf bank_mask:0xf
	v_pk_add_f32 v[40:41], v[40:41], v[42:43]
	v_mov_b32_e32 v42, v40
	v_mov_b32_e32 v43, v41
	s_nop 1
	v_permlane16_swap_b32_e32 v40, v42
	v_permlane16_swap_b32_e32 v41, v43
	s_waitcnt lgkmcnt(0)
	v_pk_add_f32 v[42:43], v[40:41], v[42:43]
	v_mov_b32_e32 v44, v42
	v_mov_b32_e32 v45, v43
	s_nop 1
	v_permlane32_swap_b32_e32 v42, v44
	v_permlane32_swap_b32_e32 v43, v45
	v_lshl_add_u64 v[40:41], s[16:17], 0, v[102:103]
	global_store_dwordx4 v[40:41], v[56:59], off
	s_and_saveexec_b64 s[56:57], s[12:13]
	s_cbranch_execz .LBB0_1719
	s_waitcnt lgkmcnt(0)
	v_pk_add_f32 v[42:43], v[42:43], v[44:45]
	v_add_co_u32_e32 v44, vcc, 0x12000, v186
	s_nop 1
	v_addc_co_u32_e32 v45, vcc, 0, v187, vcc
	global_store_dwordx2 v[44:45], v[42:43], off
.LBB0_1719:
	s_or_b64 exec, exec, s[56:57]
	ds_read_b64 v[42:43], v201 offset:1160
	s_waitcnt lgkmcnt(1)
	v_lshlrev_b32_e32 v45, 16, v88
	v_and_b32_e32 v46, 0xffff0000, v88
	v_cndmask_b32_e64 v37, v37, v50, s[6:7]
	v_cndmask_b32_e64 v36, v36, v48, s[6:7]
	s_waitcnt lgkmcnt(0)
	v_mul_f32_e32 v44, 0x3fb504f3, v43
	v_sub_f32_e32 v47, v46, v42
	v_sub_f32_e32 v46, v45, v42
	v_pk_mul_f32 v[46:47], v[46:47], v[44:45] op_sel_hi:[1,0]
	v_cndmask_b32_e64 v39, v39, v51, s[6:7]
	v_cndmask_b32_e64 v38, v38, v49, s[6:7]
	v_cndmask_b32_e64 v32, v32, v52, s[6:7]
	v_cndmask_b32_e64 v34, v34, v53, s[6:7]
	v_lshlrev_b32_e32 v48, 16, v89
	v_and_b32_e32 v49, 0xffff0000, v89
	v_lshlrev_b32_e32 v50, 16, v90
	v_and_b32_e32 v51, 0xffff0000, v90
	v_lshlrev_b32_e32 v52, 16, v91
	v_and_b32_e32 v53, 0xffff0000, v91
	v_pk_fma_f32 v[46:47], v[76:77], v[46:47], v[184:185]
	v_sub_f32_e32 v49, v49, v42
	v_sub_f32_e32 v48, v48, v42
	v_pk_add_f32 v[36:37], v[36:37], v[46:47]
	v_sub_f32_e32 v47, v51, v42
	v_sub_f32_e32 v46, v50, v42
	v_sub_f32_e32 v43, v53, v42
	v_sub_f32_e32 v42, v52, v42
	v_pk_mul_f32 v[48:49], v[48:49], v[44:45] op_sel_hi:[1,0]
	v_pk_mul_f32 v[42:43], v[42:43], v[44:45] op_sel_hi:[1,0]
	v_pk_mul_f32 v[44:45], v[46:47], v[44:45] op_sel_hi:[1,0]
	v_cndmask_b32_e64 v33, v33, v54, s[6:7]
	v_cndmask_b32_e64 v35, v35, v55, s[6:7]
	v_pk_fma_f32 v[48:49], v[78:79], v[48:49], v[182:183]
	v_pk_fma_f32 v[44:45], v[72:73], v[44:45], v[180:181]
	v_pk_fma_f32 v[42:43], v[74:75], v[42:43], v[178:179]
	v_pk_add_f32 v[38:39], v[38:39], v[48:49]
	v_pk_add_f32 v[34:35], v[34:35], v[42:43]
	v_pk_add_f32 v[32:33], v[32:33], v[44:45]
	v_cvt_pk_bf16_f32 v36, v36, v37
	v_cvt_pk_bf16_f32 v37, v38, v39
	s_nop 0
	v_cvt_pk_bf16_f32 v38, v32, v33
	v_cvt_pk_bf16_f32 v39, v34, v35
	v_lshlrev_b32_e32 v32, 16, v36
	v_and_b32_e32 v34, 0xffff0000, v36
	v_lshlrev_b32_e32 v42, 16, v37
	v_and_b32_e32 v44, 0xffff0000, v37
	v_lshlrev_b32_e32 v46, 16, v38
	v_and_b32_e32 v48, 0xffff0000, v38
	v_lshlrev_b32_e32 v50, 16, v39
	v_and_b32_e32 v52, 0xffff0000, v39
	v_mul_f32_e32 v33, v32, v32
	v_mul_f32_e32 v35, v34, v34
	v_mul_f32_e32 v43, v42, v42
	v_mul_f32_e32 v45, v44, v44
	v_mul_f32_e32 v47, v46, v46
	v_mul_f32_e32 v49, v48, v48
	v_mul_f32_e32 v51, v50, v50
	v_mul_f32_e32 v53, v52, v52
	v_pk_add_f32 v[32:33], v[32:33], v[34:35]
	v_pk_add_f32 v[34:35], v[42:43], v[44:45]
	v_pk_add_f32 v[42:43], v[50:51], v[52:53]
	v_pk_add_f32 v[32:33], v[32:33], v[34:35]
	v_pk_add_f32 v[34:35], v[46:47], v[48:49]
	global_store_dwordx4 v[40:41], v[36:39], off offset:128
	v_pk_add_f32 v[34:35], v[34:35], v[42:43]
	s_nop 0
	v_pk_add_f32 v[32:33], v[32:33], v[34:35]
	v_mov_b32_e32 v34, v165
	v_mov_b32_e32 v35, v165
	s_nop 0
	v_mov_b32_dpp v34, v32 quad_perm:[1,0,3,2] row_mask:0xf bank_mask:0xf
	v_mov_b32_dpp v35, v33 quad_perm:[1,0,3,2] row_mask:0xf bank_mask:0xf
	v_pk_add_f32 v[32:33], v[32:33], v[34:35]
	v_mov_b32_e32 v34, v32
	v_mov_b32_e32 v35, v33
	s_nop 1
	v_permlane16_swap_b32_e32 v32, v34
	v_permlane16_swap_b32_e32 v33, v35
	s_waitcnt lgkmcnt(0)
	v_pk_add_f32 v[32:33], v[32:33], v[34:35]
	v_mov_b32_e32 v34, v32
	v_mov_b32_e32 v35, v33
	s_nop 1
	v_permlane32_swap_b32_e32 v32, v34
	v_permlane32_swap_b32_e32 v33, v35
	s_and_saveexec_b64 s[56:57], s[12:13]
	s_cbranch_execz .LBB0_1721
	s_waitcnt lgkmcnt(0)
	v_pk_add_f32 v[32:33], v[32:33], v[34:35]
	v_add_co_u32_e32 v34, vcc, 0x12000, v186
	s_nop 1
	v_addc_co_u32_e32 v35, vcc, 0, v187, vcc
	global_store_dwordx2 v[34:35], v[32:33], off offset:512
; __device__ __forceinline__ u32x4 pack8f(f32x4 a, f32x4 b) { u32x4 w; w.x = cvt_pk_bf16(a[0], a[1]); w.y = cvt_pk_bf16(a[2], a[3]); w.z = cvt_pk_bf16(b[0], b[1]); w.w = cvt_pk_bf16(b[2], b[3]); return w; }
;     __device__ __forceinline__ void operator()(const f32x4 (&acc)[2][2][4][2], const Unit& u, int wr, int wc, int fr, int fq, const EpiCtx& X) const {
;     ...
;             for (int m = 0; m < 4; ++m) {
;                 const int rl = ai * HALF + m * 16; const unsigned off = lo + (unsigned)(rl * 64) * 2u;
;                 const f32x4 o0a = acc[ai][0][m][0], o0b = acc[ai][0][m][1], o1a = acc[ai][1][m][0], o1b = acc[ai][1][m][1];
;                 const f32x4 ra_ = dpp_swap1(odd ? o0a : o1a), rb_ = dpp_swap1(odd ? o0b : o1b);
;                 const f32x4 pa[2] = {odd ? ra_ : o0a, odd ? o1a : ra_}, pb[2] = {odd ? rb_ : o0b, odd ? o1b : rb_};
; #pragma unroll
;                 for (int q = 0; q < 2; ++q) {
;                     const u32x4 w0 = raw[2 * m + q];
;                     const f32x4 r0 = (f32x4){bf_lo(w0.x), bf_hi(w0.x), bf_lo(w0.y), bf_hi(w0.y)}, r1 = (f32x4){bf_lo(w0.z), bf_hi(w0.z), bf_lo(w0.w), bf_hi(w0.w)};
;                     f32x4 y0, y1;
;                     if (RESN) { const f32x2 t = tbl[rl + q]; const float mu = t.x, ra = t.y * ALPHA; y0 = (r0 - mu) * ra * g0 + b0 + pa[q]; y1 = (r1 - mu) * ra * g1 + b1 + pb[q]; }
;                     else { y0 = r0 * ALPHA + pa[q]; y1 = r1 * ALPHA + pb[q]; }
;                     { const u32x4 w = pack8f(y0, y1); *(u32x4*)(xb + off + q * 128) = w;
;                         y0 = (f32x4){bf_lo(w.x), bf_hi(w.x), bf_lo(w.y), bf_hi(w.y)}; y1 = (f32x4){bf_lo(w.z), bf_hi(w.z), bf_lo(w.w), bf_hi(w.w)}; }
;                     float sa = ((y0[0] + y0[1]) + (y0[2] + y0[3])) + ((y1[0] + y1[1]) + (y1[2] + y1[3]));
;                     float sb = ((y0[0] * y0[0] + y0[1] * y0[1]) + (y0[2] * y0[2] + y0[3] * y0[3])) + ((y1[0] * y1[0] + y1[1] * y1[1]) + (y1[2] * y1[2] + y1[3] * y1[3]));
;                     sa += dpp_x1(sa);
;                     sb += dpp_x1(sb);
;                     sa += __shfl_xor(sa, 16); sa += __shfl_xor(sa, 32); sb += __shfl_xor(sb, 16); sb += __shfl_xor(sb, 32);
;                     if (fq == 0 && !odd) ps[(size_t)(rl + q) * 64] = (f32x2){sa, sb};
;                 }
.LBB0_1721:
	s_or_b64 exec, exec, s[56:57]
	s_waitcnt lgkmcnt(0)
	v_cndmask_b32_e64 v34, v28, v20, s[6:7]
	v_mov_b32_e32 v32, 0
	v_cndmask_b32_e64 v33, v29, v21, s[6:7]
	s_waitcnt lgkmcnt(0)
	v_cndmask_b32_e64 v35, v30, v22, s[6:7]
	v_mov_b32_dpp v32, v34 quad_perm:[1,0,3,2] row_mask:0xf bank_mask:0xf
	v_mov_b32_e32 v34, 0
	v_cndmask_b32_e64 v36, v31, v23, s[6:7]
	v_cndmask_b32_e64 v38, v24, v16, s[6:7]
	v_mov_b32_dpp v34, v33 quad_perm:[1,0,3,2] row_mask:0xf bank_mask:0xf
	v_mov_b32_e32 v33, 0
	v_cndmask_b32_e64 v37, v25, v17, s[6:7]
	v_cndmask_b32_e64 v39, v26, v18, s[6:7]
	v_mov_b32_dpp v33, v35 quad_perm:[1,0,3,2] row_mask:0xf bank_mask:0xf
	v_mov_b32_e32 v35, 0
	v_cndmask_b32_e64 v40, v27, v19, s[6:7]
	s_waitcnt vmcnt(11)
	v_lshlrev_b32_e32 v43, 16, v84
	v_mov_b32_dpp v35, v36 quad_perm:[1,0,3,2] row_mask:0xf bank_mask:0xf
	v_mov_b32_e32 v36, 0
	v_and_b32_e32 v44, 0xffff0000, v84
	v_cndmask_b32_e64 v29, v34, v29, s[6:7]
	v_mov_b32_dpp v36, v38 quad_perm:[1,0,3,2] row_mask:0xf bank_mask:0xf
	v_mov_b32_e32 v38, 0
	v_cndmask_b32_e64 v28, v32, v28, s[6:7]
	v_lshlrev_b32_e32 v46, 16, v85
	v_mov_b32_dpp v38, v37 quad_perm:[1,0,3,2] row_mask:0xf bank_mask:0xf
	v_mov_b32_e32 v37, 0
	v_and_b32_e32 v47, 0xffff0000, v85
	v_lshlrev_b32_e32 v48, 16, v86
	v_mov_b32_dpp v37, v39 quad_perm:[1,0,3,2] row_mask:0xf bank_mask:0xf
	v_mov_b32_e32 v39, 0
	v_and_b32_e32 v49, 0xffff0000, v86
	v_lshlrev_b32_e32 v50, 16, v87
	v_mov_b32_dpp v39, v40 quad_perm:[1,0,3,2] row_mask:0xf bank_mask:0xf
	ds_read_b64 v[40:41], v201 offset:1280
	v_and_b32_e32 v51, 0xffff0000, v87
	v_cndmask_b32_e64 v31, v35, v31, s[6:7]
	v_cndmask_b32_e64 v30, v33, v30, s[6:7]
	v_cndmask_b32_e64 v25, v38, v25, s[6:7]
	s_waitcnt lgkmcnt(0)
	v_mul_f32_e32 v42, 0x3fb504f3, v41
	v_sub_f32_e32 v45, v44, v40
	v_sub_f32_e32 v44, v43, v40
	v_pk_mul_f32 v[44:45], v[44:45], v[42:43] op_sel_hi:[1,0]
	v_sub_f32_e32 v47, v47, v40
	v_pk_fma_f32 v[44:45], v[76:77], v[44:45], v[184:185]
	v_sub_f32_e32 v46, v46, v40
	v_pk_add_f32 v[28:29], v[28:29], v[44:45]
	v_sub_f32_e32 v45, v49, v40
	v_sub_f32_e32 v44, v48, v40
	v_sub_f32_e32 v41, v51, v40
	v_sub_f32_e32 v40, v50, v40
	v_pk_mul_f32 v[46:47], v[46:47], v[42:43] op_sel_hi:[1,0]
	v_pk_mul_f32 v[40:41], v[40:41], v[42:43] op_sel_hi:[1,0]
	v_pk_mul_f32 v[42:43], v[44:45], v[42:43] op_sel_hi:[1,0]
	v_cndmask_b32_e64 v24, v36, v24, s[6:7]
	v_cndmask_b32_e64 v27, v39, v27, s[6:7]
	v_cndmask_b32_e64 v26, v37, v26, s[6:7]
	v_pk_fma_f32 v[46:47], v[78:79], v[46:47], v[182:183]
	v_pk_fma_f32 v[42:43], v[72:73], v[42:43], v[180:181]
	v_pk_fma_f32 v[40:41], v[74:75], v[40:41], v[178:179]
	v_pk_add_f32 v[30:31], v[30:31], v[46:47]
	v_pk_add_f32 v[26:27], v[26:27], v[40:41]
	v_pk_add_f32 v[24:25], v[24:25], v[42:43]
	v_cvt_pk_bf16_f32 v40, v28, v29
	v_cvt_pk_bf16_f32 v41, v30, v31
	v_mov_b32_e32 v101, v165
	v_cvt_pk_bf16_f32 v42, v24, v25
	v_cvt_pk_bf16_f32 v43, v26, v27
	v_lshlrev_b32_e32 v24, 16, v40
	v_and_b32_e32 v26, 0xffff0000, v40
	v_lshlrev_b32_e32 v28, 16, v41
	v_and_b32_e32 v30, 0xffff0000, v41
	v_lshlrev_b32_e32 v44, 16, v42
	v_and_b32_e32 v46, 0xffff0000, v42
	v_lshlrev_b32_e32 v48, 16, v43
	v_and_b32_e32 v50, 0xffff0000, v43
	v_mul_f32_e32 v25, v24, v24
	v_mul_f32_e32 v27, v26, v26
	v_mul_f32_e32 v29, v28, v28
	v_mul_f32_e32 v31, v30, v30
	v_mul_f32_e32 v45, v44, v44
	v_mul_f32_e32 v47, v46, v46
	v_mul_f32_e32 v49, v48, v48
	v_mul_f32_e32 v51, v50, v50
	v_pk_add_f32 v[24:25], v[24:25], v[26:27]
	v_pk_add_f32 v[26:27], v[28:29], v[30:31]
	v_pk_add_f32 v[28:29], v[48:49], v[50:51]
	v_pk_add_f32 v[24:25], v[24:25], v[26:27]
	v_pk_add_f32 v[26:27], v[44:45], v[46:47]
	s_nop 0
	v_pk_add_f32 v[26:27], v[26:27], v[28:29]
	s_nop 0
	v_pk_add_f32 v[24:25], v[24:25], v[26:27]
	v_mov_b32_e32 v26, v165
	v_mov_b32_e32 v27, v165
	s_nop 0
	v_mov_b32_dpp v26, v24 quad_perm:[1,0,3,2] row_mask:0xf bank_mask:0xf
	v_mov_b32_dpp v27, v25 quad_perm:[1,0,3,2] row_mask:0xf bank_mask:0xf
	v_pk_add_f32 v[24:25], v[24:25], v[26:27]
	v_mov_b32_e32 v26, v24
	v_mov_b32_e32 v27, v25
	s_nop 1
	v_permlane16_swap_b32_e32 v24, v26
	v_permlane16_swap_b32_e32 v25, v27
	s_waitcnt lgkmcnt(0)
	v_pk_add_f32 v[26:27], v[24:25], v[26:27]
	v_mov_b32_e32 v28, v26
	v_mov_b32_e32 v29, v27
	s_nop 1
	v_permlane32_swap_b32_e32 v26, v28
	v_permlane32_swap_b32_e32 v27, v29
	v_lshl_add_u64 v[24:25], s[16:17], 0, v[100:101]
	global_store_dwordx4 v[24:25], v[40:43], off
	s_and_saveexec_b64 s[56:57], s[12:13]
	s_cbranch_execz .LBB0_1723
	s_waitcnt lgkmcnt(0)
	v_pk_add_f32 v[26:27], v[26:27], v[28:29]
	v_add_co_u32_e32 v28, vcc, 0x14000, v186
	s_nop 1
	v_addc_co_u32_e32 v29, vcc, 0, v187, vcc
	global_store_dwordx2 v[28:29], v[26:27], off
; __device__ __forceinline__ u32x4 pack8f(f32x4 a, f32x4 b) { u32x4 w; w.x = cvt_pk_bf16(a[0], a[1]); w.y = cvt_pk_bf16(a[2], a[3]); w.z = cvt_pk_bf16(b[0], b[1]); w.w = cvt_pk_bf16(b[2], b[3]); return w; }
;     __device__ __forceinline__ void operator()(const f32x4 (&acc)[2][2][4][2], const Unit& u, int wr, int wc, int fr, int fq, const EpiCtx& X) const {
;     ...
;             for (int m = 0; m < 4; ++m) {
;                 const int rl = ai * HALF + m * 16; const unsigned off = lo + (unsigned)(rl * 64) * 2u;
;                 const f32x4 o0a = acc[ai][0][m][0], o0b = acc[ai][0][m][1], o1a = acc[ai][1][m][0], o1b = acc[ai][1][m][1];
;                 const f32x4 ra_ = dpp_swap1(odd ? o0a : o1a), rb_ = dpp_swap1(odd ? o0b : o1b);
;                 const f32x4 pa[2] = {odd ? ra_ : o0a, odd ? o1a : ra_}, pb[2] = {odd ? rb_ : o0b, odd ? o1b : rb_};
; #pragma unroll
;                 for (int q = 0; q < 2; ++q) {
;                     const u32x4 w0 = raw[2 * m + q];
;                     const f32x4 r0 = (f32x4){bf_lo(w0.x), bf_hi(w0.x), bf_lo(w0.y), bf_hi(w0.y)}, r1 = (f32x4){bf_lo(w0.z), bf_hi(w0.z), bf_lo(w0.w), bf_hi(w0.w)};
;                     f32x4 y0, y1;
;                     if (RESN) { const f32x2 t = tbl[rl + q]; const float mu = t.x, ra = t.y * ALPHA; y0 = (r0 - mu) * ra * g0 + b0 + pa[q]; y1 = (r1 - mu) * ra * g1 + b1 + pb[q]; }
;                     else { y0 = r0 * ALPHA + pa[q]; y1 = r1 * ALPHA + pb[q]; }
;                     { const u32x4 w = pack8f(y0, y1); *(u32x4*)(xb + off + q * 128) = w;
;                         y0 = (f32x4){bf_lo(w.x), bf_hi(w.x), bf_lo(w.y), bf_hi(w.y)}; y1 = (f32x4){bf_lo(w.z), bf_hi(w.z), bf_lo(w.w), bf_hi(w.w)}; }
;                     float sa = ((y0[0] + y0[1]) + (y0[2] + y0[3])) + ((y1[0] + y1[1]) + (y1[2] + y1[3]));
;                     float sb = ((y0[0] * y0[0] + y0[1] * y0[1]) + (y0[2] * y0[2] + y0[3] * y0[3])) + ((y1[0] * y1[0] + y1[1] * y1[1]) + (y1[2] * y1[2] + y1[3] * y1[3]));
;                     sa += dpp_x1(sa);
;                     sb += dpp_x1(sb);
;                     sa += __shfl_xor(sa, 16); sa += __shfl_xor(sa, 32); sb += __shfl_xor(sb, 16); sb += __shfl_xor(sb, 32);
;                     if (fq == 0 && !odd) ps[(size_t)(rl + q) * 64] = (f32x2){sa, sb};
;                 }
.LBB0_1723:
	s_or_b64 exec, exec, s[56:57]
	ds_read_b64 v[26:27], v201 offset:1288
	s_waitcnt vmcnt(12) lgkmcnt(1)
	v_lshlrev_b32_e32 v29, 16, v80
	v_and_b32_e32 v30, 0xffff0000, v80
	v_cndmask_b32_e64 v21, v21, v34, s[6:7]
	v_cndmask_b32_e64 v20, v20, v32, s[6:7]
	s_waitcnt lgkmcnt(0)
	v_mul_f32_e32 v28, 0x3fb504f3, v27
	v_sub_f32_e32 v31, v30, v26
	v_sub_f32_e32 v30, v29, v26
	v_pk_mul_f32 v[30:31], v[30:31], v[28:29] op_sel_hi:[1,0]
	v_cndmask_b32_e64 v23, v23, v35, s[6:7]
	v_cndmask_b32_e64 v22, v22, v33, s[6:7]
	v_cndmask_b32_e64 v16, v16, v36, s[6:7]
	v_cndmask_b32_e64 v18, v18, v37, s[6:7]
	v_lshlrev_b32_e32 v32, 16, v81
	v_and_b32_e32 v33, 0xffff0000, v81
	v_lshlrev_b32_e32 v34, 16, v82
	v_and_b32_e32 v35, 0xffff0000, v82
	v_lshlrev_b32_e32 v36, 16, v83
	v_and_b32_e32 v37, 0xffff0000, v83
	v_pk_fma_f32 v[30:31], v[76:77], v[30:31], v[184:185]
	v_sub_f32_e32 v33, v33, v26
	v_sub_f32_e32 v32, v32, v26
	v_pk_add_f32 v[20:21], v[20:21], v[30:31]
	v_sub_f32_e32 v31, v35, v26
	v_sub_f32_e32 v30, v34, v26
	v_sub_f32_e32 v27, v37, v26
	v_sub_f32_e32 v26, v36, v26
	v_pk_mul_f32 v[32:33], v[32:33], v[28:29] op_sel_hi:[1,0]
	v_pk_mul_f32 v[26:27], v[26:27], v[28:29] op_sel_hi:[1,0]
	v_pk_mul_f32 v[28:29], v[30:31], v[28:29] op_sel_hi:[1,0]
	v_cndmask_b32_e64 v17, v17, v38, s[6:7]
	v_cndmask_b32_e64 v19, v19, v39, s[6:7]
	v_pk_fma_f32 v[32:33], v[78:79], v[32:33], v[182:183]
	v_pk_fma_f32 v[28:29], v[72:73], v[28:29], v[180:181]
	v_pk_fma_f32 v[26:27], v[74:75], v[26:27], v[178:179]
	v_pk_add_f32 v[22:23], v[22:23], v[32:33]
	v_pk_add_f32 v[18:19], v[18:19], v[26:27]
	v_pk_add_f32 v[16:17], v[16:17], v[28:29]
	v_cvt_pk_bf16_f32 v20, v20, v21
	v_cvt_pk_bf16_f32 v21, v22, v23
	s_nop 0
	v_cvt_pk_bf16_f32 v22, v16, v17
	v_cvt_pk_bf16_f32 v23, v18, v19
	v_lshlrev_b32_e32 v16, 16, v20
	v_and_b32_e32 v18, 0xffff0000, v20
	v_lshlrev_b32_e32 v26, 16, v21
	v_and_b32_e32 v28, 0xffff0000, v21
	v_lshlrev_b32_e32 v30, 16, v22
	v_and_b32_e32 v32, 0xffff0000, v22
	v_lshlrev_b32_e32 v34, 16, v23
	v_and_b32_e32 v36, 0xffff0000, v23
	v_mul_f32_e32 v17, v16, v16
	v_mul_f32_e32 v19, v18, v18
	v_mul_f32_e32 v27, v26, v26
	v_mul_f32_e32 v29, v28, v28
	v_mul_f32_e32 v31, v30, v30
	v_mul_f32_e32 v33, v32, v32
	v_mul_f32_e32 v35, v34, v34
	v_mul_f32_e32 v37, v36, v36
	v_pk_add_f32 v[16:17], v[16:17], v[18:19]
	v_pk_add_f32 v[18:19], v[26:27], v[28:29]
	v_pk_add_f32 v[26:27], v[34:35], v[36:37]
	v_pk_add_f32 v[16:17], v[16:17], v[18:19]
	v_pk_add_f32 v[18:19], v[30:31], v[32:33]
	global_store_dwordx4 v[24:25], v[20:23], off offset:128
	v_pk_add_f32 v[18:19], v[18:19], v[26:27]
	s_nop 0
	v_pk_add_f32 v[16:17], v[16:17], v[18:19]
	v_mov_b32_e32 v18, v165
	v_mov_b32_e32 v19, v165
	s_nop 0
	v_mov_b32_dpp v18, v16 quad_perm:[1,0,3,2] row_mask:0xf bank_mask:0xf
	v_mov_b32_dpp v19, v17 quad_perm:[1,0,3,2] row_mask:0xf bank_mask:0xf
	v_pk_add_f32 v[16:17], v[16:17], v[18:19]
	v_mov_b32_e32 v18, v16
	v_mov_b32_e32 v19, v17
	s_nop 1
	v_permlane16_swap_b32_e32 v16, v18
	v_permlane16_swap_b32_e32 v17, v19
	s_waitcnt lgkmcnt(0)
	v_pk_add_f32 v[16:17], v[16:17], v[18:19]
	v_mov_b32_e32 v18, v16
	v_mov_b32_e32 v19, v17
	s_nop 1
	v_permlane32_swap_b32_e32 v16, v18
	v_permlane32_swap_b32_e32 v17, v19
	s_and_saveexec_b64 s[56:57], s[12:13]
	s_cbranch_execz .LBB0_1725
	s_waitcnt lgkmcnt(0)
	v_pk_add_f32 v[16:17], v[16:17], v[18:19]
	v_add_co_u32_e32 v18, vcc, 0x14000, v186
	s_nop 1
	v_addc_co_u32_e32 v19, vcc, 0, v187, vcc
	global_store_dwordx2 v[18:19], v[16:17], off offset:512
.LBB0_1725:
	s_or_b64 exec, exec, s[56:57]
	s_waitcnt lgkmcnt(0)
	v_cndmask_b32_e64 v18, v12, v4, s[6:7]
	v_mov_b32_e32 v16, 0
	v_cndmask_b32_e64 v17, v13, v5, s[6:7]
	s_waitcnt lgkmcnt(0)
	v_cndmask_b32_e64 v19, v14, v6, s[6:7]
	v_mov_b32_dpp v16, v18 quad_perm:[1,0,3,2] row_mask:0xf bank_mask:0xf
	v_mov_b32_e32 v18, 0
	v_cndmask_b32_e64 v20, v15, v7, s[6:7]
	v_cndmask_b32_e64 v22, v8, v0, s[6:7]
	v_mov_b32_dpp v18, v17 quad_perm:[1,0,3,2] row_mask:0xf bank_mask:0xf
	v_mov_b32_e32 v17, 0
	v_cndmask_b32_e64 v21, v9, v1, s[6:7]
	v_cndmask_b32_e64 v23, v10, v2, s[6:7]
	v_mov_b32_dpp v17, v19 quad_perm:[1,0,3,2] row_mask:0xf bank_mask:0xf
	v_mov_b32_e32 v19, 0
	v_cndmask_b32_e64 v24, v11, v3, s[6:7]
	s_waitcnt vmcnt(13)
	v_lshlrev_b32_e32 v27, 16, v68
	v_mov_b32_dpp v19, v20 quad_perm:[1,0,3,2] row_mask:0xf bank_mask:0xf
	v_mov_b32_e32 v20, 0
	v_and_b32_e32 v28, 0xffff0000, v68
	v_cndmask_b32_e64 v13, v18, v13, s[6:7]
	v_mov_b32_dpp v20, v22 quad_perm:[1,0,3,2] row_mask:0xf bank_mask:0xf
	v_mov_b32_e32 v22, 0
	v_cndmask_b32_e64 v12, v16, v12, s[6:7]
	v_lshlrev_b32_e32 v30, 16, v69
	v_mov_b32_dpp v22, v21 quad_perm:[1,0,3,2] row_mask:0xf bank_mask:0xf
	v_mov_b32_e32 v21, 0
	v_and_b32_e32 v31, 0xffff0000, v69
	v_lshlrev_b32_e32 v32, 16, v70
	v_mov_b32_dpp v21, v23 quad_perm:[1,0,3,2] row_mask:0xf bank_mask:0xf
	v_mov_b32_e32 v23, 0
	v_and_b32_e32 v33, 0xffff0000, v70
	v_lshlrev_b32_e32 v34, 16, v71
	v_mov_b32_dpp v23, v24 quad_perm:[1,0,3,2] row_mask:0xf bank_mask:0xf
	ds_read_b64 v[24:25], v201 offset:1408
	v_and_b32_e32 v35, 0xffff0000, v71
	v_cndmask_b32_e64 v15, v19, v15, s[6:7]
	v_cndmask_b32_e64 v14, v17, v14, s[6:7]
	v_cndmask_b32_e64 v9, v22, v9, s[6:7]
	s_waitcnt lgkmcnt(0)
; __device__ __forceinline__ u32x4 pack8f(f32x4 a, f32x4 b) { u32x4 w; w.x = cvt_pk_bf16(a[0], a[1]); w.y = cvt_pk_bf16(a[2], a[3]); w.z = cvt_pk_bf16(b[0], b[1]); w.w = cvt_pk_bf16(b[2], b[3]); return w; }
;     __device__ __forceinline__ void operator()(const f32x4 (&acc)[2][2][4][2], const Unit& u, int wr, int wc, int fr, int fq, const EpiCtx& X) const {
;     ...
;             for (int m = 0; m < 4; ++m) {
;                 const int rl = ai * HALF + m * 16; const unsigned off = lo + (unsigned)(rl * 64) * 2u;
;                 const f32x4 o0a = acc[ai][0][m][0], o0b = acc[ai][0][m][1], o1a = acc[ai][1][m][0], o1b = acc[ai][1][m][1];
;                 const f32x4 ra_ = dpp_swap1(odd ? o0a : o1a), rb_ = dpp_swap1(odd ? o0b : o1b);
;                 const f32x4 pa[2] = {odd ? ra_ : o0a, odd ? o1a : ra_}, pb[2] = {odd ? rb_ : o0b, odd ? o1b : rb_};
; #pragma unroll
;                 for (int q = 0; q < 2; ++q) {
;                     const u32x4 w0 = raw[2 * m + q];
;                     const f32x4 r0 = (f32x4){bf_lo(w0.x), bf_hi(w0.x), bf_lo(w0.y), bf_hi(w0.y)}, r1 = (f32x4){bf_lo(w0.z), bf_hi(w0.z), bf_lo(w0.w), bf_hi(w0.w)};
;                     f32x4 y0, y1;
;                     if (RESN) { const f32x2 t = tbl[rl + q]; const float mu = t.x, ra = t.y * ALPHA; y0 = (r0 - mu) * ra * g0 + b0 + pa[q]; y1 = (r1 - mu) * ra * g1 + b1 + pb[q]; }
;                     else { y0 = r0 * ALPHA + pa[q]; y1 = r1 * ALPHA + pb[q]; }
;                     { const u32x4 w = pack8f(y0, y1); *(u32x4*)(xb + off + q * 128) = w;
;                         y0 = (f32x4){bf_lo(w.x), bf_hi(w.x), bf_lo(w.y), bf_hi(w.y)}; y1 = (f32x4){bf_lo(w.z), bf_hi(w.z), bf_lo(w.w), bf_hi(w.w)}; }
;                     float sa = ((y0[0] + y0[1]) + (y0[2] + y0[3])) + ((y1[0] + y1[1]) + (y1[2] + y1[3]));
;                     float sb = ((y0[0] * y0[0] + y0[1] * y0[1]) + (y0[2] * y0[2] + y0[3] * y0[3])) + ((y1[0] * y1[0] + y1[1] * y1[1]) + (y1[2] * y1[2] + y1[3] * y1[3]));
;                     sa += dpp_x1(sa);
;                     sb += dpp_x1(sb);
;                     sa += __shfl_xor(sa, 16); sa += __shfl_xor(sa, 32); sb += __shfl_xor(sb, 16); sb += __shfl_xor(sb, 32);
;                     if (fq == 0 && !odd) ps[(size_t)(rl + q) * 64] = (f32x2){sa, sb};
;                 }
	v_mul_f32_e32 v26, 0x3fb504f3, v25
	v_sub_f32_e32 v29, v28, v24
	v_sub_f32_e32 v28, v27, v24
	v_pk_mul_f32 v[28:29], v[28:29], v[26:27] op_sel_hi:[1,0]
	v_sub_f32_e32 v31, v31, v24
	v_pk_fma_f32 v[28:29], v[76:77], v[28:29], v[184:185]
	v_sub_f32_e32 v30, v30, v24
	v_pk_add_f32 v[12:13], v[12:13], v[28:29]
	v_sub_f32_e32 v29, v33, v24
	v_sub_f32_e32 v28, v32, v24
	v_sub_f32_e32 v25, v35, v24
	v_sub_f32_e32 v24, v34, v24
	v_pk_mul_f32 v[30:31], v[30:31], v[26:27] op_sel_hi:[1,0]
	v_pk_mul_f32 v[24:25], v[24:25], v[26:27] op_sel_hi:[1,0]
	v_pk_mul_f32 v[26:27], v[28:29], v[26:27] op_sel_hi:[1,0]
	v_cndmask_b32_e64 v8, v20, v8, s[6:7]
	v_cndmask_b32_e64 v11, v23, v11, s[6:7]
	v_cndmask_b32_e64 v10, v21, v10, s[6:7]
	v_pk_fma_f32 v[30:31], v[78:79], v[30:31], v[182:183]
	v_pk_fma_f32 v[26:27], v[72:73], v[26:27], v[180:181]
	v_pk_fma_f32 v[24:25], v[74:75], v[24:25], v[178:179]
	v_pk_add_f32 v[14:15], v[14:15], v[30:31]
	v_pk_add_f32 v[10:11], v[10:11], v[24:25]
	v_pk_add_f32 v[8:9], v[8:9], v[26:27]
	v_cvt_pk_bf16_f32 v24, v12, v13
	v_cvt_pk_bf16_f32 v25, v14, v15
	s_nop 0
	v_cvt_pk_bf16_f32 v26, v8, v9
	v_cvt_pk_bf16_f32 v27, v10, v11
	v_lshlrev_b32_e32 v8, 16, v24
	v_and_b32_e32 v10, 0xffff0000, v24
	v_lshlrev_b32_e32 v12, 16, v25
	v_and_b32_e32 v14, 0xffff0000, v25
	v_lshlrev_b32_e32 v28, 16, v26
	v_and_b32_e32 v30, 0xffff0000, v26
	v_lshlrev_b32_e32 v32, 16, v27
	v_and_b32_e32 v34, 0xffff0000, v27
	v_mul_f32_e32 v9, v8, v8
	v_mul_f32_e32 v11, v10, v10
	v_mul_f32_e32 v13, v12, v12
	v_mul_f32_e32 v15, v14, v14
	v_mul_f32_e32 v29, v28, v28
	v_mul_f32_e32 v31, v30, v30
	v_mul_f32_e32 v33, v32, v32
	v_mul_f32_e32 v35, v34, v34
	v_pk_add_f32 v[8:9], v[8:9], v[10:11]
	v_pk_add_f32 v[10:11], v[12:13], v[14:15]
	v_pk_add_f32 v[12:13], v[32:33], v[34:35]
	v_pk_add_f32 v[8:9], v[8:9], v[10:11]
	v_pk_add_f32 v[10:11], v[28:29], v[30:31]
	s_nop 0
	v_pk_add_f32 v[10:11], v[10:11], v[12:13]
	s_nop 0
	v_pk_add_f32 v[8:9], v[8:9], v[10:11]
	v_mov_b32_e32 v10, v165
	v_mov_b32_e32 v11, v165
	s_nop 0
	v_mov_b32_dpp v10, v8 quad_perm:[1,0,3,2] row_mask:0xf bank_mask:0xf
	v_mov_b32_dpp v11, v9 quad_perm:[1,0,3,2] row_mask:0xf bank_mask:0xf
	v_pk_add_f32 v[8:9], v[8:9], v[10:11]
	v_mov_b32_e32 v10, v8
	v_mov_b32_e32 v11, v9
	s_nop 1
	v_permlane16_swap_b32_e32 v8, v10
	v_permlane16_swap_b32_e32 v9, v11
	s_waitcnt lgkmcnt(0)
	v_pk_add_f32 v[10:11], v[8:9], v[10:11]
	v_mov_b32_e32 v12, v10
	v_mov_b32_e32 v13, v11
	s_nop 1
	v_permlane32_swap_b32_e32 v10, v12
	v_permlane32_swap_b32_e32 v11, v13
	v_lshl_add_u64 v[8:9], s[16:17], 0, v[164:165]
	global_store_dwordx4 v[8:9], v[24:27], off
	s_and_saveexec_b64 s[16:17], s[12:13]
	s_cbranch_execz .LBB0_1727
	s_waitcnt lgkmcnt(0)
	v_pk_add_f32 v[10:11], v[10:11], v[12:13]
	v_add_co_u32_e32 v12, vcc, 0x16000, v186
	s_nop 1
	v_addc_co_u32_e32 v13, vcc, 0, v187, vcc
	global_store_dwordx2 v[12:13], v[10:11], off
.LBB0_1727:
	s_or_b64 exec, exec, s[16:17]
	ds_read_b64 v[10:11], v201 offset:1416
	s_waitcnt vmcnt(14) lgkmcnt(1)
	v_lshlrev_b32_e32 v13, 16, v64
	v_and_b32_e32 v14, 0xffff0000, v64
	v_cndmask_b32_e64 v5, v5, v18, s[6:7]
	v_cndmask_b32_e64 v4, v4, v16, s[6:7]
	s_waitcnt lgkmcnt(0)
	v_mul_f32_e32 v12, 0x3fb504f3, v11
	v_sub_f32_e32 v15, v14, v10
	v_sub_f32_e32 v14, v13, v10
	v_pk_mul_f32 v[14:15], v[14:15], v[12:13] op_sel_hi:[1,0]
	v_cndmask_b32_e64 v7, v7, v19, s[6:7]
	v_cndmask_b32_e64 v6, v6, v17, s[6:7]
	v_cndmask_b32_e64 v0, v0, v20, s[6:7]
	v_cndmask_b32_e64 v2, v2, v21, s[6:7]
	v_lshlrev_b32_e32 v16, 16, v65
	v_and_b32_e32 v17, 0xffff0000, v65
	v_lshlrev_b32_e32 v18, 16, v66
	v_and_b32_e32 v19, 0xffff0000, v66
	v_lshlrev_b32_e32 v20, 16, v67
	v_and_b32_e32 v21, 0xffff0000, v67
	v_pk_fma_f32 v[14:15], v[76:77], v[14:15], v[184:185]
	v_sub_f32_e32 v17, v17, v10
	v_sub_f32_e32 v16, v16, v10
	v_pk_add_f32 v[4:5], v[4:5], v[14:15]
	v_sub_f32_e32 v15, v19, v10
	v_sub_f32_e32 v14, v18, v10
	v_sub_f32_e32 v11, v21, v10
	v_sub_f32_e32 v10, v20, v10
	v_pk_mul_f32 v[16:17], v[16:17], v[12:13] op_sel_hi:[1,0]
	v_pk_mul_f32 v[10:11], v[10:11], v[12:13] op_sel_hi:[1,0]
	v_pk_mul_f32 v[12:13], v[14:15], v[12:13] op_sel_hi:[1,0]
	v_cndmask_b32_e64 v1, v1, v22, s[6:7]
	v_cndmask_b32_e64 v3, v3, v23, s[6:7]
	v_pk_fma_f32 v[16:17], v[78:79], v[16:17], v[182:183]
	v_pk_fma_f32 v[12:13], v[72:73], v[12:13], v[180:181]
	v_pk_fma_f32 v[10:11], v[74:75], v[10:11], v[178:179]
	v_pk_add_f32 v[6:7], v[6:7], v[16:17]
	v_pk_add_f32 v[2:3], v[2:3], v[10:11]
	v_pk_add_f32 v[0:1], v[0:1], v[12:13]
	v_cvt_pk_bf16_f32 v4, v4, v5
	v_cvt_pk_bf16_f32 v5, v6, v7
	s_nop 0
	v_cvt_pk_bf16_f32 v6, v0, v1
	v_cvt_pk_bf16_f32 v7, v2, v3
	v_lshlrev_b32_e32 v0, 16, v4
	v_and_b32_e32 v2, 0xffff0000, v4
	v_lshlrev_b32_e32 v10, 16, v5
	v_and_b32_e32 v12, 0xffff0000, v5
	v_lshlrev_b32_e32 v14, 16, v6
	v_and_b32_e32 v16, 0xffff0000, v6
	v_lshlrev_b32_e32 v18, 16, v7
	v_and_b32_e32 v20, 0xffff0000, v7
	v_mul_f32_e32 v1, v0, v0
	v_mul_f32_e32 v3, v2, v2
	v_mul_f32_e32 v11, v10, v10
	v_mul_f32_e32 v13, v12, v12
	v_mul_f32_e32 v15, v14, v14
	v_mul_f32_e32 v17, v16, v16
	v_mul_f32_e32 v19, v18, v18
	v_mul_f32_e32 v21, v20, v20
	v_pk_add_f32 v[0:1], v[0:1], v[2:3]
	v_pk_add_f32 v[2:3], v[10:11], v[12:13]
	v_pk_add_f32 v[10:11], v[18:19], v[20:21]
	v_pk_add_f32 v[0:1], v[0:1], v[2:3]
	v_pk_add_f32 v[2:3], v[14:15], v[16:17]
	global_store_dwordx4 v[8:9], v[4:7], off offset:128
	v_pk_add_f32 v[2:3], v[2:3], v[10:11]
	s_nop 0
	v_pk_add_f32 v[0:1], v[0:1], v[2:3]
	v_mov_b32_e32 v2, v165
	v_mov_b32_e32 v3, v165
	s_nop 0
	v_mov_b32_dpp v2, v0 quad_perm:[1,0,3,2] row_mask:0xf bank_mask:0xf
	v_mov_b32_dpp v3, v1 quad_perm:[1,0,3,2] row_mask:0xf bank_mask:0xf
	v_pk_add_f32 v[0:1], v[0:1], v[2:3]
	v_mov_b32_e32 v2, v0
	v_mov_b32_e32 v3, v1
	s_nop 1
	v_permlane16_swap_b32_e32 v0, v2
	v_permlane16_swap_b32_e32 v1, v3
	s_waitcnt lgkmcnt(0)
	v_pk_add_f32 v[0:1], v[0:1], v[2:3]
	v_mov_b32_e32 v2, v0
	v_mov_b32_e32 v3, v1
	s_nop 1
	v_permlane32_swap_b32_e32 v0, v2
	v_permlane32_swap_b32_e32 v1, v3
	s_and_saveexec_b64 s[16:17], s[12:13]
	s_cbranch_execz .LBB0_1729
	s_waitcnt lgkmcnt(0)
	v_pk_add_f32 v[0:1], v[0:1], v[2:3]
	v_add_co_u32_e32 v2, vcc, 0x16000, v186
	s_nop 1
	v_addc_co_u32_e32 v3, vcc, 0, v187, vcc
	global_store_dwordx2 v[2:3], v[0:1], off offset:512
